# all units skip the accumulator reset (zero C operand in a peeled first trip), first unit keeps the original waits
# speedup vs baseline: 1.0012x; 1.0012x over previous
.LBB0_236:
	s_cmp_lt_i32 s18, 3
	s_cbranch_scc1 .Lhz_238
	s_add_i32 s2, s18, -2
	s_add_u32 s26, s4, s40
	s_addc_u32 s31, s5, s41
	s_add_u32 s33, s6, s22
	s_addc_u32 s46, s7, s23
	s_add_u32 s42, s16, s22
	s_addc_u32 s43, s17, s23
	s_add_u32 s47, s6, s42
	s_addc_u32 s48, s7, s43
	s_add_u32 s49, s6, s16
	s_addc_u32 s68, s7, s17
	s_add_u32 s42, s38, s40
	s_addc_u32 s43, s39, s41
	s_add_u32 s69, s4, s42
	s_addc_u32 s70, s5, s43
	s_add_u32 s71, s4, s38
	s_addc_u32 s72, s5, s39
	s_mov_b32 s74, 0
	s_mov_b64 s[42:43], 0
	s_cmp_eq_u32 s98, 0
	s_cbranch_scc1 .Lhf_238
	ds_read_b128 v[24:27], v191
	ds_read_b128 v[28:31], v191 offset:1024
	ds_read_b128 v[16:19], v191 offset:2048
	ds_read_b128 v[20:23], v191 offset:3072
	ds_read_b128 v[8:11], v192
	ds_read_b128 v[12:15], v192 offset:1024
	ds_read_b128 v[0:3], v192 offset:2048
	ds_read_b128 v[4:7], v192 offset:3072
	s_add_i32 s74, s74, 2
	s_add_u32 s75, s4, s42
	s_addc_u32 s77, s5, s43
	s_add_u32 s44, s75, 0x100
	s_addc_u32 s45, s77, 0
	s_add_u32 s80, s26, s42
	ds_read_b128 v[162:165], v193
	ds_read_b128 v[166:169], v193 offset:1024
	ds_read_b128 v[170:173], v193 offset:2048
	ds_read_b128 v[174:177], v193 offset:3072
	ds_read_b128 v[178:181], v193 offset:4096
	ds_read_b128 v[182:185], v193 offset:5120
	ds_read_b128 v[198:201], v193 offset:6144
	ds_read_b128 v[202:205], v193 offset:7168
	s_addc_u32 s81, s31, s43
	s_add_u32 s86, s80, 0x80
	s_addc_u32 s87, s81, 0
	s_add_u32 s83, s69, s42
	s_addc_u32 s84, s70, s43
	s_add_u32 s88, s83, 0x80
	s_mov_b32 m0, s78
	s_nop 0
	global_load_lds_dwordx4 v160, s[86:87]
	s_addc_u32 s89, s84, 0
	s_mov_b32 m0, s79
	s_nop 0
	global_load_lds_dwordx4 v160, s[88:89]
	s_waitcnt vmcnt(24)
	s_waitcnt lgkmcnt(0)
	s_barrier
	s_setprio 1
	s_waitcnt lgkmcnt(6)
	v_mfma_scale_f32_16x16x128_f8f6f4 v[156:159], v[24:31], v[162:169], 0, v195, v194 op_sel_hi:[0,0,0]
	v_mfma_scale_f32_16x16x128_f8f6f4 v[152:155], v[16:23], v[162:169], 0, v195, v194 op_sel_hi:[0,0,0]
	s_waitcnt lgkmcnt(4)
	v_mfma_scale_f32_16x16x128_f8f6f4 v[148:151], v[24:31], v[170:177], 0, v195, v194 op_sel_hi:[0,0,0]
	v_mfma_scale_f32_16x16x128_f8f6f4 v[144:147], v[16:23], v[170:177], 0, v195, v194 op_sel_hi:[0,0,0]
	s_waitcnt lgkmcnt(2)
	v_mfma_scale_f32_16x16x128_f8f6f4 v[140:143], v[24:31], v[178:185], 0, v195, v194 op_sel_hi:[0,0,0]
	v_mfma_scale_f32_16x16x128_f8f6f4 v[136:139], v[16:23], v[178:185], 0, v195, v194 op_sel_hi:[0,0,0]
	s_waitcnt lgkmcnt(0)
	v_mfma_scale_f32_16x16x128_f8f6f4 v[132:135], v[24:31], v[198:205], 0, v195, v194 op_sel_hi:[0,0,0]
	v_mfma_scale_f32_16x16x128_f8f6f4 v[128:131], v[16:23], v[198:205], 0, v195, v194 op_sel_hi:[0,0,0]
	s_setprio 0
	s_setprio 1
	v_mfma_scale_f32_16x16x128_f8f6f4 v[124:127], v[8:15], v[162:169], 0, v195, v194 op_sel_hi:[0,0,0]
	v_mfma_scale_f32_16x16x128_f8f6f4 v[120:123], v[0:7], v[162:169], 0, v195, v194 op_sel_hi:[0,0,0]
	v_mfma_scale_f32_16x16x128_f8f6f4 v[116:119], v[8:15], v[170:177], 0, v195, v194 op_sel_hi:[0,0,0]
	v_mfma_scale_f32_16x16x128_f8f6f4 v[112:115], v[0:7], v[170:177], 0, v195, v194 op_sel_hi:[0,0,0]
	v_mfma_scale_f32_16x16x128_f8f6f4 v[108:111], v[8:15], v[178:185], 0, v195, v194 op_sel_hi:[0,0,0]
	v_mfma_scale_f32_16x16x128_f8f6f4 v[104:107], v[0:7], v[178:185], 0, v195, v194 op_sel_hi:[0,0,0]
	v_mfma_scale_f32_16x16x128_f8f6f4 v[100:103], v[8:15], v[198:205], 0, v195, v194 op_sel_hi:[0,0,0]
	v_mfma_scale_f32_16x16x128_f8f6f4 v[96:99], v[0:7], v[198:205], 0, v195, v194 op_sel_hi:[0,0,0]
	s_setprio 0
	s_barrier
	s_add_u32 s85, s6, s42
	s_addc_u32 s86, s7, s43
	s_add_u32 s90, s85, 0x100
	s_addc_u32 s91, s86, 0
	s_add_u32 s87, s49, s42
	s_addc_u32 s88, s68, s43
	s_add_u32 s92, s87, 0x100
	s_addc_u32 s93, s88, 0
	s_add_u32 s89, s33, s42
	ds_read_b128 v[162:165], v193 offset:16384
	ds_read_b128 v[166:169], v193 offset:17408
	ds_read_b128 v[170:173], v193 offset:18432
	ds_read_b128 v[174:177], v193 offset:19456
	ds_read_b128 v[178:181], v193 offset:20480
	ds_read_b128 v[182:185], v193 offset:21504
	ds_read_b128 v[198:201], v193 offset:22528
	ds_read_b128 v[202:205], v193 offset:23552
	s_mov_b32 m0, s51
	s_nop 0
	global_load_lds_dwordx4 v161, s[90:91]
	s_addc_u32 s90, s46, s43
	s_add_u32 s96, s89, 0x100
	s_addc_u32 s97, s90, 0
	s_mov_b32 m0, s57
	s_nop 0
	global_load_lds_dwordx4 v161, s[92:93]
	s_add_u32 s93, s47, s42
	s_addc_u32 s94, s48, s43
	s_add_u32 s54, s93, 0x100
	s_mov_b32 m0, s58
	s_nop 0
	global_load_lds_dwordx4 v161, s[96:97]
	s_addc_u32 s55, s94, 0
	s_mov_b32 m0, s59
	s_nop 0
	global_load_lds_dwordx4 v161, s[54:55]
	s_add_u32 s91, s71, s42
	s_addc_u32 s92, s72, s43
	s_add_u32 s54, s91, 0x100
	s_mov_b32 m0, s53
	s_nop 0
	global_load_lds_dwordx4 v160, s[44:45]
	s_addc_u32 s55, s92, 0
	s_mov_b32 m0, s60
	s_nop 0
	global_load_lds_dwordx4 v160, s[54:55]
	s_waitcnt vmcnt(24)
	s_waitcnt lgkmcnt(0)
	s_barrier
	s_setprio 1
	s_waitcnt lgkmcnt(6)
	v_mfma_scale_f32_16x16x128_f8f6f4 v[92:95], v[24:31], v[162:169], 0, v195, v194 op_sel_hi:[0,0,0]
	v_mfma_scale_f32_16x16x128_f8f6f4 v[88:91], v[16:23], v[162:169], 0, v195, v194 op_sel_hi:[0,0,0]
	s_waitcnt lgkmcnt(4)
	v_mfma_scale_f32_16x16x128_f8f6f4 v[84:87], v[24:31], v[170:177], 0, v195, v194 op_sel_hi:[0,0,0]
	v_mfma_scale_f32_16x16x128_f8f6f4 v[80:83], v[16:23], v[170:177], 0, v195, v194 op_sel_hi:[0,0,0]
	s_waitcnt lgkmcnt(2)
	v_mfma_scale_f32_16x16x128_f8f6f4 v[76:79], v[24:31], v[178:185], 0, v195, v194 op_sel_hi:[0,0,0]
	v_mfma_scale_f32_16x16x128_f8f6f4 v[72:75], v[16:23], v[178:185], 0, v195, v194 op_sel_hi:[0,0,0]
	s_waitcnt lgkmcnt(0)
	v_mfma_scale_f32_16x16x128_f8f6f4 v[68:71], v[24:31], v[198:205], 0, v195, v194 op_sel_hi:[0,0,0]
	v_mfma_scale_f32_16x16x128_f8f6f4 v[64:67], v[16:23], v[198:205], 0, v195, v194 op_sel_hi:[0,0,0]
	s_setprio 0
	s_setprio 1
	v_mfma_scale_f32_16x16x128_f8f6f4 v[60:63], v[8:15], v[162:169], 0, v195, v194 op_sel_hi:[0,0,0]
	v_mfma_scale_f32_16x16x128_f8f6f4 v[56:59], v[0:7], v[162:169], 0, v195, v194 op_sel_hi:[0,0,0]
	v_mfma_scale_f32_16x16x128_f8f6f4 v[52:55], v[8:15], v[170:177], 0, v195, v194 op_sel_hi:[0,0,0]
	v_mfma_scale_f32_16x16x128_f8f6f4 v[48:51], v[0:7], v[170:177], 0, v195, v194 op_sel_hi:[0,0,0]
	v_mfma_scale_f32_16x16x128_f8f6f4 v[44:47], v[8:15], v[178:185], 0, v195, v194 op_sel_hi:[0,0,0]
	v_mfma_scale_f32_16x16x128_f8f6f4 v[40:43], v[0:7], v[178:185], 0, v195, v194 op_sel_hi:[0,0,0]
	v_mfma_scale_f32_16x16x128_f8f6f4 v[36:39], v[8:15], v[198:205], 0, v195, v194 op_sel_hi:[0,0,0]
	v_mfma_scale_f32_16x16x128_f8f6f4 v[32:35], v[0:7], v[198:205], 0, v195, v194 op_sel_hi:[0,0,0]
	s_setprio 0
	s_barrier
	ds_read_b128 v[24:27], v196
	ds_read_b128 v[28:31], v196 offset:1024
	ds_read_b128 v[16:19], v196 offset:2048
	ds_read_b128 v[20:23], v196 offset:3072
	ds_read_b128 v[8:11], v197
	ds_read_b128 v[12:15], v197 offset:1024
	ds_read_b128 v[0:3], v197 offset:2048
	ds_read_b128 v[4:7], v197 offset:3072
	ds_read_b128 v[162:165], v193 offset:32768
	ds_read_b128 v[166:169], v193 offset:33792
	ds_read_b128 v[170:173], v193 offset:34816
	ds_read_b128 v[174:177], v193 offset:35840
	ds_read_b128 v[178:181], v193 offset:36864
	ds_read_b128 v[182:185], v193 offset:37888
	ds_read_b128 v[198:201], v193 offset:38912
	ds_read_b128 v[202:205], v193 offset:39936
	s_add_u32 s44, s80, 0x100
	s_addc_u32 s45, s81, 0
	s_add_u32 s54, s83, 0x100
	s_mov_b32 m0, s61
	s_nop 0
	global_load_lds_dwordx4 v160, s[44:45]
	s_addc_u32 s55, s84, 0
	s_mov_b32 m0, s62
	s_nop 0
	global_load_lds_dwordx4 v160, s[54:55]
	s_waitcnt vmcnt(8)
	s_waitcnt lgkmcnt(0)
	s_barrier
	s_setprio 1
	s_waitcnt lgkmcnt(6)
	v_mfma_scale_f32_16x16x128_f8f6f4 v[156:159], v[24:31], v[162:169], v[156:159], v195, v194 op_sel_hi:[0,0,0]
	v_mfma_scale_f32_16x16x128_f8f6f4 v[152:155], v[16:23], v[162:169], v[152:155], v195, v194 op_sel_hi:[0,0,0]
	s_waitcnt lgkmcnt(4)
	v_mfma_scale_f32_16x16x128_f8f6f4 v[148:151], v[24:31], v[170:177], v[148:151], v195, v194 op_sel_hi:[0,0,0]
	v_mfma_scale_f32_16x16x128_f8f6f4 v[144:147], v[16:23], v[170:177], v[144:147], v195, v194 op_sel_hi:[0,0,0]
	s_waitcnt lgkmcnt(2)
	v_mfma_scale_f32_16x16x128_f8f6f4 v[140:143], v[24:31], v[178:185], v[140:143], v195, v194 op_sel_hi:[0,0,0]
	v_mfma_scale_f32_16x16x128_f8f6f4 v[136:139], v[16:23], v[178:185], v[136:139], v195, v194 op_sel_hi:[0,0,0]
	s_waitcnt lgkmcnt(0)
	v_mfma_scale_f32_16x16x128_f8f6f4 v[132:135], v[24:31], v[198:205], v[132:135], v195, v194 op_sel_hi:[0,0,0]
	v_mfma_scale_f32_16x16x128_f8f6f4 v[128:131], v[16:23], v[198:205], v[128:131], v195, v194 op_sel_hi:[0,0,0]
	s_setprio 0
	s_setprio 1
	v_mfma_scale_f32_16x16x128_f8f6f4 v[124:127], v[8:15], v[162:169], v[124:127], v195, v194 op_sel_hi:[0,0,0]
	v_mfma_scale_f32_16x16x128_f8f6f4 v[120:123], v[0:7], v[162:169], v[120:123], v195, v194 op_sel_hi:[0,0,0]
	v_mfma_scale_f32_16x16x128_f8f6f4 v[116:119], v[8:15], v[170:177], v[116:119], v195, v194 op_sel_hi:[0,0,0]
	v_mfma_scale_f32_16x16x128_f8f6f4 v[112:115], v[0:7], v[170:177], v[112:115], v195, v194 op_sel_hi:[0,0,0]
	v_mfma_scale_f32_16x16x128_f8f6f4 v[108:111], v[8:15], v[178:185], v[108:111], v195, v194 op_sel_hi:[0,0,0]
	v_mfma_scale_f32_16x16x128_f8f6f4 v[104:107], v[0:7], v[178:185], v[104:107], v195, v194 op_sel_hi:[0,0,0]
	v_mfma_scale_f32_16x16x128_f8f6f4 v[100:103], v[8:15], v[198:205], v[100:103], v195, v194 op_sel_hi:[0,0,0]
	v_mfma_scale_f32_16x16x128_f8f6f4 v[96:99], v[0:7], v[198:205], v[96:99], v195, v194 op_sel_hi:[0,0,0]
	s_setprio 0
	s_barrier
	s_add_u32 s44, s85, 0x180
	s_addc_u32 s45, s86, 0
	ds_read_b128 v[162:165], v193 offset:49152
	ds_read_b128 v[166:169], v193 offset:50176
	ds_read_b128 v[170:173], v193 offset:51200
	ds_read_b128 v[174:177], v193 offset:52224
	ds_read_b128 v[178:181], v193 offset:53248
	ds_read_b128 v[182:185], v193 offset:54272
	ds_read_b128 v[198:201], v193 offset:55296
	ds_read_b128 v[202:205], v193 offset:56320
	s_add_u32 s54, s87, 0x180
	s_mov_b32 m0, s63
	s_nop 0
	global_load_lds_dwordx4 v161, s[44:45]
	s_addc_u32 s55, s88, 0
	s_mov_b32 m0, s64
	s_nop 0
	global_load_lds_dwordx4 v161, s[54:55]
	s_add_u32 s44, s89, 0x180
	s_addc_u32 s45, s90, 0
	s_add_u32 s54, s93, 0x180
	s_mov_b32 m0, s67
	s_nop 0
	global_load_lds_dwordx4 v161, s[44:45]
	s_addc_u32 s55, s94, 0
	s_mov_b32 m0, s73
	s_nop 0
	global_load_lds_dwordx4 v161, s[54:55]
	s_add_u32 s44, s75, 0x180
	s_addc_u32 s45, s77, 0
	s_add_u32 s54, s91, 0x180
	s_mov_b32 m0, s65
	s_nop 0
	global_load_lds_dwordx4 v160, s[44:45]
	s_addc_u32 s55, s92, 0
	s_mov_b32 m0, s66
	s_nop 0
	global_load_lds_dwordx4 v160, s[54:55]
	s_waitcnt vmcnt(8)
	s_waitcnt lgkmcnt(0)
	s_barrier
	s_setprio 1
	s_waitcnt lgkmcnt(6)
	v_mfma_scale_f32_16x16x128_f8f6f4 v[92:95], v[24:31], v[162:169], v[92:95], v195, v194 op_sel_hi:[0,0,0]
	v_mfma_scale_f32_16x16x128_f8f6f4 v[88:91], v[16:23], v[162:169], v[88:91], v195, v194 op_sel_hi:[0,0,0]
	s_waitcnt lgkmcnt(4)
	v_mfma_scale_f32_16x16x128_f8f6f4 v[84:87], v[24:31], v[170:177], v[84:87], v195, v194 op_sel_hi:[0,0,0]
	v_mfma_scale_f32_16x16x128_f8f6f4 v[80:83], v[16:23], v[170:177], v[80:83], v195, v194 op_sel_hi:[0,0,0]
	s_waitcnt lgkmcnt(2)
	v_mfma_scale_f32_16x16x128_f8f6f4 v[76:79], v[24:31], v[178:185], v[76:79], v195, v194 op_sel_hi:[0,0,0]
	v_mfma_scale_f32_16x16x128_f8f6f4 v[72:75], v[16:23], v[178:185], v[72:75], v195, v194 op_sel_hi:[0,0,0]
	s_waitcnt lgkmcnt(0)
	v_mfma_scale_f32_16x16x128_f8f6f4 v[68:71], v[24:31], v[198:205], v[68:71], v195, v194 op_sel_hi:[0,0,0]
	v_mfma_scale_f32_16x16x128_f8f6f4 v[64:67], v[16:23], v[198:205], v[64:67], v195, v194 op_sel_hi:[0,0,0]
	s_setprio 0
	s_setprio 1
	v_mfma_scale_f32_16x16x128_f8f6f4 v[60:63], v[8:15], v[162:169], v[60:63], v195, v194 op_sel_hi:[0,0,0]
	v_mfma_scale_f32_16x16x128_f8f6f4 v[56:59], v[0:7], v[162:169], v[56:59], v195, v194 op_sel_hi:[0,0,0]
	v_mfma_scale_f32_16x16x128_f8f6f4 v[52:55], v[8:15], v[170:177], v[52:55], v195, v194 op_sel_hi:[0,0,0]
	v_mfma_scale_f32_16x16x128_f8f6f4 v[48:51], v[0:7], v[170:177], v[48:51], v195, v194 op_sel_hi:[0,0,0]
	v_mfma_scale_f32_16x16x128_f8f6f4 v[44:47], v[8:15], v[178:185], v[44:47], v195, v194 op_sel_hi:[0,0,0]
	v_mfma_scale_f32_16x16x128_f8f6f4 v[40:43], v[0:7], v[178:185], v[40:43], v195, v194 op_sel_hi:[0,0,0]
	v_mfma_scale_f32_16x16x128_f8f6f4 v[36:39], v[8:15], v[198:205], v[36:39], v195, v194 op_sel_hi:[0,0,0]
	v_mfma_scale_f32_16x16x128_f8f6f4 v[32:35], v[0:7], v[198:205], v[32:35], v195, v194 op_sel_hi:[0,0,0]
	s_setprio 0
	s_barrier
	s_add_u32 s42, s42, 0x100
	s_addc_u32 s43, s43, 0
	s_cmp_ge_i32 s74, s2
	s_cbranch_scc0 .LBB0_238
	s_branch .LBB0_239
.Lhf_238:
	ds_read_b128 v[24:27], v191
	ds_read_b128 v[28:31], v191 offset:1024
	ds_read_b128 v[16:19], v191 offset:2048
	ds_read_b128 v[20:23], v191 offset:3072
	ds_read_b128 v[8:11], v192
	ds_read_b128 v[12:15], v192 offset:1024
	ds_read_b128 v[0:3], v192 offset:2048
	ds_read_b128 v[4:7], v192 offset:3072
	s_add_i32 s74, s74, 2
	s_add_u32 s75, s4, s42
	s_addc_u32 s77, s5, s43
	s_add_u32 s44, s75, 0x100
	s_addc_u32 s45, s77, 0
	s_add_u32 s80, s26, s42
	ds_read_b128 v[162:165], v193
	ds_read_b128 v[166:169], v193 offset:1024
	ds_read_b128 v[170:173], v193 offset:2048
	ds_read_b128 v[174:177], v193 offset:3072
	ds_read_b128 v[178:181], v193 offset:4096
	ds_read_b128 v[182:185], v193 offset:5120
	ds_read_b128 v[198:201], v193 offset:6144
	ds_read_b128 v[202:205], v193 offset:7168
	s_addc_u32 s81, s31, s43
	s_add_u32 s86, s80, 0x80
	s_addc_u32 s87, s81, 0
	s_add_u32 s83, s69, s42
	s_addc_u32 s84, s70, s43
	s_add_u32 s88, s83, 0x80
	s_mov_b32 m0, s78
	s_nop 0
	global_load_lds_dwordx4 v160, s[86:87]
	s_addc_u32 s89, s84, 0
	s_mov_b32 m0, s79
	s_nop 0
	global_load_lds_dwordx4 v160, s[88:89]
	s_waitcnt vmcnt(8)
	s_waitcnt lgkmcnt(0)
	s_barrier
	s_setprio 1
	s_waitcnt lgkmcnt(6)
	v_mfma_scale_f32_16x16x128_f8f6f4 v[156:159], v[24:31], v[162:169], 0, v195, v194 op_sel_hi:[0,0,0]
	v_mfma_scale_f32_16x16x128_f8f6f4 v[152:155], v[16:23], v[162:169], 0, v195, v194 op_sel_hi:[0,0,0]
	s_waitcnt lgkmcnt(4)
	v_mfma_scale_f32_16x16x128_f8f6f4 v[148:151], v[24:31], v[170:177], 0, v195, v194 op_sel_hi:[0,0,0]
	v_mfma_scale_f32_16x16x128_f8f6f4 v[144:147], v[16:23], v[170:177], 0, v195, v194 op_sel_hi:[0,0,0]
	s_waitcnt lgkmcnt(2)
	v_mfma_scale_f32_16x16x128_f8f6f4 v[140:143], v[24:31], v[178:185], 0, v195, v194 op_sel_hi:[0,0,0]
	v_mfma_scale_f32_16x16x128_f8f6f4 v[136:139], v[16:23], v[178:185], 0, v195, v194 op_sel_hi:[0,0,0]
	s_waitcnt lgkmcnt(0)
	v_mfma_scale_f32_16x16x128_f8f6f4 v[132:135], v[24:31], v[198:205], 0, v195, v194 op_sel_hi:[0,0,0]
	v_mfma_scale_f32_16x16x128_f8f6f4 v[128:131], v[16:23], v[198:205], 0, v195, v194 op_sel_hi:[0,0,0]
	s_setprio 0
	s_setprio 1
	v_mfma_scale_f32_16x16x128_f8f6f4 v[124:127], v[8:15], v[162:169], 0, v195, v194 op_sel_hi:[0,0,0]
	v_mfma_scale_f32_16x16x128_f8f6f4 v[120:123], v[0:7], v[162:169], 0, v195, v194 op_sel_hi:[0,0,0]
	v_mfma_scale_f32_16x16x128_f8f6f4 v[116:119], v[8:15], v[170:177], 0, v195, v194 op_sel_hi:[0,0,0]
	v_mfma_scale_f32_16x16x128_f8f6f4 v[112:115], v[0:7], v[170:177], 0, v195, v194 op_sel_hi:[0,0,0]
	v_mfma_scale_f32_16x16x128_f8f6f4 v[108:111], v[8:15], v[178:185], 0, v195, v194 op_sel_hi:[0,0,0]
	v_mfma_scale_f32_16x16x128_f8f6f4 v[104:107], v[0:7], v[178:185], 0, v195, v194 op_sel_hi:[0,0,0]
	v_mfma_scale_f32_16x16x128_f8f6f4 v[100:103], v[8:15], v[198:205], 0, v195, v194 op_sel_hi:[0,0,0]
	v_mfma_scale_f32_16x16x128_f8f6f4 v[96:99], v[0:7], v[198:205], 0, v195, v194 op_sel_hi:[0,0,0]
	s_setprio 0
	s_barrier
	s_add_u32 s85, s6, s42
	s_addc_u32 s86, s7, s43
	s_add_u32 s90, s85, 0x100
	s_addc_u32 s91, s86, 0
	s_add_u32 s87, s49, s42
	s_addc_u32 s88, s68, s43
	s_add_u32 s92, s87, 0x100
	s_addc_u32 s93, s88, 0
	s_add_u32 s89, s33, s42
	ds_read_b128 v[162:165], v193 offset:16384
	ds_read_b128 v[166:169], v193 offset:17408
	ds_read_b128 v[170:173], v193 offset:18432
	ds_read_b128 v[174:177], v193 offset:19456
	ds_read_b128 v[178:181], v193 offset:20480
	ds_read_b128 v[182:185], v193 offset:21504
	ds_read_b128 v[198:201], v193 offset:22528
	ds_read_b128 v[202:205], v193 offset:23552
	s_mov_b32 m0, s51
	s_nop 0
	global_load_lds_dwordx4 v161, s[90:91]
	s_addc_u32 s90, s46, s43
	s_add_u32 s96, s89, 0x100
	s_addc_u32 s97, s90, 0
	s_mov_b32 m0, s57
	s_nop 0
	global_load_lds_dwordx4 v161, s[92:93]
	s_add_u32 s93, s47, s42
	s_addc_u32 s94, s48, s43
	s_add_u32 s54, s93, 0x100
	s_mov_b32 m0, s58
	s_nop 0
	global_load_lds_dwordx4 v161, s[96:97]
	s_addc_u32 s55, s94, 0
	s_mov_b32 m0, s59
	s_nop 0
	global_load_lds_dwordx4 v161, s[54:55]
	s_add_u32 s91, s71, s42
	s_addc_u32 s92, s72, s43
	s_add_u32 s54, s91, 0x100
	s_mov_b32 m0, s53
	s_nop 0
	global_load_lds_dwordx4 v160, s[44:45]
	s_addc_u32 s55, s92, 0
	s_mov_b32 m0, s60
	s_nop 0
	global_load_lds_dwordx4 v160, s[54:55]
	s_waitcnt vmcnt(8)
	s_waitcnt lgkmcnt(0)
	s_barrier
	s_setprio 1
	s_waitcnt lgkmcnt(6)
	v_mfma_scale_f32_16x16x128_f8f6f4 v[92:95], v[24:31], v[162:169], 0, v195, v194 op_sel_hi:[0,0,0]
	v_mfma_scale_f32_16x16x128_f8f6f4 v[88:91], v[16:23], v[162:169], 0, v195, v194 op_sel_hi:[0,0,0]
	s_waitcnt lgkmcnt(4)
	v_mfma_scale_f32_16x16x128_f8f6f4 v[84:87], v[24:31], v[170:177], 0, v195, v194 op_sel_hi:[0,0,0]
	v_mfma_scale_f32_16x16x128_f8f6f4 v[80:83], v[16:23], v[170:177], 0, v195, v194 op_sel_hi:[0,0,0]
	s_waitcnt lgkmcnt(2)
	v_mfma_scale_f32_16x16x128_f8f6f4 v[76:79], v[24:31], v[178:185], 0, v195, v194 op_sel_hi:[0,0,0]
	v_mfma_scale_f32_16x16x128_f8f6f4 v[72:75], v[16:23], v[178:185], 0, v195, v194 op_sel_hi:[0,0,0]
	s_waitcnt lgkmcnt(0)
	v_mfma_scale_f32_16x16x128_f8f6f4 v[68:71], v[24:31], v[198:205], 0, v195, v194 op_sel_hi:[0,0,0]
	v_mfma_scale_f32_16x16x128_f8f6f4 v[64:67], v[16:23], v[198:205], 0, v195, v194 op_sel_hi:[0,0,0]
	s_setprio 0
	s_setprio 1
	v_mfma_scale_f32_16x16x128_f8f6f4 v[60:63], v[8:15], v[162:169], 0, v195, v194 op_sel_hi:[0,0,0]
	v_mfma_scale_f32_16x16x128_f8f6f4 v[56:59], v[0:7], v[162:169], 0, v195, v194 op_sel_hi:[0,0,0]
	v_mfma_scale_f32_16x16x128_f8f6f4 v[52:55], v[8:15], v[170:177], 0, v195, v194 op_sel_hi:[0,0,0]
	v_mfma_scale_f32_16x16x128_f8f6f4 v[48:51], v[0:7], v[170:177], 0, v195, v194 op_sel_hi:[0,0,0]
	v_mfma_scale_f32_16x16x128_f8f6f4 v[44:47], v[8:15], v[178:185], 0, v195, v194 op_sel_hi:[0,0,0]
	v_mfma_scale_f32_16x16x128_f8f6f4 v[40:43], v[0:7], v[178:185], 0, v195, v194 op_sel_hi:[0,0,0]
	v_mfma_scale_f32_16x16x128_f8f6f4 v[36:39], v[8:15], v[198:205], 0, v195, v194 op_sel_hi:[0,0,0]
	v_mfma_scale_f32_16x16x128_f8f6f4 v[32:35], v[0:7], v[198:205], 0, v195, v194 op_sel_hi:[0,0,0]
	s_setprio 0
	s_barrier
	ds_read_b128 v[24:27], v196
	ds_read_b128 v[28:31], v196 offset:1024
	ds_read_b128 v[16:19], v196 offset:2048
	ds_read_b128 v[20:23], v196 offset:3072
	ds_read_b128 v[8:11], v197
	ds_read_b128 v[12:15], v197 offset:1024
	ds_read_b128 v[0:3], v197 offset:2048
	ds_read_b128 v[4:7], v197 offset:3072
	ds_read_b128 v[162:165], v193 offset:32768
	ds_read_b128 v[166:169], v193 offset:33792
	ds_read_b128 v[170:173], v193 offset:34816
	ds_read_b128 v[174:177], v193 offset:35840
	ds_read_b128 v[178:181], v193 offset:36864
	ds_read_b128 v[182:185], v193 offset:37888
	ds_read_b128 v[198:201], v193 offset:38912
	ds_read_b128 v[202:205], v193 offset:39936
	s_add_u32 s44, s80, 0x100
	s_addc_u32 s45, s81, 0
	s_add_u32 s54, s83, 0x100
	s_mov_b32 m0, s61
	s_nop 0
	global_load_lds_dwordx4 v160, s[44:45]
	s_addc_u32 s55, s84, 0
	s_mov_b32 m0, s62
	s_nop 0
	global_load_lds_dwordx4 v160, s[54:55]
	s_waitcnt vmcnt(8)
	s_waitcnt lgkmcnt(0)
	s_barrier
	s_setprio 1
	s_waitcnt lgkmcnt(6)
	v_mfma_scale_f32_16x16x128_f8f6f4 v[156:159], v[24:31], v[162:169], v[156:159], v195, v194 op_sel_hi:[0,0,0]
	v_mfma_scale_f32_16x16x128_f8f6f4 v[152:155], v[16:23], v[162:169], v[152:155], v195, v194 op_sel_hi:[0,0,0]
	s_waitcnt lgkmcnt(4)
	v_mfma_scale_f32_16x16x128_f8f6f4 v[148:151], v[24:31], v[170:177], v[148:151], v195, v194 op_sel_hi:[0,0,0]
	v_mfma_scale_f32_16x16x128_f8f6f4 v[144:147], v[16:23], v[170:177], v[144:147], v195, v194 op_sel_hi:[0,0,0]
	s_waitcnt lgkmcnt(2)
	v_mfma_scale_f32_16x16x128_f8f6f4 v[140:143], v[24:31], v[178:185], v[140:143], v195, v194 op_sel_hi:[0,0,0]
	v_mfma_scale_f32_16x16x128_f8f6f4 v[136:139], v[16:23], v[178:185], v[136:139], v195, v194 op_sel_hi:[0,0,0]
	s_waitcnt lgkmcnt(0)
	v_mfma_scale_f32_16x16x128_f8f6f4 v[132:135], v[24:31], v[198:205], v[132:135], v195, v194 op_sel_hi:[0,0,0]
	v_mfma_scale_f32_16x16x128_f8f6f4 v[128:131], v[16:23], v[198:205], v[128:131], v195, v194 op_sel_hi:[0,0,0]
	s_setprio 0
	s_setprio 1
	v_mfma_scale_f32_16x16x128_f8f6f4 v[124:127], v[8:15], v[162:169], v[124:127], v195, v194 op_sel_hi:[0,0,0]
	v_mfma_scale_f32_16x16x128_f8f6f4 v[120:123], v[0:7], v[162:169], v[120:123], v195, v194 op_sel_hi:[0,0,0]
	v_mfma_scale_f32_16x16x128_f8f6f4 v[116:119], v[8:15], v[170:177], v[116:119], v195, v194 op_sel_hi:[0,0,0]
	v_mfma_scale_f32_16x16x128_f8f6f4 v[112:115], v[0:7], v[170:177], v[112:115], v195, v194 op_sel_hi:[0,0,0]
	v_mfma_scale_f32_16x16x128_f8f6f4 v[108:111], v[8:15], v[178:185], v[108:111], v195, v194 op_sel_hi:[0,0,0]
	v_mfma_scale_f32_16x16x128_f8f6f4 v[104:107], v[0:7], v[178:185], v[104:107], v195, v194 op_sel_hi:[0,0,0]
	v_mfma_scale_f32_16x16x128_f8f6f4 v[100:103], v[8:15], v[198:205], v[100:103], v195, v194 op_sel_hi:[0,0,0]
	v_mfma_scale_f32_16x16x128_f8f6f4 v[96:99], v[0:7], v[198:205], v[96:99], v195, v194 op_sel_hi:[0,0,0]
	s_setprio 0
	s_barrier
	s_add_u32 s44, s85, 0x180
	s_addc_u32 s45, s86, 0
	ds_read_b128 v[162:165], v193 offset:49152
	ds_read_b128 v[166:169], v193 offset:50176
	ds_read_b128 v[170:173], v193 offset:51200
	ds_read_b128 v[174:177], v193 offset:52224
	ds_read_b128 v[178:181], v193 offset:53248
	ds_read_b128 v[182:185], v193 offset:54272
	ds_read_b128 v[198:201], v193 offset:55296
	ds_read_b128 v[202:205], v193 offset:56320
	s_add_u32 s54, s87, 0x180
	s_mov_b32 m0, s63
	s_nop 0
	global_load_lds_dwordx4 v161, s[44:45]
	s_addc_u32 s55, s88, 0
	s_mov_b32 m0, s64
	s_nop 0
	global_load_lds_dwordx4 v161, s[54:55]
	s_add_u32 s44, s89, 0x180
	s_addc_u32 s45, s90, 0
	s_add_u32 s54, s93, 0x180
	s_mov_b32 m0, s67
	s_nop 0
	global_load_lds_dwordx4 v161, s[44:45]
	s_addc_u32 s55, s94, 0
	s_mov_b32 m0, s73
	s_nop 0
	global_load_lds_dwordx4 v161, s[54:55]
	s_add_u32 s44, s75, 0x180
	s_addc_u32 s45, s77, 0
	s_add_u32 s54, s91, 0x180
	s_mov_b32 m0, s65
	s_nop 0
	global_load_lds_dwordx4 v160, s[44:45]
	s_addc_u32 s55, s92, 0
	s_mov_b32 m0, s66
	s_nop 0
	global_load_lds_dwordx4 v160, s[54:55]
	s_waitcnt vmcnt(8)
	s_waitcnt lgkmcnt(0)
	s_barrier
	s_setprio 1
	s_waitcnt lgkmcnt(6)
	v_mfma_scale_f32_16x16x128_f8f6f4 v[92:95], v[24:31], v[162:169], v[92:95], v195, v194 op_sel_hi:[0,0,0]
	v_mfma_scale_f32_16x16x128_f8f6f4 v[88:91], v[16:23], v[162:169], v[88:91], v195, v194 op_sel_hi:[0,0,0]
	s_waitcnt lgkmcnt(4)
	v_mfma_scale_f32_16x16x128_f8f6f4 v[84:87], v[24:31], v[170:177], v[84:87], v195, v194 op_sel_hi:[0,0,0]
	v_mfma_scale_f32_16x16x128_f8f6f4 v[80:83], v[16:23], v[170:177], v[80:83], v195, v194 op_sel_hi:[0,0,0]
	s_waitcnt lgkmcnt(2)
	v_mfma_scale_f32_16x16x128_f8f6f4 v[76:79], v[24:31], v[178:185], v[76:79], v195, v194 op_sel_hi:[0,0,0]
	v_mfma_scale_f32_16x16x128_f8f6f4 v[72:75], v[16:23], v[178:185], v[72:75], v195, v194 op_sel_hi:[0,0,0]
	s_waitcnt lgkmcnt(0)
	v_mfma_scale_f32_16x16x128_f8f6f4 v[68:71], v[24:31], v[198:205], v[68:71], v195, v194 op_sel_hi:[0,0,0]
	v_mfma_scale_f32_16x16x128_f8f6f4 v[64:67], v[16:23], v[198:205], v[64:67], v195, v194 op_sel_hi:[0,0,0]
	s_setprio 0
	s_setprio 1
	v_mfma_scale_f32_16x16x128_f8f6f4 v[60:63], v[8:15], v[162:169], v[60:63], v195, v194 op_sel_hi:[0,0,0]
	v_mfma_scale_f32_16x16x128_f8f6f4 v[56:59], v[0:7], v[162:169], v[56:59], v195, v194 op_sel_hi:[0,0,0]
	v_mfma_scale_f32_16x16x128_f8f6f4 v[52:55], v[8:15], v[170:177], v[52:55], v195, v194 op_sel_hi:[0,0,0]
	v_mfma_scale_f32_16x16x128_f8f6f4 v[48:51], v[0:7], v[170:177], v[48:51], v195, v194 op_sel_hi:[0,0,0]
	v_mfma_scale_f32_16x16x128_f8f6f4 v[44:47], v[8:15], v[178:185], v[44:47], v195, v194 op_sel_hi:[0,0,0]
	v_mfma_scale_f32_16x16x128_f8f6f4 v[40:43], v[0:7], v[178:185], v[40:43], v195, v194 op_sel_hi:[0,0,0]
	v_mfma_scale_f32_16x16x128_f8f6f4 v[36:39], v[8:15], v[198:205], v[36:39], v195, v194 op_sel_hi:[0,0,0]
	v_mfma_scale_f32_16x16x128_f8f6f4 v[32:35], v[0:7], v[198:205], v[32:35], v195, v194 op_sel_hi:[0,0,0]
	s_setprio 0
	s_barrier
	s_add_u32 s42, s42, 0x100
	s_addc_u32 s43, s43, 0
	s_cmp_ge_i32 s74, s2
	s_cbranch_scc0 .LBB0_238
	s_branch .LBB0_239

.LBB0_255:
	s_cmp_lt_i32 s20, 3
	s_cbranch_scc1 .Lhz_257
	s_add_i32 s16, s20, -2
	s_add_u32 s31, s4, s40
	s_addc_u32 s46, s5, s41
	s_add_u32 s47, s6, s24
	s_addc_u32 s48, s7, s25
	s_add_u32 s42, s18, s24
	s_addc_u32 s43, s19, s25
	s_add_u32 s49, s6, s42
	s_addc_u32 s70, s7, s43
	s_add_u32 s71, s6, s18
	s_addc_u32 s72, s7, s19
	s_add_u32 s42, s38, s40
	s_addc_u32 s43, s39, s41
	s_add_u32 s73, s4, s42
	s_addc_u32 s74, s5, s43
	s_add_u32 s75, s4, s38
	s_addc_u32 s77, s5, s39
	s_mov_b32 s78, 0
	s_mov_b64 s[42:43], 0
	s_cmp_eq_u32 s98, 0
	s_cbranch_scc1 .Lhf_257
	ds_read_b128 v[130:133], v135
	ds_read_b128 v[140:143], v135 offset:1024
	ds_read_b128 v[144:147], v135 offset:2048
	ds_read_b128 v[148:151], v135 offset:3072
	ds_read_b128 v[152:155], v136
	ds_read_b128 v[156:159], v136 offset:1024
	ds_read_b128 v[160:163], v136 offset:2048
	ds_read_b128 v[164:167], v136 offset:3072
	s_add_i32 s78, s78, 2
	s_add_u32 s79, s4, s42
	s_addc_u32 s80, s5, s43
	s_add_u32 s44, s79, 0x100
	s_addc_u32 s45, s80, 0
	s_add_u32 s81, s31, s42
	ds_read_b128 v[168:171], v137
	ds_read_b128 v[172:175], v137 offset:1024
	ds_read_b128 v[176:179], v137 offset:2048
	ds_read_b128 v[180:183], v137 offset:3072
	ds_read_b128 v[184:187], v137 offset:4096
	ds_read_b128 v[188:191], v137 offset:5120
	ds_read_b128 v[192:195], v137 offset:6144
	ds_read_b128 v[196:199], v137 offset:7168
	s_addc_u32 s84, s46, s43
	s_add_u32 s54, s81, 0x80
	s_addc_u32 s55, s84, 0
	s_add_u32 s85, s73, s42
	s_addc_u32 s86, s74, s43
	s_add_u32 s82, s85, 0x80
	s_mov_b32 m0, s67
	s_nop 0
	global_load_lds_dwordx4 v128, s[54:55]
	s_addc_u32 s83, s86, 0
	s_mov_b32 m0, s68
	s_nop 0
	global_load_lds_dwordx4 v128, s[82:83]
	s_waitcnt vmcnt(24)
	s_waitcnt lgkmcnt(0)
	s_barrier
	s_setprio 1
	s_waitcnt lgkmcnt(7)
	v_mfma_f32_16x16x32_bf16 v[124:127], v[130:133], v[168:171], 0
	v_mfma_f32_16x16x32_bf16 v[120:123], v[144:147], v[168:171], 0
	s_waitcnt lgkmcnt(5)
	v_mfma_f32_16x16x32_bf16 v[116:119], v[130:133], v[176:179], 0
	v_mfma_f32_16x16x32_bf16 v[112:115], v[144:147], v[176:179], 0
	s_waitcnt lgkmcnt(3)
	v_mfma_f32_16x16x32_bf16 v[108:111], v[130:133], v[184:187], 0
	v_mfma_f32_16x16x32_bf16 v[104:107], v[144:147], v[184:187], 0
	s_waitcnt lgkmcnt(1)
	v_mfma_f32_16x16x32_bf16 v[100:103], v[130:133], v[192:195], 0
	v_mfma_f32_16x16x32_bf16 v[96:99], v[144:147], v[192:195], 0
	v_mfma_f32_16x16x32_bf16 v[124:127], v[140:143], v[172:175], v[124:127]
	v_mfma_f32_16x16x32_bf16 v[120:123], v[148:151], v[172:175], v[120:123]
	v_mfma_f32_16x16x32_bf16 v[116:119], v[140:143], v[180:183], v[116:119]
	v_mfma_f32_16x16x32_bf16 v[112:115], v[148:151], v[180:183], v[112:115]
	v_mfma_f32_16x16x32_bf16 v[108:111], v[140:143], v[188:191], v[108:111]
	v_mfma_f32_16x16x32_bf16 v[104:107], v[148:151], v[188:191], v[104:107]
	s_waitcnt lgkmcnt(0)
	v_mfma_f32_16x16x32_bf16 v[100:103], v[140:143], v[196:199], v[100:103]
	v_mfma_f32_16x16x32_bf16 v[96:99], v[148:151], v[196:199], v[96:99]
	s_setprio 0
	s_setprio 1
	v_mfma_f32_16x16x32_bf16 v[92:95], v[152:155], v[168:171], 0
	v_mfma_f32_16x16x32_bf16 v[88:91], v[160:163], v[168:171], 0
	v_mfma_f32_16x16x32_bf16 v[84:87], v[152:155], v[176:179], 0
	v_mfma_f32_16x16x32_bf16 v[80:83], v[160:163], v[176:179], 0
	v_mfma_f32_16x16x32_bf16 v[76:79], v[152:155], v[184:187], 0
	v_mfma_f32_16x16x32_bf16 v[72:75], v[160:163], v[184:187], 0
	v_mfma_f32_16x16x32_bf16 v[68:71], v[152:155], v[192:195], 0
	v_mfma_f32_16x16x32_bf16 v[64:67], v[160:163], v[192:195], 0
	v_mfma_f32_16x16x32_bf16 v[92:95], v[156:159], v[172:175], v[92:95]
	v_mfma_f32_16x16x32_bf16 v[88:91], v[164:167], v[172:175], v[88:91]
	v_mfma_f32_16x16x32_bf16 v[84:87], v[156:159], v[180:183], v[84:87]
	v_mfma_f32_16x16x32_bf16 v[80:83], v[164:167], v[180:183], v[80:83]
	v_mfma_f32_16x16x32_bf16 v[76:79], v[156:159], v[188:191], v[76:79]
	v_mfma_f32_16x16x32_bf16 v[72:75], v[164:167], v[188:191], v[72:75]
	v_mfma_f32_16x16x32_bf16 v[68:71], v[156:159], v[196:199], v[68:71]
	v_mfma_f32_16x16x32_bf16 v[64:67], v[164:167], v[196:199], v[64:67]
	s_setprio 0
	s_barrier
	s_add_u32 s87, s6, s42
	s_addc_u32 s88, s7, s43
	s_add_u32 s54, s87, 0x100
	s_addc_u32 s55, s88, 0
	s_add_u32 s89, s71, s42
	s_addc_u32 s90, s72, s43
	s_add_u32 s82, s89, 0x100
	ds_read_b128 v[168:171], v137 offset:16384
	ds_read_b128 v[172:175], v137 offset:17408
	ds_read_b128 v[176:179], v137 offset:18432
	ds_read_b128 v[180:183], v137 offset:19456
	ds_read_b128 v[184:187], v137 offset:20480
	ds_read_b128 v[188:191], v137 offset:21504
	ds_read_b128 v[192:195], v137 offset:22528
	ds_read_b128 v[196:199], v137 offset:23552
	s_addc_u32 s83, s90, 0
	s_mov_b32 m0, s51
	s_nop 0
	global_load_lds_dwordx4 v129, s[54:55]
	s_add_u32 s91, s47, s42
	s_mov_b32 m0, s57
	s_nop 0
	global_load_lds_dwordx4 v129, s[82:83]
	s_addc_u32 s92, s48, s43
	s_add_u32 s54, s91, 0x100
	s_addc_u32 s55, s92, 0
	s_add_u32 s93, s49, s42
	s_addc_u32 s94, s70, s43
	s_add_u32 s82, s93, 0x100
	s_addc_u32 s83, s94, 0
	s_mov_b32 m0, s58
	s_nop 0
	global_load_lds_dwordx4 v129, s[54:55]
	s_mov_b32 m0, s59
	s_nop 0
	global_load_lds_dwordx4 v129, s[82:83]
	s_add_u32 s82, s75, s42
	s_addc_u32 s83, s77, s43
	s_add_u32 s54, s82, 0x100
	s_mov_b32 m0, s53
	s_nop 0
	global_load_lds_dwordx4 v128, s[44:45]
	s_addc_u32 s55, s83, 0
	s_mov_b32 m0, s2
	s_nop 0
	global_load_lds_dwordx4 v128, s[54:55]
	s_waitcnt vmcnt(24)
	s_waitcnt lgkmcnt(0)
	s_barrier
	s_setprio 1
	s_waitcnt lgkmcnt(7)
	v_mfma_f32_16x16x32_bf16 v[60:63], v[130:133], v[168:171], 0
	v_mfma_f32_16x16x32_bf16 v[56:59], v[144:147], v[168:171], 0
	s_waitcnt lgkmcnt(5)
	v_mfma_f32_16x16x32_bf16 v[52:55], v[130:133], v[176:179], 0
	v_mfma_f32_16x16x32_bf16 v[48:51], v[144:147], v[176:179], 0
	s_waitcnt lgkmcnt(3)
	v_mfma_f32_16x16x32_bf16 v[44:47], v[130:133], v[184:187], 0
	v_mfma_f32_16x16x32_bf16 v[40:43], v[144:147], v[184:187], 0
	s_waitcnt lgkmcnt(1)
	v_mfma_f32_16x16x32_bf16 v[36:39], v[130:133], v[192:195], 0
	v_mfma_f32_16x16x32_bf16 v[32:35], v[144:147], v[192:195], 0
	v_mfma_f32_16x16x32_bf16 v[60:63], v[140:143], v[172:175], v[60:63]
	v_mfma_f32_16x16x32_bf16 v[56:59], v[148:151], v[172:175], v[56:59]
	v_mfma_f32_16x16x32_bf16 v[52:55], v[140:143], v[180:183], v[52:55]
	v_mfma_f32_16x16x32_bf16 v[48:51], v[148:151], v[180:183], v[48:51]
	v_mfma_f32_16x16x32_bf16 v[44:47], v[140:143], v[188:191], v[44:47]
	v_mfma_f32_16x16x32_bf16 v[40:43], v[148:151], v[188:191], v[40:43]
	s_waitcnt lgkmcnt(0)
	v_mfma_f32_16x16x32_bf16 v[36:39], v[140:143], v[196:199], v[36:39]
	v_mfma_f32_16x16x32_bf16 v[32:35], v[148:151], v[196:199], v[32:35]
	s_setprio 0
	s_setprio 1
	v_mfma_f32_16x16x32_bf16 v[28:31], v[152:155], v[168:171], 0
	v_mfma_f32_16x16x32_bf16 v[24:27], v[160:163], v[168:171], 0
	v_mfma_f32_16x16x32_bf16 v[20:23], v[152:155], v[176:179], 0
	v_mfma_f32_16x16x32_bf16 v[16:19], v[160:163], v[176:179], 0
	v_mfma_f32_16x16x32_bf16 v[12:15], v[152:155], v[184:187], 0
	v_mfma_f32_16x16x32_bf16 v[8:11], v[160:163], v[184:187], 0
	v_mfma_f32_16x16x32_bf16 v[4:7], v[152:155], v[192:195], 0
	v_mfma_f32_16x16x32_bf16 v[0:3], v[160:163], v[192:195], 0
	v_mfma_f32_16x16x32_bf16 v[28:31], v[156:159], v[172:175], v[28:31]
	v_mfma_f32_16x16x32_bf16 v[24:27], v[164:167], v[172:175], v[24:27]
	v_mfma_f32_16x16x32_bf16 v[20:23], v[156:159], v[180:183], v[20:23]
	v_mfma_f32_16x16x32_bf16 v[16:19], v[164:167], v[180:183], v[16:19]
	v_mfma_f32_16x16x32_bf16 v[12:15], v[156:159], v[188:191], v[12:15]
	v_mfma_f32_16x16x32_bf16 v[8:11], v[164:167], v[188:191], v[8:11]
	v_mfma_f32_16x16x32_bf16 v[4:7], v[156:159], v[196:199], v[4:7]
	v_mfma_f32_16x16x32_bf16 v[0:3], v[164:167], v[196:199], v[0:3]
	s_setprio 0
	s_barrier
	ds_read_b128 v[130:133], v138
	ds_read_b128 v[140:143], v138 offset:1024
	ds_read_b128 v[144:147], v138 offset:2048
	ds_read_b128 v[148:151], v138 offset:3072
	ds_read_b128 v[152:155], v139
	ds_read_b128 v[156:159], v139 offset:1024
	ds_read_b128 v[160:163], v139 offset:2048
	ds_read_b128 v[164:167], v139 offset:3072
	ds_read_b128 v[168:171], v137 offset:32768
	ds_read_b128 v[172:175], v137 offset:33792
	ds_read_b128 v[176:179], v137 offset:34816
	ds_read_b128 v[180:183], v137 offset:35840
	ds_read_b128 v[184:187], v137 offset:36864
	ds_read_b128 v[188:191], v137 offset:37888
	ds_read_b128 v[192:195], v137 offset:38912
	ds_read_b128 v[196:199], v137 offset:39936
	s_add_u32 s44, s81, 0x100
	s_addc_u32 s45, s84, 0
	s_add_u32 s54, s85, 0x100
	s_mov_b32 m0, s33
	s_nop 0
	global_load_lds_dwordx4 v128, s[44:45]
	s_addc_u32 s55, s86, 0
	s_mov_b32 m0, s60
	s_nop 0
	global_load_lds_dwordx4 v128, s[54:55]
	s_waitcnt vmcnt(8)
	s_waitcnt lgkmcnt(0)
	s_barrier
	s_setprio 1
	s_waitcnt lgkmcnt(7)
	v_mfma_f32_16x16x32_bf16 v[124:127], v[130:133], v[168:171], v[124:127]
	v_mfma_f32_16x16x32_bf16 v[120:123], v[144:147], v[168:171], v[120:123]
	s_waitcnt lgkmcnt(5)
	v_mfma_f32_16x16x32_bf16 v[116:119], v[130:133], v[176:179], v[116:119]
	v_mfma_f32_16x16x32_bf16 v[112:115], v[144:147], v[176:179], v[112:115]
	s_waitcnt lgkmcnt(3)
	v_mfma_f32_16x16x32_bf16 v[108:111], v[130:133], v[184:187], v[108:111]
	v_mfma_f32_16x16x32_bf16 v[104:107], v[144:147], v[184:187], v[104:107]
	s_waitcnt lgkmcnt(1)
	v_mfma_f32_16x16x32_bf16 v[100:103], v[130:133], v[192:195], v[100:103]
	v_mfma_f32_16x16x32_bf16 v[96:99], v[144:147], v[192:195], v[96:99]
	v_mfma_f32_16x16x32_bf16 v[124:127], v[140:143], v[172:175], v[124:127]
	v_mfma_f32_16x16x32_bf16 v[120:123], v[148:151], v[172:175], v[120:123]
	v_mfma_f32_16x16x32_bf16 v[116:119], v[140:143], v[180:183], v[116:119]
	v_mfma_f32_16x16x32_bf16 v[112:115], v[148:151], v[180:183], v[112:115]
	v_mfma_f32_16x16x32_bf16 v[108:111], v[140:143], v[188:191], v[108:111]
	v_mfma_f32_16x16x32_bf16 v[104:107], v[148:151], v[188:191], v[104:107]
	s_waitcnt lgkmcnt(0)
	v_mfma_f32_16x16x32_bf16 v[100:103], v[140:143], v[196:199], v[100:103]
	v_mfma_f32_16x16x32_bf16 v[96:99], v[148:151], v[196:199], v[96:99]
	s_setprio 0
	s_setprio 1
	v_mfma_f32_16x16x32_bf16 v[92:95], v[152:155], v[168:171], v[92:95]
	v_mfma_f32_16x16x32_bf16 v[88:91], v[160:163], v[168:171], v[88:91]
	v_mfma_f32_16x16x32_bf16 v[84:87], v[152:155], v[176:179], v[84:87]
	v_mfma_f32_16x16x32_bf16 v[80:83], v[160:163], v[176:179], v[80:83]
	v_mfma_f32_16x16x32_bf16 v[76:79], v[152:155], v[184:187], v[76:79]
	v_mfma_f32_16x16x32_bf16 v[72:75], v[160:163], v[184:187], v[72:75]
	v_mfma_f32_16x16x32_bf16 v[68:71], v[152:155], v[192:195], v[68:71]
	v_mfma_f32_16x16x32_bf16 v[64:67], v[160:163], v[192:195], v[64:67]
	v_mfma_f32_16x16x32_bf16 v[92:95], v[156:159], v[172:175], v[92:95]
	v_mfma_f32_16x16x32_bf16 v[88:91], v[164:167], v[172:175], v[88:91]
	v_mfma_f32_16x16x32_bf16 v[84:87], v[156:159], v[180:183], v[84:87]
	v_mfma_f32_16x16x32_bf16 v[80:83], v[164:167], v[180:183], v[80:83]
	v_mfma_f32_16x16x32_bf16 v[76:79], v[156:159], v[188:191], v[76:79]
	v_mfma_f32_16x16x32_bf16 v[72:75], v[164:167], v[188:191], v[72:75]
	v_mfma_f32_16x16x32_bf16 v[68:71], v[156:159], v[196:199], v[68:71]
	v_mfma_f32_16x16x32_bf16 v[64:67], v[164:167], v[196:199], v[64:67]
	s_setprio 0
	s_barrier
	s_add_u32 s44, s87, 0x180
	s_addc_u32 s45, s88, 0
	ds_read_b128 v[168:171], v137 offset:49152
	ds_read_b128 v[172:175], v137 offset:50176
	ds_read_b128 v[176:179], v137 offset:51200
	ds_read_b128 v[180:183], v137 offset:52224
	ds_read_b128 v[184:187], v137 offset:53248
	ds_read_b128 v[188:191], v137 offset:54272
	ds_read_b128 v[192:195], v137 offset:55296
	ds_read_b128 v[196:199], v137 offset:56320
	s_add_u32 s54, s89, 0x180
	s_mov_b32 m0, s61
	s_nop 0
	global_load_lds_dwordx4 v129, s[44:45]
	s_addc_u32 s55, s90, 0
	s_mov_b32 m0, s62
	s_nop 0
	global_load_lds_dwordx4 v129, s[54:55]
	s_add_u32 s44, s91, 0x180
	s_addc_u32 s45, s92, 0
	s_add_u32 s54, s93, 0x180
	s_mov_b32 m0, s65
	s_nop 0
	global_load_lds_dwordx4 v129, s[44:45]
	s_addc_u32 s55, s94, 0
	s_mov_b32 m0, s66
	s_nop 0
	global_load_lds_dwordx4 v129, s[54:55]
	s_add_u32 s44, s79, 0x180
	s_addc_u32 s45, s80, 0
	s_add_u32 s54, s82, 0x180
	s_mov_b32 m0, s63
	s_nop 0
	global_load_lds_dwordx4 v128, s[44:45]
	s_addc_u32 s55, s83, 0
	s_mov_b32 m0, s64
	s_nop 0
	global_load_lds_dwordx4 v128, s[54:55]
	s_waitcnt vmcnt(8)
	s_waitcnt lgkmcnt(0)
	s_barrier
	s_setprio 1
	s_waitcnt lgkmcnt(7)
	v_mfma_f32_16x16x32_bf16 v[60:63], v[130:133], v[168:171], v[60:63]
	v_mfma_f32_16x16x32_bf16 v[56:59], v[144:147], v[168:171], v[56:59]
	s_waitcnt lgkmcnt(5)
	v_mfma_f32_16x16x32_bf16 v[52:55], v[130:133], v[176:179], v[52:55]
	v_mfma_f32_16x16x32_bf16 v[48:51], v[144:147], v[176:179], v[48:51]
	s_waitcnt lgkmcnt(3)
	v_mfma_f32_16x16x32_bf16 v[44:47], v[130:133], v[184:187], v[44:47]
	v_mfma_f32_16x16x32_bf16 v[40:43], v[144:147], v[184:187], v[40:43]
	s_waitcnt lgkmcnt(1)
	v_mfma_f32_16x16x32_bf16 v[36:39], v[130:133], v[192:195], v[36:39]
	v_mfma_f32_16x16x32_bf16 v[32:35], v[144:147], v[192:195], v[32:35]
	v_mfma_f32_16x16x32_bf16 v[60:63], v[140:143], v[172:175], v[60:63]
	v_mfma_f32_16x16x32_bf16 v[56:59], v[148:151], v[172:175], v[56:59]
	v_mfma_f32_16x16x32_bf16 v[52:55], v[140:143], v[180:183], v[52:55]
	v_mfma_f32_16x16x32_bf16 v[48:51], v[148:151], v[180:183], v[48:51]
	v_mfma_f32_16x16x32_bf16 v[44:47], v[140:143], v[188:191], v[44:47]
	v_mfma_f32_16x16x32_bf16 v[40:43], v[148:151], v[188:191], v[40:43]
	s_waitcnt lgkmcnt(0)
	v_mfma_f32_16x16x32_bf16 v[36:39], v[140:143], v[196:199], v[36:39]
	v_mfma_f32_16x16x32_bf16 v[32:35], v[148:151], v[196:199], v[32:35]
	s_setprio 0
	s_setprio 1
	v_mfma_f32_16x16x32_bf16 v[28:31], v[152:155], v[168:171], v[28:31]
	v_mfma_f32_16x16x32_bf16 v[24:27], v[160:163], v[168:171], v[24:27]
	v_mfma_f32_16x16x32_bf16 v[20:23], v[152:155], v[176:179], v[20:23]
	v_mfma_f32_16x16x32_bf16 v[16:19], v[160:163], v[176:179], v[16:19]
	v_mfma_f32_16x16x32_bf16 v[12:15], v[152:155], v[184:187], v[12:15]
	v_mfma_f32_16x16x32_bf16 v[8:11], v[160:163], v[184:187], v[8:11]
	v_mfma_f32_16x16x32_bf16 v[4:7], v[152:155], v[192:195], v[4:7]
	v_mfma_f32_16x16x32_bf16 v[0:3], v[160:163], v[192:195], v[0:3]
	v_mfma_f32_16x16x32_bf16 v[28:31], v[156:159], v[172:175], v[28:31]
	v_mfma_f32_16x16x32_bf16 v[24:27], v[164:167], v[172:175], v[24:27]
	v_mfma_f32_16x16x32_bf16 v[20:23], v[156:159], v[180:183], v[20:23]
	v_mfma_f32_16x16x32_bf16 v[16:19], v[164:167], v[180:183], v[16:19]
	v_mfma_f32_16x16x32_bf16 v[12:15], v[156:159], v[188:191], v[12:15]
	v_mfma_f32_16x16x32_bf16 v[8:11], v[164:167], v[188:191], v[8:11]
	v_mfma_f32_16x16x32_bf16 v[4:7], v[156:159], v[196:199], v[4:7]
	v_mfma_f32_16x16x32_bf16 v[0:3], v[164:167], v[196:199], v[0:3]
	s_setprio 0
	s_barrier
	s_add_u32 s42, s42, 0x100
	s_addc_u32 s43, s43, 0
	s_cmp_ge_i32 s78, s16
	s_cbranch_scc0 .LBB0_257
	s_branch .LBB0_258
.Lhf_257:
	ds_read_b128 v[130:133], v135
	ds_read_b128 v[140:143], v135 offset:1024
	ds_read_b128 v[144:147], v135 offset:2048
	ds_read_b128 v[148:151], v135 offset:3072
	ds_read_b128 v[152:155], v136
	ds_read_b128 v[156:159], v136 offset:1024
	ds_read_b128 v[160:163], v136 offset:2048
	ds_read_b128 v[164:167], v136 offset:3072
	s_add_i32 s78, s78, 2
	s_add_u32 s79, s4, s42
	s_addc_u32 s80, s5, s43
	s_add_u32 s44, s79, 0x100
	s_addc_u32 s45, s80, 0
	s_add_u32 s81, s31, s42
	ds_read_b128 v[168:171], v137
	ds_read_b128 v[172:175], v137 offset:1024
	ds_read_b128 v[176:179], v137 offset:2048
	ds_read_b128 v[180:183], v137 offset:3072
	ds_read_b128 v[184:187], v137 offset:4096
	ds_read_b128 v[188:191], v137 offset:5120
	ds_read_b128 v[192:195], v137 offset:6144
	ds_read_b128 v[196:199], v137 offset:7168
	s_addc_u32 s84, s46, s43
	s_add_u32 s54, s81, 0x80
	s_addc_u32 s55, s84, 0
	s_add_u32 s85, s73, s42
	s_addc_u32 s86, s74, s43
	s_add_u32 s82, s85, 0x80
	s_mov_b32 m0, s67
	s_nop 0
	global_load_lds_dwordx4 v128, s[54:55]
	s_addc_u32 s83, s86, 0
	s_mov_b32 m0, s68
	s_nop 0
	global_load_lds_dwordx4 v128, s[82:83]
	s_waitcnt vmcnt(8)
	s_waitcnt lgkmcnt(0)
	s_barrier
	s_setprio 1
	s_waitcnt lgkmcnt(7)
	v_mfma_f32_16x16x32_bf16 v[124:127], v[130:133], v[168:171], 0
	v_mfma_f32_16x16x32_bf16 v[120:123], v[144:147], v[168:171], 0
	s_waitcnt lgkmcnt(5)
	v_mfma_f32_16x16x32_bf16 v[116:119], v[130:133], v[176:179], 0
	v_mfma_f32_16x16x32_bf16 v[112:115], v[144:147], v[176:179], 0
	s_waitcnt lgkmcnt(3)
	v_mfma_f32_16x16x32_bf16 v[108:111], v[130:133], v[184:187], 0
	v_mfma_f32_16x16x32_bf16 v[104:107], v[144:147], v[184:187], 0
	s_waitcnt lgkmcnt(1)
	v_mfma_f32_16x16x32_bf16 v[100:103], v[130:133], v[192:195], 0
	v_mfma_f32_16x16x32_bf16 v[96:99], v[144:147], v[192:195], 0
	v_mfma_f32_16x16x32_bf16 v[124:127], v[140:143], v[172:175], v[124:127]
	v_mfma_f32_16x16x32_bf16 v[120:123], v[148:151], v[172:175], v[120:123]
	v_mfma_f32_16x16x32_bf16 v[116:119], v[140:143], v[180:183], v[116:119]
	v_mfma_f32_16x16x32_bf16 v[112:115], v[148:151], v[180:183], v[112:115]
	v_mfma_f32_16x16x32_bf16 v[108:111], v[140:143], v[188:191], v[108:111]
	v_mfma_f32_16x16x32_bf16 v[104:107], v[148:151], v[188:191], v[104:107]
	s_waitcnt lgkmcnt(0)
	v_mfma_f32_16x16x32_bf16 v[100:103], v[140:143], v[196:199], v[100:103]
	v_mfma_f32_16x16x32_bf16 v[96:99], v[148:151], v[196:199], v[96:99]
	s_setprio 0
	s_setprio 1
	v_mfma_f32_16x16x32_bf16 v[92:95], v[152:155], v[168:171], 0
	v_mfma_f32_16x16x32_bf16 v[88:91], v[160:163], v[168:171], 0
	v_mfma_f32_16x16x32_bf16 v[84:87], v[152:155], v[176:179], 0
	v_mfma_f32_16x16x32_bf16 v[80:83], v[160:163], v[176:179], 0
	v_mfma_f32_16x16x32_bf16 v[76:79], v[152:155], v[184:187], 0
	v_mfma_f32_16x16x32_bf16 v[72:75], v[160:163], v[184:187], 0
	v_mfma_f32_16x16x32_bf16 v[68:71], v[152:155], v[192:195], 0
	v_mfma_f32_16x16x32_bf16 v[64:67], v[160:163], v[192:195], 0
	v_mfma_f32_16x16x32_bf16 v[92:95], v[156:159], v[172:175], v[92:95]
	v_mfma_f32_16x16x32_bf16 v[88:91], v[164:167], v[172:175], v[88:91]
	v_mfma_f32_16x16x32_bf16 v[84:87], v[156:159], v[180:183], v[84:87]
	v_mfma_f32_16x16x32_bf16 v[80:83], v[164:167], v[180:183], v[80:83]
	v_mfma_f32_16x16x32_bf16 v[76:79], v[156:159], v[188:191], v[76:79]
	v_mfma_f32_16x16x32_bf16 v[72:75], v[164:167], v[188:191], v[72:75]
	v_mfma_f32_16x16x32_bf16 v[68:71], v[156:159], v[196:199], v[68:71]
	v_mfma_f32_16x16x32_bf16 v[64:67], v[164:167], v[196:199], v[64:67]
	s_setprio 0
	s_barrier
	s_add_u32 s87, s6, s42
	s_addc_u32 s88, s7, s43
	s_add_u32 s54, s87, 0x100
	s_addc_u32 s55, s88, 0
	s_add_u32 s89, s71, s42
	s_addc_u32 s90, s72, s43
	s_add_u32 s82, s89, 0x100
	ds_read_b128 v[168:171], v137 offset:16384
	ds_read_b128 v[172:175], v137 offset:17408
	ds_read_b128 v[176:179], v137 offset:18432
	ds_read_b128 v[180:183], v137 offset:19456
	ds_read_b128 v[184:187], v137 offset:20480
	ds_read_b128 v[188:191], v137 offset:21504
	ds_read_b128 v[192:195], v137 offset:22528
	ds_read_b128 v[196:199], v137 offset:23552
	s_addc_u32 s83, s90, 0
	s_mov_b32 m0, s51
	s_nop 0
	global_load_lds_dwordx4 v129, s[54:55]
	s_add_u32 s91, s47, s42
	s_mov_b32 m0, s57
	s_nop 0
	global_load_lds_dwordx4 v129, s[82:83]
	s_addc_u32 s92, s48, s43
	s_add_u32 s54, s91, 0x100
	s_addc_u32 s55, s92, 0
	s_add_u32 s93, s49, s42
	s_addc_u32 s94, s70, s43
	s_add_u32 s82, s93, 0x100
	s_addc_u32 s83, s94, 0
	s_mov_b32 m0, s58
	s_nop 0
	global_load_lds_dwordx4 v129, s[54:55]
	s_mov_b32 m0, s59
	s_nop 0
	global_load_lds_dwordx4 v129, s[82:83]
	s_add_u32 s82, s75, s42
	s_addc_u32 s83, s77, s43
	s_add_u32 s54, s82, 0x100
	s_mov_b32 m0, s53
	s_nop 0
	global_load_lds_dwordx4 v128, s[44:45]
	s_addc_u32 s55, s83, 0
	s_mov_b32 m0, s2
	s_nop 0
	global_load_lds_dwordx4 v128, s[54:55]
	s_waitcnt vmcnt(8)
	s_waitcnt lgkmcnt(0)
	s_barrier
	s_setprio 1
	s_waitcnt lgkmcnt(7)
	v_mfma_f32_16x16x32_bf16 v[60:63], v[130:133], v[168:171], 0
	v_mfma_f32_16x16x32_bf16 v[56:59], v[144:147], v[168:171], 0
	s_waitcnt lgkmcnt(5)
	v_mfma_f32_16x16x32_bf16 v[52:55], v[130:133], v[176:179], 0
	v_mfma_f32_16x16x32_bf16 v[48:51], v[144:147], v[176:179], 0
	s_waitcnt lgkmcnt(3)
	v_mfma_f32_16x16x32_bf16 v[44:47], v[130:133], v[184:187], 0
	v_mfma_f32_16x16x32_bf16 v[40:43], v[144:147], v[184:187], 0
	s_waitcnt lgkmcnt(1)
	v_mfma_f32_16x16x32_bf16 v[36:39], v[130:133], v[192:195], 0
	v_mfma_f32_16x16x32_bf16 v[32:35], v[144:147], v[192:195], 0
	v_mfma_f32_16x16x32_bf16 v[60:63], v[140:143], v[172:175], v[60:63]
	v_mfma_f32_16x16x32_bf16 v[56:59], v[148:151], v[172:175], v[56:59]
	v_mfma_f32_16x16x32_bf16 v[52:55], v[140:143], v[180:183], v[52:55]
	v_mfma_f32_16x16x32_bf16 v[48:51], v[148:151], v[180:183], v[48:51]
	v_mfma_f32_16x16x32_bf16 v[44:47], v[140:143], v[188:191], v[44:47]
	v_mfma_f32_16x16x32_bf16 v[40:43], v[148:151], v[188:191], v[40:43]
	s_waitcnt lgkmcnt(0)
	v_mfma_f32_16x16x32_bf16 v[36:39], v[140:143], v[196:199], v[36:39]
	v_mfma_f32_16x16x32_bf16 v[32:35], v[148:151], v[196:199], v[32:35]
	s_setprio 0
	s_setprio 1
	v_mfma_f32_16x16x32_bf16 v[28:31], v[152:155], v[168:171], 0
	v_mfma_f32_16x16x32_bf16 v[24:27], v[160:163], v[168:171], 0
	v_mfma_f32_16x16x32_bf16 v[20:23], v[152:155], v[176:179], 0
	v_mfma_f32_16x16x32_bf16 v[16:19], v[160:163], v[176:179], 0
	v_mfma_f32_16x16x32_bf16 v[12:15], v[152:155], v[184:187], 0
	v_mfma_f32_16x16x32_bf16 v[8:11], v[160:163], v[184:187], 0
	v_mfma_f32_16x16x32_bf16 v[4:7], v[152:155], v[192:195], 0
	v_mfma_f32_16x16x32_bf16 v[0:3], v[160:163], v[192:195], 0
	v_mfma_f32_16x16x32_bf16 v[28:31], v[156:159], v[172:175], v[28:31]
	v_mfma_f32_16x16x32_bf16 v[24:27], v[164:167], v[172:175], v[24:27]
	v_mfma_f32_16x16x32_bf16 v[20:23], v[156:159], v[180:183], v[20:23]
	v_mfma_f32_16x16x32_bf16 v[16:19], v[164:167], v[180:183], v[16:19]
	v_mfma_f32_16x16x32_bf16 v[12:15], v[156:159], v[188:191], v[12:15]
	v_mfma_f32_16x16x32_bf16 v[8:11], v[164:167], v[188:191], v[8:11]
	v_mfma_f32_16x16x32_bf16 v[4:7], v[156:159], v[196:199], v[4:7]
	v_mfma_f32_16x16x32_bf16 v[0:3], v[164:167], v[196:199], v[0:3]
	s_setprio 0
	s_barrier
	ds_read_b128 v[130:133], v138
	ds_read_b128 v[140:143], v138 offset:1024
	ds_read_b128 v[144:147], v138 offset:2048
	ds_read_b128 v[148:151], v138 offset:3072
	ds_read_b128 v[152:155], v139
	ds_read_b128 v[156:159], v139 offset:1024
	ds_read_b128 v[160:163], v139 offset:2048
	ds_read_b128 v[164:167], v139 offset:3072
	ds_read_b128 v[168:171], v137 offset:32768
	ds_read_b128 v[172:175], v137 offset:33792
	ds_read_b128 v[176:179], v137 offset:34816
	ds_read_b128 v[180:183], v137 offset:35840
	ds_read_b128 v[184:187], v137 offset:36864
	ds_read_b128 v[188:191], v137 offset:37888
	ds_read_b128 v[192:195], v137 offset:38912
	ds_read_b128 v[196:199], v137 offset:39936
	s_add_u32 s44, s81, 0x100
	s_addc_u32 s45, s84, 0
	s_add_u32 s54, s85, 0x100
	s_mov_b32 m0, s33
	s_nop 0
	global_load_lds_dwordx4 v128, s[44:45]
	s_addc_u32 s55, s86, 0
	s_mov_b32 m0, s60
	s_nop 0
	global_load_lds_dwordx4 v128, s[54:55]
	s_waitcnt vmcnt(8)
	s_waitcnt lgkmcnt(0)
	s_barrier
	s_setprio 1
	s_waitcnt lgkmcnt(7)
	v_mfma_f32_16x16x32_bf16 v[124:127], v[130:133], v[168:171], v[124:127]
	v_mfma_f32_16x16x32_bf16 v[120:123], v[144:147], v[168:171], v[120:123]
	s_waitcnt lgkmcnt(5)
	v_mfma_f32_16x16x32_bf16 v[116:119], v[130:133], v[176:179], v[116:119]
	v_mfma_f32_16x16x32_bf16 v[112:115], v[144:147], v[176:179], v[112:115]
	s_waitcnt lgkmcnt(3)
	v_mfma_f32_16x16x32_bf16 v[108:111], v[130:133], v[184:187], v[108:111]
	v_mfma_f32_16x16x32_bf16 v[104:107], v[144:147], v[184:187], v[104:107]
	s_waitcnt lgkmcnt(1)
	v_mfma_f32_16x16x32_bf16 v[100:103], v[130:133], v[192:195], v[100:103]
	v_mfma_f32_16x16x32_bf16 v[96:99], v[144:147], v[192:195], v[96:99]
	v_mfma_f32_16x16x32_bf16 v[124:127], v[140:143], v[172:175], v[124:127]
	v_mfma_f32_16x16x32_bf16 v[120:123], v[148:151], v[172:175], v[120:123]
	v_mfma_f32_16x16x32_bf16 v[116:119], v[140:143], v[180:183], v[116:119]
	v_mfma_f32_16x16x32_bf16 v[112:115], v[148:151], v[180:183], v[112:115]
	v_mfma_f32_16x16x32_bf16 v[108:111], v[140:143], v[188:191], v[108:111]
	v_mfma_f32_16x16x32_bf16 v[104:107], v[148:151], v[188:191], v[104:107]
	s_waitcnt lgkmcnt(0)
	v_mfma_f32_16x16x32_bf16 v[100:103], v[140:143], v[196:199], v[100:103]
	v_mfma_f32_16x16x32_bf16 v[96:99], v[148:151], v[196:199], v[96:99]
	s_setprio 0
	s_setprio 1
	v_mfma_f32_16x16x32_bf16 v[92:95], v[152:155], v[168:171], v[92:95]
	v_mfma_f32_16x16x32_bf16 v[88:91], v[160:163], v[168:171], v[88:91]
	v_mfma_f32_16x16x32_bf16 v[84:87], v[152:155], v[176:179], v[84:87]
	v_mfma_f32_16x16x32_bf16 v[80:83], v[160:163], v[176:179], v[80:83]
	v_mfma_f32_16x16x32_bf16 v[76:79], v[152:155], v[184:187], v[76:79]
	v_mfma_f32_16x16x32_bf16 v[72:75], v[160:163], v[184:187], v[72:75]
	v_mfma_f32_16x16x32_bf16 v[68:71], v[152:155], v[192:195], v[68:71]
	v_mfma_f32_16x16x32_bf16 v[64:67], v[160:163], v[192:195], v[64:67]
	v_mfma_f32_16x16x32_bf16 v[92:95], v[156:159], v[172:175], v[92:95]
	v_mfma_f32_16x16x32_bf16 v[88:91], v[164:167], v[172:175], v[88:91]
	v_mfma_f32_16x16x32_bf16 v[84:87], v[156:159], v[180:183], v[84:87]
	v_mfma_f32_16x16x32_bf16 v[80:83], v[164:167], v[180:183], v[80:83]
	v_mfma_f32_16x16x32_bf16 v[76:79], v[156:159], v[188:191], v[76:79]
	v_mfma_f32_16x16x32_bf16 v[72:75], v[164:167], v[188:191], v[72:75]
	v_mfma_f32_16x16x32_bf16 v[68:71], v[156:159], v[196:199], v[68:71]
	v_mfma_f32_16x16x32_bf16 v[64:67], v[164:167], v[196:199], v[64:67]
	s_setprio 0
	s_barrier
	s_add_u32 s44, s87, 0x180
	s_addc_u32 s45, s88, 0
	ds_read_b128 v[168:171], v137 offset:49152
	ds_read_b128 v[172:175], v137 offset:50176
	ds_read_b128 v[176:179], v137 offset:51200
	ds_read_b128 v[180:183], v137 offset:52224
	ds_read_b128 v[184:187], v137 offset:53248
	ds_read_b128 v[188:191], v137 offset:54272
	ds_read_b128 v[192:195], v137 offset:55296
	ds_read_b128 v[196:199], v137 offset:56320
	s_add_u32 s54, s89, 0x180
	s_mov_b32 m0, s61
	s_nop 0
	global_load_lds_dwordx4 v129, s[44:45]
	s_addc_u32 s55, s90, 0
	s_mov_b32 m0, s62
	s_nop 0
	global_load_lds_dwordx4 v129, s[54:55]
	s_add_u32 s44, s91, 0x180
	s_addc_u32 s45, s92, 0
	s_add_u32 s54, s93, 0x180
	s_mov_b32 m0, s65
	s_nop 0
	global_load_lds_dwordx4 v129, s[44:45]
	s_addc_u32 s55, s94, 0
	s_mov_b32 m0, s66
	s_nop 0
	global_load_lds_dwordx4 v129, s[54:55]
	s_add_u32 s44, s79, 0x180
	s_addc_u32 s45, s80, 0
	s_add_u32 s54, s82, 0x180
	s_mov_b32 m0, s63
	s_nop 0
	global_load_lds_dwordx4 v128, s[44:45]
	s_addc_u32 s55, s83, 0
	s_mov_b32 m0, s64
	s_nop 0
	global_load_lds_dwordx4 v128, s[54:55]
	s_waitcnt vmcnt(8)
	s_waitcnt lgkmcnt(0)
	s_barrier
	s_setprio 1
	s_waitcnt lgkmcnt(7)
	v_mfma_f32_16x16x32_bf16 v[60:63], v[130:133], v[168:171], v[60:63]
	v_mfma_f32_16x16x32_bf16 v[56:59], v[144:147], v[168:171], v[56:59]
	s_waitcnt lgkmcnt(5)
	v_mfma_f32_16x16x32_bf16 v[52:55], v[130:133], v[176:179], v[52:55]
	v_mfma_f32_16x16x32_bf16 v[48:51], v[144:147], v[176:179], v[48:51]
	s_waitcnt lgkmcnt(3)
	v_mfma_f32_16x16x32_bf16 v[44:47], v[130:133], v[184:187], v[44:47]
	v_mfma_f32_16x16x32_bf16 v[40:43], v[144:147], v[184:187], v[40:43]
	s_waitcnt lgkmcnt(1)
	v_mfma_f32_16x16x32_bf16 v[36:39], v[130:133], v[192:195], v[36:39]
	v_mfma_f32_16x16x32_bf16 v[32:35], v[144:147], v[192:195], v[32:35]
	v_mfma_f32_16x16x32_bf16 v[60:63], v[140:143], v[172:175], v[60:63]
	v_mfma_f32_16x16x32_bf16 v[56:59], v[148:151], v[172:175], v[56:59]
	v_mfma_f32_16x16x32_bf16 v[52:55], v[140:143], v[180:183], v[52:55]
	v_mfma_f32_16x16x32_bf16 v[48:51], v[148:151], v[180:183], v[48:51]
	v_mfma_f32_16x16x32_bf16 v[44:47], v[140:143], v[188:191], v[44:47]
	v_mfma_f32_16x16x32_bf16 v[40:43], v[148:151], v[188:191], v[40:43]
	s_waitcnt lgkmcnt(0)
	v_mfma_f32_16x16x32_bf16 v[36:39], v[140:143], v[196:199], v[36:39]
	v_mfma_f32_16x16x32_bf16 v[32:35], v[148:151], v[196:199], v[32:35]
	s_setprio 0
	s_setprio 1
	v_mfma_f32_16x16x32_bf16 v[28:31], v[152:155], v[168:171], v[28:31]
	v_mfma_f32_16x16x32_bf16 v[24:27], v[160:163], v[168:171], v[24:27]
	v_mfma_f32_16x16x32_bf16 v[20:23], v[152:155], v[176:179], v[20:23]
	v_mfma_f32_16x16x32_bf16 v[16:19], v[160:163], v[176:179], v[16:19]
	v_mfma_f32_16x16x32_bf16 v[12:15], v[152:155], v[184:187], v[12:15]
	v_mfma_f32_16x16x32_bf16 v[8:11], v[160:163], v[184:187], v[8:11]
	v_mfma_f32_16x16x32_bf16 v[4:7], v[152:155], v[192:195], v[4:7]
	v_mfma_f32_16x16x32_bf16 v[0:3], v[160:163], v[192:195], v[0:3]
	v_mfma_f32_16x16x32_bf16 v[28:31], v[156:159], v[172:175], v[28:31]
	v_mfma_f32_16x16x32_bf16 v[24:27], v[164:167], v[172:175], v[24:27]
	v_mfma_f32_16x16x32_bf16 v[20:23], v[156:159], v[180:183], v[20:23]
	v_mfma_f32_16x16x32_bf16 v[16:19], v[164:167], v[180:183], v[16:19]
	v_mfma_f32_16x16x32_bf16 v[12:15], v[156:159], v[188:191], v[12:15]
	v_mfma_f32_16x16x32_bf16 v[8:11], v[164:167], v[188:191], v[8:11]
	v_mfma_f32_16x16x32_bf16 v[4:7], v[156:159], v[196:199], v[4:7]
	v_mfma_f32_16x16x32_bf16 v[0:3], v[164:167], v[196:199], v[0:3]
	s_setprio 0
	s_barrier
	s_add_u32 s42, s42, 0x100
	s_addc_u32 s43, s43, 0
	s_cmp_ge_i32 s78, s16
	s_cbranch_scc0 .LBB0_257
	s_branch .LBB0_258

.LBB0_274:
	s_cmp_lt_i32 s28, 3
	s_cbranch_scc1 .Lhz_276
	s_add_i32 s2, s28, -2
	s_add_u32 s20, s4, s48
	s_addc_u32 s33, s5, s49
	s_add_u32 s42, s6, s18
	s_addc_u32 s43, s7, s19
	s_add_u32 s38, s0, s18
	s_addc_u32 s39, s1, s19
	s_add_u32 s50, s6, s38
	s_addc_u32 s51, s7, s39
	s_add_u32 s68, s6, s0
	s_addc_u32 s69, s7, s1
	s_add_u32 s38, s46, s48
	s_addc_u32 s39, s47, s49
	s_add_u32 s70, s4, s38
	s_addc_u32 s71, s5, s39
	s_add_u32 s72, s4, s46
	s_addc_u32 s74, s5, s47
	s_mov_b32 s75, 0
	s_mov_b64 s[38:39], 0
	s_cmp_eq_u32 s98, 0
	s_cbranch_scc1 .Lhf_276
	ds_read_b128 v[130:133], v143
	ds_read_b128 v[134:137], v143 offset:1024
	ds_read_b128 v[138:141], v143 offset:2048
	ds_read_b128 v[148:151], v143 offset:3072
	ds_read_b128 v[152:155], v144
	ds_read_b128 v[156:159], v144 offset:1024
	ds_read_b128 v[160:163], v144 offset:2048
	ds_read_b128 v[164:167], v144 offset:3072
	s_add_i32 s75, s75, 2
	s_add_u32 s77, s4, s38
	s_addc_u32 s80, s5, s39
	s_add_u32 s40, s77, 0x100
	s_addc_u32 s41, s80, 0
	s_add_u32 s81, s20, s38
	ds_read_b128 v[168:171], v145
	ds_read_b128 v[172:175], v145 offset:1024
	ds_read_b128 v[176:179], v145 offset:2048
	ds_read_b128 v[180:183], v145 offset:3072
	ds_read_b128 v[184:187], v145 offset:4096
	ds_read_b128 v[188:191], v145 offset:5120
	ds_read_b128 v[192:195], v145 offset:6144
	ds_read_b128 v[196:199], v145 offset:7168
	s_addc_u32 s86, s33, s39
	s_add_u32 s54, s81, 0x80
	s_addc_u32 s55, s86, 0
	s_add_u32 s87, s70, s38
	s_addc_u32 s88, s71, s39
	s_add_u32 s84, s87, 0x80
	s_mov_b32 m0, s82
	s_nop 0
	global_load_lds_dwordx4 v128, s[54:55]
	s_addc_u32 s85, s88, 0
	s_mov_b32 m0, s83
	s_nop 0
	global_load_lds_dwordx4 v128, s[84:85]
	s_waitcnt vmcnt(24)
	s_waitcnt lgkmcnt(0)
	s_barrier
	s_setprio 1
	s_waitcnt lgkmcnt(7)
	v_mfma_f32_16x16x32_bf16 v[124:127], v[130:133], v[168:171], 0
	v_mfma_f32_16x16x32_bf16 v[120:123], v[138:141], v[168:171], 0
	s_waitcnt lgkmcnt(5)
	v_mfma_f32_16x16x32_bf16 v[116:119], v[130:133], v[176:179], 0
	v_mfma_f32_16x16x32_bf16 v[112:115], v[138:141], v[176:179], 0
	s_waitcnt lgkmcnt(3)
	v_mfma_f32_16x16x32_bf16 v[108:111], v[130:133], v[184:187], 0
	v_mfma_f32_16x16x32_bf16 v[104:107], v[138:141], v[184:187], 0
	s_waitcnt lgkmcnt(1)
	v_mfma_f32_16x16x32_bf16 v[100:103], v[130:133], v[192:195], 0
	v_mfma_f32_16x16x32_bf16 v[96:99], v[138:141], v[192:195], 0
	v_mfma_f32_16x16x32_bf16 v[124:127], v[134:137], v[172:175], v[124:127]
	v_mfma_f32_16x16x32_bf16 v[120:123], v[148:151], v[172:175], v[120:123]
	v_mfma_f32_16x16x32_bf16 v[116:119], v[134:137], v[180:183], v[116:119]
	v_mfma_f32_16x16x32_bf16 v[112:115], v[148:151], v[180:183], v[112:115]
	v_mfma_f32_16x16x32_bf16 v[108:111], v[134:137], v[188:191], v[108:111]
	v_mfma_f32_16x16x32_bf16 v[104:107], v[148:151], v[188:191], v[104:107]
	s_waitcnt lgkmcnt(0)
	v_mfma_f32_16x16x32_bf16 v[100:103], v[134:137], v[196:199], v[100:103]
	v_mfma_f32_16x16x32_bf16 v[96:99], v[148:151], v[196:199], v[96:99]
	s_setprio 0
	s_setprio 1
	v_mfma_f32_16x16x32_bf16 v[92:95], v[152:155], v[168:171], 0
	v_mfma_f32_16x16x32_bf16 v[88:91], v[160:163], v[168:171], 0
	v_mfma_f32_16x16x32_bf16 v[84:87], v[152:155], v[176:179], 0
	v_mfma_f32_16x16x32_bf16 v[80:83], v[160:163], v[176:179], 0
	v_mfma_f32_16x16x32_bf16 v[76:79], v[152:155], v[184:187], 0
	v_mfma_f32_16x16x32_bf16 v[72:75], v[160:163], v[184:187], 0
	v_mfma_f32_16x16x32_bf16 v[68:71], v[152:155], v[192:195], 0
	v_mfma_f32_16x16x32_bf16 v[64:67], v[160:163], v[192:195], 0
	v_mfma_f32_16x16x32_bf16 v[92:95], v[156:159], v[172:175], v[92:95]
	v_mfma_f32_16x16x32_bf16 v[88:91], v[164:167], v[172:175], v[88:91]
	v_mfma_f32_16x16x32_bf16 v[84:87], v[156:159], v[180:183], v[84:87]
	v_mfma_f32_16x16x32_bf16 v[80:83], v[164:167], v[180:183], v[80:83]
	v_mfma_f32_16x16x32_bf16 v[76:79], v[156:159], v[188:191], v[76:79]
	v_mfma_f32_16x16x32_bf16 v[72:75], v[164:167], v[188:191], v[72:75]
	v_mfma_f32_16x16x32_bf16 v[68:71], v[156:159], v[196:199], v[68:71]
	v_mfma_f32_16x16x32_bf16 v[64:67], v[164:167], v[196:199], v[64:67]
	s_setprio 0
	s_barrier
	s_add_u32 s89, s6, s38
	s_addc_u32 s90, s7, s39
	s_add_u32 s54, s89, 0x100
	s_addc_u32 s55, s90, 0
	s_add_u32 s91, s68, s38
	s_addc_u32 s92, s69, s39
	s_add_u32 s84, s91, 0x100
	ds_read_b128 v[168:171], v145 offset:16384
	ds_read_b128 v[172:175], v145 offset:17408
	ds_read_b128 v[176:179], v145 offset:18432
	ds_read_b128 v[180:183], v145 offset:19456
	ds_read_b128 v[184:187], v145 offset:20480
	ds_read_b128 v[188:191], v145 offset:21504
	ds_read_b128 v[192:195], v145 offset:22528
	ds_read_b128 v[196:199], v145 offset:23552
	s_addc_u32 s85, s92, 0
	s_mov_b32 m0, s58
	s_nop 0
	global_load_lds_dwordx4 v129, s[54:55]
	s_add_u32 s93, s42, s38
	s_mov_b32 m0, s59
	s_nop 0
	global_load_lds_dwordx4 v129, s[84:85]
	s_addc_u32 s94, s43, s39
	s_add_u32 s54, s93, 0x100
	s_addc_u32 s55, s94, 0
	s_add_u32 s96, s50, s38
	s_addc_u32 s97, s51, s39
	s_add_u32 s84, s96, 0x100
	s_addc_u32 s85, s97, 0
	s_mov_b32 m0, s60
	s_nop 0
	global_load_lds_dwordx4 v129, s[54:55]
	s_mov_b32 m0, s61
	s_nop 0
	global_load_lds_dwordx4 v129, s[84:85]
	s_add_u32 s84, s72, s38
	s_addc_u32 s85, s74, s39
	s_add_u32 s54, s84, 0x100
	s_mov_b32 m0, s53
	s_nop 0
	global_load_lds_dwordx4 v128, s[40:41]
	s_addc_u32 s55, s85, 0
	s_mov_b32 m0, s62
	s_nop 0
	global_load_lds_dwordx4 v128, s[54:55]
	s_waitcnt vmcnt(24)
	s_waitcnt lgkmcnt(0)
	s_barrier
	s_setprio 1
	s_waitcnt lgkmcnt(7)
	v_mfma_f32_16x16x32_bf16 v[60:63], v[130:133], v[168:171], 0
	v_mfma_f32_16x16x32_bf16 v[56:59], v[138:141], v[168:171], 0
	s_waitcnt lgkmcnt(5)
	v_mfma_f32_16x16x32_bf16 v[52:55], v[130:133], v[176:179], 0
	v_mfma_f32_16x16x32_bf16 v[48:51], v[138:141], v[176:179], 0
	s_waitcnt lgkmcnt(3)
	v_mfma_f32_16x16x32_bf16 v[44:47], v[130:133], v[184:187], 0
	v_mfma_f32_16x16x32_bf16 v[40:43], v[138:141], v[184:187], 0
	s_waitcnt lgkmcnt(1)
	v_mfma_f32_16x16x32_bf16 v[36:39], v[130:133], v[192:195], 0
	v_mfma_f32_16x16x32_bf16 v[32:35], v[138:141], v[192:195], 0
	v_mfma_f32_16x16x32_bf16 v[60:63], v[134:137], v[172:175], v[60:63]
	v_mfma_f32_16x16x32_bf16 v[56:59], v[148:151], v[172:175], v[56:59]
	v_mfma_f32_16x16x32_bf16 v[52:55], v[134:137], v[180:183], v[52:55]
	v_mfma_f32_16x16x32_bf16 v[48:51], v[148:151], v[180:183], v[48:51]
	v_mfma_f32_16x16x32_bf16 v[44:47], v[134:137], v[188:191], v[44:47]
	v_mfma_f32_16x16x32_bf16 v[40:43], v[148:151], v[188:191], v[40:43]
	s_waitcnt lgkmcnt(0)
	v_mfma_f32_16x16x32_bf16 v[36:39], v[134:137], v[196:199], v[36:39]
	v_mfma_f32_16x16x32_bf16 v[32:35], v[148:151], v[196:199], v[32:35]
	s_setprio 0
	s_setprio 1
	v_mfma_f32_16x16x32_bf16 v[28:31], v[152:155], v[168:171], 0
	v_mfma_f32_16x16x32_bf16 v[24:27], v[160:163], v[168:171], 0
	v_mfma_f32_16x16x32_bf16 v[20:23], v[152:155], v[176:179], 0
	v_mfma_f32_16x16x32_bf16 v[16:19], v[160:163], v[176:179], 0
	v_mfma_f32_16x16x32_bf16 v[12:15], v[152:155], v[184:187], 0
	v_mfma_f32_16x16x32_bf16 v[8:11], v[160:163], v[184:187], 0
	v_mfma_f32_16x16x32_bf16 v[4:7], v[152:155], v[192:195], 0
	v_mfma_f32_16x16x32_bf16 v[0:3], v[160:163], v[192:195], 0
	v_mfma_f32_16x16x32_bf16 v[28:31], v[156:159], v[172:175], v[28:31]
	v_mfma_f32_16x16x32_bf16 v[24:27], v[164:167], v[172:175], v[24:27]
	v_mfma_f32_16x16x32_bf16 v[20:23], v[156:159], v[180:183], v[20:23]
	v_mfma_f32_16x16x32_bf16 v[16:19], v[164:167], v[180:183], v[16:19]
	v_mfma_f32_16x16x32_bf16 v[12:15], v[156:159], v[188:191], v[12:15]
	v_mfma_f32_16x16x32_bf16 v[8:11], v[164:167], v[188:191], v[8:11]
	v_mfma_f32_16x16x32_bf16 v[4:7], v[156:159], v[196:199], v[4:7]
	v_mfma_f32_16x16x32_bf16 v[0:3], v[164:167], v[196:199], v[0:3]
	s_setprio 0
	s_barrier
	ds_read_b128 v[130:133], v146
	ds_read_b128 v[134:137], v146 offset:1024
	ds_read_b128 v[138:141], v146 offset:2048
	ds_read_b128 v[148:151], v146 offset:3072
	ds_read_b128 v[152:155], v147
	ds_read_b128 v[156:159], v147 offset:1024
	ds_read_b128 v[160:163], v147 offset:2048
	ds_read_b128 v[164:167], v147 offset:3072
	ds_read_b128 v[168:171], v145 offset:32768
	ds_read_b128 v[172:175], v145 offset:33792
	ds_read_b128 v[176:179], v145 offset:34816
	ds_read_b128 v[180:183], v145 offset:35840
	ds_read_b128 v[184:187], v145 offset:36864
	ds_read_b128 v[188:191], v145 offset:37888
	ds_read_b128 v[192:195], v145 offset:38912
	ds_read_b128 v[196:199], v145 offset:39936
	s_add_u32 s40, s81, 0x100
	s_addc_u32 s41, s86, 0
	s_add_u32 s54, s87, 0x100
	s_mov_b32 m0, s63
	s_nop 0
	global_load_lds_dwordx4 v128, s[40:41]
	s_addc_u32 s55, s88, 0
	s_mov_b32 m0, s64
	s_nop 0
	global_load_lds_dwordx4 v128, s[54:55]
	s_waitcnt vmcnt(8)
	s_waitcnt lgkmcnt(0)
	s_barrier
	s_setprio 1
	s_waitcnt lgkmcnt(7)
	v_mfma_f32_16x16x32_bf16 v[124:127], v[130:133], v[168:171], v[124:127]
	v_mfma_f32_16x16x32_bf16 v[120:123], v[138:141], v[168:171], v[120:123]
	s_waitcnt lgkmcnt(5)
	v_mfma_f32_16x16x32_bf16 v[116:119], v[130:133], v[176:179], v[116:119]
	v_mfma_f32_16x16x32_bf16 v[112:115], v[138:141], v[176:179], v[112:115]
	s_waitcnt lgkmcnt(3)
	v_mfma_f32_16x16x32_bf16 v[108:111], v[130:133], v[184:187], v[108:111]
	v_mfma_f32_16x16x32_bf16 v[104:107], v[138:141], v[184:187], v[104:107]
	s_waitcnt lgkmcnt(1)
	v_mfma_f32_16x16x32_bf16 v[100:103], v[130:133], v[192:195], v[100:103]
	v_mfma_f32_16x16x32_bf16 v[96:99], v[138:141], v[192:195], v[96:99]
	v_mfma_f32_16x16x32_bf16 v[124:127], v[134:137], v[172:175], v[124:127]
	v_mfma_f32_16x16x32_bf16 v[120:123], v[148:151], v[172:175], v[120:123]
	v_mfma_f32_16x16x32_bf16 v[116:119], v[134:137], v[180:183], v[116:119]
	v_mfma_f32_16x16x32_bf16 v[112:115], v[148:151], v[180:183], v[112:115]
	v_mfma_f32_16x16x32_bf16 v[108:111], v[134:137], v[188:191], v[108:111]
	v_mfma_f32_16x16x32_bf16 v[104:107], v[148:151], v[188:191], v[104:107]
	s_waitcnt lgkmcnt(0)
	v_mfma_f32_16x16x32_bf16 v[100:103], v[134:137], v[196:199], v[100:103]
	v_mfma_f32_16x16x32_bf16 v[96:99], v[148:151], v[196:199], v[96:99]
	s_setprio 0
	s_setprio 1
	v_mfma_f32_16x16x32_bf16 v[92:95], v[152:155], v[168:171], v[92:95]
	v_mfma_f32_16x16x32_bf16 v[88:91], v[160:163], v[168:171], v[88:91]
	v_mfma_f32_16x16x32_bf16 v[84:87], v[152:155], v[176:179], v[84:87]
	v_mfma_f32_16x16x32_bf16 v[80:83], v[160:163], v[176:179], v[80:83]
	v_mfma_f32_16x16x32_bf16 v[76:79], v[152:155], v[184:187], v[76:79]
	v_mfma_f32_16x16x32_bf16 v[72:75], v[160:163], v[184:187], v[72:75]
	v_mfma_f32_16x16x32_bf16 v[68:71], v[152:155], v[192:195], v[68:71]
	v_mfma_f32_16x16x32_bf16 v[64:67], v[160:163], v[192:195], v[64:67]
	v_mfma_f32_16x16x32_bf16 v[92:95], v[156:159], v[172:175], v[92:95]
	v_mfma_f32_16x16x32_bf16 v[88:91], v[164:167], v[172:175], v[88:91]
	v_mfma_f32_16x16x32_bf16 v[84:87], v[156:159], v[180:183], v[84:87]
	v_mfma_f32_16x16x32_bf16 v[80:83], v[164:167], v[180:183], v[80:83]
	v_mfma_f32_16x16x32_bf16 v[76:79], v[156:159], v[188:191], v[76:79]
	v_mfma_f32_16x16x32_bf16 v[72:75], v[164:167], v[188:191], v[72:75]
	v_mfma_f32_16x16x32_bf16 v[68:71], v[156:159], v[196:199], v[68:71]
	v_mfma_f32_16x16x32_bf16 v[64:67], v[164:167], v[196:199], v[64:67]
	s_setprio 0
	s_barrier
	s_add_u32 s40, s89, 0x180
	s_addc_u32 s41, s90, 0
	ds_read_b128 v[168:171], v145 offset:49152
	ds_read_b128 v[172:175], v145 offset:50176
	ds_read_b128 v[176:179], v145 offset:51200
	ds_read_b128 v[180:183], v145 offset:52224
	ds_read_b128 v[184:187], v145 offset:53248
	ds_read_b128 v[188:191], v145 offset:54272
	ds_read_b128 v[192:195], v145 offset:55296
	ds_read_b128 v[196:199], v145 offset:56320
	s_add_u32 s54, s91, 0x180
	s_mov_b32 m0, s65
	s_nop 0
	global_load_lds_dwordx4 v129, s[40:41]
	s_addc_u32 s55, s92, 0
	s_mov_b32 m0, s66
	s_nop 0
	global_load_lds_dwordx4 v129, s[54:55]
	s_add_u32 s40, s93, 0x180
	s_addc_u32 s41, s94, 0
	s_add_u32 s54, s96, 0x180
	s_mov_b32 m0, s78
	s_nop 0
	global_load_lds_dwordx4 v129, s[40:41]
	s_addc_u32 s55, s97, 0
	s_mov_b32 m0, s79
	s_nop 0
	global_load_lds_dwordx4 v129, s[54:55]
	s_add_u32 s40, s77, 0x180
	s_addc_u32 s41, s80, 0
	s_add_u32 s54, s84, 0x180
	s_mov_b32 m0, s67
	s_nop 0
	global_load_lds_dwordx4 v128, s[40:41]
	s_addc_u32 s55, s85, 0
	s_mov_b32 m0, s73
	s_nop 0
	global_load_lds_dwordx4 v128, s[54:55]
	s_waitcnt vmcnt(8)
	s_waitcnt lgkmcnt(0)
	s_barrier
	s_setprio 1
	s_waitcnt lgkmcnt(7)
	v_mfma_f32_16x16x32_bf16 v[60:63], v[130:133], v[168:171], v[60:63]
	v_mfma_f32_16x16x32_bf16 v[56:59], v[138:141], v[168:171], v[56:59]
	s_waitcnt lgkmcnt(5)
	v_mfma_f32_16x16x32_bf16 v[52:55], v[130:133], v[176:179], v[52:55]
	v_mfma_f32_16x16x32_bf16 v[48:51], v[138:141], v[176:179], v[48:51]
	s_waitcnt lgkmcnt(3)
	v_mfma_f32_16x16x32_bf16 v[44:47], v[130:133], v[184:187], v[44:47]
	v_mfma_f32_16x16x32_bf16 v[40:43], v[138:141], v[184:187], v[40:43]
	s_waitcnt lgkmcnt(1)
	v_mfma_f32_16x16x32_bf16 v[36:39], v[130:133], v[192:195], v[36:39]
	v_mfma_f32_16x16x32_bf16 v[32:35], v[138:141], v[192:195], v[32:35]
	v_mfma_f32_16x16x32_bf16 v[60:63], v[134:137], v[172:175], v[60:63]
	v_mfma_f32_16x16x32_bf16 v[56:59], v[148:151], v[172:175], v[56:59]
	v_mfma_f32_16x16x32_bf16 v[52:55], v[134:137], v[180:183], v[52:55]
	v_mfma_f32_16x16x32_bf16 v[48:51], v[148:151], v[180:183], v[48:51]
	v_mfma_f32_16x16x32_bf16 v[44:47], v[134:137], v[188:191], v[44:47]
	v_mfma_f32_16x16x32_bf16 v[40:43], v[148:151], v[188:191], v[40:43]
	s_waitcnt lgkmcnt(0)
	v_mfma_f32_16x16x32_bf16 v[36:39], v[134:137], v[196:199], v[36:39]
	v_mfma_f32_16x16x32_bf16 v[32:35], v[148:151], v[196:199], v[32:35]
	s_setprio 0
	s_setprio 1
	v_mfma_f32_16x16x32_bf16 v[28:31], v[152:155], v[168:171], v[28:31]
	v_mfma_f32_16x16x32_bf16 v[24:27], v[160:163], v[168:171], v[24:27]
	v_mfma_f32_16x16x32_bf16 v[20:23], v[152:155], v[176:179], v[20:23]
	v_mfma_f32_16x16x32_bf16 v[16:19], v[160:163], v[176:179], v[16:19]
	v_mfma_f32_16x16x32_bf16 v[12:15], v[152:155], v[184:187], v[12:15]
	v_mfma_f32_16x16x32_bf16 v[8:11], v[160:163], v[184:187], v[8:11]
	v_mfma_f32_16x16x32_bf16 v[4:7], v[152:155], v[192:195], v[4:7]
	v_mfma_f32_16x16x32_bf16 v[0:3], v[160:163], v[192:195], v[0:3]
	v_mfma_f32_16x16x32_bf16 v[28:31], v[156:159], v[172:175], v[28:31]
	v_mfma_f32_16x16x32_bf16 v[24:27], v[164:167], v[172:175], v[24:27]
	v_mfma_f32_16x16x32_bf16 v[20:23], v[156:159], v[180:183], v[20:23]
	v_mfma_f32_16x16x32_bf16 v[16:19], v[164:167], v[180:183], v[16:19]
	v_mfma_f32_16x16x32_bf16 v[12:15], v[156:159], v[188:191], v[12:15]
	v_mfma_f32_16x16x32_bf16 v[8:11], v[164:167], v[188:191], v[8:11]
	v_mfma_f32_16x16x32_bf16 v[4:7], v[156:159], v[196:199], v[4:7]
	v_mfma_f32_16x16x32_bf16 v[0:3], v[164:167], v[196:199], v[0:3]
	s_setprio 0
	s_barrier
	s_add_u32 s38, s38, 0x100
	s_addc_u32 s39, s39, 0
	s_cmp_ge_i32 s75, s2
	s_cbranch_scc0 .LBB0_276
	s_branch .LBB0_277
.Lhf_276:
	ds_read_b128 v[130:133], v143
	ds_read_b128 v[134:137], v143 offset:1024
	ds_read_b128 v[138:141], v143 offset:2048
	ds_read_b128 v[148:151], v143 offset:3072
	ds_read_b128 v[152:155], v144
	ds_read_b128 v[156:159], v144 offset:1024
	ds_read_b128 v[160:163], v144 offset:2048
	ds_read_b128 v[164:167], v144 offset:3072
	s_add_i32 s75, s75, 2
	s_add_u32 s77, s4, s38
	s_addc_u32 s80, s5, s39
	s_add_u32 s40, s77, 0x100
	s_addc_u32 s41, s80, 0
	s_add_u32 s81, s20, s38
	ds_read_b128 v[168:171], v145
	ds_read_b128 v[172:175], v145 offset:1024
	ds_read_b128 v[176:179], v145 offset:2048
	ds_read_b128 v[180:183], v145 offset:3072
	ds_read_b128 v[184:187], v145 offset:4096
	ds_read_b128 v[188:191], v145 offset:5120
	ds_read_b128 v[192:195], v145 offset:6144
	ds_read_b128 v[196:199], v145 offset:7168
	s_addc_u32 s86, s33, s39
	s_add_u32 s54, s81, 0x80
	s_addc_u32 s55, s86, 0
	s_add_u32 s87, s70, s38
	s_addc_u32 s88, s71, s39
	s_add_u32 s84, s87, 0x80
	s_mov_b32 m0, s82
	s_nop 0
	global_load_lds_dwordx4 v128, s[54:55]
	s_addc_u32 s85, s88, 0
	s_mov_b32 m0, s83
	s_nop 0
	global_load_lds_dwordx4 v128, s[84:85]
	s_waitcnt vmcnt(8)
	s_waitcnt lgkmcnt(0)
	s_barrier
	s_setprio 1
	s_waitcnt lgkmcnt(7)
	v_mfma_f32_16x16x32_bf16 v[124:127], v[130:133], v[168:171], 0
	v_mfma_f32_16x16x32_bf16 v[120:123], v[138:141], v[168:171], 0
	s_waitcnt lgkmcnt(5)
	v_mfma_f32_16x16x32_bf16 v[116:119], v[130:133], v[176:179], 0
	v_mfma_f32_16x16x32_bf16 v[112:115], v[138:141], v[176:179], 0
	s_waitcnt lgkmcnt(3)
	v_mfma_f32_16x16x32_bf16 v[108:111], v[130:133], v[184:187], 0
	v_mfma_f32_16x16x32_bf16 v[104:107], v[138:141], v[184:187], 0
	s_waitcnt lgkmcnt(1)
	v_mfma_f32_16x16x32_bf16 v[100:103], v[130:133], v[192:195], 0
	v_mfma_f32_16x16x32_bf16 v[96:99], v[138:141], v[192:195], 0
	v_mfma_f32_16x16x32_bf16 v[124:127], v[134:137], v[172:175], v[124:127]
	v_mfma_f32_16x16x32_bf16 v[120:123], v[148:151], v[172:175], v[120:123]
	v_mfma_f32_16x16x32_bf16 v[116:119], v[134:137], v[180:183], v[116:119]
	v_mfma_f32_16x16x32_bf16 v[112:115], v[148:151], v[180:183], v[112:115]
	v_mfma_f32_16x16x32_bf16 v[108:111], v[134:137], v[188:191], v[108:111]
	v_mfma_f32_16x16x32_bf16 v[104:107], v[148:151], v[188:191], v[104:107]
	s_waitcnt lgkmcnt(0)
	v_mfma_f32_16x16x32_bf16 v[100:103], v[134:137], v[196:199], v[100:103]
	v_mfma_f32_16x16x32_bf16 v[96:99], v[148:151], v[196:199], v[96:99]
	s_setprio 0
	s_setprio 1
	v_mfma_f32_16x16x32_bf16 v[92:95], v[152:155], v[168:171], 0
	v_mfma_f32_16x16x32_bf16 v[88:91], v[160:163], v[168:171], 0
	v_mfma_f32_16x16x32_bf16 v[84:87], v[152:155], v[176:179], 0
	v_mfma_f32_16x16x32_bf16 v[80:83], v[160:163], v[176:179], 0
	v_mfma_f32_16x16x32_bf16 v[76:79], v[152:155], v[184:187], 0
	v_mfma_f32_16x16x32_bf16 v[72:75], v[160:163], v[184:187], 0
	v_mfma_f32_16x16x32_bf16 v[68:71], v[152:155], v[192:195], 0
	v_mfma_f32_16x16x32_bf16 v[64:67], v[160:163], v[192:195], 0
	v_mfma_f32_16x16x32_bf16 v[92:95], v[156:159], v[172:175], v[92:95]
	v_mfma_f32_16x16x32_bf16 v[88:91], v[164:167], v[172:175], v[88:91]
	v_mfma_f32_16x16x32_bf16 v[84:87], v[156:159], v[180:183], v[84:87]
	v_mfma_f32_16x16x32_bf16 v[80:83], v[164:167], v[180:183], v[80:83]
	v_mfma_f32_16x16x32_bf16 v[76:79], v[156:159], v[188:191], v[76:79]
	v_mfma_f32_16x16x32_bf16 v[72:75], v[164:167], v[188:191], v[72:75]
	v_mfma_f32_16x16x32_bf16 v[68:71], v[156:159], v[196:199], v[68:71]
	v_mfma_f32_16x16x32_bf16 v[64:67], v[164:167], v[196:199], v[64:67]
	s_setprio 0
	s_barrier
	s_add_u32 s89, s6, s38
	s_addc_u32 s90, s7, s39
	s_add_u32 s54, s89, 0x100
	s_addc_u32 s55, s90, 0
	s_add_u32 s91, s68, s38
	s_addc_u32 s92, s69, s39
	s_add_u32 s84, s91, 0x100
	ds_read_b128 v[168:171], v145 offset:16384
	ds_read_b128 v[172:175], v145 offset:17408
	ds_read_b128 v[176:179], v145 offset:18432
	ds_read_b128 v[180:183], v145 offset:19456
	ds_read_b128 v[184:187], v145 offset:20480
	ds_read_b128 v[188:191], v145 offset:21504
	ds_read_b128 v[192:195], v145 offset:22528
	ds_read_b128 v[196:199], v145 offset:23552
	s_addc_u32 s85, s92, 0
	s_mov_b32 m0, s58
	s_nop 0
	global_load_lds_dwordx4 v129, s[54:55]
	s_add_u32 s93, s42, s38
	s_mov_b32 m0, s59
	s_nop 0
	global_load_lds_dwordx4 v129, s[84:85]
	s_addc_u32 s94, s43, s39
	s_add_u32 s54, s93, 0x100
	s_addc_u32 s55, s94, 0
	s_add_u32 s96, s50, s38
	s_addc_u32 s97, s51, s39
	s_add_u32 s84, s96, 0x100
	s_addc_u32 s85, s97, 0
	s_mov_b32 m0, s60
	s_nop 0
	global_load_lds_dwordx4 v129, s[54:55]
	s_mov_b32 m0, s61
	s_nop 0
	global_load_lds_dwordx4 v129, s[84:85]
	s_add_u32 s84, s72, s38
	s_addc_u32 s85, s74, s39
	s_add_u32 s54, s84, 0x100
	s_mov_b32 m0, s53
	s_nop 0
	global_load_lds_dwordx4 v128, s[40:41]
	s_addc_u32 s55, s85, 0
	s_mov_b32 m0, s62
	s_nop 0
	global_load_lds_dwordx4 v128, s[54:55]
	s_waitcnt vmcnt(8)
	s_waitcnt lgkmcnt(0)
	s_barrier
	s_setprio 1
	s_waitcnt lgkmcnt(7)
	v_mfma_f32_16x16x32_bf16 v[60:63], v[130:133], v[168:171], 0
	v_mfma_f32_16x16x32_bf16 v[56:59], v[138:141], v[168:171], 0
	s_waitcnt lgkmcnt(5)
	v_mfma_f32_16x16x32_bf16 v[52:55], v[130:133], v[176:179], 0
	v_mfma_f32_16x16x32_bf16 v[48:51], v[138:141], v[176:179], 0
	s_waitcnt lgkmcnt(3)
	v_mfma_f32_16x16x32_bf16 v[44:47], v[130:133], v[184:187], 0
	v_mfma_f32_16x16x32_bf16 v[40:43], v[138:141], v[184:187], 0
	s_waitcnt lgkmcnt(1)
	v_mfma_f32_16x16x32_bf16 v[36:39], v[130:133], v[192:195], 0
	v_mfma_f32_16x16x32_bf16 v[32:35], v[138:141], v[192:195], 0
	v_mfma_f32_16x16x32_bf16 v[60:63], v[134:137], v[172:175], v[60:63]
	v_mfma_f32_16x16x32_bf16 v[56:59], v[148:151], v[172:175], v[56:59]
	v_mfma_f32_16x16x32_bf16 v[52:55], v[134:137], v[180:183], v[52:55]
	v_mfma_f32_16x16x32_bf16 v[48:51], v[148:151], v[180:183], v[48:51]
	v_mfma_f32_16x16x32_bf16 v[44:47], v[134:137], v[188:191], v[44:47]
	v_mfma_f32_16x16x32_bf16 v[40:43], v[148:151], v[188:191], v[40:43]
	s_waitcnt lgkmcnt(0)
	v_mfma_f32_16x16x32_bf16 v[36:39], v[134:137], v[196:199], v[36:39]
	v_mfma_f32_16x16x32_bf16 v[32:35], v[148:151], v[196:199], v[32:35]
	s_setprio 0
	s_setprio 1
	v_mfma_f32_16x16x32_bf16 v[28:31], v[152:155], v[168:171], 0
	v_mfma_f32_16x16x32_bf16 v[24:27], v[160:163], v[168:171], 0
	v_mfma_f32_16x16x32_bf16 v[20:23], v[152:155], v[176:179], 0
	v_mfma_f32_16x16x32_bf16 v[16:19], v[160:163], v[176:179], 0
	v_mfma_f32_16x16x32_bf16 v[12:15], v[152:155], v[184:187], 0
	v_mfma_f32_16x16x32_bf16 v[8:11], v[160:163], v[184:187], 0
	v_mfma_f32_16x16x32_bf16 v[4:7], v[152:155], v[192:195], 0
	v_mfma_f32_16x16x32_bf16 v[0:3], v[160:163], v[192:195], 0
	v_mfma_f32_16x16x32_bf16 v[28:31], v[156:159], v[172:175], v[28:31]
	v_mfma_f32_16x16x32_bf16 v[24:27], v[164:167], v[172:175], v[24:27]
	v_mfma_f32_16x16x32_bf16 v[20:23], v[156:159], v[180:183], v[20:23]
	v_mfma_f32_16x16x32_bf16 v[16:19], v[164:167], v[180:183], v[16:19]
	v_mfma_f32_16x16x32_bf16 v[12:15], v[156:159], v[188:191], v[12:15]
	v_mfma_f32_16x16x32_bf16 v[8:11], v[164:167], v[188:191], v[8:11]
	v_mfma_f32_16x16x32_bf16 v[4:7], v[156:159], v[196:199], v[4:7]
	v_mfma_f32_16x16x32_bf16 v[0:3], v[164:167], v[196:199], v[0:3]
	s_setprio 0
	s_barrier
	ds_read_b128 v[130:133], v146
	ds_read_b128 v[134:137], v146 offset:1024
	ds_read_b128 v[138:141], v146 offset:2048
	ds_read_b128 v[148:151], v146 offset:3072
	ds_read_b128 v[152:155], v147
	ds_read_b128 v[156:159], v147 offset:1024
	ds_read_b128 v[160:163], v147 offset:2048
	ds_read_b128 v[164:167], v147 offset:3072
	ds_read_b128 v[168:171], v145 offset:32768
	ds_read_b128 v[172:175], v145 offset:33792
	ds_read_b128 v[176:179], v145 offset:34816
	ds_read_b128 v[180:183], v145 offset:35840
	ds_read_b128 v[184:187], v145 offset:36864
	ds_read_b128 v[188:191], v145 offset:37888
	ds_read_b128 v[192:195], v145 offset:38912
	ds_read_b128 v[196:199], v145 offset:39936
	s_add_u32 s40, s81, 0x100
	s_addc_u32 s41, s86, 0
	s_add_u32 s54, s87, 0x100
	s_mov_b32 m0, s63
	s_nop 0
	global_load_lds_dwordx4 v128, s[40:41]
	s_addc_u32 s55, s88, 0
	s_mov_b32 m0, s64
	s_nop 0
	global_load_lds_dwordx4 v128, s[54:55]
	s_waitcnt vmcnt(8)
	s_waitcnt lgkmcnt(0)
	s_barrier
	s_setprio 1
	s_waitcnt lgkmcnt(7)
	v_mfma_f32_16x16x32_bf16 v[124:127], v[130:133], v[168:171], v[124:127]
	v_mfma_f32_16x16x32_bf16 v[120:123], v[138:141], v[168:171], v[120:123]
	s_waitcnt lgkmcnt(5)
	v_mfma_f32_16x16x32_bf16 v[116:119], v[130:133], v[176:179], v[116:119]
	v_mfma_f32_16x16x32_bf16 v[112:115], v[138:141], v[176:179], v[112:115]
	s_waitcnt lgkmcnt(3)
	v_mfma_f32_16x16x32_bf16 v[108:111], v[130:133], v[184:187], v[108:111]
	v_mfma_f32_16x16x32_bf16 v[104:107], v[138:141], v[184:187], v[104:107]
	s_waitcnt lgkmcnt(1)
	v_mfma_f32_16x16x32_bf16 v[100:103], v[130:133], v[192:195], v[100:103]
	v_mfma_f32_16x16x32_bf16 v[96:99], v[138:141], v[192:195], v[96:99]
	v_mfma_f32_16x16x32_bf16 v[124:127], v[134:137], v[172:175], v[124:127]
	v_mfma_f32_16x16x32_bf16 v[120:123], v[148:151], v[172:175], v[120:123]
	v_mfma_f32_16x16x32_bf16 v[116:119], v[134:137], v[180:183], v[116:119]
	v_mfma_f32_16x16x32_bf16 v[112:115], v[148:151], v[180:183], v[112:115]
	v_mfma_f32_16x16x32_bf16 v[108:111], v[134:137], v[188:191], v[108:111]
	v_mfma_f32_16x16x32_bf16 v[104:107], v[148:151], v[188:191], v[104:107]
	s_waitcnt lgkmcnt(0)
	v_mfma_f32_16x16x32_bf16 v[100:103], v[134:137], v[196:199], v[100:103]
	v_mfma_f32_16x16x32_bf16 v[96:99], v[148:151], v[196:199], v[96:99]
	s_setprio 0
	s_setprio 1
	v_mfma_f32_16x16x32_bf16 v[92:95], v[152:155], v[168:171], v[92:95]
	v_mfma_f32_16x16x32_bf16 v[88:91], v[160:163], v[168:171], v[88:91]
	v_mfma_f32_16x16x32_bf16 v[84:87], v[152:155], v[176:179], v[84:87]
	v_mfma_f32_16x16x32_bf16 v[80:83], v[160:163], v[176:179], v[80:83]
	v_mfma_f32_16x16x32_bf16 v[76:79], v[152:155], v[184:187], v[76:79]
	v_mfma_f32_16x16x32_bf16 v[72:75], v[160:163], v[184:187], v[72:75]
	v_mfma_f32_16x16x32_bf16 v[68:71], v[152:155], v[192:195], v[68:71]
	v_mfma_f32_16x16x32_bf16 v[64:67], v[160:163], v[192:195], v[64:67]
	v_mfma_f32_16x16x32_bf16 v[92:95], v[156:159], v[172:175], v[92:95]
	v_mfma_f32_16x16x32_bf16 v[88:91], v[164:167], v[172:175], v[88:91]
	v_mfma_f32_16x16x32_bf16 v[84:87], v[156:159], v[180:183], v[84:87]
	v_mfma_f32_16x16x32_bf16 v[80:83], v[164:167], v[180:183], v[80:83]
	v_mfma_f32_16x16x32_bf16 v[76:79], v[156:159], v[188:191], v[76:79]
	v_mfma_f32_16x16x32_bf16 v[72:75], v[164:167], v[188:191], v[72:75]
	v_mfma_f32_16x16x32_bf16 v[68:71], v[156:159], v[196:199], v[68:71]
	v_mfma_f32_16x16x32_bf16 v[64:67], v[164:167], v[196:199], v[64:67]
	s_setprio 0
	s_barrier
	s_add_u32 s40, s89, 0x180
	s_addc_u32 s41, s90, 0
	ds_read_b128 v[168:171], v145 offset:49152
	ds_read_b128 v[172:175], v145 offset:50176
	ds_read_b128 v[176:179], v145 offset:51200
	ds_read_b128 v[180:183], v145 offset:52224
	ds_read_b128 v[184:187], v145 offset:53248
	ds_read_b128 v[188:191], v145 offset:54272
	ds_read_b128 v[192:195], v145 offset:55296
	ds_read_b128 v[196:199], v145 offset:56320
	s_add_u32 s54, s91, 0x180
	s_mov_b32 m0, s65
	s_nop 0
	global_load_lds_dwordx4 v129, s[40:41]
	s_addc_u32 s55, s92, 0
	s_mov_b32 m0, s66
	s_nop 0
	global_load_lds_dwordx4 v129, s[54:55]
	s_add_u32 s40, s93, 0x180
	s_addc_u32 s41, s94, 0
	s_add_u32 s54, s96, 0x180
	s_mov_b32 m0, s78
	s_nop 0
	global_load_lds_dwordx4 v129, s[40:41]
	s_addc_u32 s55, s97, 0
	s_mov_b32 m0, s79
	s_nop 0
	global_load_lds_dwordx4 v129, s[54:55]
	s_add_u32 s40, s77, 0x180
	s_addc_u32 s41, s80, 0
	s_add_u32 s54, s84, 0x180
	s_mov_b32 m0, s67
	s_nop 0
	global_load_lds_dwordx4 v128, s[40:41]
	s_addc_u32 s55, s85, 0
	s_mov_b32 m0, s73
	s_nop 0
	global_load_lds_dwordx4 v128, s[54:55]
	s_waitcnt vmcnt(8)
	s_waitcnt lgkmcnt(0)
	s_barrier
	s_setprio 1
	s_waitcnt lgkmcnt(7)
	v_mfma_f32_16x16x32_bf16 v[60:63], v[130:133], v[168:171], v[60:63]
	v_mfma_f32_16x16x32_bf16 v[56:59], v[138:141], v[168:171], v[56:59]
	s_waitcnt lgkmcnt(5)
	v_mfma_f32_16x16x32_bf16 v[52:55], v[130:133], v[176:179], v[52:55]
	v_mfma_f32_16x16x32_bf16 v[48:51], v[138:141], v[176:179], v[48:51]
	s_waitcnt lgkmcnt(3)
	v_mfma_f32_16x16x32_bf16 v[44:47], v[130:133], v[184:187], v[44:47]
	v_mfma_f32_16x16x32_bf16 v[40:43], v[138:141], v[184:187], v[40:43]
	s_waitcnt lgkmcnt(1)
	v_mfma_f32_16x16x32_bf16 v[36:39], v[130:133], v[192:195], v[36:39]
	v_mfma_f32_16x16x32_bf16 v[32:35], v[138:141], v[192:195], v[32:35]
	v_mfma_f32_16x16x32_bf16 v[60:63], v[134:137], v[172:175], v[60:63]
	v_mfma_f32_16x16x32_bf16 v[56:59], v[148:151], v[172:175], v[56:59]
	v_mfma_f32_16x16x32_bf16 v[52:55], v[134:137], v[180:183], v[52:55]
	v_mfma_f32_16x16x32_bf16 v[48:51], v[148:151], v[180:183], v[48:51]
	v_mfma_f32_16x16x32_bf16 v[44:47], v[134:137], v[188:191], v[44:47]
	v_mfma_f32_16x16x32_bf16 v[40:43], v[148:151], v[188:191], v[40:43]
	s_waitcnt lgkmcnt(0)
	v_mfma_f32_16x16x32_bf16 v[36:39], v[134:137], v[196:199], v[36:39]
	v_mfma_f32_16x16x32_bf16 v[32:35], v[148:151], v[196:199], v[32:35]
	s_setprio 0
	s_setprio 1
	v_mfma_f32_16x16x32_bf16 v[28:31], v[152:155], v[168:171], v[28:31]
	v_mfma_f32_16x16x32_bf16 v[24:27], v[160:163], v[168:171], v[24:27]
	v_mfma_f32_16x16x32_bf16 v[20:23], v[152:155], v[176:179], v[20:23]
	v_mfma_f32_16x16x32_bf16 v[16:19], v[160:163], v[176:179], v[16:19]
	v_mfma_f32_16x16x32_bf16 v[12:15], v[152:155], v[184:187], v[12:15]
	v_mfma_f32_16x16x32_bf16 v[8:11], v[160:163], v[184:187], v[8:11]
	v_mfma_f32_16x16x32_bf16 v[4:7], v[152:155], v[192:195], v[4:7]
	v_mfma_f32_16x16x32_bf16 v[0:3], v[160:163], v[192:195], v[0:3]
	v_mfma_f32_16x16x32_bf16 v[28:31], v[156:159], v[172:175], v[28:31]
	v_mfma_f32_16x16x32_bf16 v[24:27], v[164:167], v[172:175], v[24:27]
	v_mfma_f32_16x16x32_bf16 v[20:23], v[156:159], v[180:183], v[20:23]
	v_mfma_f32_16x16x32_bf16 v[16:19], v[164:167], v[180:183], v[16:19]
	v_mfma_f32_16x16x32_bf16 v[12:15], v[156:159], v[188:191], v[12:15]
	v_mfma_f32_16x16x32_bf16 v[8:11], v[164:167], v[188:191], v[8:11]
	v_mfma_f32_16x16x32_bf16 v[4:7], v[156:159], v[196:199], v[4:7]
	v_mfma_f32_16x16x32_bf16 v[0:3], v[164:167], v[196:199], v[0:3]
	s_setprio 0
	s_barrier
	s_add_u32 s38, s38, 0x100
	s_addc_u32 s39, s39, 0
	s_cmp_ge_i32 s75, s2
	s_cbranch_scc0 .LBB0_276
	s_branch .LBB0_277

.LBB0_293:
	s_cmp_lt_i32 s30, 3
	s_cbranch_scc1 .Lhz_295
	s_add_i32 s0, s30, -2
	s_add_u32 s2, s4, s44
	s_addc_u32 s33, s5, s45
	s_add_u32 s38, s6, s22
	s_addc_u32 s39, s7, s23
	s_add_u32 s34, s16, s22
	s_addc_u32 s35, s17, s23
	s_add_u32 s46, s6, s34
	s_addc_u32 s47, s7, s35
	s_add_u32 s68, s6, s16
	s_addc_u32 s69, s7, s17
	s_add_u32 s34, s42, s44
	s_addc_u32 s35, s43, s45
	s_add_u32 s70, s4, s34
	s_addc_u32 s71, s5, s35
	s_add_u32 s72, s4, s42
	s_addc_u32 s74, s5, s43
	s_mov_b32 s75, 0
	s_mov_b64 s[34:35], 0
	s_cmp_eq_u32 s98, 0
	s_cbranch_scc1 .Lhf_295
	ds_read_b128 v[132:135], v137
	ds_read_b128 v[142:145], v137 offset:1024
	ds_read_b128 v[146:149], v137 offset:2048
	ds_read_b128 v[150:153], v137 offset:3072
	ds_read_b128 v[154:157], v138
	ds_read_b128 v[158:161], v138 offset:1024
	ds_read_b128 v[162:165], v138 offset:2048
	ds_read_b128 v[166:169], v138 offset:3072
	s_add_i32 s75, s75, 2
	s_add_u32 s77, s4, s34
	s_addc_u32 s80, s5, s35
	s_add_u32 s36, s77, 0x100
	s_addc_u32 s37, s80, 0
	s_add_u32 s81, s2, s34
	ds_read_b128 v[170:173], v139
	ds_read_b128 v[174:177], v139 offset:1024
	ds_read_b128 v[178:181], v139 offset:2048
	ds_read_b128 v[182:185], v139 offset:3072
	ds_read_b128 v[186:189], v139 offset:4096
	ds_read_b128 v[190:193], v139 offset:5120
	ds_read_b128 v[194:197], v139 offset:6144
	ds_read_b128 v[198:201], v139 offset:7168
	s_addc_u32 s84, s33, s35
	s_add_u32 s54, s81, 0x80
	s_addc_u32 s55, s84, 0
	s_add_u32 s85, s70, s34
	s_addc_u32 s86, s71, s35
	s_add_u32 s82, s85, 0x80
	s_mov_b32 m0, s67
	s_nop 0
	global_load_lds_dwordx4 v130, s[54:55]
	s_addc_u32 s83, s86, 0
	s_mov_b32 m0, s73
	s_nop 0
	global_load_lds_dwordx4 v130, s[82:83]
	s_waitcnt vmcnt(24)
	s_waitcnt lgkmcnt(0)
	s_barrier
	s_setprio 1
	s_waitcnt lgkmcnt(7)
	v_mfma_f32_16x16x32_bf16 v[124:127], v[132:135], v[170:173], 0
	v_mfma_f32_16x16x32_bf16 v[120:123], v[146:149], v[170:173], 0
	s_waitcnt lgkmcnt(5)
	v_mfma_f32_16x16x32_bf16 v[116:119], v[132:135], v[178:181], 0
	v_mfma_f32_16x16x32_bf16 v[112:115], v[146:149], v[178:181], 0
	s_waitcnt lgkmcnt(3)
	v_mfma_f32_16x16x32_bf16 v[108:111], v[132:135], v[186:189], 0
	v_mfma_f32_16x16x32_bf16 v[104:107], v[146:149], v[186:189], 0
	s_waitcnt lgkmcnt(1)
	v_mfma_f32_16x16x32_bf16 v[100:103], v[132:135], v[194:197], 0
	v_mfma_f32_16x16x32_bf16 v[96:99], v[146:149], v[194:197], 0
	v_mfma_f32_16x16x32_bf16 v[124:127], v[142:145], v[174:177], v[124:127]
	v_mfma_f32_16x16x32_bf16 v[120:123], v[150:153], v[174:177], v[120:123]
	v_mfma_f32_16x16x32_bf16 v[116:119], v[142:145], v[182:185], v[116:119]
	v_mfma_f32_16x16x32_bf16 v[112:115], v[150:153], v[182:185], v[112:115]
	v_mfma_f32_16x16x32_bf16 v[108:111], v[142:145], v[190:193], v[108:111]
	v_mfma_f32_16x16x32_bf16 v[104:107], v[150:153], v[190:193], v[104:107]
	s_waitcnt lgkmcnt(0)
	v_mfma_f32_16x16x32_bf16 v[100:103], v[142:145], v[198:201], v[100:103]
	v_mfma_f32_16x16x32_bf16 v[96:99], v[150:153], v[198:201], v[96:99]
	s_setprio 0
	s_setprio 1
	v_mfma_f32_16x16x32_bf16 v[92:95], v[154:157], v[170:173], 0
	v_mfma_f32_16x16x32_bf16 v[88:91], v[162:165], v[170:173], 0
	v_mfma_f32_16x16x32_bf16 v[84:87], v[154:157], v[178:181], 0
	v_mfma_f32_16x16x32_bf16 v[80:83], v[162:165], v[178:181], 0
	v_mfma_f32_16x16x32_bf16 v[76:79], v[154:157], v[186:189], 0
	v_mfma_f32_16x16x32_bf16 v[72:75], v[162:165], v[186:189], 0
	v_mfma_f32_16x16x32_bf16 v[68:71], v[154:157], v[194:197], 0
	v_mfma_f32_16x16x32_bf16 v[64:67], v[162:165], v[194:197], 0
	v_mfma_f32_16x16x32_bf16 v[92:95], v[158:161], v[174:177], v[92:95]
	v_mfma_f32_16x16x32_bf16 v[88:91], v[166:169], v[174:177], v[88:91]
	v_mfma_f32_16x16x32_bf16 v[84:87], v[158:161], v[182:185], v[84:87]
	v_mfma_f32_16x16x32_bf16 v[80:83], v[166:169], v[182:185], v[80:83]
	v_mfma_f32_16x16x32_bf16 v[76:79], v[158:161], v[190:193], v[76:79]
	v_mfma_f32_16x16x32_bf16 v[72:75], v[166:169], v[190:193], v[72:75]
	v_mfma_f32_16x16x32_bf16 v[68:71], v[158:161], v[198:201], v[68:71]
	v_mfma_f32_16x16x32_bf16 v[64:67], v[166:169], v[198:201], v[64:67]
	s_setprio 0
	s_barrier
	s_add_u32 s87, s6, s34
	s_addc_u32 s88, s7, s35
	s_add_u32 s54, s87, 0x100
	s_addc_u32 s55, s88, 0
	s_add_u32 s89, s68, s34
	s_addc_u32 s90, s69, s35
	s_add_u32 s82, s89, 0x100
	ds_read_b128 v[170:173], v139 offset:16384
	ds_read_b128 v[174:177], v139 offset:17408
	ds_read_b128 v[178:181], v139 offset:18432
	ds_read_b128 v[182:185], v139 offset:19456
	ds_read_b128 v[186:189], v139 offset:20480
	ds_read_b128 v[190:193], v139 offset:21504
	ds_read_b128 v[194:197], v139 offset:22528
	ds_read_b128 v[198:201], v139 offset:23552
	s_addc_u32 s83, s90, 0
	s_mov_b32 m0, s49
	s_nop 0
	global_load_lds_dwordx4 v131, s[54:55]
	s_add_u32 s91, s38, s34
	s_mov_b32 m0, s50
	s_nop 0
	global_load_lds_dwordx4 v131, s[82:83]
	s_addc_u32 s92, s39, s35
	s_add_u32 s54, s91, 0x100
	s_addc_u32 s55, s92, 0
	s_add_u32 s93, s46, s34
	s_addc_u32 s94, s47, s35
	s_add_u32 s82, s93, 0x100
	s_addc_u32 s83, s94, 0
	s_mov_b32 m0, s51
	s_nop 0
	global_load_lds_dwordx4 v131, s[54:55]
	s_mov_b32 m0, s57
	s_nop 0
	global_load_lds_dwordx4 v131, s[82:83]
	s_add_u32 s82, s72, s34
	s_addc_u32 s83, s74, s35
	s_add_u32 s54, s82, 0x100
	s_mov_b32 m0, s53
	s_nop 0
	global_load_lds_dwordx4 v130, s[36:37]
	s_addc_u32 s55, s83, 0
	s_mov_b32 m0, s58
	s_nop 0
	global_load_lds_dwordx4 v130, s[54:55]
	s_waitcnt vmcnt(24)
	s_waitcnt lgkmcnt(0)
	s_barrier
	s_setprio 1
	s_waitcnt lgkmcnt(7)
	v_mfma_f32_16x16x32_bf16 v[60:63], v[132:135], v[170:173], 0
	v_mfma_f32_16x16x32_bf16 v[56:59], v[146:149], v[170:173], 0
	s_waitcnt lgkmcnt(5)
	v_mfma_f32_16x16x32_bf16 v[52:55], v[132:135], v[178:181], 0
	v_mfma_f32_16x16x32_bf16 v[48:51], v[146:149], v[178:181], 0
	s_waitcnt lgkmcnt(3)
	v_mfma_f32_16x16x32_bf16 v[44:47], v[132:135], v[186:189], 0
	v_mfma_f32_16x16x32_bf16 v[40:43], v[146:149], v[186:189], 0
	s_waitcnt lgkmcnt(1)
	v_mfma_f32_16x16x32_bf16 v[36:39], v[132:135], v[194:197], 0
	v_mfma_f32_16x16x32_bf16 v[32:35], v[146:149], v[194:197], 0
	v_mfma_f32_16x16x32_bf16 v[60:63], v[142:145], v[174:177], v[60:63]
	v_mfma_f32_16x16x32_bf16 v[56:59], v[150:153], v[174:177], v[56:59]
	v_mfma_f32_16x16x32_bf16 v[52:55], v[142:145], v[182:185], v[52:55]
	v_mfma_f32_16x16x32_bf16 v[48:51], v[150:153], v[182:185], v[48:51]
	v_mfma_f32_16x16x32_bf16 v[44:47], v[142:145], v[190:193], v[44:47]
	v_mfma_f32_16x16x32_bf16 v[40:43], v[150:153], v[190:193], v[40:43]
	s_waitcnt lgkmcnt(0)
	v_mfma_f32_16x16x32_bf16 v[36:39], v[142:145], v[198:201], v[36:39]
	v_mfma_f32_16x16x32_bf16 v[32:35], v[150:153], v[198:201], v[32:35]
	s_setprio 0
	s_setprio 1
	v_mfma_f32_16x16x32_bf16 v[28:31], v[154:157], v[170:173], 0
	v_mfma_f32_16x16x32_bf16 v[24:27], v[162:165], v[170:173], 0
	v_mfma_f32_16x16x32_bf16 v[20:23], v[154:157], v[178:181], 0
	v_mfma_f32_16x16x32_bf16 v[16:19], v[162:165], v[178:181], 0
	v_mfma_f32_16x16x32_bf16 v[12:15], v[154:157], v[186:189], 0
	v_mfma_f32_16x16x32_bf16 v[8:11], v[162:165], v[186:189], 0
	v_mfma_f32_16x16x32_bf16 v[4:7], v[154:157], v[194:197], 0
	v_mfma_f32_16x16x32_bf16 v[0:3], v[162:165], v[194:197], 0
	v_mfma_f32_16x16x32_bf16 v[28:31], v[158:161], v[174:177], v[28:31]
	v_mfma_f32_16x16x32_bf16 v[24:27], v[166:169], v[174:177], v[24:27]
	v_mfma_f32_16x16x32_bf16 v[20:23], v[158:161], v[182:185], v[20:23]
	v_mfma_f32_16x16x32_bf16 v[16:19], v[166:169], v[182:185], v[16:19]
	v_mfma_f32_16x16x32_bf16 v[12:15], v[158:161], v[190:193], v[12:15]
	v_mfma_f32_16x16x32_bf16 v[8:11], v[166:169], v[190:193], v[8:11]
	v_mfma_f32_16x16x32_bf16 v[4:7], v[158:161], v[198:201], v[4:7]
	v_mfma_f32_16x16x32_bf16 v[0:3], v[166:169], v[198:201], v[0:3]
	s_setprio 0
	s_barrier
	ds_read_b128 v[132:135], v140
	ds_read_b128 v[142:145], v140 offset:1024
	ds_read_b128 v[146:149], v140 offset:2048
	ds_read_b128 v[150:153], v140 offset:3072
	ds_read_b128 v[154:157], v141
	ds_read_b128 v[158:161], v141 offset:1024
	ds_read_b128 v[162:165], v141 offset:2048
	ds_read_b128 v[166:169], v141 offset:3072
	ds_read_b128 v[170:173], v139 offset:32768
	ds_read_b128 v[174:177], v139 offset:33792
	ds_read_b128 v[178:181], v139 offset:34816
	ds_read_b128 v[182:185], v139 offset:35840
	ds_read_b128 v[186:189], v139 offset:36864
	ds_read_b128 v[190:193], v139 offset:37888
	ds_read_b128 v[194:197], v139 offset:38912
	ds_read_b128 v[198:201], v139 offset:39936
	s_add_u32 s36, s81, 0x100
	s_addc_u32 s37, s84, 0
	s_add_u32 s54, s85, 0x100
	s_mov_b32 m0, s59
	s_nop 0
	global_load_lds_dwordx4 v130, s[36:37]
	s_addc_u32 s55, s86, 0
	s_mov_b32 m0, s60
	s_nop 0
	global_load_lds_dwordx4 v130, s[54:55]
	s_waitcnt vmcnt(8)
	s_waitcnt lgkmcnt(0)
	s_barrier
	s_setprio 1
	s_waitcnt lgkmcnt(7)
	v_mfma_f32_16x16x32_bf16 v[124:127], v[132:135], v[170:173], v[124:127]
	v_mfma_f32_16x16x32_bf16 v[120:123], v[146:149], v[170:173], v[120:123]
	s_waitcnt lgkmcnt(5)
	v_mfma_f32_16x16x32_bf16 v[116:119], v[132:135], v[178:181], v[116:119]
	v_mfma_f32_16x16x32_bf16 v[112:115], v[146:149], v[178:181], v[112:115]
	s_waitcnt lgkmcnt(3)
	v_mfma_f32_16x16x32_bf16 v[108:111], v[132:135], v[186:189], v[108:111]
	v_mfma_f32_16x16x32_bf16 v[104:107], v[146:149], v[186:189], v[104:107]
	s_waitcnt lgkmcnt(1)
	v_mfma_f32_16x16x32_bf16 v[100:103], v[132:135], v[194:197], v[100:103]
	v_mfma_f32_16x16x32_bf16 v[96:99], v[146:149], v[194:197], v[96:99]
	v_mfma_f32_16x16x32_bf16 v[124:127], v[142:145], v[174:177], v[124:127]
	v_mfma_f32_16x16x32_bf16 v[120:123], v[150:153], v[174:177], v[120:123]
	v_mfma_f32_16x16x32_bf16 v[116:119], v[142:145], v[182:185], v[116:119]
	v_mfma_f32_16x16x32_bf16 v[112:115], v[150:153], v[182:185], v[112:115]
	v_mfma_f32_16x16x32_bf16 v[108:111], v[142:145], v[190:193], v[108:111]
	v_mfma_f32_16x16x32_bf16 v[104:107], v[150:153], v[190:193], v[104:107]
	s_waitcnt lgkmcnt(0)
	v_mfma_f32_16x16x32_bf16 v[100:103], v[142:145], v[198:201], v[100:103]
	v_mfma_f32_16x16x32_bf16 v[96:99], v[150:153], v[198:201], v[96:99]
	s_setprio 0
	s_setprio 1
	v_mfma_f32_16x16x32_bf16 v[92:95], v[154:157], v[170:173], v[92:95]
	v_mfma_f32_16x16x32_bf16 v[88:91], v[162:165], v[170:173], v[88:91]
	v_mfma_f32_16x16x32_bf16 v[84:87], v[154:157], v[178:181], v[84:87]
	v_mfma_f32_16x16x32_bf16 v[80:83], v[162:165], v[178:181], v[80:83]
	v_mfma_f32_16x16x32_bf16 v[76:79], v[154:157], v[186:189], v[76:79]
	v_mfma_f32_16x16x32_bf16 v[72:75], v[162:165], v[186:189], v[72:75]
	v_mfma_f32_16x16x32_bf16 v[68:71], v[154:157], v[194:197], v[68:71]
	v_mfma_f32_16x16x32_bf16 v[64:67], v[162:165], v[194:197], v[64:67]
	v_mfma_f32_16x16x32_bf16 v[92:95], v[158:161], v[174:177], v[92:95]
	v_mfma_f32_16x16x32_bf16 v[88:91], v[166:169], v[174:177], v[88:91]
	v_mfma_f32_16x16x32_bf16 v[84:87], v[158:161], v[182:185], v[84:87]
	v_mfma_f32_16x16x32_bf16 v[80:83], v[166:169], v[182:185], v[80:83]
	v_mfma_f32_16x16x32_bf16 v[76:79], v[158:161], v[190:193], v[76:79]
	v_mfma_f32_16x16x32_bf16 v[72:75], v[166:169], v[190:193], v[72:75]
	v_mfma_f32_16x16x32_bf16 v[68:71], v[158:161], v[198:201], v[68:71]
	v_mfma_f32_16x16x32_bf16 v[64:67], v[166:169], v[198:201], v[64:67]
	s_setprio 0
	s_barrier
	s_add_u32 s36, s87, 0x180
	s_addc_u32 s37, s88, 0
	ds_read_b128 v[170:173], v139 offset:49152
	ds_read_b128 v[174:177], v139 offset:50176
	ds_read_b128 v[178:181], v139 offset:51200
	ds_read_b128 v[182:185], v139 offset:52224
	ds_read_b128 v[186:189], v139 offset:53248
	ds_read_b128 v[190:193], v139 offset:54272
	ds_read_b128 v[194:197], v139 offset:55296
	ds_read_b128 v[198:201], v139 offset:56320
	s_add_u32 s54, s89, 0x180
	s_mov_b32 m0, s61
	s_nop 0
	global_load_lds_dwordx4 v131, s[36:37]
	s_addc_u32 s55, s90, 0
	s_mov_b32 m0, s62
	s_nop 0
	global_load_lds_dwordx4 v131, s[54:55]
	s_add_u32 s36, s91, 0x180
	s_addc_u32 s37, s92, 0
	s_add_u32 s54, s93, 0x180
	s_mov_b32 m0, s65
	s_nop 0
	global_load_lds_dwordx4 v131, s[36:37]
	s_addc_u32 s55, s94, 0
	s_mov_b32 m0, s66
	s_nop 0
	global_load_lds_dwordx4 v131, s[54:55]
	s_add_u32 s36, s77, 0x180
	s_addc_u32 s37, s80, 0
	s_add_u32 s54, s82, 0x180
	s_mov_b32 m0, s63
	s_nop 0
	global_load_lds_dwordx4 v130, s[36:37]
	s_addc_u32 s55, s83, 0
	s_mov_b32 m0, s64
	s_nop 0
	global_load_lds_dwordx4 v130, s[54:55]
	s_waitcnt vmcnt(8)
	s_waitcnt lgkmcnt(0)
	s_barrier
	s_setprio 1
	s_waitcnt lgkmcnt(7)
	v_mfma_f32_16x16x32_bf16 v[60:63], v[132:135], v[170:173], v[60:63]
	v_mfma_f32_16x16x32_bf16 v[56:59], v[146:149], v[170:173], v[56:59]
	s_waitcnt lgkmcnt(5)
	v_mfma_f32_16x16x32_bf16 v[52:55], v[132:135], v[178:181], v[52:55]
	v_mfma_f32_16x16x32_bf16 v[48:51], v[146:149], v[178:181], v[48:51]
	s_waitcnt lgkmcnt(3)
	v_mfma_f32_16x16x32_bf16 v[44:47], v[132:135], v[186:189], v[44:47]
	v_mfma_f32_16x16x32_bf16 v[40:43], v[146:149], v[186:189], v[40:43]
	s_waitcnt lgkmcnt(1)
	v_mfma_f32_16x16x32_bf16 v[36:39], v[132:135], v[194:197], v[36:39]
	v_mfma_f32_16x16x32_bf16 v[32:35], v[146:149], v[194:197], v[32:35]
	v_mfma_f32_16x16x32_bf16 v[60:63], v[142:145], v[174:177], v[60:63]
	v_mfma_f32_16x16x32_bf16 v[56:59], v[150:153], v[174:177], v[56:59]
	v_mfma_f32_16x16x32_bf16 v[52:55], v[142:145], v[182:185], v[52:55]
	v_mfma_f32_16x16x32_bf16 v[48:51], v[150:153], v[182:185], v[48:51]
	v_mfma_f32_16x16x32_bf16 v[44:47], v[142:145], v[190:193], v[44:47]
	v_mfma_f32_16x16x32_bf16 v[40:43], v[150:153], v[190:193], v[40:43]
	s_waitcnt lgkmcnt(0)
	v_mfma_f32_16x16x32_bf16 v[36:39], v[142:145], v[198:201], v[36:39]
	v_mfma_f32_16x16x32_bf16 v[32:35], v[150:153], v[198:201], v[32:35]
	s_setprio 0
	s_setprio 1
	v_mfma_f32_16x16x32_bf16 v[28:31], v[154:157], v[170:173], v[28:31]
	v_mfma_f32_16x16x32_bf16 v[24:27], v[162:165], v[170:173], v[24:27]
	v_mfma_f32_16x16x32_bf16 v[20:23], v[154:157], v[178:181], v[20:23]
	v_mfma_f32_16x16x32_bf16 v[16:19], v[162:165], v[178:181], v[16:19]
	v_mfma_f32_16x16x32_bf16 v[12:15], v[154:157], v[186:189], v[12:15]
	v_mfma_f32_16x16x32_bf16 v[8:11], v[162:165], v[186:189], v[8:11]
	v_mfma_f32_16x16x32_bf16 v[4:7], v[154:157], v[194:197], v[4:7]
	v_mfma_f32_16x16x32_bf16 v[0:3], v[162:165], v[194:197], v[0:3]
	v_mfma_f32_16x16x32_bf16 v[28:31], v[158:161], v[174:177], v[28:31]
	v_mfma_f32_16x16x32_bf16 v[24:27], v[166:169], v[174:177], v[24:27]
	v_mfma_f32_16x16x32_bf16 v[20:23], v[158:161], v[182:185], v[20:23]
	v_mfma_f32_16x16x32_bf16 v[16:19], v[166:169], v[182:185], v[16:19]
	v_mfma_f32_16x16x32_bf16 v[12:15], v[158:161], v[190:193], v[12:15]
	v_mfma_f32_16x16x32_bf16 v[8:11], v[166:169], v[190:193], v[8:11]
	v_mfma_f32_16x16x32_bf16 v[4:7], v[158:161], v[198:201], v[4:7]
	v_mfma_f32_16x16x32_bf16 v[0:3], v[166:169], v[198:201], v[0:3]
	s_setprio 0
	s_barrier
	s_add_u32 s34, s34, 0x100
	s_addc_u32 s35, s35, 0
	s_cmp_ge_i32 s75, s0
	s_cbranch_scc0 .LBB0_295
	s_branch .LBB0_296
.Lhf_295:
	ds_read_b128 v[132:135], v137
	ds_read_b128 v[142:145], v137 offset:1024
	ds_read_b128 v[146:149], v137 offset:2048
	ds_read_b128 v[150:153], v137 offset:3072
	ds_read_b128 v[154:157], v138
	ds_read_b128 v[158:161], v138 offset:1024
	ds_read_b128 v[162:165], v138 offset:2048
	ds_read_b128 v[166:169], v138 offset:3072
	s_add_i32 s75, s75, 2
	s_add_u32 s77, s4, s34
	s_addc_u32 s80, s5, s35
	s_add_u32 s36, s77, 0x100
	s_addc_u32 s37, s80, 0
	s_add_u32 s81, s2, s34
	ds_read_b128 v[170:173], v139
	ds_read_b128 v[174:177], v139 offset:1024
	ds_read_b128 v[178:181], v139 offset:2048
	ds_read_b128 v[182:185], v139 offset:3072
	ds_read_b128 v[186:189], v139 offset:4096
	ds_read_b128 v[190:193], v139 offset:5120
	ds_read_b128 v[194:197], v139 offset:6144
	ds_read_b128 v[198:201], v139 offset:7168
	s_addc_u32 s84, s33, s35
	s_add_u32 s54, s81, 0x80
	s_addc_u32 s55, s84, 0
	s_add_u32 s85, s70, s34
	s_addc_u32 s86, s71, s35
	s_add_u32 s82, s85, 0x80
	s_mov_b32 m0, s67
	s_nop 0
	global_load_lds_dwordx4 v130, s[54:55]
	s_addc_u32 s83, s86, 0
	s_mov_b32 m0, s73
	s_nop 0
	global_load_lds_dwordx4 v130, s[82:83]
	s_waitcnt vmcnt(8)
	s_waitcnt lgkmcnt(0)
	s_barrier
	s_setprio 1
	s_waitcnt lgkmcnt(7)
	v_mfma_f32_16x16x32_bf16 v[124:127], v[132:135], v[170:173], 0
	v_mfma_f32_16x16x32_bf16 v[120:123], v[146:149], v[170:173], 0
	s_waitcnt lgkmcnt(5)
	v_mfma_f32_16x16x32_bf16 v[116:119], v[132:135], v[178:181], 0
	v_mfma_f32_16x16x32_bf16 v[112:115], v[146:149], v[178:181], 0
	s_waitcnt lgkmcnt(3)
	v_mfma_f32_16x16x32_bf16 v[108:111], v[132:135], v[186:189], 0
	v_mfma_f32_16x16x32_bf16 v[104:107], v[146:149], v[186:189], 0
	s_waitcnt lgkmcnt(1)
	v_mfma_f32_16x16x32_bf16 v[100:103], v[132:135], v[194:197], 0
	v_mfma_f32_16x16x32_bf16 v[96:99], v[146:149], v[194:197], 0
	v_mfma_f32_16x16x32_bf16 v[124:127], v[142:145], v[174:177], v[124:127]
	v_mfma_f32_16x16x32_bf16 v[120:123], v[150:153], v[174:177], v[120:123]
	v_mfma_f32_16x16x32_bf16 v[116:119], v[142:145], v[182:185], v[116:119]
	v_mfma_f32_16x16x32_bf16 v[112:115], v[150:153], v[182:185], v[112:115]
	v_mfma_f32_16x16x32_bf16 v[108:111], v[142:145], v[190:193], v[108:111]
	v_mfma_f32_16x16x32_bf16 v[104:107], v[150:153], v[190:193], v[104:107]
	s_waitcnt lgkmcnt(0)
	v_mfma_f32_16x16x32_bf16 v[100:103], v[142:145], v[198:201], v[100:103]
	v_mfma_f32_16x16x32_bf16 v[96:99], v[150:153], v[198:201], v[96:99]
	s_setprio 0
	s_setprio 1
	v_mfma_f32_16x16x32_bf16 v[92:95], v[154:157], v[170:173], 0
	v_mfma_f32_16x16x32_bf16 v[88:91], v[162:165], v[170:173], 0
	v_mfma_f32_16x16x32_bf16 v[84:87], v[154:157], v[178:181], 0
	v_mfma_f32_16x16x32_bf16 v[80:83], v[162:165], v[178:181], 0
	v_mfma_f32_16x16x32_bf16 v[76:79], v[154:157], v[186:189], 0
	v_mfma_f32_16x16x32_bf16 v[72:75], v[162:165], v[186:189], 0
	v_mfma_f32_16x16x32_bf16 v[68:71], v[154:157], v[194:197], 0
	v_mfma_f32_16x16x32_bf16 v[64:67], v[162:165], v[194:197], 0
	v_mfma_f32_16x16x32_bf16 v[92:95], v[158:161], v[174:177], v[92:95]
	v_mfma_f32_16x16x32_bf16 v[88:91], v[166:169], v[174:177], v[88:91]
	v_mfma_f32_16x16x32_bf16 v[84:87], v[158:161], v[182:185], v[84:87]
	v_mfma_f32_16x16x32_bf16 v[80:83], v[166:169], v[182:185], v[80:83]
	v_mfma_f32_16x16x32_bf16 v[76:79], v[158:161], v[190:193], v[76:79]
	v_mfma_f32_16x16x32_bf16 v[72:75], v[166:169], v[190:193], v[72:75]
	v_mfma_f32_16x16x32_bf16 v[68:71], v[158:161], v[198:201], v[68:71]
	v_mfma_f32_16x16x32_bf16 v[64:67], v[166:169], v[198:201], v[64:67]
	s_setprio 0
	s_barrier
	s_add_u32 s87, s6, s34
	s_addc_u32 s88, s7, s35
	s_add_u32 s54, s87, 0x100
	s_addc_u32 s55, s88, 0
	s_add_u32 s89, s68, s34
	s_addc_u32 s90, s69, s35
	s_add_u32 s82, s89, 0x100
	ds_read_b128 v[170:173], v139 offset:16384
	ds_read_b128 v[174:177], v139 offset:17408
	ds_read_b128 v[178:181], v139 offset:18432
	ds_read_b128 v[182:185], v139 offset:19456
	ds_read_b128 v[186:189], v139 offset:20480
	ds_read_b128 v[190:193], v139 offset:21504
	ds_read_b128 v[194:197], v139 offset:22528
	ds_read_b128 v[198:201], v139 offset:23552
	s_addc_u32 s83, s90, 0
	s_mov_b32 m0, s49
	s_nop 0
	global_load_lds_dwordx4 v131, s[54:55]
	s_add_u32 s91, s38, s34
	s_mov_b32 m0, s50
	s_nop 0
	global_load_lds_dwordx4 v131, s[82:83]
	s_addc_u32 s92, s39, s35
	s_add_u32 s54, s91, 0x100
	s_addc_u32 s55, s92, 0
	s_add_u32 s93, s46, s34
	s_addc_u32 s94, s47, s35
	s_add_u32 s82, s93, 0x100
	s_addc_u32 s83, s94, 0
	s_mov_b32 m0, s51
	s_nop 0
	global_load_lds_dwordx4 v131, s[54:55]
	s_mov_b32 m0, s57
	s_nop 0
	global_load_lds_dwordx4 v131, s[82:83]
	s_add_u32 s82, s72, s34
	s_addc_u32 s83, s74, s35
	s_add_u32 s54, s82, 0x100
	s_mov_b32 m0, s53
	s_nop 0
	global_load_lds_dwordx4 v130, s[36:37]
	s_addc_u32 s55, s83, 0
	s_mov_b32 m0, s58
	s_nop 0
	global_load_lds_dwordx4 v130, s[54:55]
	s_waitcnt vmcnt(8)
	s_waitcnt lgkmcnt(0)
	s_barrier
	s_setprio 1
	s_waitcnt lgkmcnt(7)
	v_mfma_f32_16x16x32_bf16 v[60:63], v[132:135], v[170:173], 0
	v_mfma_f32_16x16x32_bf16 v[56:59], v[146:149], v[170:173], 0
	s_waitcnt lgkmcnt(5)
	v_mfma_f32_16x16x32_bf16 v[52:55], v[132:135], v[178:181], 0
	v_mfma_f32_16x16x32_bf16 v[48:51], v[146:149], v[178:181], 0
	s_waitcnt lgkmcnt(3)
	v_mfma_f32_16x16x32_bf16 v[44:47], v[132:135], v[186:189], 0
	v_mfma_f32_16x16x32_bf16 v[40:43], v[146:149], v[186:189], 0
	s_waitcnt lgkmcnt(1)
	v_mfma_f32_16x16x32_bf16 v[36:39], v[132:135], v[194:197], 0
	v_mfma_f32_16x16x32_bf16 v[32:35], v[146:149], v[194:197], 0
	v_mfma_f32_16x16x32_bf16 v[60:63], v[142:145], v[174:177], v[60:63]
	v_mfma_f32_16x16x32_bf16 v[56:59], v[150:153], v[174:177], v[56:59]
	v_mfma_f32_16x16x32_bf16 v[52:55], v[142:145], v[182:185], v[52:55]
	v_mfma_f32_16x16x32_bf16 v[48:51], v[150:153], v[182:185], v[48:51]
	v_mfma_f32_16x16x32_bf16 v[44:47], v[142:145], v[190:193], v[44:47]
	v_mfma_f32_16x16x32_bf16 v[40:43], v[150:153], v[190:193], v[40:43]
	s_waitcnt lgkmcnt(0)
	v_mfma_f32_16x16x32_bf16 v[36:39], v[142:145], v[198:201], v[36:39]
	v_mfma_f32_16x16x32_bf16 v[32:35], v[150:153], v[198:201], v[32:35]
	s_setprio 0
	s_setprio 1
	v_mfma_f32_16x16x32_bf16 v[28:31], v[154:157], v[170:173], 0
	v_mfma_f32_16x16x32_bf16 v[24:27], v[162:165], v[170:173], 0
	v_mfma_f32_16x16x32_bf16 v[20:23], v[154:157], v[178:181], 0
	v_mfma_f32_16x16x32_bf16 v[16:19], v[162:165], v[178:181], 0
	v_mfma_f32_16x16x32_bf16 v[12:15], v[154:157], v[186:189], 0
	v_mfma_f32_16x16x32_bf16 v[8:11], v[162:165], v[186:189], 0
	v_mfma_f32_16x16x32_bf16 v[4:7], v[154:157], v[194:197], 0
	v_mfma_f32_16x16x32_bf16 v[0:3], v[162:165], v[194:197], 0
	v_mfma_f32_16x16x32_bf16 v[28:31], v[158:161], v[174:177], v[28:31]
	v_mfma_f32_16x16x32_bf16 v[24:27], v[166:169], v[174:177], v[24:27]
	v_mfma_f32_16x16x32_bf16 v[20:23], v[158:161], v[182:185], v[20:23]
	v_mfma_f32_16x16x32_bf16 v[16:19], v[166:169], v[182:185], v[16:19]
	v_mfma_f32_16x16x32_bf16 v[12:15], v[158:161], v[190:193], v[12:15]
	v_mfma_f32_16x16x32_bf16 v[8:11], v[166:169], v[190:193], v[8:11]
	v_mfma_f32_16x16x32_bf16 v[4:7], v[158:161], v[198:201], v[4:7]
	v_mfma_f32_16x16x32_bf16 v[0:3], v[166:169], v[198:201], v[0:3]
	s_setprio 0
	s_barrier
	ds_read_b128 v[132:135], v140
	ds_read_b128 v[142:145], v140 offset:1024
	ds_read_b128 v[146:149], v140 offset:2048
	ds_read_b128 v[150:153], v140 offset:3072
	ds_read_b128 v[154:157], v141
	ds_read_b128 v[158:161], v141 offset:1024
	ds_read_b128 v[162:165], v141 offset:2048
	ds_read_b128 v[166:169], v141 offset:3072
	ds_read_b128 v[170:173], v139 offset:32768
	ds_read_b128 v[174:177], v139 offset:33792
	ds_read_b128 v[178:181], v139 offset:34816
	ds_read_b128 v[182:185], v139 offset:35840
	ds_read_b128 v[186:189], v139 offset:36864
	ds_read_b128 v[190:193], v139 offset:37888
	ds_read_b128 v[194:197], v139 offset:38912
	ds_read_b128 v[198:201], v139 offset:39936
	s_add_u32 s36, s81, 0x100
	s_addc_u32 s37, s84, 0
	s_add_u32 s54, s85, 0x100
	s_mov_b32 m0, s59
	s_nop 0
	global_load_lds_dwordx4 v130, s[36:37]
	s_addc_u32 s55, s86, 0
	s_mov_b32 m0, s60
	s_nop 0
	global_load_lds_dwordx4 v130, s[54:55]
	s_waitcnt vmcnt(8)
	s_waitcnt lgkmcnt(0)
	s_barrier
	s_setprio 1
	s_waitcnt lgkmcnt(7)
	v_mfma_f32_16x16x32_bf16 v[124:127], v[132:135], v[170:173], v[124:127]
	v_mfma_f32_16x16x32_bf16 v[120:123], v[146:149], v[170:173], v[120:123]
	s_waitcnt lgkmcnt(5)
	v_mfma_f32_16x16x32_bf16 v[116:119], v[132:135], v[178:181], v[116:119]
	v_mfma_f32_16x16x32_bf16 v[112:115], v[146:149], v[178:181], v[112:115]
	s_waitcnt lgkmcnt(3)
	v_mfma_f32_16x16x32_bf16 v[108:111], v[132:135], v[186:189], v[108:111]
	v_mfma_f32_16x16x32_bf16 v[104:107], v[146:149], v[186:189], v[104:107]
	s_waitcnt lgkmcnt(1)
	v_mfma_f32_16x16x32_bf16 v[100:103], v[132:135], v[194:197], v[100:103]
	v_mfma_f32_16x16x32_bf16 v[96:99], v[146:149], v[194:197], v[96:99]
	v_mfma_f32_16x16x32_bf16 v[124:127], v[142:145], v[174:177], v[124:127]
	v_mfma_f32_16x16x32_bf16 v[120:123], v[150:153], v[174:177], v[120:123]
	v_mfma_f32_16x16x32_bf16 v[116:119], v[142:145], v[182:185], v[116:119]
	v_mfma_f32_16x16x32_bf16 v[112:115], v[150:153], v[182:185], v[112:115]
	v_mfma_f32_16x16x32_bf16 v[108:111], v[142:145], v[190:193], v[108:111]
	v_mfma_f32_16x16x32_bf16 v[104:107], v[150:153], v[190:193], v[104:107]
	s_waitcnt lgkmcnt(0)
	v_mfma_f32_16x16x32_bf16 v[100:103], v[142:145], v[198:201], v[100:103]
	v_mfma_f32_16x16x32_bf16 v[96:99], v[150:153], v[198:201], v[96:99]
	s_setprio 0
	s_setprio 1
	v_mfma_f32_16x16x32_bf16 v[92:95], v[154:157], v[170:173], v[92:95]
	v_mfma_f32_16x16x32_bf16 v[88:91], v[162:165], v[170:173], v[88:91]
	v_mfma_f32_16x16x32_bf16 v[84:87], v[154:157], v[178:181], v[84:87]
	v_mfma_f32_16x16x32_bf16 v[80:83], v[162:165], v[178:181], v[80:83]
	v_mfma_f32_16x16x32_bf16 v[76:79], v[154:157], v[186:189], v[76:79]
	v_mfma_f32_16x16x32_bf16 v[72:75], v[162:165], v[186:189], v[72:75]
	v_mfma_f32_16x16x32_bf16 v[68:71], v[154:157], v[194:197], v[68:71]
	v_mfma_f32_16x16x32_bf16 v[64:67], v[162:165], v[194:197], v[64:67]
	v_mfma_f32_16x16x32_bf16 v[92:95], v[158:161], v[174:177], v[92:95]
	v_mfma_f32_16x16x32_bf16 v[88:91], v[166:169], v[174:177], v[88:91]
	v_mfma_f32_16x16x32_bf16 v[84:87], v[158:161], v[182:185], v[84:87]
	v_mfma_f32_16x16x32_bf16 v[80:83], v[166:169], v[182:185], v[80:83]
	v_mfma_f32_16x16x32_bf16 v[76:79], v[158:161], v[190:193], v[76:79]
	v_mfma_f32_16x16x32_bf16 v[72:75], v[166:169], v[190:193], v[72:75]
	v_mfma_f32_16x16x32_bf16 v[68:71], v[158:161], v[198:201], v[68:71]
	v_mfma_f32_16x16x32_bf16 v[64:67], v[166:169], v[198:201], v[64:67]
	s_setprio 0
	s_barrier
	s_add_u32 s36, s87, 0x180
	s_addc_u32 s37, s88, 0
	ds_read_b128 v[170:173], v139 offset:49152
	ds_read_b128 v[174:177], v139 offset:50176
	ds_read_b128 v[178:181], v139 offset:51200
	ds_read_b128 v[182:185], v139 offset:52224
	ds_read_b128 v[186:189], v139 offset:53248
	ds_read_b128 v[190:193], v139 offset:54272
	ds_read_b128 v[194:197], v139 offset:55296
	ds_read_b128 v[198:201], v139 offset:56320
	s_add_u32 s54, s89, 0x180
	s_mov_b32 m0, s61
	s_nop 0
	global_load_lds_dwordx4 v131, s[36:37]
	s_addc_u32 s55, s90, 0
	s_mov_b32 m0, s62
	s_nop 0
	global_load_lds_dwordx4 v131, s[54:55]
	s_add_u32 s36, s91, 0x180
	s_addc_u32 s37, s92, 0
	s_add_u32 s54, s93, 0x180
	s_mov_b32 m0, s65
	s_nop 0
	global_load_lds_dwordx4 v131, s[36:37]
	s_addc_u32 s55, s94, 0
	s_mov_b32 m0, s66
	s_nop 0
	global_load_lds_dwordx4 v131, s[54:55]
	s_add_u32 s36, s77, 0x180
	s_addc_u32 s37, s80, 0
	s_add_u32 s54, s82, 0x180
	s_mov_b32 m0, s63
	s_nop 0
	global_load_lds_dwordx4 v130, s[36:37]
	s_addc_u32 s55, s83, 0
	s_mov_b32 m0, s64
	s_nop 0
	global_load_lds_dwordx4 v130, s[54:55]
	s_waitcnt vmcnt(8)
	s_waitcnt lgkmcnt(0)
	s_barrier
	s_setprio 1
	s_waitcnt lgkmcnt(7)
	v_mfma_f32_16x16x32_bf16 v[60:63], v[132:135], v[170:173], v[60:63]
	v_mfma_f32_16x16x32_bf16 v[56:59], v[146:149], v[170:173], v[56:59]
	s_waitcnt lgkmcnt(5)
	v_mfma_f32_16x16x32_bf16 v[52:55], v[132:135], v[178:181], v[52:55]
	v_mfma_f32_16x16x32_bf16 v[48:51], v[146:149], v[178:181], v[48:51]
	s_waitcnt lgkmcnt(3)
	v_mfma_f32_16x16x32_bf16 v[44:47], v[132:135], v[186:189], v[44:47]
	v_mfma_f32_16x16x32_bf16 v[40:43], v[146:149], v[186:189], v[40:43]
	s_waitcnt lgkmcnt(1)
	v_mfma_f32_16x16x32_bf16 v[36:39], v[132:135], v[194:197], v[36:39]
	v_mfma_f32_16x16x32_bf16 v[32:35], v[146:149], v[194:197], v[32:35]
	v_mfma_f32_16x16x32_bf16 v[60:63], v[142:145], v[174:177], v[60:63]
	v_mfma_f32_16x16x32_bf16 v[56:59], v[150:153], v[174:177], v[56:59]
	v_mfma_f32_16x16x32_bf16 v[52:55], v[142:145], v[182:185], v[52:55]
	v_mfma_f32_16x16x32_bf16 v[48:51], v[150:153], v[182:185], v[48:51]
	v_mfma_f32_16x16x32_bf16 v[44:47], v[142:145], v[190:193], v[44:47]
	v_mfma_f32_16x16x32_bf16 v[40:43], v[150:153], v[190:193], v[40:43]
	s_waitcnt lgkmcnt(0)
	v_mfma_f32_16x16x32_bf16 v[36:39], v[142:145], v[198:201], v[36:39]
	v_mfma_f32_16x16x32_bf16 v[32:35], v[150:153], v[198:201], v[32:35]
	s_setprio 0
	s_setprio 1
	v_mfma_f32_16x16x32_bf16 v[28:31], v[154:157], v[170:173], v[28:31]
	v_mfma_f32_16x16x32_bf16 v[24:27], v[162:165], v[170:173], v[24:27]
	v_mfma_f32_16x16x32_bf16 v[20:23], v[154:157], v[178:181], v[20:23]
	v_mfma_f32_16x16x32_bf16 v[16:19], v[162:165], v[178:181], v[16:19]
	v_mfma_f32_16x16x32_bf16 v[12:15], v[154:157], v[186:189], v[12:15]
	v_mfma_f32_16x16x32_bf16 v[8:11], v[162:165], v[186:189], v[8:11]
	v_mfma_f32_16x16x32_bf16 v[4:7], v[154:157], v[194:197], v[4:7]
	v_mfma_f32_16x16x32_bf16 v[0:3], v[162:165], v[194:197], v[0:3]
	v_mfma_f32_16x16x32_bf16 v[28:31], v[158:161], v[174:177], v[28:31]
	v_mfma_f32_16x16x32_bf16 v[24:27], v[166:169], v[174:177], v[24:27]
	v_mfma_f32_16x16x32_bf16 v[20:23], v[158:161], v[182:185], v[20:23]
	v_mfma_f32_16x16x32_bf16 v[16:19], v[166:169], v[182:185], v[16:19]
	v_mfma_f32_16x16x32_bf16 v[12:15], v[158:161], v[190:193], v[12:15]
	v_mfma_f32_16x16x32_bf16 v[8:11], v[166:169], v[190:193], v[8:11]
	v_mfma_f32_16x16x32_bf16 v[4:7], v[158:161], v[198:201], v[4:7]
	v_mfma_f32_16x16x32_bf16 v[0:3], v[166:169], v[198:201], v[0:3]
	s_setprio 0
	s_barrier
	s_add_u32 s34, s34, 0x100
	s_addc_u32 s35, s35, 0
	s_cmp_ge_i32 s75, s0
	s_cbranch_scc0 .LBB0_295
	s_branch .LBB0_296

.LBB0_312:
	s_cmp_lt_i32 s20, 3
	s_cbranch_scc1 .Lhz_314
	s_add_i32 s2, s20, -2
	s_add_u32 s22, s4, s36
	s_addc_u32 s33, s5, s37
	s_add_u32 s42, s6, s18
	s_addc_u32 s43, s7, s19
	s_add_u32 s38, s0, s18
	s_addc_u32 s39, s1, s19
	s_add_u32 s44, s6, s38
	s_addc_u32 s45, s7, s39
	s_add_u32 s68, s6, s0
	s_addc_u32 s69, s7, s1
	s_add_u32 s38, s34, s36
	s_addc_u32 s39, s35, s37
	s_add_u32 s70, s4, s38
	s_addc_u32 s71, s5, s39
	s_add_u32 s72, s4, s34
	s_addc_u32 s73, s5, s35
	s_mov_b32 s74, 0
	s_mov_b64 s[38:39], 0
	s_cmp_eq_u32 s98, 0
	s_cbranch_scc1 .Lhf_314
	ds_read_b128 v[24:27], v194
	ds_read_b128 v[28:31], v194 offset:1024
	ds_read_b128 v[16:19], v194 offset:2048
	ds_read_b128 v[20:23], v194 offset:3072
	ds_read_b128 v[8:11], v248
	ds_read_b128 v[12:15], v248 offset:1024
	ds_read_b128 v[0:3], v248 offset:2048
	ds_read_b128 v[4:7], v248 offset:3072
	s_add_i32 s74, s74, 2
	s_add_u32 s75, s4, s38
	s_addc_u32 s77, s5, s39
	s_add_u32 s40, s75, 0x100
	s_addc_u32 s41, s77, 0
	s_add_u32 s78, s22, s38
	ds_read_b128 v[162:165], v249
	ds_read_b128 v[166:169], v249 offset:1024
	ds_read_b128 v[170:173], v249 offset:2048
	ds_read_b128 v[174:177], v249 offset:3072
	ds_read_b128 v[178:181], v249 offset:4096
	ds_read_b128 v[182:185], v249 offset:5120
	ds_read_b128 v[186:189], v249 offset:6144
	ds_read_b128 v[190:193], v249 offset:7168
	s_addc_u32 s79, s33, s39
	s_add_u32 s82, s78, 0x80
	s_addc_u32 s83, s79, 0
	s_add_u32 s80, s70, s38
	s_addc_u32 s81, s71, s39
	s_add_u32 s84, s80, 0x80
	s_mov_b32 m0, s64
	s_nop 0
	global_load_lds_dwordx4 v160, s[82:83]
	s_addc_u32 s85, s81, 0
	s_mov_b32 m0, s65
	s_nop 0
	global_load_lds_dwordx4 v160, s[84:85]
	s_waitcnt vmcnt(24)
	s_waitcnt lgkmcnt(0)
	s_barrier
	s_setprio 1
	s_waitcnt lgkmcnt(6)
	v_mfma_scale_f32_16x16x128_f8f6f4 v[156:159], v[24:31], v[162:169], 0, v251, v250 op_sel_hi:[0,0,0]
	v_mfma_scale_f32_16x16x128_f8f6f4 v[152:155], v[16:23], v[162:169], 0, v251, v250 op_sel_hi:[0,0,0]
	s_waitcnt lgkmcnt(4)
	v_mfma_scale_f32_16x16x128_f8f6f4 v[148:151], v[24:31], v[170:177], 0, v251, v250 op_sel_hi:[0,0,0]
	v_mfma_scale_f32_16x16x128_f8f6f4 v[144:147], v[16:23], v[170:177], 0, v251, v250 op_sel_hi:[0,0,0]
	s_waitcnt lgkmcnt(2)
	v_mfma_scale_f32_16x16x128_f8f6f4 v[140:143], v[24:31], v[178:185], 0, v251, v250 op_sel_hi:[0,0,0]
	v_mfma_scale_f32_16x16x128_f8f6f4 v[136:139], v[16:23], v[178:185], 0, v251, v250 op_sel_hi:[0,0,0]
	s_waitcnt lgkmcnt(0)
	v_mfma_scale_f32_16x16x128_f8f6f4 v[132:135], v[24:31], v[186:193], 0, v251, v250 op_sel_hi:[0,0,0]
	v_mfma_scale_f32_16x16x128_f8f6f4 v[128:131], v[16:23], v[186:193], 0, v251, v250 op_sel_hi:[0,0,0]
	s_setprio 0
	s_setprio 1
	v_mfma_scale_f32_16x16x128_f8f6f4 v[124:127], v[8:15], v[162:169], 0, v251, v250 op_sel_hi:[0,0,0]
	v_mfma_scale_f32_16x16x128_f8f6f4 v[120:123], v[0:7], v[162:169], 0, v251, v250 op_sel_hi:[0,0,0]
	v_mfma_scale_f32_16x16x128_f8f6f4 v[116:119], v[8:15], v[170:177], 0, v251, v250 op_sel_hi:[0,0,0]
	v_mfma_scale_f32_16x16x128_f8f6f4 v[112:115], v[0:7], v[170:177], 0, v251, v250 op_sel_hi:[0,0,0]
	v_mfma_scale_f32_16x16x128_f8f6f4 v[108:111], v[8:15], v[178:185], 0, v251, v250 op_sel_hi:[0,0,0]
	v_mfma_scale_f32_16x16x128_f8f6f4 v[104:107], v[0:7], v[178:185], 0, v251, v250 op_sel_hi:[0,0,0]
	v_mfma_scale_f32_16x16x128_f8f6f4 v[100:103], v[8:15], v[186:193], 0, v251, v250 op_sel_hi:[0,0,0]
	v_mfma_scale_f32_16x16x128_f8f6f4 v[96:99], v[0:7], v[186:193], 0, v251, v250 op_sel_hi:[0,0,0]
	s_setprio 0
	s_barrier
	s_add_u32 s82, s6, s38
	s_addc_u32 s83, s7, s39
	s_add_u32 s86, s82, 0x100
	s_addc_u32 s87, s83, 0
	s_add_u32 s84, s68, s38
	s_addc_u32 s85, s69, s39
	ds_read_b128 v[162:165], v249 offset:16384
	ds_read_b128 v[166:169], v249 offset:17408
	ds_read_b128 v[170:173], v249 offset:18432
	ds_read_b128 v[174:177], v249 offset:19456
	ds_read_b128 v[178:181], v249 offset:20480
	ds_read_b128 v[182:185], v249 offset:21504
	ds_read_b128 v[186:189], v249 offset:22528
	ds_read_b128 v[190:193], v249 offset:23552
	s_add_u32 s88, s84, 0x100
	s_mov_b32 m0, s49
	s_nop 0
	global_load_lds_dwordx4 v161, s[86:87]
	s_addc_u32 s89, s85, 0
	s_mov_b32 m0, s50
	s_nop 0
	global_load_lds_dwordx4 v161, s[88:89]
	s_add_u32 s86, s42, s38
	s_addc_u32 s87, s43, s39
	s_add_u32 s88, s86, 0x100
	s_addc_u32 s89, s87, 0
	s_add_u32 s90, s44, s38
	s_addc_u32 s91, s45, s39
	s_add_u32 s92, s90, 0x100
	s_mov_b32 m0, s51
	s_nop 0
	global_load_lds_dwordx4 v161, s[88:89]
	s_addc_u32 s93, s91, 0
	s_mov_b32 m0, s57
	s_nop 0
	global_load_lds_dwordx4 v161, s[92:93]
	s_add_u32 s88, s72, s38
	s_addc_u32 s89, s73, s39
	s_add_u32 s92, s88, 0x100
	s_mov_b32 m0, s53
	s_nop 0
	global_load_lds_dwordx4 v160, s[40:41]
	s_addc_u32 s93, s89, 0
	s_mov_b32 m0, s58
	s_nop 0
	global_load_lds_dwordx4 v160, s[92:93]
	s_waitcnt vmcnt(24)
	s_waitcnt lgkmcnt(0)
	s_barrier
	s_setprio 1
	s_waitcnt lgkmcnt(6)
	v_mfma_scale_f32_16x16x128_f8f6f4 v[92:95], v[24:31], v[162:169], 0, v251, v250 op_sel_hi:[0,0,0]
	v_mfma_scale_f32_16x16x128_f8f6f4 v[88:91], v[16:23], v[162:169], 0, v251, v250 op_sel_hi:[0,0,0]
	s_waitcnt lgkmcnt(4)
	v_mfma_scale_f32_16x16x128_f8f6f4 v[84:87], v[24:31], v[170:177], 0, v251, v250 op_sel_hi:[0,0,0]
	v_mfma_scale_f32_16x16x128_f8f6f4 v[80:83], v[16:23], v[170:177], 0, v251, v250 op_sel_hi:[0,0,0]
	s_waitcnt lgkmcnt(2)
	v_mfma_scale_f32_16x16x128_f8f6f4 v[76:79], v[24:31], v[178:185], 0, v251, v250 op_sel_hi:[0,0,0]
	v_mfma_scale_f32_16x16x128_f8f6f4 v[72:75], v[16:23], v[178:185], 0, v251, v250 op_sel_hi:[0,0,0]
	s_waitcnt lgkmcnt(0)
	v_mfma_scale_f32_16x16x128_f8f6f4 v[68:71], v[24:31], v[186:193], 0, v251, v250 op_sel_hi:[0,0,0]
	v_mfma_scale_f32_16x16x128_f8f6f4 v[64:67], v[16:23], v[186:193], 0, v251, v250 op_sel_hi:[0,0,0]
	s_setprio 0
	s_setprio 1
	v_mfma_scale_f32_16x16x128_f8f6f4 v[60:63], v[8:15], v[162:169], 0, v251, v250 op_sel_hi:[0,0,0]
	v_mfma_scale_f32_16x16x128_f8f6f4 v[56:59], v[0:7], v[162:169], 0, v251, v250 op_sel_hi:[0,0,0]
	v_mfma_scale_f32_16x16x128_f8f6f4 v[52:55], v[8:15], v[170:177], 0, v251, v250 op_sel_hi:[0,0,0]
	v_mfma_scale_f32_16x16x128_f8f6f4 v[48:51], v[0:7], v[170:177], 0, v251, v250 op_sel_hi:[0,0,0]
	v_mfma_scale_f32_16x16x128_f8f6f4 v[44:47], v[8:15], v[178:185], 0, v251, v250 op_sel_hi:[0,0,0]
	v_mfma_scale_f32_16x16x128_f8f6f4 v[40:43], v[0:7], v[178:185], 0, v251, v250 op_sel_hi:[0,0,0]
	v_mfma_scale_f32_16x16x128_f8f6f4 v[36:39], v[8:15], v[186:193], 0, v251, v250 op_sel_hi:[0,0,0]
	v_mfma_scale_f32_16x16x128_f8f6f4 v[32:35], v[0:7], v[186:193], 0, v251, v250 op_sel_hi:[0,0,0]
	s_setprio 0
	s_barrier
	ds_read_b128 v[24:27], v252
	ds_read_b128 v[28:31], v252 offset:1024
	ds_read_b128 v[16:19], v252 offset:2048
	ds_read_b128 v[20:23], v252 offset:3072
	ds_read_b128 v[8:11], v253
	ds_read_b128 v[12:15], v253 offset:1024
	ds_read_b128 v[0:3], v253 offset:2048
	ds_read_b128 v[4:7], v253 offset:3072
	ds_read_b128 v[162:165], v249 offset:32768
	ds_read_b128 v[166:169], v249 offset:33792
	ds_read_b128 v[170:173], v249 offset:34816
	ds_read_b128 v[174:177], v249 offset:35840
	ds_read_b128 v[178:181], v249 offset:36864
	ds_read_b128 v[182:185], v249 offset:37888
	ds_read_b128 v[186:189], v249 offset:38912
	ds_read_b128 v[190:193], v249 offset:39936
	s_add_u32 s40, s78, 0x100
	s_addc_u32 s41, s79, 0
	s_add_u32 s78, s80, 0x100
	s_mov_b32 m0, s59
	s_nop 0
	global_load_lds_dwordx4 v160, s[40:41]
	s_addc_u32 s79, s81, 0
	s_mov_b32 m0, s60
	s_nop 0
	global_load_lds_dwordx4 v160, s[78:79]
	s_waitcnt vmcnt(8)
	s_waitcnt lgkmcnt(0)
	s_barrier
	s_setprio 1
	s_waitcnt lgkmcnt(6)
	v_mfma_scale_f32_16x16x128_f8f6f4 v[156:159], v[24:31], v[162:169], v[156:159], v251, v250 op_sel_hi:[0,0,0]
	v_mfma_scale_f32_16x16x128_f8f6f4 v[152:155], v[16:23], v[162:169], v[152:155], v251, v250 op_sel_hi:[0,0,0]
	s_waitcnt lgkmcnt(4)
	v_mfma_scale_f32_16x16x128_f8f6f4 v[148:151], v[24:31], v[170:177], v[148:151], v251, v250 op_sel_hi:[0,0,0]
	v_mfma_scale_f32_16x16x128_f8f6f4 v[144:147], v[16:23], v[170:177], v[144:147], v251, v250 op_sel_hi:[0,0,0]
	s_waitcnt lgkmcnt(2)
	v_mfma_scale_f32_16x16x128_f8f6f4 v[140:143], v[24:31], v[178:185], v[140:143], v251, v250 op_sel_hi:[0,0,0]
	v_mfma_scale_f32_16x16x128_f8f6f4 v[136:139], v[16:23], v[178:185], v[136:139], v251, v250 op_sel_hi:[0,0,0]
	s_waitcnt lgkmcnt(0)
	v_mfma_scale_f32_16x16x128_f8f6f4 v[132:135], v[24:31], v[186:193], v[132:135], v251, v250 op_sel_hi:[0,0,0]
	v_mfma_scale_f32_16x16x128_f8f6f4 v[128:131], v[16:23], v[186:193], v[128:131], v251, v250 op_sel_hi:[0,0,0]
	s_setprio 0
	s_setprio 1
	v_mfma_scale_f32_16x16x128_f8f6f4 v[124:127], v[8:15], v[162:169], v[124:127], v251, v250 op_sel_hi:[0,0,0]
	v_mfma_scale_f32_16x16x128_f8f6f4 v[120:123], v[0:7], v[162:169], v[120:123], v251, v250 op_sel_hi:[0,0,0]
	v_mfma_scale_f32_16x16x128_f8f6f4 v[116:119], v[8:15], v[170:177], v[116:119], v251, v250 op_sel_hi:[0,0,0]
	v_mfma_scale_f32_16x16x128_f8f6f4 v[112:115], v[0:7], v[170:177], v[112:115], v251, v250 op_sel_hi:[0,0,0]
	v_mfma_scale_f32_16x16x128_f8f6f4 v[108:111], v[8:15], v[178:185], v[108:111], v251, v250 op_sel_hi:[0,0,0]
	v_mfma_scale_f32_16x16x128_f8f6f4 v[104:107], v[0:7], v[178:185], v[104:107], v251, v250 op_sel_hi:[0,0,0]
	v_mfma_scale_f32_16x16x128_f8f6f4 v[100:103], v[8:15], v[186:193], v[100:103], v251, v250 op_sel_hi:[0,0,0]
	v_mfma_scale_f32_16x16x128_f8f6f4 v[96:99], v[0:7], v[186:193], v[96:99], v251, v250 op_sel_hi:[0,0,0]
	s_setprio 0
	s_barrier
	s_add_u32 s40, s82, 0x180
	s_addc_u32 s41, s83, 0
	ds_read_b128 v[162:165], v249 offset:49152
	ds_read_b128 v[166:169], v249 offset:50176
	ds_read_b128 v[170:173], v249 offset:51200
	ds_read_b128 v[174:177], v249 offset:52224
	ds_read_b128 v[178:181], v249 offset:53248
	ds_read_b128 v[182:185], v249 offset:54272
	ds_read_b128 v[186:189], v249 offset:55296
	ds_read_b128 v[190:193], v249 offset:56320
	s_add_u32 s78, s84, 0x180
	s_mov_b32 m0, s54
	s_nop 0
	global_load_lds_dwordx4 v161, s[40:41]
	s_addc_u32 s79, s85, 0
	s_mov_b32 m0, s55
	s_nop 0
	global_load_lds_dwordx4 v161, s[78:79]
	s_add_u32 s40, s86, 0x180
	s_addc_u32 s41, s87, 0
	s_add_u32 s78, s90, 0x180
	s_mov_b32 m0, s62
	s_nop 0
	global_load_lds_dwordx4 v161, s[40:41]
	s_addc_u32 s79, s91, 0
	s_mov_b32 m0, s63
	s_nop 0
	global_load_lds_dwordx4 v161, s[78:79]
	s_add_u32 s40, s75, 0x180
	s_addc_u32 s41, s77, 0
	s_add_u32 s78, s88, 0x180
	s_mov_b32 m0, s56
	s_nop 0
	global_load_lds_dwordx4 v160, s[40:41]
	s_addc_u32 s79, s89, 0
	s_mov_b32 m0, s61
	s_nop 0
	global_load_lds_dwordx4 v160, s[78:79]
	s_waitcnt vmcnt(8)
	s_waitcnt lgkmcnt(0)
	s_barrier
	s_setprio 1
	s_waitcnt lgkmcnt(6)
	v_mfma_scale_f32_16x16x128_f8f6f4 v[92:95], v[24:31], v[162:169], v[92:95], v251, v250 op_sel_hi:[0,0,0]
	v_mfma_scale_f32_16x16x128_f8f6f4 v[88:91], v[16:23], v[162:169], v[88:91], v251, v250 op_sel_hi:[0,0,0]
	s_waitcnt lgkmcnt(4)
	v_mfma_scale_f32_16x16x128_f8f6f4 v[84:87], v[24:31], v[170:177], v[84:87], v251, v250 op_sel_hi:[0,0,0]
	v_mfma_scale_f32_16x16x128_f8f6f4 v[80:83], v[16:23], v[170:177], v[80:83], v251, v250 op_sel_hi:[0,0,0]
	s_waitcnt lgkmcnt(2)
	v_mfma_scale_f32_16x16x128_f8f6f4 v[76:79], v[24:31], v[178:185], v[76:79], v251, v250 op_sel_hi:[0,0,0]
	v_mfma_scale_f32_16x16x128_f8f6f4 v[72:75], v[16:23], v[178:185], v[72:75], v251, v250 op_sel_hi:[0,0,0]
	s_waitcnt lgkmcnt(0)
	v_mfma_scale_f32_16x16x128_f8f6f4 v[68:71], v[24:31], v[186:193], v[68:71], v251, v250 op_sel_hi:[0,0,0]
	v_mfma_scale_f32_16x16x128_f8f6f4 v[64:67], v[16:23], v[186:193], v[64:67], v251, v250 op_sel_hi:[0,0,0]
	s_setprio 0
	s_setprio 1
	v_mfma_scale_f32_16x16x128_f8f6f4 v[60:63], v[8:15], v[162:169], v[60:63], v251, v250 op_sel_hi:[0,0,0]
	v_mfma_scale_f32_16x16x128_f8f6f4 v[56:59], v[0:7], v[162:169], v[56:59], v251, v250 op_sel_hi:[0,0,0]
	v_mfma_scale_f32_16x16x128_f8f6f4 v[52:55], v[8:15], v[170:177], v[52:55], v251, v250 op_sel_hi:[0,0,0]
	v_mfma_scale_f32_16x16x128_f8f6f4 v[48:51], v[0:7], v[170:177], v[48:51], v251, v250 op_sel_hi:[0,0,0]
	v_mfma_scale_f32_16x16x128_f8f6f4 v[44:47], v[8:15], v[178:185], v[44:47], v251, v250 op_sel_hi:[0,0,0]
	v_mfma_scale_f32_16x16x128_f8f6f4 v[40:43], v[0:7], v[178:185], v[40:43], v251, v250 op_sel_hi:[0,0,0]
	v_mfma_scale_f32_16x16x128_f8f6f4 v[36:39], v[8:15], v[186:193], v[36:39], v251, v250 op_sel_hi:[0,0,0]
	v_mfma_scale_f32_16x16x128_f8f6f4 v[32:35], v[0:7], v[186:193], v[32:35], v251, v250 op_sel_hi:[0,0,0]
	s_setprio 0
	s_barrier
	s_add_u32 s38, s38, 0x100
	s_addc_u32 s39, s39, 0
	s_cmp_ge_i32 s74, s2
	s_cbranch_scc0 .LBB0_314
	s_branch .LBB0_315
.Lhf_314:
	ds_read_b128 v[24:27], v194
	ds_read_b128 v[28:31], v194 offset:1024
	ds_read_b128 v[16:19], v194 offset:2048
	ds_read_b128 v[20:23], v194 offset:3072
	ds_read_b128 v[8:11], v248
	ds_read_b128 v[12:15], v248 offset:1024
	ds_read_b128 v[0:3], v248 offset:2048
	ds_read_b128 v[4:7], v248 offset:3072
	s_add_i32 s74, s74, 2
	s_add_u32 s75, s4, s38
	s_addc_u32 s77, s5, s39
	s_add_u32 s40, s75, 0x100
	s_addc_u32 s41, s77, 0
	s_add_u32 s78, s22, s38
	ds_read_b128 v[162:165], v249
	ds_read_b128 v[166:169], v249 offset:1024
	ds_read_b128 v[170:173], v249 offset:2048
	ds_read_b128 v[174:177], v249 offset:3072
	ds_read_b128 v[178:181], v249 offset:4096
	ds_read_b128 v[182:185], v249 offset:5120
	ds_read_b128 v[186:189], v249 offset:6144
	ds_read_b128 v[190:193], v249 offset:7168
	s_addc_u32 s79, s33, s39
	s_add_u32 s82, s78, 0x80
	s_addc_u32 s83, s79, 0
	s_add_u32 s80, s70, s38
	s_addc_u32 s81, s71, s39
	s_add_u32 s84, s80, 0x80
	s_mov_b32 m0, s64
	s_nop 0
	global_load_lds_dwordx4 v160, s[82:83]
	s_addc_u32 s85, s81, 0
	s_mov_b32 m0, s65
	s_nop 0
	global_load_lds_dwordx4 v160, s[84:85]
	s_waitcnt vmcnt(8)
	s_waitcnt lgkmcnt(0)
	s_barrier
	s_setprio 1
	s_waitcnt lgkmcnt(6)
	v_mfma_scale_f32_16x16x128_f8f6f4 v[156:159], v[24:31], v[162:169], 0, v251, v250 op_sel_hi:[0,0,0]
	v_mfma_scale_f32_16x16x128_f8f6f4 v[152:155], v[16:23], v[162:169], 0, v251, v250 op_sel_hi:[0,0,0]
	s_waitcnt lgkmcnt(4)
	v_mfma_scale_f32_16x16x128_f8f6f4 v[148:151], v[24:31], v[170:177], 0, v251, v250 op_sel_hi:[0,0,0]
	v_mfma_scale_f32_16x16x128_f8f6f4 v[144:147], v[16:23], v[170:177], 0, v251, v250 op_sel_hi:[0,0,0]
	s_waitcnt lgkmcnt(2)
	v_mfma_scale_f32_16x16x128_f8f6f4 v[140:143], v[24:31], v[178:185], 0, v251, v250 op_sel_hi:[0,0,0]
	v_mfma_scale_f32_16x16x128_f8f6f4 v[136:139], v[16:23], v[178:185], 0, v251, v250 op_sel_hi:[0,0,0]
	s_waitcnt lgkmcnt(0)
	v_mfma_scale_f32_16x16x128_f8f6f4 v[132:135], v[24:31], v[186:193], 0, v251, v250 op_sel_hi:[0,0,0]
	v_mfma_scale_f32_16x16x128_f8f6f4 v[128:131], v[16:23], v[186:193], 0, v251, v250 op_sel_hi:[0,0,0]
	s_setprio 0
	s_setprio 1
	v_mfma_scale_f32_16x16x128_f8f6f4 v[124:127], v[8:15], v[162:169], 0, v251, v250 op_sel_hi:[0,0,0]
	v_mfma_scale_f32_16x16x128_f8f6f4 v[120:123], v[0:7], v[162:169], 0, v251, v250 op_sel_hi:[0,0,0]
	v_mfma_scale_f32_16x16x128_f8f6f4 v[116:119], v[8:15], v[170:177], 0, v251, v250 op_sel_hi:[0,0,0]
	v_mfma_scale_f32_16x16x128_f8f6f4 v[112:115], v[0:7], v[170:177], 0, v251, v250 op_sel_hi:[0,0,0]
	v_mfma_scale_f32_16x16x128_f8f6f4 v[108:111], v[8:15], v[178:185], 0, v251, v250 op_sel_hi:[0,0,0]
	v_mfma_scale_f32_16x16x128_f8f6f4 v[104:107], v[0:7], v[178:185], 0, v251, v250 op_sel_hi:[0,0,0]
	v_mfma_scale_f32_16x16x128_f8f6f4 v[100:103], v[8:15], v[186:193], 0, v251, v250 op_sel_hi:[0,0,0]
	v_mfma_scale_f32_16x16x128_f8f6f4 v[96:99], v[0:7], v[186:193], 0, v251, v250 op_sel_hi:[0,0,0]
	s_setprio 0
	s_barrier
	s_add_u32 s82, s6, s38
	s_addc_u32 s83, s7, s39
	s_add_u32 s86, s82, 0x100
	s_addc_u32 s87, s83, 0
	s_add_u32 s84, s68, s38
	s_addc_u32 s85, s69, s39
	ds_read_b128 v[162:165], v249 offset:16384
	ds_read_b128 v[166:169], v249 offset:17408
	ds_read_b128 v[170:173], v249 offset:18432
	ds_read_b128 v[174:177], v249 offset:19456
	ds_read_b128 v[178:181], v249 offset:20480
	ds_read_b128 v[182:185], v249 offset:21504
	ds_read_b128 v[186:189], v249 offset:22528
	ds_read_b128 v[190:193], v249 offset:23552
	s_add_u32 s88, s84, 0x100
	s_mov_b32 m0, s49
	s_nop 0
	global_load_lds_dwordx4 v161, s[86:87]
	s_addc_u32 s89, s85, 0
	s_mov_b32 m0, s50
	s_nop 0
	global_load_lds_dwordx4 v161, s[88:89]
	s_add_u32 s86, s42, s38
	s_addc_u32 s87, s43, s39
	s_add_u32 s88, s86, 0x100
	s_addc_u32 s89, s87, 0
	s_add_u32 s90, s44, s38
	s_addc_u32 s91, s45, s39
	s_add_u32 s92, s90, 0x100
	s_mov_b32 m0, s51
	s_nop 0
	global_load_lds_dwordx4 v161, s[88:89]
	s_addc_u32 s93, s91, 0
	s_mov_b32 m0, s57
	s_nop 0
	global_load_lds_dwordx4 v161, s[92:93]
	s_add_u32 s88, s72, s38
	s_addc_u32 s89, s73, s39
	s_add_u32 s92, s88, 0x100
	s_mov_b32 m0, s53
	s_nop 0
	global_load_lds_dwordx4 v160, s[40:41]
	s_addc_u32 s93, s89, 0
	s_mov_b32 m0, s58
	s_nop 0
	global_load_lds_dwordx4 v160, s[92:93]
	s_waitcnt vmcnt(8)
	s_waitcnt lgkmcnt(0)
	s_barrier
	s_setprio 1
	s_waitcnt lgkmcnt(6)
	v_mfma_scale_f32_16x16x128_f8f6f4 v[92:95], v[24:31], v[162:169], 0, v251, v250 op_sel_hi:[0,0,0]
	v_mfma_scale_f32_16x16x128_f8f6f4 v[88:91], v[16:23], v[162:169], 0, v251, v250 op_sel_hi:[0,0,0]
	s_waitcnt lgkmcnt(4)
	v_mfma_scale_f32_16x16x128_f8f6f4 v[84:87], v[24:31], v[170:177], 0, v251, v250 op_sel_hi:[0,0,0]
	v_mfma_scale_f32_16x16x128_f8f6f4 v[80:83], v[16:23], v[170:177], 0, v251, v250 op_sel_hi:[0,0,0]
	s_waitcnt lgkmcnt(2)
	v_mfma_scale_f32_16x16x128_f8f6f4 v[76:79], v[24:31], v[178:185], 0, v251, v250 op_sel_hi:[0,0,0]
	v_mfma_scale_f32_16x16x128_f8f6f4 v[72:75], v[16:23], v[178:185], 0, v251, v250 op_sel_hi:[0,0,0]
	s_waitcnt lgkmcnt(0)
	v_mfma_scale_f32_16x16x128_f8f6f4 v[68:71], v[24:31], v[186:193], 0, v251, v250 op_sel_hi:[0,0,0]
	v_mfma_scale_f32_16x16x128_f8f6f4 v[64:67], v[16:23], v[186:193], 0, v251, v250 op_sel_hi:[0,0,0]
	s_setprio 0
	s_setprio 1
	v_mfma_scale_f32_16x16x128_f8f6f4 v[60:63], v[8:15], v[162:169], 0, v251, v250 op_sel_hi:[0,0,0]
	v_mfma_scale_f32_16x16x128_f8f6f4 v[56:59], v[0:7], v[162:169], 0, v251, v250 op_sel_hi:[0,0,0]
	v_mfma_scale_f32_16x16x128_f8f6f4 v[52:55], v[8:15], v[170:177], 0, v251, v250 op_sel_hi:[0,0,0]
	v_mfma_scale_f32_16x16x128_f8f6f4 v[48:51], v[0:7], v[170:177], 0, v251, v250 op_sel_hi:[0,0,0]
	v_mfma_scale_f32_16x16x128_f8f6f4 v[44:47], v[8:15], v[178:185], 0, v251, v250 op_sel_hi:[0,0,0]
	v_mfma_scale_f32_16x16x128_f8f6f4 v[40:43], v[0:7], v[178:185], 0, v251, v250 op_sel_hi:[0,0,0]
	v_mfma_scale_f32_16x16x128_f8f6f4 v[36:39], v[8:15], v[186:193], 0, v251, v250 op_sel_hi:[0,0,0]
	v_mfma_scale_f32_16x16x128_f8f6f4 v[32:35], v[0:7], v[186:193], 0, v251, v250 op_sel_hi:[0,0,0]
	s_setprio 0
	s_barrier
	ds_read_b128 v[24:27], v252
	ds_read_b128 v[28:31], v252 offset:1024
	ds_read_b128 v[16:19], v252 offset:2048
	ds_read_b128 v[20:23], v252 offset:3072
	ds_read_b128 v[8:11], v253
	ds_read_b128 v[12:15], v253 offset:1024
	ds_read_b128 v[0:3], v253 offset:2048
	ds_read_b128 v[4:7], v253 offset:3072
	ds_read_b128 v[162:165], v249 offset:32768
	ds_read_b128 v[166:169], v249 offset:33792
	ds_read_b128 v[170:173], v249 offset:34816
	ds_read_b128 v[174:177], v249 offset:35840
	ds_read_b128 v[178:181], v249 offset:36864
	ds_read_b128 v[182:185], v249 offset:37888
	ds_read_b128 v[186:189], v249 offset:38912
	ds_read_b128 v[190:193], v249 offset:39936
	s_add_u32 s40, s78, 0x100
	s_addc_u32 s41, s79, 0
	s_add_u32 s78, s80, 0x100
	s_mov_b32 m0, s59
	s_nop 0
	global_load_lds_dwordx4 v160, s[40:41]
	s_addc_u32 s79, s81, 0
	s_mov_b32 m0, s60
	s_nop 0
	global_load_lds_dwordx4 v160, s[78:79]
	s_waitcnt vmcnt(8)
	s_waitcnt lgkmcnt(0)
	s_barrier
	s_setprio 1
	s_waitcnt lgkmcnt(6)
	v_mfma_scale_f32_16x16x128_f8f6f4 v[156:159], v[24:31], v[162:169], v[156:159], v251, v250 op_sel_hi:[0,0,0]
	v_mfma_scale_f32_16x16x128_f8f6f4 v[152:155], v[16:23], v[162:169], v[152:155], v251, v250 op_sel_hi:[0,0,0]
	s_waitcnt lgkmcnt(4)
	v_mfma_scale_f32_16x16x128_f8f6f4 v[148:151], v[24:31], v[170:177], v[148:151], v251, v250 op_sel_hi:[0,0,0]
	v_mfma_scale_f32_16x16x128_f8f6f4 v[144:147], v[16:23], v[170:177], v[144:147], v251, v250 op_sel_hi:[0,0,0]
	s_waitcnt lgkmcnt(2)
	v_mfma_scale_f32_16x16x128_f8f6f4 v[140:143], v[24:31], v[178:185], v[140:143], v251, v250 op_sel_hi:[0,0,0]
	v_mfma_scale_f32_16x16x128_f8f6f4 v[136:139], v[16:23], v[178:185], v[136:139], v251, v250 op_sel_hi:[0,0,0]
	s_waitcnt lgkmcnt(0)
	v_mfma_scale_f32_16x16x128_f8f6f4 v[132:135], v[24:31], v[186:193], v[132:135], v251, v250 op_sel_hi:[0,0,0]
	v_mfma_scale_f32_16x16x128_f8f6f4 v[128:131], v[16:23], v[186:193], v[128:131], v251, v250 op_sel_hi:[0,0,0]
	s_setprio 0
	s_setprio 1
	v_mfma_scale_f32_16x16x128_f8f6f4 v[124:127], v[8:15], v[162:169], v[124:127], v251, v250 op_sel_hi:[0,0,0]
	v_mfma_scale_f32_16x16x128_f8f6f4 v[120:123], v[0:7], v[162:169], v[120:123], v251, v250 op_sel_hi:[0,0,0]
	v_mfma_scale_f32_16x16x128_f8f6f4 v[116:119], v[8:15], v[170:177], v[116:119], v251, v250 op_sel_hi:[0,0,0]
	v_mfma_scale_f32_16x16x128_f8f6f4 v[112:115], v[0:7], v[170:177], v[112:115], v251, v250 op_sel_hi:[0,0,0]
	v_mfma_scale_f32_16x16x128_f8f6f4 v[108:111], v[8:15], v[178:185], v[108:111], v251, v250 op_sel_hi:[0,0,0]
	v_mfma_scale_f32_16x16x128_f8f6f4 v[104:107], v[0:7], v[178:185], v[104:107], v251, v250 op_sel_hi:[0,0,0]
	v_mfma_scale_f32_16x16x128_f8f6f4 v[100:103], v[8:15], v[186:193], v[100:103], v251, v250 op_sel_hi:[0,0,0]
	v_mfma_scale_f32_16x16x128_f8f6f4 v[96:99], v[0:7], v[186:193], v[96:99], v251, v250 op_sel_hi:[0,0,0]
	s_setprio 0
	s_barrier
	s_add_u32 s40, s82, 0x180
	s_addc_u32 s41, s83, 0
	ds_read_b128 v[162:165], v249 offset:49152
	ds_read_b128 v[166:169], v249 offset:50176
	ds_read_b128 v[170:173], v249 offset:51200
	ds_read_b128 v[174:177], v249 offset:52224
	ds_read_b128 v[178:181], v249 offset:53248
	ds_read_b128 v[182:185], v249 offset:54272
	ds_read_b128 v[186:189], v249 offset:55296
	ds_read_b128 v[190:193], v249 offset:56320
	s_add_u32 s78, s84, 0x180
	s_mov_b32 m0, s54
	s_nop 0
	global_load_lds_dwordx4 v161, s[40:41]
	s_addc_u32 s79, s85, 0
	s_mov_b32 m0, s55
	s_nop 0
	global_load_lds_dwordx4 v161, s[78:79]
	s_add_u32 s40, s86, 0x180
	s_addc_u32 s41, s87, 0
	s_add_u32 s78, s90, 0x180
	s_mov_b32 m0, s62
	s_nop 0
	global_load_lds_dwordx4 v161, s[40:41]
	s_addc_u32 s79, s91, 0
	s_mov_b32 m0, s63
	s_nop 0
	global_load_lds_dwordx4 v161, s[78:79]
	s_add_u32 s40, s75, 0x180
	s_addc_u32 s41, s77, 0
	s_add_u32 s78, s88, 0x180
	s_mov_b32 m0, s56
	s_nop 0
	global_load_lds_dwordx4 v160, s[40:41]
	s_addc_u32 s79, s89, 0
	s_mov_b32 m0, s61
	s_nop 0
	global_load_lds_dwordx4 v160, s[78:79]
	s_waitcnt vmcnt(8)
	s_waitcnt lgkmcnt(0)
	s_barrier
	s_setprio 1
	s_waitcnt lgkmcnt(6)
	v_mfma_scale_f32_16x16x128_f8f6f4 v[92:95], v[24:31], v[162:169], v[92:95], v251, v250 op_sel_hi:[0,0,0]
	v_mfma_scale_f32_16x16x128_f8f6f4 v[88:91], v[16:23], v[162:169], v[88:91], v251, v250 op_sel_hi:[0,0,0]
	s_waitcnt lgkmcnt(4)
	v_mfma_scale_f32_16x16x128_f8f6f4 v[84:87], v[24:31], v[170:177], v[84:87], v251, v250 op_sel_hi:[0,0,0]
	v_mfma_scale_f32_16x16x128_f8f6f4 v[80:83], v[16:23], v[170:177], v[80:83], v251, v250 op_sel_hi:[0,0,0]
	s_waitcnt lgkmcnt(2)
	v_mfma_scale_f32_16x16x128_f8f6f4 v[76:79], v[24:31], v[178:185], v[76:79], v251, v250 op_sel_hi:[0,0,0]
	v_mfma_scale_f32_16x16x128_f8f6f4 v[72:75], v[16:23], v[178:185], v[72:75], v251, v250 op_sel_hi:[0,0,0]
	s_waitcnt lgkmcnt(0)
	v_mfma_scale_f32_16x16x128_f8f6f4 v[68:71], v[24:31], v[186:193], v[68:71], v251, v250 op_sel_hi:[0,0,0]
	v_mfma_scale_f32_16x16x128_f8f6f4 v[64:67], v[16:23], v[186:193], v[64:67], v251, v250 op_sel_hi:[0,0,0]
	s_setprio 0
	s_setprio 1
	v_mfma_scale_f32_16x16x128_f8f6f4 v[60:63], v[8:15], v[162:169], v[60:63], v251, v250 op_sel_hi:[0,0,0]
	v_mfma_scale_f32_16x16x128_f8f6f4 v[56:59], v[0:7], v[162:169], v[56:59], v251, v250 op_sel_hi:[0,0,0]
	v_mfma_scale_f32_16x16x128_f8f6f4 v[52:55], v[8:15], v[170:177], v[52:55], v251, v250 op_sel_hi:[0,0,0]
	v_mfma_scale_f32_16x16x128_f8f6f4 v[48:51], v[0:7], v[170:177], v[48:51], v251, v250 op_sel_hi:[0,0,0]
	v_mfma_scale_f32_16x16x128_f8f6f4 v[44:47], v[8:15], v[178:185], v[44:47], v251, v250 op_sel_hi:[0,0,0]
	v_mfma_scale_f32_16x16x128_f8f6f4 v[40:43], v[0:7], v[178:185], v[40:43], v251, v250 op_sel_hi:[0,0,0]
	v_mfma_scale_f32_16x16x128_f8f6f4 v[36:39], v[8:15], v[186:193], v[36:39], v251, v250 op_sel_hi:[0,0,0]
	v_mfma_scale_f32_16x16x128_f8f6f4 v[32:35], v[0:7], v[186:193], v[32:35], v251, v250 op_sel_hi:[0,0,0]
	s_setprio 0
	s_barrier
	s_add_u32 s38, s38, 0x100
	s_addc_u32 s39, s39, 0
	s_cmp_ge_i32 s74, s2
	s_cbranch_scc0 .LBB0_314
	s_branch .LBB0_315

.LBB0_467:
	s_cmp_lt_i32 s24, 3
	s_cbranch_scc1 .Lhz_469
	s_add_i32 s2, s24, -2
	s_add_u32 s3, s4, s38
	s_addc_u32 s16, s5, s39
	s_add_u32 s33, s6, s22
	s_addc_u32 s44, s7, s23
	s_add_u32 s40, s18, s22
	s_addc_u32 s41, s19, s23
	s_add_u32 s45, s6, s40
	s_addc_u32 s46, s7, s41
	s_add_u32 s47, s6, s18
	s_addc_u32 s68, s7, s19
	s_add_u32 s40, s36, s38
	s_addc_u32 s41, s37, s39
	s_add_u32 s69, s4, s40
	s_addc_u32 s70, s5, s41
	s_add_u32 s71, s4, s36
	s_addc_u32 s72, s5, s37
	s_mov_b32 s74, 0
	s_mov_b64 s[40:41], 0
	s_cmp_eq_u32 s98, 0
	s_cbranch_scc1 .Lhf_469
	ds_read_b128 v[24:27], v194
	ds_read_b128 v[28:31], v194 offset:1024
	ds_read_b128 v[16:19], v194 offset:2048
	ds_read_b128 v[20:23], v194 offset:3072
	ds_read_b128 v[8:11], v248
	ds_read_b128 v[12:15], v248 offset:1024
	ds_read_b128 v[0:3], v248 offset:2048
	ds_read_b128 v[4:7], v248 offset:3072
	s_add_i32 s74, s74, 2
	s_add_u32 s75, s4, s40
	s_addc_u32 s77, s5, s41
	s_add_u32 s42, s75, 0x100
	s_addc_u32 s43, s77, 0
	s_add_u32 s80, s3, s40
	ds_read_b128 v[162:165], v249
	ds_read_b128 v[166:169], v249 offset:1024
	ds_read_b128 v[170:173], v249 offset:2048
	ds_read_b128 v[174:177], v249 offset:3072
	ds_read_b128 v[178:181], v249 offset:4096
	ds_read_b128 v[182:185], v249 offset:5120
	ds_read_b128 v[186:189], v249 offset:6144
	ds_read_b128 v[190:193], v249 offset:7168
	s_addc_u32 s81, s16, s41
	s_add_u32 s84, s80, 0x80
	s_addc_u32 s85, s81, 0
	s_add_u32 s82, s69, s40
	s_addc_u32 s83, s70, s41
	s_add_u32 s86, s82, 0x80
	s_mov_b32 m0, s67
	s_nop 0
	global_load_lds_dwordx4 v160, s[84:85]
	s_addc_u32 s87, s83, 0
	s_mov_b32 m0, s73
	s_nop 0
	global_load_lds_dwordx4 v160, s[86:87]
	s_waitcnt vmcnt(24)
	s_waitcnt lgkmcnt(0)
	s_barrier
	s_setprio 1
	s_waitcnt lgkmcnt(6)
	v_mfma_scale_f32_16x16x128_f8f6f4 v[156:159], v[24:31], v[162:169], 0, v251, v250 op_sel_hi:[0,0,0]
	v_mfma_scale_f32_16x16x128_f8f6f4 v[152:155], v[16:23], v[162:169], 0, v251, v250 op_sel_hi:[0,0,0]
	s_waitcnt lgkmcnt(4)
	v_mfma_scale_f32_16x16x128_f8f6f4 v[148:151], v[24:31], v[170:177], 0, v251, v250 op_sel_hi:[0,0,0]
	v_mfma_scale_f32_16x16x128_f8f6f4 v[144:147], v[16:23], v[170:177], 0, v251, v250 op_sel_hi:[0,0,0]
	s_waitcnt lgkmcnt(2)
	v_mfma_scale_f32_16x16x128_f8f6f4 v[140:143], v[24:31], v[178:185], 0, v251, v250 op_sel_hi:[0,0,0]
	v_mfma_scale_f32_16x16x128_f8f6f4 v[136:139], v[16:23], v[178:185], 0, v251, v250 op_sel_hi:[0,0,0]
	s_waitcnt lgkmcnt(0)
	v_mfma_scale_f32_16x16x128_f8f6f4 v[132:135], v[24:31], v[186:193], 0, v251, v250 op_sel_hi:[0,0,0]
	v_mfma_scale_f32_16x16x128_f8f6f4 v[128:131], v[16:23], v[186:193], 0, v251, v250 op_sel_hi:[0,0,0]
	s_setprio 0
	s_setprio 1
	v_mfma_scale_f32_16x16x128_f8f6f4 v[124:127], v[8:15], v[162:169], 0, v251, v250 op_sel_hi:[0,0,0]
	v_mfma_scale_f32_16x16x128_f8f6f4 v[120:123], v[0:7], v[162:169], 0, v251, v250 op_sel_hi:[0,0,0]
	v_mfma_scale_f32_16x16x128_f8f6f4 v[116:119], v[8:15], v[170:177], 0, v251, v250 op_sel_hi:[0,0,0]
	v_mfma_scale_f32_16x16x128_f8f6f4 v[112:115], v[0:7], v[170:177], 0, v251, v250 op_sel_hi:[0,0,0]
	v_mfma_scale_f32_16x16x128_f8f6f4 v[108:111], v[8:15], v[178:185], 0, v251, v250 op_sel_hi:[0,0,0]
	v_mfma_scale_f32_16x16x128_f8f6f4 v[104:107], v[0:7], v[178:185], 0, v251, v250 op_sel_hi:[0,0,0]
	v_mfma_scale_f32_16x16x128_f8f6f4 v[100:103], v[8:15], v[186:193], 0, v251, v250 op_sel_hi:[0,0,0]
	v_mfma_scale_f32_16x16x128_f8f6f4 v[96:99], v[0:7], v[186:193], 0, v251, v250 op_sel_hi:[0,0,0]
	s_setprio 0
	s_barrier
	s_add_u32 s84, s6, s40
	s_addc_u32 s85, s7, s41
	s_add_u32 s88, s84, 0x100
	s_addc_u32 s89, s85, 0
	s_add_u32 s86, s47, s40
	s_addc_u32 s87, s68, s41
	ds_read_b128 v[162:165], v249 offset:16384
	ds_read_b128 v[166:169], v249 offset:17408
	ds_read_b128 v[170:173], v249 offset:18432
	ds_read_b128 v[174:177], v249 offset:19456
	ds_read_b128 v[178:181], v249 offset:20480
	ds_read_b128 v[182:185], v249 offset:21504
	ds_read_b128 v[186:189], v249 offset:22528
	ds_read_b128 v[190:193], v249 offset:23552
	s_add_u32 s90, s86, 0x100
	s_mov_b32 m0, s51
	s_nop 0
	global_load_lds_dwordx4 v161, s[88:89]
	s_addc_u32 s91, s87, 0
	s_mov_b32 m0, s55
	s_nop 0
	global_load_lds_dwordx4 v161, s[90:91]
	s_add_u32 s88, s33, s40
	s_addc_u32 s89, s44, s41
	s_add_u32 s90, s88, 0x100
	s_addc_u32 s91, s89, 0
	s_add_u32 s92, s45, s40
	s_addc_u32 s93, s46, s41
	s_add_u32 s94, s92, 0x100
	s_mov_b32 m0, s56
	s_nop 0
	global_load_lds_dwordx4 v161, s[90:91]
	s_addc_u32 s95, s93, 0
	s_mov_b32 m0, s57
	s_nop 0
	global_load_lds_dwordx4 v161, s[94:95]
	s_add_u32 s90, s71, s40
	s_addc_u32 s91, s72, s41
	s_add_u32 s94, s90, 0x100
	s_mov_b32 m0, s54
	s_nop 0
	global_load_lds_dwordx4 v160, s[42:43]
	s_addc_u32 s95, s91, 0
	s_mov_b32 m0, s58
	s_nop 0
	global_load_lds_dwordx4 v160, s[94:95]
	s_waitcnt vmcnt(24)
	s_waitcnt lgkmcnt(0)
	s_barrier
	s_setprio 1
	s_waitcnt lgkmcnt(6)
	v_mfma_scale_f32_16x16x128_f8f6f4 v[92:95], v[24:31], v[162:169], 0, v251, v250 op_sel_hi:[0,0,0]
	v_mfma_scale_f32_16x16x128_f8f6f4 v[88:91], v[16:23], v[162:169], 0, v251, v250 op_sel_hi:[0,0,0]
	s_waitcnt lgkmcnt(4)
	v_mfma_scale_f32_16x16x128_f8f6f4 v[84:87], v[24:31], v[170:177], 0, v251, v250 op_sel_hi:[0,0,0]
	v_mfma_scale_f32_16x16x128_f8f6f4 v[80:83], v[16:23], v[170:177], 0, v251, v250 op_sel_hi:[0,0,0]
	s_waitcnt lgkmcnt(2)
	v_mfma_scale_f32_16x16x128_f8f6f4 v[76:79], v[24:31], v[178:185], 0, v251, v250 op_sel_hi:[0,0,0]
	v_mfma_scale_f32_16x16x128_f8f6f4 v[72:75], v[16:23], v[178:185], 0, v251, v250 op_sel_hi:[0,0,0]
	s_waitcnt lgkmcnt(0)
	v_mfma_scale_f32_16x16x128_f8f6f4 v[68:71], v[24:31], v[186:193], 0, v251, v250 op_sel_hi:[0,0,0]
	v_mfma_scale_f32_16x16x128_f8f6f4 v[64:67], v[16:23], v[186:193], 0, v251, v250 op_sel_hi:[0,0,0]
	s_setprio 0
	s_setprio 1
	v_mfma_scale_f32_16x16x128_f8f6f4 v[60:63], v[8:15], v[162:169], 0, v251, v250 op_sel_hi:[0,0,0]
	v_mfma_scale_f32_16x16x128_f8f6f4 v[56:59], v[0:7], v[162:169], 0, v251, v250 op_sel_hi:[0,0,0]
	v_mfma_scale_f32_16x16x128_f8f6f4 v[52:55], v[8:15], v[170:177], 0, v251, v250 op_sel_hi:[0,0,0]
	v_mfma_scale_f32_16x16x128_f8f6f4 v[48:51], v[0:7], v[170:177], 0, v251, v250 op_sel_hi:[0,0,0]
	v_mfma_scale_f32_16x16x128_f8f6f4 v[44:47], v[8:15], v[178:185], 0, v251, v250 op_sel_hi:[0,0,0]
	v_mfma_scale_f32_16x16x128_f8f6f4 v[40:43], v[0:7], v[178:185], 0, v251, v250 op_sel_hi:[0,0,0]
	v_mfma_scale_f32_16x16x128_f8f6f4 v[36:39], v[8:15], v[186:193], 0, v251, v250 op_sel_hi:[0,0,0]
	v_mfma_scale_f32_16x16x128_f8f6f4 v[32:35], v[0:7], v[186:193], 0, v251, v250 op_sel_hi:[0,0,0]
	s_setprio 0
	s_barrier
	ds_read_b128 v[24:27], v252
	ds_read_b128 v[28:31], v252 offset:1024
	ds_read_b128 v[16:19], v252 offset:2048
	ds_read_b128 v[20:23], v252 offset:3072
	ds_read_b128 v[8:11], v253
	ds_read_b128 v[12:15], v253 offset:1024
	ds_read_b128 v[0:3], v253 offset:2048
	ds_read_b128 v[4:7], v253 offset:3072
	ds_read_b128 v[162:165], v249 offset:32768
	ds_read_b128 v[166:169], v249 offset:33792
	ds_read_b128 v[170:173], v249 offset:34816
	ds_read_b128 v[174:177], v249 offset:35840
	ds_read_b128 v[178:181], v249 offset:36864
	ds_read_b128 v[182:185], v249 offset:37888
	ds_read_b128 v[186:189], v249 offset:38912
	ds_read_b128 v[190:193], v249 offset:39936
	s_add_u32 s42, s80, 0x100
	s_addc_u32 s43, s81, 0
	s_add_u32 s80, s82, 0x100
	s_mov_b32 m0, s59
	s_nop 0
	global_load_lds_dwordx4 v160, s[42:43]
	s_addc_u32 s81, s83, 0
	s_mov_b32 m0, s60
	s_nop 0
	global_load_lds_dwordx4 v160, s[80:81]
	s_waitcnt vmcnt(8)
	s_waitcnt lgkmcnt(0)
	s_barrier
	s_setprio 1
	s_waitcnt lgkmcnt(6)
	v_mfma_scale_f32_16x16x128_f8f6f4 v[156:159], v[24:31], v[162:169], v[156:159], v251, v250 op_sel_hi:[0,0,0]
	v_mfma_scale_f32_16x16x128_f8f6f4 v[152:155], v[16:23], v[162:169], v[152:155], v251, v250 op_sel_hi:[0,0,0]
	s_waitcnt lgkmcnt(4)
	v_mfma_scale_f32_16x16x128_f8f6f4 v[148:151], v[24:31], v[170:177], v[148:151], v251, v250 op_sel_hi:[0,0,0]
	v_mfma_scale_f32_16x16x128_f8f6f4 v[144:147], v[16:23], v[170:177], v[144:147], v251, v250 op_sel_hi:[0,0,0]
	s_waitcnt lgkmcnt(2)
	v_mfma_scale_f32_16x16x128_f8f6f4 v[140:143], v[24:31], v[178:185], v[140:143], v251, v250 op_sel_hi:[0,0,0]
	v_mfma_scale_f32_16x16x128_f8f6f4 v[136:139], v[16:23], v[178:185], v[136:139], v251, v250 op_sel_hi:[0,0,0]
	s_waitcnt lgkmcnt(0)
	v_mfma_scale_f32_16x16x128_f8f6f4 v[132:135], v[24:31], v[186:193], v[132:135], v251, v250 op_sel_hi:[0,0,0]
	v_mfma_scale_f32_16x16x128_f8f6f4 v[128:131], v[16:23], v[186:193], v[128:131], v251, v250 op_sel_hi:[0,0,0]
	s_setprio 0
	s_setprio 1
	v_mfma_scale_f32_16x16x128_f8f6f4 v[124:127], v[8:15], v[162:169], v[124:127], v251, v250 op_sel_hi:[0,0,0]
	v_mfma_scale_f32_16x16x128_f8f6f4 v[120:123], v[0:7], v[162:169], v[120:123], v251, v250 op_sel_hi:[0,0,0]
	v_mfma_scale_f32_16x16x128_f8f6f4 v[116:119], v[8:15], v[170:177], v[116:119], v251, v250 op_sel_hi:[0,0,0]
	v_mfma_scale_f32_16x16x128_f8f6f4 v[112:115], v[0:7], v[170:177], v[112:115], v251, v250 op_sel_hi:[0,0,0]
	v_mfma_scale_f32_16x16x128_f8f6f4 v[108:111], v[8:15], v[178:185], v[108:111], v251, v250 op_sel_hi:[0,0,0]
	v_mfma_scale_f32_16x16x128_f8f6f4 v[104:107], v[0:7], v[178:185], v[104:107], v251, v250 op_sel_hi:[0,0,0]
	v_mfma_scale_f32_16x16x128_f8f6f4 v[100:103], v[8:15], v[186:193], v[100:103], v251, v250 op_sel_hi:[0,0,0]
	v_mfma_scale_f32_16x16x128_f8f6f4 v[96:99], v[0:7], v[186:193], v[96:99], v251, v250 op_sel_hi:[0,0,0]
	s_setprio 0
	s_barrier
	s_add_u32 s42, s84, 0x180
	s_addc_u32 s43, s85, 0
	ds_read_b128 v[162:165], v249 offset:49152
	ds_read_b128 v[166:169], v249 offset:50176
	ds_read_b128 v[170:173], v249 offset:51200
	ds_read_b128 v[174:177], v249 offset:52224
	ds_read_b128 v[178:181], v249 offset:53248
	ds_read_b128 v[182:185], v249 offset:54272
	ds_read_b128 v[186:189], v249 offset:55296
	ds_read_b128 v[190:193], v249 offset:56320
	s_add_u32 s80, s86, 0x180
	s_mov_b32 m0, s61
	s_nop 0
	global_load_lds_dwordx4 v161, s[42:43]
	s_addc_u32 s81, s87, 0
	s_mov_b32 m0, s62
	s_nop 0
	global_load_lds_dwordx4 v161, s[80:81]
	s_add_u32 s42, s88, 0x180
	s_addc_u32 s43, s89, 0
	s_add_u32 s80, s92, 0x180
	s_mov_b32 m0, s65
	s_nop 0
	global_load_lds_dwordx4 v161, s[42:43]
	s_addc_u32 s81, s93, 0
	s_mov_b32 m0, s66
	s_nop 0
	global_load_lds_dwordx4 v161, s[80:81]
	s_add_u32 s42, s75, 0x180
	s_addc_u32 s43, s77, 0
	s_add_u32 s80, s90, 0x180
	s_mov_b32 m0, s63
	s_nop 0
	global_load_lds_dwordx4 v160, s[42:43]
	s_addc_u32 s81, s91, 0
	s_mov_b32 m0, s64
	s_nop 0
	global_load_lds_dwordx4 v160, s[80:81]
	s_waitcnt vmcnt(8)
	s_waitcnt lgkmcnt(0)
	s_barrier
	s_setprio 1
	s_waitcnt lgkmcnt(6)
	v_mfma_scale_f32_16x16x128_f8f6f4 v[92:95], v[24:31], v[162:169], v[92:95], v251, v250 op_sel_hi:[0,0,0]
	v_mfma_scale_f32_16x16x128_f8f6f4 v[88:91], v[16:23], v[162:169], v[88:91], v251, v250 op_sel_hi:[0,0,0]
	s_waitcnt lgkmcnt(4)
	v_mfma_scale_f32_16x16x128_f8f6f4 v[84:87], v[24:31], v[170:177], v[84:87], v251, v250 op_sel_hi:[0,0,0]
	v_mfma_scale_f32_16x16x128_f8f6f4 v[80:83], v[16:23], v[170:177], v[80:83], v251, v250 op_sel_hi:[0,0,0]
	s_waitcnt lgkmcnt(2)
	v_mfma_scale_f32_16x16x128_f8f6f4 v[76:79], v[24:31], v[178:185], v[76:79], v251, v250 op_sel_hi:[0,0,0]
	v_mfma_scale_f32_16x16x128_f8f6f4 v[72:75], v[16:23], v[178:185], v[72:75], v251, v250 op_sel_hi:[0,0,0]
	s_waitcnt lgkmcnt(0)
	v_mfma_scale_f32_16x16x128_f8f6f4 v[68:71], v[24:31], v[186:193], v[68:71], v251, v250 op_sel_hi:[0,0,0]
	v_mfma_scale_f32_16x16x128_f8f6f4 v[64:67], v[16:23], v[186:193], v[64:67], v251, v250 op_sel_hi:[0,0,0]
	s_setprio 0
	s_setprio 1
	v_mfma_scale_f32_16x16x128_f8f6f4 v[60:63], v[8:15], v[162:169], v[60:63], v251, v250 op_sel_hi:[0,0,0]
	v_mfma_scale_f32_16x16x128_f8f6f4 v[56:59], v[0:7], v[162:169], v[56:59], v251, v250 op_sel_hi:[0,0,0]
	v_mfma_scale_f32_16x16x128_f8f6f4 v[52:55], v[8:15], v[170:177], v[52:55], v251, v250 op_sel_hi:[0,0,0]
	v_mfma_scale_f32_16x16x128_f8f6f4 v[48:51], v[0:7], v[170:177], v[48:51], v251, v250 op_sel_hi:[0,0,0]
	v_mfma_scale_f32_16x16x128_f8f6f4 v[44:47], v[8:15], v[178:185], v[44:47], v251, v250 op_sel_hi:[0,0,0]
	v_mfma_scale_f32_16x16x128_f8f6f4 v[40:43], v[0:7], v[178:185], v[40:43], v251, v250 op_sel_hi:[0,0,0]
	v_mfma_scale_f32_16x16x128_f8f6f4 v[36:39], v[8:15], v[186:193], v[36:39], v251, v250 op_sel_hi:[0,0,0]
	v_mfma_scale_f32_16x16x128_f8f6f4 v[32:35], v[0:7], v[186:193], v[32:35], v251, v250 op_sel_hi:[0,0,0]
	s_setprio 0
	s_barrier
	s_add_u32 s40, s40, 0x100
	s_addc_u32 s41, s41, 0
	s_cmp_ge_i32 s74, s2
	s_cbranch_scc0 .LBB0_469
	s_branch .LBB0_470
.Lhf_469:
	ds_read_b128 v[24:27], v194
	ds_read_b128 v[28:31], v194 offset:1024
	ds_read_b128 v[16:19], v194 offset:2048
	ds_read_b128 v[20:23], v194 offset:3072
	ds_read_b128 v[8:11], v248
	ds_read_b128 v[12:15], v248 offset:1024
	ds_read_b128 v[0:3], v248 offset:2048
	ds_read_b128 v[4:7], v248 offset:3072
	s_add_i32 s74, s74, 2
	s_add_u32 s75, s4, s40
	s_addc_u32 s77, s5, s41
	s_add_u32 s42, s75, 0x100
	s_addc_u32 s43, s77, 0
	s_add_u32 s80, s3, s40
	ds_read_b128 v[162:165], v249
	ds_read_b128 v[166:169], v249 offset:1024
	ds_read_b128 v[170:173], v249 offset:2048
	ds_read_b128 v[174:177], v249 offset:3072
	ds_read_b128 v[178:181], v249 offset:4096
	ds_read_b128 v[182:185], v249 offset:5120
	ds_read_b128 v[186:189], v249 offset:6144
	ds_read_b128 v[190:193], v249 offset:7168
	s_addc_u32 s81, s16, s41
	s_add_u32 s84, s80, 0x80
	s_addc_u32 s85, s81, 0
	s_add_u32 s82, s69, s40
	s_addc_u32 s83, s70, s41
	s_add_u32 s86, s82, 0x80
	s_mov_b32 m0, s67
	s_nop 0
	global_load_lds_dwordx4 v160, s[84:85]
	s_addc_u32 s87, s83, 0
	s_mov_b32 m0, s73
	s_nop 0
	global_load_lds_dwordx4 v160, s[86:87]
	s_waitcnt vmcnt(8)
	s_waitcnt lgkmcnt(0)
	s_barrier
	s_setprio 1
	s_waitcnt lgkmcnt(6)
	v_mfma_scale_f32_16x16x128_f8f6f4 v[156:159], v[24:31], v[162:169], 0, v251, v250 op_sel_hi:[0,0,0]
	v_mfma_scale_f32_16x16x128_f8f6f4 v[152:155], v[16:23], v[162:169], 0, v251, v250 op_sel_hi:[0,0,0]
	s_waitcnt lgkmcnt(4)
	v_mfma_scale_f32_16x16x128_f8f6f4 v[148:151], v[24:31], v[170:177], 0, v251, v250 op_sel_hi:[0,0,0]
	v_mfma_scale_f32_16x16x128_f8f6f4 v[144:147], v[16:23], v[170:177], 0, v251, v250 op_sel_hi:[0,0,0]
	s_waitcnt lgkmcnt(2)
	v_mfma_scale_f32_16x16x128_f8f6f4 v[140:143], v[24:31], v[178:185], 0, v251, v250 op_sel_hi:[0,0,0]
	v_mfma_scale_f32_16x16x128_f8f6f4 v[136:139], v[16:23], v[178:185], 0, v251, v250 op_sel_hi:[0,0,0]
	s_waitcnt lgkmcnt(0)
	v_mfma_scale_f32_16x16x128_f8f6f4 v[132:135], v[24:31], v[186:193], 0, v251, v250 op_sel_hi:[0,0,0]
	v_mfma_scale_f32_16x16x128_f8f6f4 v[128:131], v[16:23], v[186:193], 0, v251, v250 op_sel_hi:[0,0,0]
	s_setprio 0
	s_setprio 1
	v_mfma_scale_f32_16x16x128_f8f6f4 v[124:127], v[8:15], v[162:169], 0, v251, v250 op_sel_hi:[0,0,0]
	v_mfma_scale_f32_16x16x128_f8f6f4 v[120:123], v[0:7], v[162:169], 0, v251, v250 op_sel_hi:[0,0,0]
	v_mfma_scale_f32_16x16x128_f8f6f4 v[116:119], v[8:15], v[170:177], 0, v251, v250 op_sel_hi:[0,0,0]
	v_mfma_scale_f32_16x16x128_f8f6f4 v[112:115], v[0:7], v[170:177], 0, v251, v250 op_sel_hi:[0,0,0]
	v_mfma_scale_f32_16x16x128_f8f6f4 v[108:111], v[8:15], v[178:185], 0, v251, v250 op_sel_hi:[0,0,0]
	v_mfma_scale_f32_16x16x128_f8f6f4 v[104:107], v[0:7], v[178:185], 0, v251, v250 op_sel_hi:[0,0,0]
	v_mfma_scale_f32_16x16x128_f8f6f4 v[100:103], v[8:15], v[186:193], 0, v251, v250 op_sel_hi:[0,0,0]
	v_mfma_scale_f32_16x16x128_f8f6f4 v[96:99], v[0:7], v[186:193], 0, v251, v250 op_sel_hi:[0,0,0]
	s_setprio 0
	s_barrier
	s_add_u32 s84, s6, s40
	s_addc_u32 s85, s7, s41
	s_add_u32 s88, s84, 0x100
	s_addc_u32 s89, s85, 0
	s_add_u32 s86, s47, s40
	s_addc_u32 s87, s68, s41
	ds_read_b128 v[162:165], v249 offset:16384
	ds_read_b128 v[166:169], v249 offset:17408
	ds_read_b128 v[170:173], v249 offset:18432
	ds_read_b128 v[174:177], v249 offset:19456
	ds_read_b128 v[178:181], v249 offset:20480
	ds_read_b128 v[182:185], v249 offset:21504
	ds_read_b128 v[186:189], v249 offset:22528
	ds_read_b128 v[190:193], v249 offset:23552
	s_add_u32 s90, s86, 0x100
	s_mov_b32 m0, s51
	s_nop 0
	global_load_lds_dwordx4 v161, s[88:89]
	s_addc_u32 s91, s87, 0
	s_mov_b32 m0, s55
	s_nop 0
	global_load_lds_dwordx4 v161, s[90:91]
	s_add_u32 s88, s33, s40
	s_addc_u32 s89, s44, s41
	s_add_u32 s90, s88, 0x100
	s_addc_u32 s91, s89, 0
	s_add_u32 s92, s45, s40
	s_addc_u32 s93, s46, s41
	s_add_u32 s94, s92, 0x100
	s_mov_b32 m0, s56
	s_nop 0
	global_load_lds_dwordx4 v161, s[90:91]
	s_addc_u32 s95, s93, 0
	s_mov_b32 m0, s57
	s_nop 0
	global_load_lds_dwordx4 v161, s[94:95]
	s_add_u32 s90, s71, s40
	s_addc_u32 s91, s72, s41
	s_add_u32 s94, s90, 0x100
	s_mov_b32 m0, s54
	s_nop 0
	global_load_lds_dwordx4 v160, s[42:43]
	s_addc_u32 s95, s91, 0
	s_mov_b32 m0, s58
	s_nop 0
	global_load_lds_dwordx4 v160, s[94:95]
	s_waitcnt vmcnt(8)
	s_waitcnt lgkmcnt(0)
	s_barrier
	s_setprio 1
	s_waitcnt lgkmcnt(6)
	v_mfma_scale_f32_16x16x128_f8f6f4 v[92:95], v[24:31], v[162:169], 0, v251, v250 op_sel_hi:[0,0,0]
	v_mfma_scale_f32_16x16x128_f8f6f4 v[88:91], v[16:23], v[162:169], 0, v251, v250 op_sel_hi:[0,0,0]
	s_waitcnt lgkmcnt(4)
	v_mfma_scale_f32_16x16x128_f8f6f4 v[84:87], v[24:31], v[170:177], 0, v251, v250 op_sel_hi:[0,0,0]
	v_mfma_scale_f32_16x16x128_f8f6f4 v[80:83], v[16:23], v[170:177], 0, v251, v250 op_sel_hi:[0,0,0]
	s_waitcnt lgkmcnt(2)
	v_mfma_scale_f32_16x16x128_f8f6f4 v[76:79], v[24:31], v[178:185], 0, v251, v250 op_sel_hi:[0,0,0]
	v_mfma_scale_f32_16x16x128_f8f6f4 v[72:75], v[16:23], v[178:185], 0, v251, v250 op_sel_hi:[0,0,0]
	s_waitcnt lgkmcnt(0)
	v_mfma_scale_f32_16x16x128_f8f6f4 v[68:71], v[24:31], v[186:193], 0, v251, v250 op_sel_hi:[0,0,0]
	v_mfma_scale_f32_16x16x128_f8f6f4 v[64:67], v[16:23], v[186:193], 0, v251, v250 op_sel_hi:[0,0,0]
	s_setprio 0
	s_setprio 1
	v_mfma_scale_f32_16x16x128_f8f6f4 v[60:63], v[8:15], v[162:169], 0, v251, v250 op_sel_hi:[0,0,0]
	v_mfma_scale_f32_16x16x128_f8f6f4 v[56:59], v[0:7], v[162:169], 0, v251, v250 op_sel_hi:[0,0,0]
	v_mfma_scale_f32_16x16x128_f8f6f4 v[52:55], v[8:15], v[170:177], 0, v251, v250 op_sel_hi:[0,0,0]
	v_mfma_scale_f32_16x16x128_f8f6f4 v[48:51], v[0:7], v[170:177], 0, v251, v250 op_sel_hi:[0,0,0]
	v_mfma_scale_f32_16x16x128_f8f6f4 v[44:47], v[8:15], v[178:185], 0, v251, v250 op_sel_hi:[0,0,0]
	v_mfma_scale_f32_16x16x128_f8f6f4 v[40:43], v[0:7], v[178:185], 0, v251, v250 op_sel_hi:[0,0,0]
	v_mfma_scale_f32_16x16x128_f8f6f4 v[36:39], v[8:15], v[186:193], 0, v251, v250 op_sel_hi:[0,0,0]
	v_mfma_scale_f32_16x16x128_f8f6f4 v[32:35], v[0:7], v[186:193], 0, v251, v250 op_sel_hi:[0,0,0]
	s_setprio 0
	s_barrier
	ds_read_b128 v[24:27], v252
	ds_read_b128 v[28:31], v252 offset:1024
	ds_read_b128 v[16:19], v252 offset:2048
	ds_read_b128 v[20:23], v252 offset:3072
	ds_read_b128 v[8:11], v253
	ds_read_b128 v[12:15], v253 offset:1024
	ds_read_b128 v[0:3], v253 offset:2048
	ds_read_b128 v[4:7], v253 offset:3072
	ds_read_b128 v[162:165], v249 offset:32768
	ds_read_b128 v[166:169], v249 offset:33792
	ds_read_b128 v[170:173], v249 offset:34816
	ds_read_b128 v[174:177], v249 offset:35840
	ds_read_b128 v[178:181], v249 offset:36864
	ds_read_b128 v[182:185], v249 offset:37888
	ds_read_b128 v[186:189], v249 offset:38912
	ds_read_b128 v[190:193], v249 offset:39936
	s_add_u32 s42, s80, 0x100
	s_addc_u32 s43, s81, 0
	s_add_u32 s80, s82, 0x100
	s_mov_b32 m0, s59
	s_nop 0
	global_load_lds_dwordx4 v160, s[42:43]
	s_addc_u32 s81, s83, 0
	s_mov_b32 m0, s60
	s_nop 0
	global_load_lds_dwordx4 v160, s[80:81]
	s_waitcnt vmcnt(8)
	s_waitcnt lgkmcnt(0)
	s_barrier
	s_setprio 1
	s_waitcnt lgkmcnt(6)
	v_mfma_scale_f32_16x16x128_f8f6f4 v[156:159], v[24:31], v[162:169], v[156:159], v251, v250 op_sel_hi:[0,0,0]
	v_mfma_scale_f32_16x16x128_f8f6f4 v[152:155], v[16:23], v[162:169], v[152:155], v251, v250 op_sel_hi:[0,0,0]
	s_waitcnt lgkmcnt(4)
	v_mfma_scale_f32_16x16x128_f8f6f4 v[148:151], v[24:31], v[170:177], v[148:151], v251, v250 op_sel_hi:[0,0,0]
	v_mfma_scale_f32_16x16x128_f8f6f4 v[144:147], v[16:23], v[170:177], v[144:147], v251, v250 op_sel_hi:[0,0,0]
	s_waitcnt lgkmcnt(2)
	v_mfma_scale_f32_16x16x128_f8f6f4 v[140:143], v[24:31], v[178:185], v[140:143], v251, v250 op_sel_hi:[0,0,0]
	v_mfma_scale_f32_16x16x128_f8f6f4 v[136:139], v[16:23], v[178:185], v[136:139], v251, v250 op_sel_hi:[0,0,0]
	s_waitcnt lgkmcnt(0)
	v_mfma_scale_f32_16x16x128_f8f6f4 v[132:135], v[24:31], v[186:193], v[132:135], v251, v250 op_sel_hi:[0,0,0]
	v_mfma_scale_f32_16x16x128_f8f6f4 v[128:131], v[16:23], v[186:193], v[128:131], v251, v250 op_sel_hi:[0,0,0]
	s_setprio 0
	s_setprio 1
	v_mfma_scale_f32_16x16x128_f8f6f4 v[124:127], v[8:15], v[162:169], v[124:127], v251, v250 op_sel_hi:[0,0,0]
	v_mfma_scale_f32_16x16x128_f8f6f4 v[120:123], v[0:7], v[162:169], v[120:123], v251, v250 op_sel_hi:[0,0,0]
	v_mfma_scale_f32_16x16x128_f8f6f4 v[116:119], v[8:15], v[170:177], v[116:119], v251, v250 op_sel_hi:[0,0,0]
	v_mfma_scale_f32_16x16x128_f8f6f4 v[112:115], v[0:7], v[170:177], v[112:115], v251, v250 op_sel_hi:[0,0,0]
	v_mfma_scale_f32_16x16x128_f8f6f4 v[108:111], v[8:15], v[178:185], v[108:111], v251, v250 op_sel_hi:[0,0,0]
	v_mfma_scale_f32_16x16x128_f8f6f4 v[104:107], v[0:7], v[178:185], v[104:107], v251, v250 op_sel_hi:[0,0,0]
	v_mfma_scale_f32_16x16x128_f8f6f4 v[100:103], v[8:15], v[186:193], v[100:103], v251, v250 op_sel_hi:[0,0,0]
	v_mfma_scale_f32_16x16x128_f8f6f4 v[96:99], v[0:7], v[186:193], v[96:99], v251, v250 op_sel_hi:[0,0,0]
	s_setprio 0
	s_barrier
	s_add_u32 s42, s84, 0x180
	s_addc_u32 s43, s85, 0
	ds_read_b128 v[162:165], v249 offset:49152
	ds_read_b128 v[166:169], v249 offset:50176
	ds_read_b128 v[170:173], v249 offset:51200
	ds_read_b128 v[174:177], v249 offset:52224
	ds_read_b128 v[178:181], v249 offset:53248
	ds_read_b128 v[182:185], v249 offset:54272
	ds_read_b128 v[186:189], v249 offset:55296
	ds_read_b128 v[190:193], v249 offset:56320
	s_add_u32 s80, s86, 0x180
	s_mov_b32 m0, s61
	s_nop 0
	global_load_lds_dwordx4 v161, s[42:43]
	s_addc_u32 s81, s87, 0
	s_mov_b32 m0, s62
	s_nop 0
	global_load_lds_dwordx4 v161, s[80:81]
	s_add_u32 s42, s88, 0x180
	s_addc_u32 s43, s89, 0
	s_add_u32 s80, s92, 0x180
	s_mov_b32 m0, s65
	s_nop 0
	global_load_lds_dwordx4 v161, s[42:43]
	s_addc_u32 s81, s93, 0
	s_mov_b32 m0, s66
	s_nop 0
	global_load_lds_dwordx4 v161, s[80:81]
	s_add_u32 s42, s75, 0x180
	s_addc_u32 s43, s77, 0
	s_add_u32 s80, s90, 0x180
	s_mov_b32 m0, s63
	s_nop 0
	global_load_lds_dwordx4 v160, s[42:43]
	s_addc_u32 s81, s91, 0
	s_mov_b32 m0, s64
	s_nop 0
	global_load_lds_dwordx4 v160, s[80:81]
	s_waitcnt vmcnt(8)
	s_waitcnt lgkmcnt(0)
	s_barrier
	s_setprio 1
	s_waitcnt lgkmcnt(6)
	v_mfma_scale_f32_16x16x128_f8f6f4 v[92:95], v[24:31], v[162:169], v[92:95], v251, v250 op_sel_hi:[0,0,0]
	v_mfma_scale_f32_16x16x128_f8f6f4 v[88:91], v[16:23], v[162:169], v[88:91], v251, v250 op_sel_hi:[0,0,0]
	s_waitcnt lgkmcnt(4)
	v_mfma_scale_f32_16x16x128_f8f6f4 v[84:87], v[24:31], v[170:177], v[84:87], v251, v250 op_sel_hi:[0,0,0]
	v_mfma_scale_f32_16x16x128_f8f6f4 v[80:83], v[16:23], v[170:177], v[80:83], v251, v250 op_sel_hi:[0,0,0]
	s_waitcnt lgkmcnt(2)
	v_mfma_scale_f32_16x16x128_f8f6f4 v[76:79], v[24:31], v[178:185], v[76:79], v251, v250 op_sel_hi:[0,0,0]
	v_mfma_scale_f32_16x16x128_f8f6f4 v[72:75], v[16:23], v[178:185], v[72:75], v251, v250 op_sel_hi:[0,0,0]
	s_waitcnt lgkmcnt(0)
	v_mfma_scale_f32_16x16x128_f8f6f4 v[68:71], v[24:31], v[186:193], v[68:71], v251, v250 op_sel_hi:[0,0,0]
	v_mfma_scale_f32_16x16x128_f8f6f4 v[64:67], v[16:23], v[186:193], v[64:67], v251, v250 op_sel_hi:[0,0,0]
	s_setprio 0
	s_setprio 1
	v_mfma_scale_f32_16x16x128_f8f6f4 v[60:63], v[8:15], v[162:169], v[60:63], v251, v250 op_sel_hi:[0,0,0]
	v_mfma_scale_f32_16x16x128_f8f6f4 v[56:59], v[0:7], v[162:169], v[56:59], v251, v250 op_sel_hi:[0,0,0]
	v_mfma_scale_f32_16x16x128_f8f6f4 v[52:55], v[8:15], v[170:177], v[52:55], v251, v250 op_sel_hi:[0,0,0]
	v_mfma_scale_f32_16x16x128_f8f6f4 v[48:51], v[0:7], v[170:177], v[48:51], v251, v250 op_sel_hi:[0,0,0]
	v_mfma_scale_f32_16x16x128_f8f6f4 v[44:47], v[8:15], v[178:185], v[44:47], v251, v250 op_sel_hi:[0,0,0]
	v_mfma_scale_f32_16x16x128_f8f6f4 v[40:43], v[0:7], v[178:185], v[40:43], v251, v250 op_sel_hi:[0,0,0]
	v_mfma_scale_f32_16x16x128_f8f6f4 v[36:39], v[8:15], v[186:193], v[36:39], v251, v250 op_sel_hi:[0,0,0]
	v_mfma_scale_f32_16x16x128_f8f6f4 v[32:35], v[0:7], v[186:193], v[32:35], v251, v250 op_sel_hi:[0,0,0]
	s_setprio 0
	s_barrier
	s_add_u32 s40, s40, 0x100
	s_addc_u32 s41, s41, 0
	s_cmp_ge_i32 s74, s2
	s_cbranch_scc0 .LBB0_469
	s_branch .LBB0_470

.LBB0_681:
	s_cmp_lt_i32 s18, 3
	s_cbranch_scc1 .Lhz_683
	s_add_i32 s26, s18, -2
	s_add_u32 s31, s4, s40
	s_addc_u32 s46, s5, s41
	s_add_u32 s47, s6, s22
	s_addc_u32 s48, s7, s23
	s_add_u32 s42, s16, s22
	s_addc_u32 s43, s17, s23
	s_add_u32 s49, s6, s42
	s_addc_u32 s71, s7, s43
	s_add_u32 s72, s6, s16
	s_addc_u32 s73, s7, s17
	s_add_u32 s42, s38, s40
	s_addc_u32 s43, s39, s41
	s_add_u32 s74, s4, s42
	s_addc_u32 s75, s5, s43
	s_add_u32 s77, s4, s38
	s_addc_u32 s78, s5, s39
	s_mov_b32 s79, 0
	s_mov_b64 s[42:43], 0
	s_cmp_eq_u32 s98, 0
	s_cbranch_scc1 .Lhf_683
	ds_read_b128 v[130:133], v135
	ds_read_b128 v[140:143], v135 offset:1024
	ds_read_b128 v[144:147], v135 offset:2048
	ds_read_b128 v[148:151], v135 offset:3072
	ds_read_b128 v[152:155], v136
	ds_read_b128 v[156:159], v136 offset:1024
	ds_read_b128 v[160:163], v136 offset:2048
	ds_read_b128 v[164:167], v136 offset:3072
	s_add_i32 s79, s79, 2
	s_add_u32 s80, s4, s42
	s_addc_u32 s81, s5, s43
	s_add_u32 s44, s80, 0x100
	s_addc_u32 s45, s81, 0
	s_add_u32 s86, s31, s42
	ds_read_b128 v[168:171], v137
	ds_read_b128 v[172:175], v137 offset:1024
	ds_read_b128 v[176:179], v137 offset:2048
	ds_read_b128 v[180:183], v137 offset:3072
	ds_read_b128 v[184:187], v137 offset:4096
	ds_read_b128 v[188:191], v137 offset:5120
	ds_read_b128 v[192:195], v137 offset:6144
	ds_read_b128 v[196:199], v137 offset:7168
	s_addc_u32 s87, s46, s43
	s_add_u32 s82, s86, 0x80
	s_addc_u32 s83, s87, 0
	s_add_u32 s88, s74, s42
	s_addc_u32 s89, s75, s43
	s_add_u32 s84, s88, 0x80
	s_mov_b32 m0, s68
	s_nop 0
	global_load_lds_dwordx4 v128, s[82:83]
	s_addc_u32 s85, s89, 0
	s_mov_b32 m0, s69
	s_nop 0
	global_load_lds_dwordx4 v128, s[84:85]
	s_waitcnt vmcnt(24)
	s_waitcnt lgkmcnt(0)
	s_barrier
	s_setprio 1
	s_waitcnt lgkmcnt(7)
	v_mfma_f32_16x16x32_bf16 v[124:127], v[130:133], v[168:171], 0
	v_mfma_f32_16x16x32_bf16 v[120:123], v[144:147], v[168:171], 0
	s_waitcnt lgkmcnt(5)
	v_mfma_f32_16x16x32_bf16 v[116:119], v[130:133], v[176:179], 0
	v_mfma_f32_16x16x32_bf16 v[112:115], v[144:147], v[176:179], 0
	s_waitcnt lgkmcnt(3)
	v_mfma_f32_16x16x32_bf16 v[108:111], v[130:133], v[184:187], 0
	v_mfma_f32_16x16x32_bf16 v[104:107], v[144:147], v[184:187], 0
	s_waitcnt lgkmcnt(1)
	v_mfma_f32_16x16x32_bf16 v[100:103], v[130:133], v[192:195], 0
	v_mfma_f32_16x16x32_bf16 v[96:99], v[144:147], v[192:195], 0
	v_mfma_f32_16x16x32_bf16 v[124:127], v[140:143], v[172:175], v[124:127]
	v_mfma_f32_16x16x32_bf16 v[120:123], v[148:151], v[172:175], v[120:123]
	v_mfma_f32_16x16x32_bf16 v[116:119], v[140:143], v[180:183], v[116:119]
	v_mfma_f32_16x16x32_bf16 v[112:115], v[148:151], v[180:183], v[112:115]
	v_mfma_f32_16x16x32_bf16 v[108:111], v[140:143], v[188:191], v[108:111]
	v_mfma_f32_16x16x32_bf16 v[104:107], v[148:151], v[188:191], v[104:107]
	s_waitcnt lgkmcnt(0)
	v_mfma_f32_16x16x32_bf16 v[100:103], v[140:143], v[196:199], v[100:103]
	v_mfma_f32_16x16x32_bf16 v[96:99], v[148:151], v[196:199], v[96:99]
	s_setprio 0
	s_setprio 1
	v_mfma_f32_16x16x32_bf16 v[92:95], v[152:155], v[168:171], 0
	v_mfma_f32_16x16x32_bf16 v[88:91], v[160:163], v[168:171], 0
	v_mfma_f32_16x16x32_bf16 v[84:87], v[152:155], v[176:179], 0
	v_mfma_f32_16x16x32_bf16 v[80:83], v[160:163], v[176:179], 0
	v_mfma_f32_16x16x32_bf16 v[76:79], v[152:155], v[184:187], 0
	v_mfma_f32_16x16x32_bf16 v[72:75], v[160:163], v[184:187], 0
	v_mfma_f32_16x16x32_bf16 v[68:71], v[152:155], v[192:195], 0
	v_mfma_f32_16x16x32_bf16 v[64:67], v[160:163], v[192:195], 0
	v_mfma_f32_16x16x32_bf16 v[92:95], v[156:159], v[172:175], v[92:95]
	v_mfma_f32_16x16x32_bf16 v[88:91], v[164:167], v[172:175], v[88:91]
	v_mfma_f32_16x16x32_bf16 v[84:87], v[156:159], v[180:183], v[84:87]
	v_mfma_f32_16x16x32_bf16 v[80:83], v[164:167], v[180:183], v[80:83]
	v_mfma_f32_16x16x32_bf16 v[76:79], v[156:159], v[188:191], v[76:79]
	v_mfma_f32_16x16x32_bf16 v[72:75], v[164:167], v[188:191], v[72:75]
	v_mfma_f32_16x16x32_bf16 v[68:71], v[156:159], v[196:199], v[68:71]
	v_mfma_f32_16x16x32_bf16 v[64:67], v[164:167], v[196:199], v[64:67]
	s_setprio 0
	s_barrier
	s_add_u32 s90, s6, s42
	s_addc_u32 s91, s7, s43
	s_add_u32 s82, s90, 0x100
	s_addc_u32 s83, s91, 0
	s_add_u32 s92, s72, s42
	s_addc_u32 s93, s73, s43
	s_add_u32 s84, s92, 0x100
	ds_read_b128 v[168:171], v137 offset:16384
	ds_read_b128 v[172:175], v137 offset:17408
	ds_read_b128 v[176:179], v137 offset:18432
	ds_read_b128 v[180:183], v137 offset:19456
	ds_read_b128 v[184:187], v137 offset:20480
	ds_read_b128 v[188:191], v137 offset:21504
	ds_read_b128 v[192:195], v137 offset:22528
	ds_read_b128 v[196:199], v137 offset:23552
	s_addc_u32 s85, s93, 0
	s_mov_b32 m0, s55
	s_nop 0
	global_load_lds_dwordx4 v129, s[82:83]
	s_add_u32 s94, s47, s42
	s_mov_b32 m0, s58
	s_nop 0
	global_load_lds_dwordx4 v129, s[84:85]
	s_addc_u32 s95, s48, s43
	s_add_u32 s82, s94, 0x100
	s_addc_u32 s83, s95, 0
	s_add_u32 s96, s49, s42
	s_addc_u32 s97, s71, s43
	s_add_u32 s84, s96, 0x100
	s_addc_u32 s85, s97, 0
	s_mov_b32 m0, s2
	s_nop 0
	global_load_lds_dwordx4 v129, s[82:83]
	s_mov_b32 m0, s59
	s_nop 0
	global_load_lds_dwordx4 v129, s[84:85]
	s_add_u32 s84, s77, s42
	s_addc_u32 s85, s78, s43
	s_add_u32 s82, s84, 0x100
	s_mov_b32 m0, s57
	s_nop 0
	global_load_lds_dwordx4 v128, s[44:45]
	s_addc_u32 s83, s85, 0
	s_mov_b32 m0, s60
	s_nop 0
	global_load_lds_dwordx4 v128, s[82:83]
	s_waitcnt vmcnt(24)
	s_waitcnt lgkmcnt(0)
	s_barrier
	s_setprio 1
	s_waitcnt lgkmcnt(7)
	v_mfma_f32_16x16x32_bf16 v[60:63], v[130:133], v[168:171], 0
	v_mfma_f32_16x16x32_bf16 v[56:59], v[144:147], v[168:171], 0
	s_waitcnt lgkmcnt(5)
	v_mfma_f32_16x16x32_bf16 v[52:55], v[130:133], v[176:179], 0
	v_mfma_f32_16x16x32_bf16 v[48:51], v[144:147], v[176:179], 0
	s_waitcnt lgkmcnt(3)
	v_mfma_f32_16x16x32_bf16 v[44:47], v[130:133], v[184:187], 0
	v_mfma_f32_16x16x32_bf16 v[40:43], v[144:147], v[184:187], 0
	s_waitcnt lgkmcnt(1)
	v_mfma_f32_16x16x32_bf16 v[36:39], v[130:133], v[192:195], 0
	v_mfma_f32_16x16x32_bf16 v[32:35], v[144:147], v[192:195], 0
	v_mfma_f32_16x16x32_bf16 v[60:63], v[140:143], v[172:175], v[60:63]
	v_mfma_f32_16x16x32_bf16 v[56:59], v[148:151], v[172:175], v[56:59]
	v_mfma_f32_16x16x32_bf16 v[52:55], v[140:143], v[180:183], v[52:55]
	v_mfma_f32_16x16x32_bf16 v[48:51], v[148:151], v[180:183], v[48:51]
	v_mfma_f32_16x16x32_bf16 v[44:47], v[140:143], v[188:191], v[44:47]
	v_mfma_f32_16x16x32_bf16 v[40:43], v[148:151], v[188:191], v[40:43]
	s_waitcnt lgkmcnt(0)
	v_mfma_f32_16x16x32_bf16 v[36:39], v[140:143], v[196:199], v[36:39]
	v_mfma_f32_16x16x32_bf16 v[32:35], v[148:151], v[196:199], v[32:35]
	s_setprio 0
	s_setprio 1
	v_mfma_f32_16x16x32_bf16 v[28:31], v[152:155], v[168:171], 0
	v_mfma_f32_16x16x32_bf16 v[24:27], v[160:163], v[168:171], 0
	v_mfma_f32_16x16x32_bf16 v[20:23], v[152:155], v[176:179], 0
	v_mfma_f32_16x16x32_bf16 v[16:19], v[160:163], v[176:179], 0
	v_mfma_f32_16x16x32_bf16 v[12:15], v[152:155], v[184:187], 0
	v_mfma_f32_16x16x32_bf16 v[8:11], v[160:163], v[184:187], 0
	v_mfma_f32_16x16x32_bf16 v[4:7], v[152:155], v[192:195], 0
	v_mfma_f32_16x16x32_bf16 v[0:3], v[160:163], v[192:195], 0
	v_mfma_f32_16x16x32_bf16 v[28:31], v[156:159], v[172:175], v[28:31]
	v_mfma_f32_16x16x32_bf16 v[24:27], v[164:167], v[172:175], v[24:27]
	v_mfma_f32_16x16x32_bf16 v[20:23], v[156:159], v[180:183], v[20:23]
	v_mfma_f32_16x16x32_bf16 v[16:19], v[164:167], v[180:183], v[16:19]
	v_mfma_f32_16x16x32_bf16 v[12:15], v[156:159], v[188:191], v[12:15]
	v_mfma_f32_16x16x32_bf16 v[8:11], v[164:167], v[188:191], v[8:11]
	v_mfma_f32_16x16x32_bf16 v[4:7], v[156:159], v[196:199], v[4:7]
	v_mfma_f32_16x16x32_bf16 v[0:3], v[164:167], v[196:199], v[0:3]
	s_setprio 0
	s_barrier
	ds_read_b128 v[130:133], v138
	ds_read_b128 v[140:143], v138 offset:1024
	ds_read_b128 v[144:147], v138 offset:2048
	ds_read_b128 v[148:151], v138 offset:3072
	ds_read_b128 v[152:155], v139
	ds_read_b128 v[156:159], v139 offset:1024
	ds_read_b128 v[160:163], v139 offset:2048
	ds_read_b128 v[164:167], v139 offset:3072
	ds_read_b128 v[168:171], v137 offset:32768
	ds_read_b128 v[172:175], v137 offset:33792
	ds_read_b128 v[176:179], v137 offset:34816
	ds_read_b128 v[180:183], v137 offset:35840
	ds_read_b128 v[184:187], v137 offset:36864
	ds_read_b128 v[188:191], v137 offset:37888
	ds_read_b128 v[192:195], v137 offset:38912
	ds_read_b128 v[196:199], v137 offset:39936
	s_add_u32 s44, s86, 0x100
	s_addc_u32 s45, s87, 0
	s_add_u32 s82, s88, 0x100
	s_mov_b32 m0, s33
	s_nop 0
	global_load_lds_dwordx4 v128, s[44:45]
	s_addc_u32 s83, s89, 0
	s_mov_b32 m0, s61
	s_nop 0
	global_load_lds_dwordx4 v128, s[82:83]
	s_waitcnt vmcnt(8)
	s_waitcnt lgkmcnt(0)
	s_barrier
	s_setprio 1
	s_waitcnt lgkmcnt(7)
	v_mfma_f32_16x16x32_bf16 v[124:127], v[130:133], v[168:171], v[124:127]
	v_mfma_f32_16x16x32_bf16 v[120:123], v[144:147], v[168:171], v[120:123]
	s_waitcnt lgkmcnt(5)
	v_mfma_f32_16x16x32_bf16 v[116:119], v[130:133], v[176:179], v[116:119]
	v_mfma_f32_16x16x32_bf16 v[112:115], v[144:147], v[176:179], v[112:115]
	s_waitcnt lgkmcnt(3)
	v_mfma_f32_16x16x32_bf16 v[108:111], v[130:133], v[184:187], v[108:111]
	v_mfma_f32_16x16x32_bf16 v[104:107], v[144:147], v[184:187], v[104:107]
	s_waitcnt lgkmcnt(1)
	v_mfma_f32_16x16x32_bf16 v[100:103], v[130:133], v[192:195], v[100:103]
	v_mfma_f32_16x16x32_bf16 v[96:99], v[144:147], v[192:195], v[96:99]
	v_mfma_f32_16x16x32_bf16 v[124:127], v[140:143], v[172:175], v[124:127]
	v_mfma_f32_16x16x32_bf16 v[120:123], v[148:151], v[172:175], v[120:123]
	v_mfma_f32_16x16x32_bf16 v[116:119], v[140:143], v[180:183], v[116:119]
	v_mfma_f32_16x16x32_bf16 v[112:115], v[148:151], v[180:183], v[112:115]
	v_mfma_f32_16x16x32_bf16 v[108:111], v[140:143], v[188:191], v[108:111]
	v_mfma_f32_16x16x32_bf16 v[104:107], v[148:151], v[188:191], v[104:107]
	s_waitcnt lgkmcnt(0)
	v_mfma_f32_16x16x32_bf16 v[100:103], v[140:143], v[196:199], v[100:103]
	v_mfma_f32_16x16x32_bf16 v[96:99], v[148:151], v[196:199], v[96:99]
	s_setprio 0
	s_setprio 1
	v_mfma_f32_16x16x32_bf16 v[92:95], v[152:155], v[168:171], v[92:95]
	v_mfma_f32_16x16x32_bf16 v[88:91], v[160:163], v[168:171], v[88:91]
	v_mfma_f32_16x16x32_bf16 v[84:87], v[152:155], v[176:179], v[84:87]
	v_mfma_f32_16x16x32_bf16 v[80:83], v[160:163], v[176:179], v[80:83]
	v_mfma_f32_16x16x32_bf16 v[76:79], v[152:155], v[184:187], v[76:79]
	v_mfma_f32_16x16x32_bf16 v[72:75], v[160:163], v[184:187], v[72:75]
	v_mfma_f32_16x16x32_bf16 v[68:71], v[152:155], v[192:195], v[68:71]
	v_mfma_f32_16x16x32_bf16 v[64:67], v[160:163], v[192:195], v[64:67]
	v_mfma_f32_16x16x32_bf16 v[92:95], v[156:159], v[172:175], v[92:95]
	v_mfma_f32_16x16x32_bf16 v[88:91], v[164:167], v[172:175], v[88:91]
	v_mfma_f32_16x16x32_bf16 v[84:87], v[156:159], v[180:183], v[84:87]
	v_mfma_f32_16x16x32_bf16 v[80:83], v[164:167], v[180:183], v[80:83]
	v_mfma_f32_16x16x32_bf16 v[76:79], v[156:159], v[188:191], v[76:79]
	v_mfma_f32_16x16x32_bf16 v[72:75], v[164:167], v[188:191], v[72:75]
	v_mfma_f32_16x16x32_bf16 v[68:71], v[156:159], v[196:199], v[68:71]
	v_mfma_f32_16x16x32_bf16 v[64:67], v[164:167], v[196:199], v[64:67]
	s_setprio 0
	s_barrier
	s_add_u32 s44, s90, 0x180
	s_addc_u32 s45, s91, 0
	ds_read_b128 v[168:171], v137 offset:49152
	ds_read_b128 v[172:175], v137 offset:50176
	ds_read_b128 v[176:179], v137 offset:51200
	ds_read_b128 v[180:183], v137 offset:52224
	ds_read_b128 v[184:187], v137 offset:53248
	ds_read_b128 v[188:191], v137 offset:54272
	ds_read_b128 v[192:195], v137 offset:55296
	ds_read_b128 v[196:199], v137 offset:56320
	s_add_u32 s82, s92, 0x180
	s_mov_b32 m0, s62
	s_nop 0
	global_load_lds_dwordx4 v129, s[44:45]
	s_addc_u32 s83, s93, 0
	s_mov_b32 m0, s63
	s_nop 0
	global_load_lds_dwordx4 v129, s[82:83]
	s_add_u32 s44, s94, 0x180
	s_addc_u32 s45, s95, 0
	s_add_u32 s82, s96, 0x180
	s_mov_b32 m0, s66
	s_nop 0
	global_load_lds_dwordx4 v129, s[44:45]
	s_addc_u32 s83, s97, 0
	s_mov_b32 m0, s67
	s_nop 0
	global_load_lds_dwordx4 v129, s[82:83]
	s_add_u32 s44, s80, 0x180
	s_addc_u32 s45, s81, 0
	s_add_u32 s80, s84, 0x180
	s_mov_b32 m0, s64
	s_nop 0
	global_load_lds_dwordx4 v128, s[44:45]
	s_addc_u32 s81, s85, 0
	s_mov_b32 m0, s65
	s_nop 0
	global_load_lds_dwordx4 v128, s[80:81]
	s_waitcnt vmcnt(8)
	s_waitcnt lgkmcnt(0)
	s_barrier
	s_setprio 1
	s_waitcnt lgkmcnt(7)
	v_mfma_f32_16x16x32_bf16 v[60:63], v[130:133], v[168:171], v[60:63]
	v_mfma_f32_16x16x32_bf16 v[56:59], v[144:147], v[168:171], v[56:59]
	s_waitcnt lgkmcnt(5)
	v_mfma_f32_16x16x32_bf16 v[52:55], v[130:133], v[176:179], v[52:55]
	v_mfma_f32_16x16x32_bf16 v[48:51], v[144:147], v[176:179], v[48:51]
	s_waitcnt lgkmcnt(3)
	v_mfma_f32_16x16x32_bf16 v[44:47], v[130:133], v[184:187], v[44:47]
	v_mfma_f32_16x16x32_bf16 v[40:43], v[144:147], v[184:187], v[40:43]
	s_waitcnt lgkmcnt(1)
	v_mfma_f32_16x16x32_bf16 v[36:39], v[130:133], v[192:195], v[36:39]
	v_mfma_f32_16x16x32_bf16 v[32:35], v[144:147], v[192:195], v[32:35]
	v_mfma_f32_16x16x32_bf16 v[60:63], v[140:143], v[172:175], v[60:63]
	v_mfma_f32_16x16x32_bf16 v[56:59], v[148:151], v[172:175], v[56:59]
	v_mfma_f32_16x16x32_bf16 v[52:55], v[140:143], v[180:183], v[52:55]
	v_mfma_f32_16x16x32_bf16 v[48:51], v[148:151], v[180:183], v[48:51]
	v_mfma_f32_16x16x32_bf16 v[44:47], v[140:143], v[188:191], v[44:47]
	v_mfma_f32_16x16x32_bf16 v[40:43], v[148:151], v[188:191], v[40:43]
	s_waitcnt lgkmcnt(0)
	v_mfma_f32_16x16x32_bf16 v[36:39], v[140:143], v[196:199], v[36:39]
	v_mfma_f32_16x16x32_bf16 v[32:35], v[148:151], v[196:199], v[32:35]
	s_setprio 0
	s_setprio 1
	v_mfma_f32_16x16x32_bf16 v[28:31], v[152:155], v[168:171], v[28:31]
	v_mfma_f32_16x16x32_bf16 v[24:27], v[160:163], v[168:171], v[24:27]
	v_mfma_f32_16x16x32_bf16 v[20:23], v[152:155], v[176:179], v[20:23]
	v_mfma_f32_16x16x32_bf16 v[16:19], v[160:163], v[176:179], v[16:19]
	v_mfma_f32_16x16x32_bf16 v[12:15], v[152:155], v[184:187], v[12:15]
	v_mfma_f32_16x16x32_bf16 v[8:11], v[160:163], v[184:187], v[8:11]
	v_mfma_f32_16x16x32_bf16 v[4:7], v[152:155], v[192:195], v[4:7]
	v_mfma_f32_16x16x32_bf16 v[0:3], v[160:163], v[192:195], v[0:3]
	v_mfma_f32_16x16x32_bf16 v[28:31], v[156:159], v[172:175], v[28:31]
	v_mfma_f32_16x16x32_bf16 v[24:27], v[164:167], v[172:175], v[24:27]
	v_mfma_f32_16x16x32_bf16 v[20:23], v[156:159], v[180:183], v[20:23]
	v_mfma_f32_16x16x32_bf16 v[16:19], v[164:167], v[180:183], v[16:19]
	v_mfma_f32_16x16x32_bf16 v[12:15], v[156:159], v[188:191], v[12:15]
	v_mfma_f32_16x16x32_bf16 v[8:11], v[164:167], v[188:191], v[8:11]
	v_mfma_f32_16x16x32_bf16 v[4:7], v[156:159], v[196:199], v[4:7]
	v_mfma_f32_16x16x32_bf16 v[0:3], v[164:167], v[196:199], v[0:3]
	s_setprio 0
	s_barrier
	s_add_u32 s42, s42, 0x100
	s_addc_u32 s43, s43, 0
	s_cmp_ge_i32 s79, s26
	s_cbranch_scc0 .LBB0_683
	s_branch .LBB0_684
.Lhf_683:
	ds_read_b128 v[130:133], v135
	ds_read_b128 v[140:143], v135 offset:1024
	ds_read_b128 v[144:147], v135 offset:2048
	ds_read_b128 v[148:151], v135 offset:3072
	ds_read_b128 v[152:155], v136
	ds_read_b128 v[156:159], v136 offset:1024
	ds_read_b128 v[160:163], v136 offset:2048
	ds_read_b128 v[164:167], v136 offset:3072
	s_add_i32 s79, s79, 2
	s_add_u32 s80, s4, s42
	s_addc_u32 s81, s5, s43
	s_add_u32 s44, s80, 0x100
	s_addc_u32 s45, s81, 0
	s_add_u32 s86, s31, s42
	ds_read_b128 v[168:171], v137
	ds_read_b128 v[172:175], v137 offset:1024
	ds_read_b128 v[176:179], v137 offset:2048
	ds_read_b128 v[180:183], v137 offset:3072
	ds_read_b128 v[184:187], v137 offset:4096
	ds_read_b128 v[188:191], v137 offset:5120
	ds_read_b128 v[192:195], v137 offset:6144
	ds_read_b128 v[196:199], v137 offset:7168
	s_addc_u32 s87, s46, s43
	s_add_u32 s82, s86, 0x80
	s_addc_u32 s83, s87, 0
	s_add_u32 s88, s74, s42
	s_addc_u32 s89, s75, s43
	s_add_u32 s84, s88, 0x80
	s_mov_b32 m0, s68
	s_nop 0
	global_load_lds_dwordx4 v128, s[82:83]
	s_addc_u32 s85, s89, 0
	s_mov_b32 m0, s69
	s_nop 0
	global_load_lds_dwordx4 v128, s[84:85]
	s_waitcnt vmcnt(8)
	s_waitcnt lgkmcnt(0)
	s_barrier
	s_setprio 1
	s_waitcnt lgkmcnt(7)
	v_mfma_f32_16x16x32_bf16 v[124:127], v[130:133], v[168:171], 0
	v_mfma_f32_16x16x32_bf16 v[120:123], v[144:147], v[168:171], 0
	s_waitcnt lgkmcnt(5)
	v_mfma_f32_16x16x32_bf16 v[116:119], v[130:133], v[176:179], 0
	v_mfma_f32_16x16x32_bf16 v[112:115], v[144:147], v[176:179], 0
	s_waitcnt lgkmcnt(3)
	v_mfma_f32_16x16x32_bf16 v[108:111], v[130:133], v[184:187], 0
	v_mfma_f32_16x16x32_bf16 v[104:107], v[144:147], v[184:187], 0
	s_waitcnt lgkmcnt(1)
	v_mfma_f32_16x16x32_bf16 v[100:103], v[130:133], v[192:195], 0
	v_mfma_f32_16x16x32_bf16 v[96:99], v[144:147], v[192:195], 0
	v_mfma_f32_16x16x32_bf16 v[124:127], v[140:143], v[172:175], v[124:127]
	v_mfma_f32_16x16x32_bf16 v[120:123], v[148:151], v[172:175], v[120:123]
	v_mfma_f32_16x16x32_bf16 v[116:119], v[140:143], v[180:183], v[116:119]
	v_mfma_f32_16x16x32_bf16 v[112:115], v[148:151], v[180:183], v[112:115]
	v_mfma_f32_16x16x32_bf16 v[108:111], v[140:143], v[188:191], v[108:111]
	v_mfma_f32_16x16x32_bf16 v[104:107], v[148:151], v[188:191], v[104:107]
	s_waitcnt lgkmcnt(0)
	v_mfma_f32_16x16x32_bf16 v[100:103], v[140:143], v[196:199], v[100:103]
	v_mfma_f32_16x16x32_bf16 v[96:99], v[148:151], v[196:199], v[96:99]
	s_setprio 0
	s_setprio 1
	v_mfma_f32_16x16x32_bf16 v[92:95], v[152:155], v[168:171], 0
	v_mfma_f32_16x16x32_bf16 v[88:91], v[160:163], v[168:171], 0
	v_mfma_f32_16x16x32_bf16 v[84:87], v[152:155], v[176:179], 0
	v_mfma_f32_16x16x32_bf16 v[80:83], v[160:163], v[176:179], 0
	v_mfma_f32_16x16x32_bf16 v[76:79], v[152:155], v[184:187], 0
	v_mfma_f32_16x16x32_bf16 v[72:75], v[160:163], v[184:187], 0
	v_mfma_f32_16x16x32_bf16 v[68:71], v[152:155], v[192:195], 0
	v_mfma_f32_16x16x32_bf16 v[64:67], v[160:163], v[192:195], 0
	v_mfma_f32_16x16x32_bf16 v[92:95], v[156:159], v[172:175], v[92:95]
	v_mfma_f32_16x16x32_bf16 v[88:91], v[164:167], v[172:175], v[88:91]
	v_mfma_f32_16x16x32_bf16 v[84:87], v[156:159], v[180:183], v[84:87]
	v_mfma_f32_16x16x32_bf16 v[80:83], v[164:167], v[180:183], v[80:83]
	v_mfma_f32_16x16x32_bf16 v[76:79], v[156:159], v[188:191], v[76:79]
	v_mfma_f32_16x16x32_bf16 v[72:75], v[164:167], v[188:191], v[72:75]
	v_mfma_f32_16x16x32_bf16 v[68:71], v[156:159], v[196:199], v[68:71]
	v_mfma_f32_16x16x32_bf16 v[64:67], v[164:167], v[196:199], v[64:67]
	s_setprio 0
	s_barrier
	s_add_u32 s90, s6, s42
	s_addc_u32 s91, s7, s43
	s_add_u32 s82, s90, 0x100
	s_addc_u32 s83, s91, 0
	s_add_u32 s92, s72, s42
	s_addc_u32 s93, s73, s43
	s_add_u32 s84, s92, 0x100
	ds_read_b128 v[168:171], v137 offset:16384
	ds_read_b128 v[172:175], v137 offset:17408
	ds_read_b128 v[176:179], v137 offset:18432
	ds_read_b128 v[180:183], v137 offset:19456
	ds_read_b128 v[184:187], v137 offset:20480
	ds_read_b128 v[188:191], v137 offset:21504
	ds_read_b128 v[192:195], v137 offset:22528
	ds_read_b128 v[196:199], v137 offset:23552
	s_addc_u32 s85, s93, 0
	s_mov_b32 m0, s55
	s_nop 0
	global_load_lds_dwordx4 v129, s[82:83]
	s_add_u32 s94, s47, s42
	s_mov_b32 m0, s58
	s_nop 0
	global_load_lds_dwordx4 v129, s[84:85]
	s_addc_u32 s95, s48, s43
	s_add_u32 s82, s94, 0x100
	s_addc_u32 s83, s95, 0
	s_add_u32 s96, s49, s42
	s_addc_u32 s97, s71, s43
	s_add_u32 s84, s96, 0x100
	s_addc_u32 s85, s97, 0
	s_mov_b32 m0, s2
	s_nop 0
	global_load_lds_dwordx4 v129, s[82:83]
	s_mov_b32 m0, s59
	s_nop 0
	global_load_lds_dwordx4 v129, s[84:85]
	s_add_u32 s84, s77, s42
	s_addc_u32 s85, s78, s43
	s_add_u32 s82, s84, 0x100
	s_mov_b32 m0, s57
	s_nop 0
	global_load_lds_dwordx4 v128, s[44:45]
	s_addc_u32 s83, s85, 0
	s_mov_b32 m0, s60
	s_nop 0
	global_load_lds_dwordx4 v128, s[82:83]
	s_waitcnt vmcnt(8)
	s_waitcnt lgkmcnt(0)
	s_barrier
	s_setprio 1
	s_waitcnt lgkmcnt(7)
	v_mfma_f32_16x16x32_bf16 v[60:63], v[130:133], v[168:171], 0
	v_mfma_f32_16x16x32_bf16 v[56:59], v[144:147], v[168:171], 0
	s_waitcnt lgkmcnt(5)
	v_mfma_f32_16x16x32_bf16 v[52:55], v[130:133], v[176:179], 0
	v_mfma_f32_16x16x32_bf16 v[48:51], v[144:147], v[176:179], 0
	s_waitcnt lgkmcnt(3)
	v_mfma_f32_16x16x32_bf16 v[44:47], v[130:133], v[184:187], 0
	v_mfma_f32_16x16x32_bf16 v[40:43], v[144:147], v[184:187], 0
	s_waitcnt lgkmcnt(1)
	v_mfma_f32_16x16x32_bf16 v[36:39], v[130:133], v[192:195], 0
	v_mfma_f32_16x16x32_bf16 v[32:35], v[144:147], v[192:195], 0
	v_mfma_f32_16x16x32_bf16 v[60:63], v[140:143], v[172:175], v[60:63]
	v_mfma_f32_16x16x32_bf16 v[56:59], v[148:151], v[172:175], v[56:59]
	v_mfma_f32_16x16x32_bf16 v[52:55], v[140:143], v[180:183], v[52:55]
	v_mfma_f32_16x16x32_bf16 v[48:51], v[148:151], v[180:183], v[48:51]
	v_mfma_f32_16x16x32_bf16 v[44:47], v[140:143], v[188:191], v[44:47]
	v_mfma_f32_16x16x32_bf16 v[40:43], v[148:151], v[188:191], v[40:43]
	s_waitcnt lgkmcnt(0)
	v_mfma_f32_16x16x32_bf16 v[36:39], v[140:143], v[196:199], v[36:39]
	v_mfma_f32_16x16x32_bf16 v[32:35], v[148:151], v[196:199], v[32:35]
	s_setprio 0
	s_setprio 1
	v_mfma_f32_16x16x32_bf16 v[28:31], v[152:155], v[168:171], 0
	v_mfma_f32_16x16x32_bf16 v[24:27], v[160:163], v[168:171], 0
	v_mfma_f32_16x16x32_bf16 v[20:23], v[152:155], v[176:179], 0
	v_mfma_f32_16x16x32_bf16 v[16:19], v[160:163], v[176:179], 0
	v_mfma_f32_16x16x32_bf16 v[12:15], v[152:155], v[184:187], 0
	v_mfma_f32_16x16x32_bf16 v[8:11], v[160:163], v[184:187], 0
	v_mfma_f32_16x16x32_bf16 v[4:7], v[152:155], v[192:195], 0
	v_mfma_f32_16x16x32_bf16 v[0:3], v[160:163], v[192:195], 0
	v_mfma_f32_16x16x32_bf16 v[28:31], v[156:159], v[172:175], v[28:31]
	v_mfma_f32_16x16x32_bf16 v[24:27], v[164:167], v[172:175], v[24:27]
	v_mfma_f32_16x16x32_bf16 v[20:23], v[156:159], v[180:183], v[20:23]
	v_mfma_f32_16x16x32_bf16 v[16:19], v[164:167], v[180:183], v[16:19]
	v_mfma_f32_16x16x32_bf16 v[12:15], v[156:159], v[188:191], v[12:15]
	v_mfma_f32_16x16x32_bf16 v[8:11], v[164:167], v[188:191], v[8:11]
	v_mfma_f32_16x16x32_bf16 v[4:7], v[156:159], v[196:199], v[4:7]
	v_mfma_f32_16x16x32_bf16 v[0:3], v[164:167], v[196:199], v[0:3]
	s_setprio 0
	s_barrier
	ds_read_b128 v[130:133], v138
	ds_read_b128 v[140:143], v138 offset:1024
	ds_read_b128 v[144:147], v138 offset:2048
	ds_read_b128 v[148:151], v138 offset:3072
	ds_read_b128 v[152:155], v139
	ds_read_b128 v[156:159], v139 offset:1024
	ds_read_b128 v[160:163], v139 offset:2048
	ds_read_b128 v[164:167], v139 offset:3072
	ds_read_b128 v[168:171], v137 offset:32768
	ds_read_b128 v[172:175], v137 offset:33792
	ds_read_b128 v[176:179], v137 offset:34816
	ds_read_b128 v[180:183], v137 offset:35840
	ds_read_b128 v[184:187], v137 offset:36864
	ds_read_b128 v[188:191], v137 offset:37888
	ds_read_b128 v[192:195], v137 offset:38912
	ds_read_b128 v[196:199], v137 offset:39936
	s_add_u32 s44, s86, 0x100
	s_addc_u32 s45, s87, 0
	s_add_u32 s82, s88, 0x100
	s_mov_b32 m0, s33
	s_nop 0
	global_load_lds_dwordx4 v128, s[44:45]
	s_addc_u32 s83, s89, 0
	s_mov_b32 m0, s61
	s_nop 0
	global_load_lds_dwordx4 v128, s[82:83]
	s_waitcnt vmcnt(8)
	s_waitcnt lgkmcnt(0)
	s_barrier
	s_setprio 1
	s_waitcnt lgkmcnt(7)
	v_mfma_f32_16x16x32_bf16 v[124:127], v[130:133], v[168:171], v[124:127]
	v_mfma_f32_16x16x32_bf16 v[120:123], v[144:147], v[168:171], v[120:123]
	s_waitcnt lgkmcnt(5)
	v_mfma_f32_16x16x32_bf16 v[116:119], v[130:133], v[176:179], v[116:119]
	v_mfma_f32_16x16x32_bf16 v[112:115], v[144:147], v[176:179], v[112:115]
	s_waitcnt lgkmcnt(3)
	v_mfma_f32_16x16x32_bf16 v[108:111], v[130:133], v[184:187], v[108:111]
	v_mfma_f32_16x16x32_bf16 v[104:107], v[144:147], v[184:187], v[104:107]
	s_waitcnt lgkmcnt(1)
	v_mfma_f32_16x16x32_bf16 v[100:103], v[130:133], v[192:195], v[100:103]
	v_mfma_f32_16x16x32_bf16 v[96:99], v[144:147], v[192:195], v[96:99]
	v_mfma_f32_16x16x32_bf16 v[124:127], v[140:143], v[172:175], v[124:127]
	v_mfma_f32_16x16x32_bf16 v[120:123], v[148:151], v[172:175], v[120:123]
	v_mfma_f32_16x16x32_bf16 v[116:119], v[140:143], v[180:183], v[116:119]
	v_mfma_f32_16x16x32_bf16 v[112:115], v[148:151], v[180:183], v[112:115]
	v_mfma_f32_16x16x32_bf16 v[108:111], v[140:143], v[188:191], v[108:111]
	v_mfma_f32_16x16x32_bf16 v[104:107], v[148:151], v[188:191], v[104:107]
	s_waitcnt lgkmcnt(0)
	v_mfma_f32_16x16x32_bf16 v[100:103], v[140:143], v[196:199], v[100:103]
	v_mfma_f32_16x16x32_bf16 v[96:99], v[148:151], v[196:199], v[96:99]
	s_setprio 0
	s_setprio 1
	v_mfma_f32_16x16x32_bf16 v[92:95], v[152:155], v[168:171], v[92:95]
	v_mfma_f32_16x16x32_bf16 v[88:91], v[160:163], v[168:171], v[88:91]
	v_mfma_f32_16x16x32_bf16 v[84:87], v[152:155], v[176:179], v[84:87]
	v_mfma_f32_16x16x32_bf16 v[80:83], v[160:163], v[176:179], v[80:83]
	v_mfma_f32_16x16x32_bf16 v[76:79], v[152:155], v[184:187], v[76:79]
	v_mfma_f32_16x16x32_bf16 v[72:75], v[160:163], v[184:187], v[72:75]
	v_mfma_f32_16x16x32_bf16 v[68:71], v[152:155], v[192:195], v[68:71]
	v_mfma_f32_16x16x32_bf16 v[64:67], v[160:163], v[192:195], v[64:67]
	v_mfma_f32_16x16x32_bf16 v[92:95], v[156:159], v[172:175], v[92:95]
	v_mfma_f32_16x16x32_bf16 v[88:91], v[164:167], v[172:175], v[88:91]
	v_mfma_f32_16x16x32_bf16 v[84:87], v[156:159], v[180:183], v[84:87]
	v_mfma_f32_16x16x32_bf16 v[80:83], v[164:167], v[180:183], v[80:83]
	v_mfma_f32_16x16x32_bf16 v[76:79], v[156:159], v[188:191], v[76:79]
	v_mfma_f32_16x16x32_bf16 v[72:75], v[164:167], v[188:191], v[72:75]
	v_mfma_f32_16x16x32_bf16 v[68:71], v[156:159], v[196:199], v[68:71]
	v_mfma_f32_16x16x32_bf16 v[64:67], v[164:167], v[196:199], v[64:67]
	s_setprio 0
	s_barrier
	s_add_u32 s44, s90, 0x180
	s_addc_u32 s45, s91, 0
	ds_read_b128 v[168:171], v137 offset:49152
	ds_read_b128 v[172:175], v137 offset:50176
	ds_read_b128 v[176:179], v137 offset:51200
	ds_read_b128 v[180:183], v137 offset:52224
	ds_read_b128 v[184:187], v137 offset:53248
	ds_read_b128 v[188:191], v137 offset:54272
	ds_read_b128 v[192:195], v137 offset:55296
	ds_read_b128 v[196:199], v137 offset:56320
	s_add_u32 s82, s92, 0x180
	s_mov_b32 m0, s62
	s_nop 0
	global_load_lds_dwordx4 v129, s[44:45]
	s_addc_u32 s83, s93, 0
	s_mov_b32 m0, s63
	s_nop 0
	global_load_lds_dwordx4 v129, s[82:83]
	s_add_u32 s44, s94, 0x180
	s_addc_u32 s45, s95, 0
	s_add_u32 s82, s96, 0x180
	s_mov_b32 m0, s66
	s_nop 0
	global_load_lds_dwordx4 v129, s[44:45]
	s_addc_u32 s83, s97, 0
	s_mov_b32 m0, s67
	s_nop 0
	global_load_lds_dwordx4 v129, s[82:83]
	s_add_u32 s44, s80, 0x180
	s_addc_u32 s45, s81, 0
	s_add_u32 s80, s84, 0x180
	s_mov_b32 m0, s64
	s_nop 0
	global_load_lds_dwordx4 v128, s[44:45]
	s_addc_u32 s81, s85, 0
	s_mov_b32 m0, s65
	s_nop 0
	global_load_lds_dwordx4 v128, s[80:81]
	s_waitcnt vmcnt(8)
	s_waitcnt lgkmcnt(0)
	s_barrier
	s_setprio 1
	s_waitcnt lgkmcnt(7)
	v_mfma_f32_16x16x32_bf16 v[60:63], v[130:133], v[168:171], v[60:63]
	v_mfma_f32_16x16x32_bf16 v[56:59], v[144:147], v[168:171], v[56:59]
	s_waitcnt lgkmcnt(5)
	v_mfma_f32_16x16x32_bf16 v[52:55], v[130:133], v[176:179], v[52:55]
	v_mfma_f32_16x16x32_bf16 v[48:51], v[144:147], v[176:179], v[48:51]
	s_waitcnt lgkmcnt(3)
	v_mfma_f32_16x16x32_bf16 v[44:47], v[130:133], v[184:187], v[44:47]
	v_mfma_f32_16x16x32_bf16 v[40:43], v[144:147], v[184:187], v[40:43]
	s_waitcnt lgkmcnt(1)
	v_mfma_f32_16x16x32_bf16 v[36:39], v[130:133], v[192:195], v[36:39]
	v_mfma_f32_16x16x32_bf16 v[32:35], v[144:147], v[192:195], v[32:35]
	v_mfma_f32_16x16x32_bf16 v[60:63], v[140:143], v[172:175], v[60:63]
	v_mfma_f32_16x16x32_bf16 v[56:59], v[148:151], v[172:175], v[56:59]
	v_mfma_f32_16x16x32_bf16 v[52:55], v[140:143], v[180:183], v[52:55]
	v_mfma_f32_16x16x32_bf16 v[48:51], v[148:151], v[180:183], v[48:51]
	v_mfma_f32_16x16x32_bf16 v[44:47], v[140:143], v[188:191], v[44:47]
	v_mfma_f32_16x16x32_bf16 v[40:43], v[148:151], v[188:191], v[40:43]
	s_waitcnt lgkmcnt(0)
	v_mfma_f32_16x16x32_bf16 v[36:39], v[140:143], v[196:199], v[36:39]
	v_mfma_f32_16x16x32_bf16 v[32:35], v[148:151], v[196:199], v[32:35]
	s_setprio 0
	s_setprio 1
	v_mfma_f32_16x16x32_bf16 v[28:31], v[152:155], v[168:171], v[28:31]
	v_mfma_f32_16x16x32_bf16 v[24:27], v[160:163], v[168:171], v[24:27]
	v_mfma_f32_16x16x32_bf16 v[20:23], v[152:155], v[176:179], v[20:23]
	v_mfma_f32_16x16x32_bf16 v[16:19], v[160:163], v[176:179], v[16:19]
	v_mfma_f32_16x16x32_bf16 v[12:15], v[152:155], v[184:187], v[12:15]
	v_mfma_f32_16x16x32_bf16 v[8:11], v[160:163], v[184:187], v[8:11]
	v_mfma_f32_16x16x32_bf16 v[4:7], v[152:155], v[192:195], v[4:7]
	v_mfma_f32_16x16x32_bf16 v[0:3], v[160:163], v[192:195], v[0:3]
	v_mfma_f32_16x16x32_bf16 v[28:31], v[156:159], v[172:175], v[28:31]
	v_mfma_f32_16x16x32_bf16 v[24:27], v[164:167], v[172:175], v[24:27]
	v_mfma_f32_16x16x32_bf16 v[20:23], v[156:159], v[180:183], v[20:23]
	v_mfma_f32_16x16x32_bf16 v[16:19], v[164:167], v[180:183], v[16:19]
	v_mfma_f32_16x16x32_bf16 v[12:15], v[156:159], v[188:191], v[12:15]
	v_mfma_f32_16x16x32_bf16 v[8:11], v[164:167], v[188:191], v[8:11]
	v_mfma_f32_16x16x32_bf16 v[4:7], v[156:159], v[196:199], v[4:7]
	v_mfma_f32_16x16x32_bf16 v[0:3], v[164:167], v[196:199], v[0:3]
	s_setprio 0
	s_barrier
	s_add_u32 s42, s42, 0x100
	s_addc_u32 s43, s43, 0
	s_cmp_ge_i32 s79, s26
	s_cbranch_scc0 .LBB0_683
	s_branch .LBB0_684

.LBB0_781:
	s_cmp_lt_i32 s24, 3
	s_cbranch_scc1 .Lhz_783
	s_add_i32 s2, s24, -2
	s_add_u32 s23, s4, s48
	s_addc_u32 s25, s5, s49
	s_add_u32 s27, s6, s30
	s_addc_u32 s33, s7, s31
	s_add_u32 s34, s0, s30
	s_addc_u32 s41, s1, s31
	s_add_u32 s34, s6, s34
	s_addc_u32 s41, s7, s41
	s_add_u32 s54, s6, s0
	s_addc_u32 s55, s7, s1
	s_add_u32 s50, s46, s48
	s_addc_u32 s51, s47, s49
	s_add_u32 s68, s4, s50
	s_addc_u32 s69, s5, s51
	s_add_u32 s70, s4, s46
	s_addc_u32 s71, s5, s47
	s_mov_b32 s72, 0
	s_mov_b64 s[50:51], 0
	s_cmp_eq_u32 s98, 0
	s_cbranch_scc1 .Lhf_783
	ds_read_b128 v[130:133], v137
	ds_read_b128 v[142:145], v137 offset:1024
	ds_read_b128 v[146:149], v137 offset:2048
	ds_read_b128 v[150:153], v137 offset:3072
	ds_read_b128 v[154:157], v138
	ds_read_b128 v[158:161], v138 offset:1024
	ds_read_b128 v[162:165], v138 offset:2048
	ds_read_b128 v[166:169], v138 offset:3072
	s_add_i32 s72, s72, 2
	s_add_u32 s74, s4, s50
	s_addc_u32 s75, s5, s51
	s_add_u32 s52, s74, 0x100
	s_addc_u32 s53, s75, 0
	s_add_u32 s77, s23, s50
	ds_read_b128 v[170:173], v139
	ds_read_b128 v[174:177], v139 offset:1024
	ds_read_b128 v[178:181], v139 offset:2048
	ds_read_b128 v[182:185], v139 offset:3072
	ds_read_b128 v[186:189], v139 offset:4096
	ds_read_b128 v[190:193], v139 offset:5120
	ds_read_b128 v[194:197], v139 offset:6144
	ds_read_b128 v[198:201], v139 offset:7168
	s_addc_u32 s87, s25, s51
	s_add_u32 s80, s77, 0x80
	s_addc_u32 s81, s87, 0
	s_add_u32 s90, s68, s50
	s_addc_u32 s91, s69, s51
	s_add_u32 s88, s90, 0x80
	s_mov_b32 m0, s84
	s_nop 0
	global_load_lds_dwordx4 v128, s[80:81]
	s_addc_u32 s89, s91, 0
	s_mov_b32 m0, s85
	s_nop 0
	global_load_lds_dwordx4 v128, s[88:89]
	s_waitcnt vmcnt(24)
	s_waitcnt lgkmcnt(0)
	s_barrier
	s_setprio 1
	s_waitcnt lgkmcnt(7)
	v_mfma_f32_16x16x32_bf16 v[124:127], v[130:133], v[170:173], 0
	v_mfma_f32_16x16x32_bf16 v[120:123], v[146:149], v[170:173], 0
	s_waitcnt lgkmcnt(5)
	v_mfma_f32_16x16x32_bf16 v[116:119], v[130:133], v[178:181], 0
	v_mfma_f32_16x16x32_bf16 v[112:115], v[146:149], v[178:181], 0
	s_waitcnt lgkmcnt(3)
	v_mfma_f32_16x16x32_bf16 v[108:111], v[130:133], v[186:189], 0
	v_mfma_f32_16x16x32_bf16 v[104:107], v[146:149], v[186:189], 0
	s_waitcnt lgkmcnt(1)
	v_mfma_f32_16x16x32_bf16 v[100:103], v[130:133], v[194:197], 0
	v_mfma_f32_16x16x32_bf16 v[96:99], v[146:149], v[194:197], 0
	v_mfma_f32_16x16x32_bf16 v[124:127], v[142:145], v[174:177], v[124:127]
	v_mfma_f32_16x16x32_bf16 v[120:123], v[150:153], v[174:177], v[120:123]
	v_mfma_f32_16x16x32_bf16 v[116:119], v[142:145], v[182:185], v[116:119]
	v_mfma_f32_16x16x32_bf16 v[112:115], v[150:153], v[182:185], v[112:115]
	v_mfma_f32_16x16x32_bf16 v[108:111], v[142:145], v[190:193], v[108:111]
	v_mfma_f32_16x16x32_bf16 v[104:107], v[150:153], v[190:193], v[104:107]
	s_waitcnt lgkmcnt(0)
	v_mfma_f32_16x16x32_bf16 v[100:103], v[142:145], v[198:201], v[100:103]
	v_mfma_f32_16x16x32_bf16 v[96:99], v[150:153], v[198:201], v[96:99]
	s_setprio 0
	s_setprio 1
	v_mfma_f32_16x16x32_bf16 v[92:95], v[154:157], v[170:173], 0
	v_mfma_f32_16x16x32_bf16 v[88:91], v[162:165], v[170:173], 0
	v_mfma_f32_16x16x32_bf16 v[84:87], v[154:157], v[178:181], 0
	v_mfma_f32_16x16x32_bf16 v[80:83], v[162:165], v[178:181], 0
	v_mfma_f32_16x16x32_bf16 v[76:79], v[154:157], v[186:189], 0
	v_mfma_f32_16x16x32_bf16 v[72:75], v[162:165], v[186:189], 0
	v_mfma_f32_16x16x32_bf16 v[68:71], v[154:157], v[194:197], 0
	v_mfma_f32_16x16x32_bf16 v[64:67], v[162:165], v[194:197], 0
	v_mfma_f32_16x16x32_bf16 v[92:95], v[158:161], v[174:177], v[92:95]
	v_mfma_f32_16x16x32_bf16 v[88:91], v[166:169], v[174:177], v[88:91]
	v_mfma_f32_16x16x32_bf16 v[84:87], v[158:161], v[182:185], v[84:87]
	v_mfma_f32_16x16x32_bf16 v[80:83], v[166:169], v[182:185], v[80:83]
	v_mfma_f32_16x16x32_bf16 v[76:79], v[158:161], v[190:193], v[76:79]
	v_mfma_f32_16x16x32_bf16 v[72:75], v[166:169], v[190:193], v[72:75]
	v_mfma_f32_16x16x32_bf16 v[68:71], v[158:161], v[198:201], v[68:71]
	v_mfma_f32_16x16x32_bf16 v[64:67], v[166:169], v[198:201], v[64:67]
	s_setprio 0
	s_barrier
	s_add_u32 s92, s6, s50
	s_addc_u32 s93, s7, s51
	s_add_u32 s80, s92, 0x100
	s_addc_u32 s81, s93, 0
	s_add_u32 s94, s54, s50
	s_addc_u32 s95, s55, s51
	s_add_u32 s88, s94, 0x100
	ds_read_b128 v[170:173], v139 offset:16384
	ds_read_b128 v[174:177], v139 offset:17408
	ds_read_b128 v[178:181], v139 offset:18432
	ds_read_b128 v[182:185], v139 offset:19456
	ds_read_b128 v[186:189], v139 offset:20480
	ds_read_b128 v[190:193], v139 offset:21504
	ds_read_b128 v[194:197], v139 offset:22528
	ds_read_b128 v[198:201], v139 offset:23552
	s_addc_u32 s89, s95, 0
	s_mov_b32 m0, s58
	s_nop 0
	global_load_lds_dwordx4 v129, s[80:81]
	s_add_u32 s96, s27, s50
	s_mov_b32 m0, s59
	s_nop 0
	global_load_lds_dwordx4 v129, s[88:89]
	s_addc_u32 s97, s33, s51
	s_add_u32 s80, s96, 0x100
	s_addc_u32 s81, s97, 0
	s_add_u32 vcc_lo, s34, s50
	s_addc_u32 vcc_hi, s41, s51
	s_add_u32 s88, vcc_lo, 0x100
	s_mov_b32 m0, s60
	s_nop 0
	global_load_lds_dwordx4 v129, s[80:81]
	s_addc_u32 s89, vcc_hi, 0
	s_mov_b32 m0, s61
	s_nop 0
	global_load_lds_dwordx4 v129, s[88:89]
	s_add_u32 s57, s70, s50
	s_addc_u32 s88, s71, s51
	s_add_u32 s80, s57, 0x100
	s_mov_b32 m0, s3
	s_nop 0
	global_load_lds_dwordx4 v128, s[52:53]
	s_addc_u32 s81, s88, 0
	s_mov_b32 m0, s62
	s_nop 0
	global_load_lds_dwordx4 v128, s[80:81]
	s_waitcnt vmcnt(24)
	s_waitcnt lgkmcnt(0)
	s_barrier
	s_setprio 1
	s_waitcnt lgkmcnt(7)
	v_mfma_f32_16x16x32_bf16 v[60:63], v[130:133], v[170:173], 0
	v_mfma_f32_16x16x32_bf16 v[56:59], v[146:149], v[170:173], 0
	s_waitcnt lgkmcnt(5)
	v_mfma_f32_16x16x32_bf16 v[52:55], v[130:133], v[178:181], 0
	v_mfma_f32_16x16x32_bf16 v[48:51], v[146:149], v[178:181], 0
	s_waitcnt lgkmcnt(3)
	v_mfma_f32_16x16x32_bf16 v[44:47], v[130:133], v[186:189], 0
	v_mfma_f32_16x16x32_bf16 v[40:43], v[146:149], v[186:189], 0
	s_waitcnt lgkmcnt(1)
	v_mfma_f32_16x16x32_bf16 v[36:39], v[130:133], v[194:197], 0
	v_mfma_f32_16x16x32_bf16 v[32:35], v[146:149], v[194:197], 0
	v_mfma_f32_16x16x32_bf16 v[60:63], v[142:145], v[174:177], v[60:63]
	v_mfma_f32_16x16x32_bf16 v[56:59], v[150:153], v[174:177], v[56:59]
	v_mfma_f32_16x16x32_bf16 v[52:55], v[142:145], v[182:185], v[52:55]
	v_mfma_f32_16x16x32_bf16 v[48:51], v[150:153], v[182:185], v[48:51]
	v_mfma_f32_16x16x32_bf16 v[44:47], v[142:145], v[190:193], v[44:47]
	v_mfma_f32_16x16x32_bf16 v[40:43], v[150:153], v[190:193], v[40:43]
	s_waitcnt lgkmcnt(0)
	v_mfma_f32_16x16x32_bf16 v[36:39], v[142:145], v[198:201], v[36:39]
	v_mfma_f32_16x16x32_bf16 v[32:35], v[150:153], v[198:201], v[32:35]
	s_setprio 0
	s_setprio 1
	v_mfma_f32_16x16x32_bf16 v[28:31], v[154:157], v[170:173], 0
	v_mfma_f32_16x16x32_bf16 v[24:27], v[162:165], v[170:173], 0
	v_mfma_f32_16x16x32_bf16 v[20:23], v[154:157], v[178:181], 0
	v_mfma_f32_16x16x32_bf16 v[16:19], v[162:165], v[178:181], 0
	v_mfma_f32_16x16x32_bf16 v[12:15], v[154:157], v[186:189], 0
	v_mfma_f32_16x16x32_bf16 v[8:11], v[162:165], v[186:189], 0
	v_mfma_f32_16x16x32_bf16 v[4:7], v[154:157], v[194:197], 0
	v_mfma_f32_16x16x32_bf16 v[0:3], v[162:165], v[194:197], 0
	v_mfma_f32_16x16x32_bf16 v[28:31], v[158:161], v[174:177], v[28:31]
	v_mfma_f32_16x16x32_bf16 v[24:27], v[166:169], v[174:177], v[24:27]
	v_mfma_f32_16x16x32_bf16 v[20:23], v[158:161], v[182:185], v[20:23]
	v_mfma_f32_16x16x32_bf16 v[16:19], v[166:169], v[182:185], v[16:19]
	v_mfma_f32_16x16x32_bf16 v[12:15], v[158:161], v[190:193], v[12:15]
	v_mfma_f32_16x16x32_bf16 v[8:11], v[166:169], v[190:193], v[8:11]
	v_mfma_f32_16x16x32_bf16 v[4:7], v[158:161], v[198:201], v[4:7]
	v_mfma_f32_16x16x32_bf16 v[0:3], v[166:169], v[198:201], v[0:3]
	s_setprio 0
	s_barrier
	ds_read_b128 v[130:133], v140
	ds_read_b128 v[142:145], v140 offset:1024
	ds_read_b128 v[146:149], v140 offset:2048
	ds_read_b128 v[150:153], v140 offset:3072
	ds_read_b128 v[154:157], v141
	ds_read_b128 v[158:161], v141 offset:1024
	ds_read_b128 v[162:165], v141 offset:2048
	ds_read_b128 v[166:169], v141 offset:3072
	ds_read_b128 v[170:173], v139 offset:32768
	ds_read_b128 v[174:177], v139 offset:33792
	ds_read_b128 v[178:181], v139 offset:34816
	ds_read_b128 v[182:185], v139 offset:35840
	ds_read_b128 v[186:189], v139 offset:36864
	ds_read_b128 v[190:193], v139 offset:37888
	ds_read_b128 v[194:197], v139 offset:38912
	ds_read_b128 v[198:201], v139 offset:39936
	s_add_u32 s52, s77, 0x100
	s_addc_u32 s53, s87, 0
	s_add_u32 s80, s90, 0x100
	s_mov_b32 m0, s63
	s_nop 0
	global_load_lds_dwordx4 v128, s[52:53]
	s_addc_u32 s81, s91, 0
	s_mov_b32 m0, s64
	s_nop 0
	global_load_lds_dwordx4 v128, s[80:81]
	s_waitcnt vmcnt(8)
	s_waitcnt lgkmcnt(0)
	s_barrier
	s_setprio 1
	s_waitcnt lgkmcnt(7)
	v_mfma_f32_16x16x32_bf16 v[124:127], v[130:133], v[170:173], v[124:127]
	v_mfma_f32_16x16x32_bf16 v[120:123], v[146:149], v[170:173], v[120:123]
	s_waitcnt lgkmcnt(5)
	v_mfma_f32_16x16x32_bf16 v[116:119], v[130:133], v[178:181], v[116:119]
	v_mfma_f32_16x16x32_bf16 v[112:115], v[146:149], v[178:181], v[112:115]
	s_waitcnt lgkmcnt(3)
	v_mfma_f32_16x16x32_bf16 v[108:111], v[130:133], v[186:189], v[108:111]
	v_mfma_f32_16x16x32_bf16 v[104:107], v[146:149], v[186:189], v[104:107]
	s_waitcnt lgkmcnt(1)
	v_mfma_f32_16x16x32_bf16 v[100:103], v[130:133], v[194:197], v[100:103]
	v_mfma_f32_16x16x32_bf16 v[96:99], v[146:149], v[194:197], v[96:99]
	v_mfma_f32_16x16x32_bf16 v[124:127], v[142:145], v[174:177], v[124:127]
	v_mfma_f32_16x16x32_bf16 v[120:123], v[150:153], v[174:177], v[120:123]
	v_mfma_f32_16x16x32_bf16 v[116:119], v[142:145], v[182:185], v[116:119]
	v_mfma_f32_16x16x32_bf16 v[112:115], v[150:153], v[182:185], v[112:115]
	v_mfma_f32_16x16x32_bf16 v[108:111], v[142:145], v[190:193], v[108:111]
	v_mfma_f32_16x16x32_bf16 v[104:107], v[150:153], v[190:193], v[104:107]
	s_waitcnt lgkmcnt(0)
	v_mfma_f32_16x16x32_bf16 v[100:103], v[142:145], v[198:201], v[100:103]
	v_mfma_f32_16x16x32_bf16 v[96:99], v[150:153], v[198:201], v[96:99]
	s_setprio 0
	s_setprio 1
	v_mfma_f32_16x16x32_bf16 v[92:95], v[154:157], v[170:173], v[92:95]
	v_mfma_f32_16x16x32_bf16 v[88:91], v[162:165], v[170:173], v[88:91]
	v_mfma_f32_16x16x32_bf16 v[84:87], v[154:157], v[178:181], v[84:87]
	v_mfma_f32_16x16x32_bf16 v[80:83], v[162:165], v[178:181], v[80:83]
	v_mfma_f32_16x16x32_bf16 v[76:79], v[154:157], v[186:189], v[76:79]
	v_mfma_f32_16x16x32_bf16 v[72:75], v[162:165], v[186:189], v[72:75]
	v_mfma_f32_16x16x32_bf16 v[68:71], v[154:157], v[194:197], v[68:71]
	v_mfma_f32_16x16x32_bf16 v[64:67], v[162:165], v[194:197], v[64:67]
	v_mfma_f32_16x16x32_bf16 v[92:95], v[158:161], v[174:177], v[92:95]
	v_mfma_f32_16x16x32_bf16 v[88:91], v[166:169], v[174:177], v[88:91]
	v_mfma_f32_16x16x32_bf16 v[84:87], v[158:161], v[182:185], v[84:87]
	v_mfma_f32_16x16x32_bf16 v[80:83], v[166:169], v[182:185], v[80:83]
	v_mfma_f32_16x16x32_bf16 v[76:79], v[158:161], v[190:193], v[76:79]
	v_mfma_f32_16x16x32_bf16 v[72:75], v[166:169], v[190:193], v[72:75]
	v_mfma_f32_16x16x32_bf16 v[68:71], v[158:161], v[198:201], v[68:71]
	v_mfma_f32_16x16x32_bf16 v[64:67], v[166:169], v[198:201], v[64:67]
	s_setprio 0
	s_barrier
	s_add_u32 s52, s92, 0x180
	s_addc_u32 s53, s93, 0
	ds_read_b128 v[170:173], v139 offset:49152
	ds_read_b128 v[174:177], v139 offset:50176
	ds_read_b128 v[178:181], v139 offset:51200
	ds_read_b128 v[182:185], v139 offset:52224
	ds_read_b128 v[186:189], v139 offset:53248
	ds_read_b128 v[190:193], v139 offset:54272
	ds_read_b128 v[194:197], v139 offset:55296
	ds_read_b128 v[198:201], v139 offset:56320
	s_add_u32 s80, s94, 0x180
	s_mov_b32 m0, s67
	s_nop 0
	global_load_lds_dwordx4 v129, s[52:53]
	s_addc_u32 s81, s95, 0
	s_mov_b32 m0, s73
	s_nop 0
	global_load_lds_dwordx4 v129, s[80:81]
	s_add_u32 s52, s96, 0x180
	s_addc_u32 s53, s97, 0
	s_add_u32 s80, vcc_lo, 0x180
	s_mov_b32 m0, s82
	s_nop 0
	global_load_lds_dwordx4 v129, s[52:53]
	s_addc_u32 s81, vcc_hi, 0
	s_mov_b32 m0, s83
	s_nop 0
	global_load_lds_dwordx4 v129, s[80:81]
	s_add_u32 s52, s74, 0x180
	s_addc_u32 s53, s75, 0
	s_add_u32 s74, s57, 0x180
	s_mov_b32 m0, s78
	s_nop 0
	global_load_lds_dwordx4 v128, s[52:53]
	s_addc_u32 s75, s88, 0
	s_mov_b32 m0, s79
	s_nop 0
	global_load_lds_dwordx4 v128, s[74:75]
	s_waitcnt vmcnt(8)
	s_waitcnt lgkmcnt(0)
	s_barrier
	s_setprio 1
	s_waitcnt lgkmcnt(7)
	v_mfma_f32_16x16x32_bf16 v[60:63], v[130:133], v[170:173], v[60:63]
	v_mfma_f32_16x16x32_bf16 v[56:59], v[146:149], v[170:173], v[56:59]
	s_waitcnt lgkmcnt(5)
	v_mfma_f32_16x16x32_bf16 v[52:55], v[130:133], v[178:181], v[52:55]
	v_mfma_f32_16x16x32_bf16 v[48:51], v[146:149], v[178:181], v[48:51]
	s_waitcnt lgkmcnt(3)
	v_mfma_f32_16x16x32_bf16 v[44:47], v[130:133], v[186:189], v[44:47]
	v_mfma_f32_16x16x32_bf16 v[40:43], v[146:149], v[186:189], v[40:43]
	s_waitcnt lgkmcnt(1)
	v_mfma_f32_16x16x32_bf16 v[36:39], v[130:133], v[194:197], v[36:39]
	v_mfma_f32_16x16x32_bf16 v[32:35], v[146:149], v[194:197], v[32:35]
	v_mfma_f32_16x16x32_bf16 v[60:63], v[142:145], v[174:177], v[60:63]
	v_mfma_f32_16x16x32_bf16 v[56:59], v[150:153], v[174:177], v[56:59]
	v_mfma_f32_16x16x32_bf16 v[52:55], v[142:145], v[182:185], v[52:55]
	v_mfma_f32_16x16x32_bf16 v[48:51], v[150:153], v[182:185], v[48:51]
	v_mfma_f32_16x16x32_bf16 v[44:47], v[142:145], v[190:193], v[44:47]
	v_mfma_f32_16x16x32_bf16 v[40:43], v[150:153], v[190:193], v[40:43]
	s_waitcnt lgkmcnt(0)
	v_mfma_f32_16x16x32_bf16 v[36:39], v[142:145], v[198:201], v[36:39]
	v_mfma_f32_16x16x32_bf16 v[32:35], v[150:153], v[198:201], v[32:35]
	s_setprio 0
	s_setprio 1
	v_mfma_f32_16x16x32_bf16 v[28:31], v[154:157], v[170:173], v[28:31]
	v_mfma_f32_16x16x32_bf16 v[24:27], v[162:165], v[170:173], v[24:27]
	v_mfma_f32_16x16x32_bf16 v[20:23], v[154:157], v[178:181], v[20:23]
	v_mfma_f32_16x16x32_bf16 v[16:19], v[162:165], v[178:181], v[16:19]
	v_mfma_f32_16x16x32_bf16 v[12:15], v[154:157], v[186:189], v[12:15]
	v_mfma_f32_16x16x32_bf16 v[8:11], v[162:165], v[186:189], v[8:11]
	v_mfma_f32_16x16x32_bf16 v[4:7], v[154:157], v[194:197], v[4:7]
	v_mfma_f32_16x16x32_bf16 v[0:3], v[162:165], v[194:197], v[0:3]
	v_mfma_f32_16x16x32_bf16 v[28:31], v[158:161], v[174:177], v[28:31]
	v_mfma_f32_16x16x32_bf16 v[24:27], v[166:169], v[174:177], v[24:27]
	v_mfma_f32_16x16x32_bf16 v[20:23], v[158:161], v[182:185], v[20:23]
	v_mfma_f32_16x16x32_bf16 v[16:19], v[166:169], v[182:185], v[16:19]
	v_mfma_f32_16x16x32_bf16 v[12:15], v[158:161], v[190:193], v[12:15]
	v_mfma_f32_16x16x32_bf16 v[8:11], v[166:169], v[190:193], v[8:11]
	v_mfma_f32_16x16x32_bf16 v[4:7], v[158:161], v[198:201], v[4:7]
	v_mfma_f32_16x16x32_bf16 v[0:3], v[166:169], v[198:201], v[0:3]
	s_setprio 0
	s_barrier
	s_add_u32 s50, s50, 0x100
	s_addc_u32 s51, s51, 0
	s_cmp_ge_i32 s72, s2
	s_cbranch_scc0 .LBB0_783
	s_branch .LBB0_784
.Lhf_783:
	ds_read_b128 v[130:133], v137
	ds_read_b128 v[142:145], v137 offset:1024
	ds_read_b128 v[146:149], v137 offset:2048
	ds_read_b128 v[150:153], v137 offset:3072
	ds_read_b128 v[154:157], v138
	ds_read_b128 v[158:161], v138 offset:1024
	ds_read_b128 v[162:165], v138 offset:2048
	ds_read_b128 v[166:169], v138 offset:3072
	s_add_i32 s72, s72, 2
	s_add_u32 s74, s4, s50
	s_addc_u32 s75, s5, s51
	s_add_u32 s52, s74, 0x100
	s_addc_u32 s53, s75, 0
	s_add_u32 s77, s23, s50
	ds_read_b128 v[170:173], v139
	ds_read_b128 v[174:177], v139 offset:1024
	ds_read_b128 v[178:181], v139 offset:2048
	ds_read_b128 v[182:185], v139 offset:3072
	ds_read_b128 v[186:189], v139 offset:4096
	ds_read_b128 v[190:193], v139 offset:5120
	ds_read_b128 v[194:197], v139 offset:6144
	ds_read_b128 v[198:201], v139 offset:7168
	s_addc_u32 s87, s25, s51
	s_add_u32 s80, s77, 0x80
	s_addc_u32 s81, s87, 0
	s_add_u32 s90, s68, s50
	s_addc_u32 s91, s69, s51
	s_add_u32 s88, s90, 0x80
	s_mov_b32 m0, s84
	s_nop 0
	global_load_lds_dwordx4 v128, s[80:81]
	s_addc_u32 s89, s91, 0
	s_mov_b32 m0, s85
	s_nop 0
	global_load_lds_dwordx4 v128, s[88:89]
	s_waitcnt vmcnt(8)
	s_waitcnt lgkmcnt(0)
	s_barrier
	s_setprio 1
	s_waitcnt lgkmcnt(7)
	v_mfma_f32_16x16x32_bf16 v[124:127], v[130:133], v[170:173], 0
	v_mfma_f32_16x16x32_bf16 v[120:123], v[146:149], v[170:173], 0
	s_waitcnt lgkmcnt(5)
	v_mfma_f32_16x16x32_bf16 v[116:119], v[130:133], v[178:181], 0
	v_mfma_f32_16x16x32_bf16 v[112:115], v[146:149], v[178:181], 0
	s_waitcnt lgkmcnt(3)
	v_mfma_f32_16x16x32_bf16 v[108:111], v[130:133], v[186:189], 0
	v_mfma_f32_16x16x32_bf16 v[104:107], v[146:149], v[186:189], 0
	s_waitcnt lgkmcnt(1)
	v_mfma_f32_16x16x32_bf16 v[100:103], v[130:133], v[194:197], 0
	v_mfma_f32_16x16x32_bf16 v[96:99], v[146:149], v[194:197], 0
	v_mfma_f32_16x16x32_bf16 v[124:127], v[142:145], v[174:177], v[124:127]
	v_mfma_f32_16x16x32_bf16 v[120:123], v[150:153], v[174:177], v[120:123]
	v_mfma_f32_16x16x32_bf16 v[116:119], v[142:145], v[182:185], v[116:119]
	v_mfma_f32_16x16x32_bf16 v[112:115], v[150:153], v[182:185], v[112:115]
	v_mfma_f32_16x16x32_bf16 v[108:111], v[142:145], v[190:193], v[108:111]
	v_mfma_f32_16x16x32_bf16 v[104:107], v[150:153], v[190:193], v[104:107]
	s_waitcnt lgkmcnt(0)
	v_mfma_f32_16x16x32_bf16 v[100:103], v[142:145], v[198:201], v[100:103]
	v_mfma_f32_16x16x32_bf16 v[96:99], v[150:153], v[198:201], v[96:99]
	s_setprio 0
	s_setprio 1
	v_mfma_f32_16x16x32_bf16 v[92:95], v[154:157], v[170:173], 0
	v_mfma_f32_16x16x32_bf16 v[88:91], v[162:165], v[170:173], 0
	v_mfma_f32_16x16x32_bf16 v[84:87], v[154:157], v[178:181], 0
	v_mfma_f32_16x16x32_bf16 v[80:83], v[162:165], v[178:181], 0
	v_mfma_f32_16x16x32_bf16 v[76:79], v[154:157], v[186:189], 0
	v_mfma_f32_16x16x32_bf16 v[72:75], v[162:165], v[186:189], 0
	v_mfma_f32_16x16x32_bf16 v[68:71], v[154:157], v[194:197], 0
	v_mfma_f32_16x16x32_bf16 v[64:67], v[162:165], v[194:197], 0
	v_mfma_f32_16x16x32_bf16 v[92:95], v[158:161], v[174:177], v[92:95]
	v_mfma_f32_16x16x32_bf16 v[88:91], v[166:169], v[174:177], v[88:91]
	v_mfma_f32_16x16x32_bf16 v[84:87], v[158:161], v[182:185], v[84:87]
	v_mfma_f32_16x16x32_bf16 v[80:83], v[166:169], v[182:185], v[80:83]
	v_mfma_f32_16x16x32_bf16 v[76:79], v[158:161], v[190:193], v[76:79]
	v_mfma_f32_16x16x32_bf16 v[72:75], v[166:169], v[190:193], v[72:75]
	v_mfma_f32_16x16x32_bf16 v[68:71], v[158:161], v[198:201], v[68:71]
	v_mfma_f32_16x16x32_bf16 v[64:67], v[166:169], v[198:201], v[64:67]
	s_setprio 0
	s_barrier
	s_add_u32 s92, s6, s50
	s_addc_u32 s93, s7, s51
	s_add_u32 s80, s92, 0x100
	s_addc_u32 s81, s93, 0
	s_add_u32 s94, s54, s50
	s_addc_u32 s95, s55, s51
	s_add_u32 s88, s94, 0x100
	ds_read_b128 v[170:173], v139 offset:16384
	ds_read_b128 v[174:177], v139 offset:17408
	ds_read_b128 v[178:181], v139 offset:18432
	ds_read_b128 v[182:185], v139 offset:19456
	ds_read_b128 v[186:189], v139 offset:20480
	ds_read_b128 v[190:193], v139 offset:21504
	ds_read_b128 v[194:197], v139 offset:22528
	ds_read_b128 v[198:201], v139 offset:23552
	s_addc_u32 s89, s95, 0
	s_mov_b32 m0, s58
	s_nop 0
	global_load_lds_dwordx4 v129, s[80:81]
	s_add_u32 s96, s27, s50
	s_mov_b32 m0, s59
	s_nop 0
	global_load_lds_dwordx4 v129, s[88:89]
	s_addc_u32 s97, s33, s51
	s_add_u32 s80, s96, 0x100
	s_addc_u32 s81, s97, 0
	s_add_u32 vcc_lo, s34, s50
	s_addc_u32 vcc_hi, s41, s51
	s_add_u32 s88, vcc_lo, 0x100
	s_mov_b32 m0, s60
	s_nop 0
	global_load_lds_dwordx4 v129, s[80:81]
	s_addc_u32 s89, vcc_hi, 0
	s_mov_b32 m0, s61
	s_nop 0
	global_load_lds_dwordx4 v129, s[88:89]
	s_add_u32 s57, s70, s50
	s_addc_u32 s88, s71, s51
	s_add_u32 s80, s57, 0x100
	s_mov_b32 m0, s3
	s_nop 0
	global_load_lds_dwordx4 v128, s[52:53]
	s_addc_u32 s81, s88, 0
	s_mov_b32 m0, s62
	s_nop 0
	global_load_lds_dwordx4 v128, s[80:81]
	s_waitcnt vmcnt(8)
	s_waitcnt lgkmcnt(0)
	s_barrier
	s_setprio 1
	s_waitcnt lgkmcnt(7)
	v_mfma_f32_16x16x32_bf16 v[60:63], v[130:133], v[170:173], 0
	v_mfma_f32_16x16x32_bf16 v[56:59], v[146:149], v[170:173], 0
	s_waitcnt lgkmcnt(5)
	v_mfma_f32_16x16x32_bf16 v[52:55], v[130:133], v[178:181], 0
	v_mfma_f32_16x16x32_bf16 v[48:51], v[146:149], v[178:181], 0
	s_waitcnt lgkmcnt(3)
	v_mfma_f32_16x16x32_bf16 v[44:47], v[130:133], v[186:189], 0
	v_mfma_f32_16x16x32_bf16 v[40:43], v[146:149], v[186:189], 0
	s_waitcnt lgkmcnt(1)
	v_mfma_f32_16x16x32_bf16 v[36:39], v[130:133], v[194:197], 0
	v_mfma_f32_16x16x32_bf16 v[32:35], v[146:149], v[194:197], 0
	v_mfma_f32_16x16x32_bf16 v[60:63], v[142:145], v[174:177], v[60:63]
	v_mfma_f32_16x16x32_bf16 v[56:59], v[150:153], v[174:177], v[56:59]
	v_mfma_f32_16x16x32_bf16 v[52:55], v[142:145], v[182:185], v[52:55]
	v_mfma_f32_16x16x32_bf16 v[48:51], v[150:153], v[182:185], v[48:51]
	v_mfma_f32_16x16x32_bf16 v[44:47], v[142:145], v[190:193], v[44:47]
	v_mfma_f32_16x16x32_bf16 v[40:43], v[150:153], v[190:193], v[40:43]
	s_waitcnt lgkmcnt(0)
	v_mfma_f32_16x16x32_bf16 v[36:39], v[142:145], v[198:201], v[36:39]
	v_mfma_f32_16x16x32_bf16 v[32:35], v[150:153], v[198:201], v[32:35]
	s_setprio 0
	s_setprio 1
	v_mfma_f32_16x16x32_bf16 v[28:31], v[154:157], v[170:173], 0
	v_mfma_f32_16x16x32_bf16 v[24:27], v[162:165], v[170:173], 0
	v_mfma_f32_16x16x32_bf16 v[20:23], v[154:157], v[178:181], 0
	v_mfma_f32_16x16x32_bf16 v[16:19], v[162:165], v[178:181], 0
	v_mfma_f32_16x16x32_bf16 v[12:15], v[154:157], v[186:189], 0
	v_mfma_f32_16x16x32_bf16 v[8:11], v[162:165], v[186:189], 0
	v_mfma_f32_16x16x32_bf16 v[4:7], v[154:157], v[194:197], 0
	v_mfma_f32_16x16x32_bf16 v[0:3], v[162:165], v[194:197], 0
	v_mfma_f32_16x16x32_bf16 v[28:31], v[158:161], v[174:177], v[28:31]
	v_mfma_f32_16x16x32_bf16 v[24:27], v[166:169], v[174:177], v[24:27]
	v_mfma_f32_16x16x32_bf16 v[20:23], v[158:161], v[182:185], v[20:23]
	v_mfma_f32_16x16x32_bf16 v[16:19], v[166:169], v[182:185], v[16:19]
	v_mfma_f32_16x16x32_bf16 v[12:15], v[158:161], v[190:193], v[12:15]
	v_mfma_f32_16x16x32_bf16 v[8:11], v[166:169], v[190:193], v[8:11]
	v_mfma_f32_16x16x32_bf16 v[4:7], v[158:161], v[198:201], v[4:7]
	v_mfma_f32_16x16x32_bf16 v[0:3], v[166:169], v[198:201], v[0:3]
	s_setprio 0
	s_barrier
	ds_read_b128 v[130:133], v140
	ds_read_b128 v[142:145], v140 offset:1024
	ds_read_b128 v[146:149], v140 offset:2048
	ds_read_b128 v[150:153], v140 offset:3072
	ds_read_b128 v[154:157], v141
	ds_read_b128 v[158:161], v141 offset:1024
	ds_read_b128 v[162:165], v141 offset:2048
	ds_read_b128 v[166:169], v141 offset:3072
	ds_read_b128 v[170:173], v139 offset:32768
	ds_read_b128 v[174:177], v139 offset:33792
	ds_read_b128 v[178:181], v139 offset:34816
	ds_read_b128 v[182:185], v139 offset:35840
	ds_read_b128 v[186:189], v139 offset:36864
	ds_read_b128 v[190:193], v139 offset:37888
	ds_read_b128 v[194:197], v139 offset:38912
	ds_read_b128 v[198:201], v139 offset:39936
	s_add_u32 s52, s77, 0x100
	s_addc_u32 s53, s87, 0
	s_add_u32 s80, s90, 0x100
	s_mov_b32 m0, s63
	s_nop 0
	global_load_lds_dwordx4 v128, s[52:53]
	s_addc_u32 s81, s91, 0
	s_mov_b32 m0, s64
	s_nop 0
	global_load_lds_dwordx4 v128, s[80:81]
	s_waitcnt vmcnt(8)
	s_waitcnt lgkmcnt(0)
	s_barrier
	s_setprio 1
	s_waitcnt lgkmcnt(7)
	v_mfma_f32_16x16x32_bf16 v[124:127], v[130:133], v[170:173], v[124:127]
	v_mfma_f32_16x16x32_bf16 v[120:123], v[146:149], v[170:173], v[120:123]
	s_waitcnt lgkmcnt(5)
	v_mfma_f32_16x16x32_bf16 v[116:119], v[130:133], v[178:181], v[116:119]
	v_mfma_f32_16x16x32_bf16 v[112:115], v[146:149], v[178:181], v[112:115]
	s_waitcnt lgkmcnt(3)
	v_mfma_f32_16x16x32_bf16 v[108:111], v[130:133], v[186:189], v[108:111]
	v_mfma_f32_16x16x32_bf16 v[104:107], v[146:149], v[186:189], v[104:107]
	s_waitcnt lgkmcnt(1)
	v_mfma_f32_16x16x32_bf16 v[100:103], v[130:133], v[194:197], v[100:103]
	v_mfma_f32_16x16x32_bf16 v[96:99], v[146:149], v[194:197], v[96:99]
	v_mfma_f32_16x16x32_bf16 v[124:127], v[142:145], v[174:177], v[124:127]
	v_mfma_f32_16x16x32_bf16 v[120:123], v[150:153], v[174:177], v[120:123]
	v_mfma_f32_16x16x32_bf16 v[116:119], v[142:145], v[182:185], v[116:119]
	v_mfma_f32_16x16x32_bf16 v[112:115], v[150:153], v[182:185], v[112:115]
	v_mfma_f32_16x16x32_bf16 v[108:111], v[142:145], v[190:193], v[108:111]
	v_mfma_f32_16x16x32_bf16 v[104:107], v[150:153], v[190:193], v[104:107]
	s_waitcnt lgkmcnt(0)
	v_mfma_f32_16x16x32_bf16 v[100:103], v[142:145], v[198:201], v[100:103]
	v_mfma_f32_16x16x32_bf16 v[96:99], v[150:153], v[198:201], v[96:99]
	s_setprio 0
	s_setprio 1
	v_mfma_f32_16x16x32_bf16 v[92:95], v[154:157], v[170:173], v[92:95]
	v_mfma_f32_16x16x32_bf16 v[88:91], v[162:165], v[170:173], v[88:91]
	v_mfma_f32_16x16x32_bf16 v[84:87], v[154:157], v[178:181], v[84:87]
	v_mfma_f32_16x16x32_bf16 v[80:83], v[162:165], v[178:181], v[80:83]
	v_mfma_f32_16x16x32_bf16 v[76:79], v[154:157], v[186:189], v[76:79]
	v_mfma_f32_16x16x32_bf16 v[72:75], v[162:165], v[186:189], v[72:75]
	v_mfma_f32_16x16x32_bf16 v[68:71], v[154:157], v[194:197], v[68:71]
	v_mfma_f32_16x16x32_bf16 v[64:67], v[162:165], v[194:197], v[64:67]
	v_mfma_f32_16x16x32_bf16 v[92:95], v[158:161], v[174:177], v[92:95]
	v_mfma_f32_16x16x32_bf16 v[88:91], v[166:169], v[174:177], v[88:91]
	v_mfma_f32_16x16x32_bf16 v[84:87], v[158:161], v[182:185], v[84:87]
	v_mfma_f32_16x16x32_bf16 v[80:83], v[166:169], v[182:185], v[80:83]
	v_mfma_f32_16x16x32_bf16 v[76:79], v[158:161], v[190:193], v[76:79]
	v_mfma_f32_16x16x32_bf16 v[72:75], v[166:169], v[190:193], v[72:75]
	v_mfma_f32_16x16x32_bf16 v[68:71], v[158:161], v[198:201], v[68:71]
	v_mfma_f32_16x16x32_bf16 v[64:67], v[166:169], v[198:201], v[64:67]
	s_setprio 0
	s_barrier
	s_add_u32 s52, s92, 0x180
	s_addc_u32 s53, s93, 0
	ds_read_b128 v[170:173], v139 offset:49152
	ds_read_b128 v[174:177], v139 offset:50176
	ds_read_b128 v[178:181], v139 offset:51200
	ds_read_b128 v[182:185], v139 offset:52224
	ds_read_b128 v[186:189], v139 offset:53248
	ds_read_b128 v[190:193], v139 offset:54272
	ds_read_b128 v[194:197], v139 offset:55296
	ds_read_b128 v[198:201], v139 offset:56320
	s_add_u32 s80, s94, 0x180
	s_mov_b32 m0, s67
	s_nop 0
	global_load_lds_dwordx4 v129, s[52:53]
	s_addc_u32 s81, s95, 0
	s_mov_b32 m0, s73
	s_nop 0
	global_load_lds_dwordx4 v129, s[80:81]
	s_add_u32 s52, s96, 0x180
	s_addc_u32 s53, s97, 0
	s_add_u32 s80, vcc_lo, 0x180
	s_mov_b32 m0, s82
	s_nop 0
	global_load_lds_dwordx4 v129, s[52:53]
	s_addc_u32 s81, vcc_hi, 0
	s_mov_b32 m0, s83
	s_nop 0
	global_load_lds_dwordx4 v129, s[80:81]
	s_add_u32 s52, s74, 0x180
	s_addc_u32 s53, s75, 0
	s_add_u32 s74, s57, 0x180
	s_mov_b32 m0, s78
	s_nop 0
	global_load_lds_dwordx4 v128, s[52:53]
	s_addc_u32 s75, s88, 0
	s_mov_b32 m0, s79
	s_nop 0
	global_load_lds_dwordx4 v128, s[74:75]
	s_waitcnt vmcnt(8)
	s_waitcnt lgkmcnt(0)
	s_barrier
	s_setprio 1
	s_waitcnt lgkmcnt(7)
	v_mfma_f32_16x16x32_bf16 v[60:63], v[130:133], v[170:173], v[60:63]
	v_mfma_f32_16x16x32_bf16 v[56:59], v[146:149], v[170:173], v[56:59]
	s_waitcnt lgkmcnt(5)
	v_mfma_f32_16x16x32_bf16 v[52:55], v[130:133], v[178:181], v[52:55]
	v_mfma_f32_16x16x32_bf16 v[48:51], v[146:149], v[178:181], v[48:51]
	s_waitcnt lgkmcnt(3)
	v_mfma_f32_16x16x32_bf16 v[44:47], v[130:133], v[186:189], v[44:47]
	v_mfma_f32_16x16x32_bf16 v[40:43], v[146:149], v[186:189], v[40:43]
	s_waitcnt lgkmcnt(1)
	v_mfma_f32_16x16x32_bf16 v[36:39], v[130:133], v[194:197], v[36:39]
	v_mfma_f32_16x16x32_bf16 v[32:35], v[146:149], v[194:197], v[32:35]
	v_mfma_f32_16x16x32_bf16 v[60:63], v[142:145], v[174:177], v[60:63]
	v_mfma_f32_16x16x32_bf16 v[56:59], v[150:153], v[174:177], v[56:59]
	v_mfma_f32_16x16x32_bf16 v[52:55], v[142:145], v[182:185], v[52:55]
	v_mfma_f32_16x16x32_bf16 v[48:51], v[150:153], v[182:185], v[48:51]
	v_mfma_f32_16x16x32_bf16 v[44:47], v[142:145], v[190:193], v[44:47]
	v_mfma_f32_16x16x32_bf16 v[40:43], v[150:153], v[190:193], v[40:43]
	s_waitcnt lgkmcnt(0)
	v_mfma_f32_16x16x32_bf16 v[36:39], v[142:145], v[198:201], v[36:39]
	v_mfma_f32_16x16x32_bf16 v[32:35], v[150:153], v[198:201], v[32:35]
	s_setprio 0
	s_setprio 1
	v_mfma_f32_16x16x32_bf16 v[28:31], v[154:157], v[170:173], v[28:31]
	v_mfma_f32_16x16x32_bf16 v[24:27], v[162:165], v[170:173], v[24:27]
	v_mfma_f32_16x16x32_bf16 v[20:23], v[154:157], v[178:181], v[20:23]
	v_mfma_f32_16x16x32_bf16 v[16:19], v[162:165], v[178:181], v[16:19]
	v_mfma_f32_16x16x32_bf16 v[12:15], v[154:157], v[186:189], v[12:15]
	v_mfma_f32_16x16x32_bf16 v[8:11], v[162:165], v[186:189], v[8:11]
	v_mfma_f32_16x16x32_bf16 v[4:7], v[154:157], v[194:197], v[4:7]
	v_mfma_f32_16x16x32_bf16 v[0:3], v[162:165], v[194:197], v[0:3]
	v_mfma_f32_16x16x32_bf16 v[28:31], v[158:161], v[174:177], v[28:31]
	v_mfma_f32_16x16x32_bf16 v[24:27], v[166:169], v[174:177], v[24:27]
	v_mfma_f32_16x16x32_bf16 v[20:23], v[158:161], v[182:185], v[20:23]
	v_mfma_f32_16x16x32_bf16 v[16:19], v[166:169], v[182:185], v[16:19]
	v_mfma_f32_16x16x32_bf16 v[12:15], v[158:161], v[190:193], v[12:15]
	v_mfma_f32_16x16x32_bf16 v[8:11], v[166:169], v[190:193], v[8:11]
	v_mfma_f32_16x16x32_bf16 v[4:7], v[158:161], v[198:201], v[4:7]
	v_mfma_f32_16x16x32_bf16 v[0:3], v[166:169], v[198:201], v[0:3]
	s_setprio 0
	s_barrier
	s_add_u32 s50, s50, 0x100
	s_addc_u32 s51, s51, 0
	s_cmp_ge_i32 s72, s2
	s_cbranch_scc0 .LBB0_783
	s_branch .LBB0_784

.LBB0_921:
	s_cmp_lt_i32 s0, 3
	s_cbranch_scc1 .Lhz_923
	s_add_i32 s2, s0, -2
	s_add_u32 s22, s4, s36
	s_addc_u32 s33, s5, s37
	s_add_u32 s42, s6, s20
	s_addc_u32 s43, s7, s21
	s_add_u32 s38, s16, s20
	s_addc_u32 s39, s17, s21
	s_add_u32 s44, s6, s38
	s_addc_u32 s45, s7, s39
	s_add_u32 s68, s6, s16
	s_addc_u32 s69, s7, s17
	s_add_u32 s38, s34, s36
	s_addc_u32 s39, s35, s37
	s_add_u32 s70, s4, s38
	s_addc_u32 s71, s5, s39
	s_add_u32 s72, s4, s34
	s_addc_u32 s74, s5, s35
	s_mov_b32 s75, 0
	s_mov_b64 s[38:39], 0
	s_cmp_eq_u32 s98, 0
	s_cbranch_scc1 .Lhf_923
	ds_read_b128 v[138:141], v133
	ds_read_b128 v[142:145], v133 offset:1024
	ds_read_b128 v[146:149], v133 offset:2048
	ds_read_b128 v[150:153], v133 offset:3072
	ds_read_b128 v[154:157], v134
	ds_read_b128 v[158:161], v134 offset:1024
	ds_read_b128 v[162:165], v134 offset:2048
	ds_read_b128 v[166:169], v134 offset:3072
	s_add_i32 s75, s75, 2
	s_add_u32 s77, s4, s38
	s_addc_u32 s78, s5, s39
	s_add_u32 s40, s77, 0x100
	s_addc_u32 s41, s78, 0
	s_add_u32 s79, s22, s38
	ds_read_b128 v[170:173], v135
	ds_read_b128 v[174:177], v135 offset:1024
	ds_read_b128 v[178:181], v135 offset:2048
	ds_read_b128 v[182:185], v135 offset:3072
	ds_read_b128 v[186:189], v135 offset:4096
	ds_read_b128 v[190:193], v135 offset:5120
	ds_read_b128 v[194:197], v135 offset:6144
	ds_read_b128 v[198:201], v135 offset:7168
	s_addc_u32 s84, s33, s39
	s_add_u32 s80, s79, 0x80
	s_addc_u32 s81, s84, 0
	s_add_u32 s85, s70, s38
	s_addc_u32 s86, s71, s39
	s_add_u32 s82, s85, 0x80
	s_mov_b32 m0, s66
	s_nop 0
	global_load_lds_dwordx4 v128, s[80:81]
	s_addc_u32 s83, s86, 0
	s_mov_b32 m0, s67
	s_nop 0
	global_load_lds_dwordx4 v128, s[82:83]
	s_waitcnt vmcnt(16)
	s_waitcnt lgkmcnt(0)
	s_barrier
	s_setprio 1
	s_waitcnt lgkmcnt(7)
	v_mfma_f32_16x16x32_bf16 v[124:127], v[138:141], v[170:173], 0
	v_mfma_f32_16x16x32_bf16 v[120:123], v[146:149], v[170:173], 0
	s_waitcnt lgkmcnt(5)
	v_mfma_f32_16x16x32_bf16 v[116:119], v[138:141], v[178:181], 0
	v_mfma_f32_16x16x32_bf16 v[112:115], v[146:149], v[178:181], 0
	s_waitcnt lgkmcnt(3)
	v_mfma_f32_16x16x32_bf16 v[108:111], v[138:141], v[186:189], 0
	v_mfma_f32_16x16x32_bf16 v[104:107], v[146:149], v[186:189], 0
	s_waitcnt lgkmcnt(1)
	v_mfma_f32_16x16x32_bf16 v[100:103], v[138:141], v[194:197], 0
	v_mfma_f32_16x16x32_bf16 v[96:99], v[146:149], v[194:197], 0
	v_mfma_f32_16x16x32_bf16 v[124:127], v[142:145], v[174:177], v[124:127]
	v_mfma_f32_16x16x32_bf16 v[120:123], v[150:153], v[174:177], v[120:123]
	v_mfma_f32_16x16x32_bf16 v[116:119], v[142:145], v[182:185], v[116:119]
	v_mfma_f32_16x16x32_bf16 v[112:115], v[150:153], v[182:185], v[112:115]
	v_mfma_f32_16x16x32_bf16 v[108:111], v[142:145], v[190:193], v[108:111]
	v_mfma_f32_16x16x32_bf16 v[104:107], v[150:153], v[190:193], v[104:107]
	s_waitcnt lgkmcnt(0)
	v_mfma_f32_16x16x32_bf16 v[100:103], v[142:145], v[198:201], v[100:103]
	v_mfma_f32_16x16x32_bf16 v[96:99], v[150:153], v[198:201], v[96:99]
	s_setprio 0
	s_setprio 1
	v_mfma_f32_16x16x32_bf16 v[92:95], v[154:157], v[170:173], 0
	v_mfma_f32_16x16x32_bf16 v[88:91], v[162:165], v[170:173], 0
	v_mfma_f32_16x16x32_bf16 v[84:87], v[154:157], v[178:181], 0
	v_mfma_f32_16x16x32_bf16 v[80:83], v[162:165], v[178:181], 0
	v_mfma_f32_16x16x32_bf16 v[76:79], v[154:157], v[186:189], 0
	v_mfma_f32_16x16x32_bf16 v[72:75], v[162:165], v[186:189], 0
	v_mfma_f32_16x16x32_bf16 v[68:71], v[154:157], v[194:197], 0
	v_mfma_f32_16x16x32_bf16 v[64:67], v[162:165], v[194:197], 0
	v_mfma_f32_16x16x32_bf16 v[92:95], v[158:161], v[174:177], v[92:95]
	v_mfma_f32_16x16x32_bf16 v[88:91], v[166:169], v[174:177], v[88:91]
	v_mfma_f32_16x16x32_bf16 v[84:87], v[158:161], v[182:185], v[84:87]
	v_mfma_f32_16x16x32_bf16 v[80:83], v[166:169], v[182:185], v[80:83]
	v_mfma_f32_16x16x32_bf16 v[76:79], v[158:161], v[190:193], v[76:79]
	v_mfma_f32_16x16x32_bf16 v[72:75], v[166:169], v[190:193], v[72:75]
	v_mfma_f32_16x16x32_bf16 v[68:71], v[158:161], v[198:201], v[68:71]
	v_mfma_f32_16x16x32_bf16 v[64:67], v[166:169], v[198:201], v[64:67]
	s_setprio 0
	s_barrier
	s_add_u32 s87, s6, s38
	s_addc_u32 s88, s7, s39
	s_add_u32 s80, s87, 0x100
	s_addc_u32 s81, s88, 0
	s_add_u32 s89, s68, s38
	s_addc_u32 s90, s69, s39
	s_add_u32 s82, s89, 0x100
	ds_read_b128 v[170:173], v135 offset:16384
	ds_read_b128 v[174:177], v135 offset:17408
	ds_read_b128 v[178:181], v135 offset:18432
	ds_read_b128 v[182:185], v135 offset:19456
	ds_read_b128 v[186:189], v135 offset:20480
	ds_read_b128 v[190:193], v135 offset:21504
	ds_read_b128 v[194:197], v135 offset:22528
	ds_read_b128 v[198:201], v135 offset:23552
	s_addc_u32 s83, s90, 0
	s_mov_b32 m0, s51
	s_nop 0
	global_load_lds_dwordx4 v129, s[80:81]
	s_add_u32 s91, s42, s38
	s_mov_b32 m0, s52
	s_nop 0
	global_load_lds_dwordx4 v129, s[82:83]
	s_addc_u32 s92, s43, s39
	s_add_u32 s80, s91, 0x100
	s_addc_u32 s81, s92, 0
	s_add_u32 s93, s44, s38
	s_addc_u32 s94, s45, s39
	s_add_u32 s82, s93, 0x100
	s_addc_u32 s83, s94, 0
	s_mov_b32 m0, s53
	s_nop 0
	global_load_lds_dwordx4 v129, s[80:81]
	s_mov_b32 m0, s56
	s_nop 0
	global_load_lds_dwordx4 v129, s[82:83]
	s_add_u32 s82, s72, s38
	s_addc_u32 s83, s74, s39
	s_add_u32 s80, s82, 0x100
	s_mov_b32 m0, s55
	s_nop 0
	global_load_lds_dwordx4 v128, s[40:41]
	s_addc_u32 s81, s83, 0
	s_mov_b32 m0, s57
	s_nop 0
	global_load_lds_dwordx4 v128, s[80:81]
	s_waitcnt vmcnt(16)
	s_waitcnt lgkmcnt(0)
	s_barrier
	s_setprio 1
	s_waitcnt lgkmcnt(7)
	v_mfma_f32_16x16x32_bf16 v[60:63], v[138:141], v[170:173], 0
	v_mfma_f32_16x16x32_bf16 v[56:59], v[146:149], v[170:173], 0
	s_waitcnt lgkmcnt(5)
	v_mfma_f32_16x16x32_bf16 v[52:55], v[138:141], v[178:181], 0
	v_mfma_f32_16x16x32_bf16 v[48:51], v[146:149], v[178:181], 0
	s_waitcnt lgkmcnt(3)
	v_mfma_f32_16x16x32_bf16 v[44:47], v[138:141], v[186:189], 0
	v_mfma_f32_16x16x32_bf16 v[40:43], v[146:149], v[186:189], 0
	s_waitcnt lgkmcnt(1)
	v_mfma_f32_16x16x32_bf16 v[36:39], v[138:141], v[194:197], 0
	v_mfma_f32_16x16x32_bf16 v[32:35], v[146:149], v[194:197], 0
	v_mfma_f32_16x16x32_bf16 v[60:63], v[142:145], v[174:177], v[60:63]
	v_mfma_f32_16x16x32_bf16 v[56:59], v[150:153], v[174:177], v[56:59]
	v_mfma_f32_16x16x32_bf16 v[52:55], v[142:145], v[182:185], v[52:55]
	v_mfma_f32_16x16x32_bf16 v[48:51], v[150:153], v[182:185], v[48:51]
	v_mfma_f32_16x16x32_bf16 v[44:47], v[142:145], v[190:193], v[44:47]
	v_mfma_f32_16x16x32_bf16 v[40:43], v[150:153], v[190:193], v[40:43]
	s_waitcnt lgkmcnt(0)
	v_mfma_f32_16x16x32_bf16 v[36:39], v[142:145], v[198:201], v[36:39]
	v_mfma_f32_16x16x32_bf16 v[32:35], v[150:153], v[198:201], v[32:35]
	s_setprio 0
	s_setprio 1
	v_mfma_f32_16x16x32_bf16 v[28:31], v[154:157], v[170:173], 0
	v_mfma_f32_16x16x32_bf16 v[24:27], v[162:165], v[170:173], 0
	v_mfma_f32_16x16x32_bf16 v[20:23], v[154:157], v[178:181], 0
	v_mfma_f32_16x16x32_bf16 v[16:19], v[162:165], v[178:181], 0
	v_mfma_f32_16x16x32_bf16 v[12:15], v[154:157], v[186:189], 0
	v_mfma_f32_16x16x32_bf16 v[8:11], v[162:165], v[186:189], 0
	v_mfma_f32_16x16x32_bf16 v[4:7], v[154:157], v[194:197], 0
	v_mfma_f32_16x16x32_bf16 v[0:3], v[162:165], v[194:197], 0
	v_mfma_f32_16x16x32_bf16 v[28:31], v[158:161], v[174:177], v[28:31]
	v_mfma_f32_16x16x32_bf16 v[24:27], v[166:169], v[174:177], v[24:27]
	v_mfma_f32_16x16x32_bf16 v[20:23], v[158:161], v[182:185], v[20:23]
	v_mfma_f32_16x16x32_bf16 v[16:19], v[166:169], v[182:185], v[16:19]
	v_mfma_f32_16x16x32_bf16 v[12:15], v[158:161], v[190:193], v[12:15]
	v_mfma_f32_16x16x32_bf16 v[8:11], v[166:169], v[190:193], v[8:11]
	v_mfma_f32_16x16x32_bf16 v[4:7], v[158:161], v[198:201], v[4:7]
	v_mfma_f32_16x16x32_bf16 v[0:3], v[166:169], v[198:201], v[0:3]
	s_setprio 0
	s_barrier
	ds_read_b128 v[138:141], v136
	ds_read_b128 v[142:145], v136 offset:1024
	ds_read_b128 v[146:149], v136 offset:2048
	ds_read_b128 v[150:153], v136 offset:3072
	ds_read_b128 v[154:157], v137
	ds_read_b128 v[158:161], v137 offset:1024
	ds_read_b128 v[162:165], v137 offset:2048
	ds_read_b128 v[166:169], v137 offset:3072
	ds_read_b128 v[170:173], v135 offset:32768
	ds_read_b128 v[174:177], v135 offset:33792
	ds_read_b128 v[178:181], v135 offset:34816
	ds_read_b128 v[182:185], v135 offset:35840
	ds_read_b128 v[186:189], v135 offset:36864
	ds_read_b128 v[190:193], v135 offset:37888
	ds_read_b128 v[194:197], v135 offset:38912
	ds_read_b128 v[198:201], v135 offset:39936
	s_add_u32 s40, s79, 0x100
	s_addc_u32 s41, s84, 0
	s_add_u32 s80, s85, 0x100
	s_mov_b32 m0, s58
	s_nop 0
	global_load_lds_dwordx4 v128, s[40:41]
	s_addc_u32 s81, s86, 0
	s_mov_b32 m0, s59
	s_nop 0
	global_load_lds_dwordx4 v128, s[80:81]
	s_waitcnt vmcnt(8)
	s_waitcnt lgkmcnt(0)
	s_barrier
	s_setprio 1
	s_waitcnt lgkmcnt(7)
	v_mfma_f32_16x16x32_bf16 v[124:127], v[138:141], v[170:173], v[124:127]
	v_mfma_f32_16x16x32_bf16 v[120:123], v[146:149], v[170:173], v[120:123]
	s_waitcnt lgkmcnt(5)
	v_mfma_f32_16x16x32_bf16 v[116:119], v[138:141], v[178:181], v[116:119]
	v_mfma_f32_16x16x32_bf16 v[112:115], v[146:149], v[178:181], v[112:115]
	s_waitcnt lgkmcnt(3)
	v_mfma_f32_16x16x32_bf16 v[108:111], v[138:141], v[186:189], v[108:111]
	v_mfma_f32_16x16x32_bf16 v[104:107], v[146:149], v[186:189], v[104:107]
	s_waitcnt lgkmcnt(1)
	v_mfma_f32_16x16x32_bf16 v[100:103], v[138:141], v[194:197], v[100:103]
	v_mfma_f32_16x16x32_bf16 v[96:99], v[146:149], v[194:197], v[96:99]
	v_mfma_f32_16x16x32_bf16 v[124:127], v[142:145], v[174:177], v[124:127]
	v_mfma_f32_16x16x32_bf16 v[120:123], v[150:153], v[174:177], v[120:123]
	v_mfma_f32_16x16x32_bf16 v[116:119], v[142:145], v[182:185], v[116:119]
	v_mfma_f32_16x16x32_bf16 v[112:115], v[150:153], v[182:185], v[112:115]
	v_mfma_f32_16x16x32_bf16 v[108:111], v[142:145], v[190:193], v[108:111]
	v_mfma_f32_16x16x32_bf16 v[104:107], v[150:153], v[190:193], v[104:107]
	s_waitcnt lgkmcnt(0)
	v_mfma_f32_16x16x32_bf16 v[100:103], v[142:145], v[198:201], v[100:103]
	v_mfma_f32_16x16x32_bf16 v[96:99], v[150:153], v[198:201], v[96:99]
	s_setprio 0
	s_setprio 1
	v_mfma_f32_16x16x32_bf16 v[92:95], v[154:157], v[170:173], v[92:95]
	v_mfma_f32_16x16x32_bf16 v[88:91], v[162:165], v[170:173], v[88:91]
	v_mfma_f32_16x16x32_bf16 v[84:87], v[154:157], v[178:181], v[84:87]
	v_mfma_f32_16x16x32_bf16 v[80:83], v[162:165], v[178:181], v[80:83]
	v_mfma_f32_16x16x32_bf16 v[76:79], v[154:157], v[186:189], v[76:79]
	v_mfma_f32_16x16x32_bf16 v[72:75], v[162:165], v[186:189], v[72:75]
	v_mfma_f32_16x16x32_bf16 v[68:71], v[154:157], v[194:197], v[68:71]
	v_mfma_f32_16x16x32_bf16 v[64:67], v[162:165], v[194:197], v[64:67]
	v_mfma_f32_16x16x32_bf16 v[92:95], v[158:161], v[174:177], v[92:95]
	v_mfma_f32_16x16x32_bf16 v[88:91], v[166:169], v[174:177], v[88:91]
	v_mfma_f32_16x16x32_bf16 v[84:87], v[158:161], v[182:185], v[84:87]
	v_mfma_f32_16x16x32_bf16 v[80:83], v[166:169], v[182:185], v[80:83]
	v_mfma_f32_16x16x32_bf16 v[76:79], v[158:161], v[190:193], v[76:79]
	v_mfma_f32_16x16x32_bf16 v[72:75], v[166:169], v[190:193], v[72:75]
	v_mfma_f32_16x16x32_bf16 v[68:71], v[158:161], v[198:201], v[68:71]
	v_mfma_f32_16x16x32_bf16 v[64:67], v[166:169], v[198:201], v[64:67]
	s_setprio 0
	s_barrier
	s_add_u32 s40, s87, 0x180
	s_addc_u32 s41, s88, 0
	ds_read_b128 v[170:173], v135 offset:49152
	ds_read_b128 v[174:177], v135 offset:50176
	ds_read_b128 v[178:181], v135 offset:51200
	ds_read_b128 v[182:185], v135 offset:52224
	ds_read_b128 v[186:189], v135 offset:53248
	ds_read_b128 v[190:193], v135 offset:54272
	ds_read_b128 v[194:197], v135 offset:55296
	ds_read_b128 v[198:201], v135 offset:56320
	s_add_u32 s80, s89, 0x180
	s_mov_b32 m0, s60
	s_nop 0
	global_load_lds_dwordx4 v129, s[40:41]
	s_addc_u32 s81, s90, 0
	s_mov_b32 m0, s61
	s_nop 0
	global_load_lds_dwordx4 v129, s[80:81]
	s_add_u32 s40, s91, 0x180
	s_addc_u32 s41, s92, 0
	s_add_u32 s80, s93, 0x180
	s_mov_b32 m0, s64
	s_nop 0
	global_load_lds_dwordx4 v129, s[40:41]
	s_addc_u32 s81, s94, 0
	s_mov_b32 m0, s65
	s_nop 0
	global_load_lds_dwordx4 v129, s[80:81]
	s_add_u32 s40, s77, 0x180
	s_addc_u32 s41, s78, 0
	s_add_u32 s78, s82, 0x180
	s_mov_b32 m0, s62
	s_nop 0
	global_load_lds_dwordx4 v128, s[40:41]
	s_addc_u32 s79, s83, 0
	s_mov_b32 m0, s63
	s_nop 0
	global_load_lds_dwordx4 v128, s[78:79]
	s_waitcnt vmcnt(8)
	s_waitcnt lgkmcnt(0)
	s_barrier
	s_setprio 1
	s_waitcnt lgkmcnt(7)
	v_mfma_f32_16x16x32_bf16 v[60:63], v[138:141], v[170:173], v[60:63]
	v_mfma_f32_16x16x32_bf16 v[56:59], v[146:149], v[170:173], v[56:59]
	s_waitcnt lgkmcnt(5)
	v_mfma_f32_16x16x32_bf16 v[52:55], v[138:141], v[178:181], v[52:55]
	v_mfma_f32_16x16x32_bf16 v[48:51], v[146:149], v[178:181], v[48:51]
	s_waitcnt lgkmcnt(3)
	v_mfma_f32_16x16x32_bf16 v[44:47], v[138:141], v[186:189], v[44:47]
	v_mfma_f32_16x16x32_bf16 v[40:43], v[146:149], v[186:189], v[40:43]
	s_waitcnt lgkmcnt(1)
	v_mfma_f32_16x16x32_bf16 v[36:39], v[138:141], v[194:197], v[36:39]
	v_mfma_f32_16x16x32_bf16 v[32:35], v[146:149], v[194:197], v[32:35]
	v_mfma_f32_16x16x32_bf16 v[60:63], v[142:145], v[174:177], v[60:63]
	v_mfma_f32_16x16x32_bf16 v[56:59], v[150:153], v[174:177], v[56:59]
	v_mfma_f32_16x16x32_bf16 v[52:55], v[142:145], v[182:185], v[52:55]
	v_mfma_f32_16x16x32_bf16 v[48:51], v[150:153], v[182:185], v[48:51]
	v_mfma_f32_16x16x32_bf16 v[44:47], v[142:145], v[190:193], v[44:47]
	v_mfma_f32_16x16x32_bf16 v[40:43], v[150:153], v[190:193], v[40:43]
	s_waitcnt lgkmcnt(0)
	v_mfma_f32_16x16x32_bf16 v[36:39], v[142:145], v[198:201], v[36:39]
	v_mfma_f32_16x16x32_bf16 v[32:35], v[150:153], v[198:201], v[32:35]
	s_setprio 0
	s_setprio 1
	v_mfma_f32_16x16x32_bf16 v[28:31], v[154:157], v[170:173], v[28:31]
	v_mfma_f32_16x16x32_bf16 v[24:27], v[162:165], v[170:173], v[24:27]
	v_mfma_f32_16x16x32_bf16 v[20:23], v[154:157], v[178:181], v[20:23]
	v_mfma_f32_16x16x32_bf16 v[16:19], v[162:165], v[178:181], v[16:19]
	v_mfma_f32_16x16x32_bf16 v[12:15], v[154:157], v[186:189], v[12:15]
	v_mfma_f32_16x16x32_bf16 v[8:11], v[162:165], v[186:189], v[8:11]
	v_mfma_f32_16x16x32_bf16 v[4:7], v[154:157], v[194:197], v[4:7]
	v_mfma_f32_16x16x32_bf16 v[0:3], v[162:165], v[194:197], v[0:3]
	v_mfma_f32_16x16x32_bf16 v[28:31], v[158:161], v[174:177], v[28:31]
	v_mfma_f32_16x16x32_bf16 v[24:27], v[166:169], v[174:177], v[24:27]
	v_mfma_f32_16x16x32_bf16 v[20:23], v[158:161], v[182:185], v[20:23]
	v_mfma_f32_16x16x32_bf16 v[16:19], v[166:169], v[182:185], v[16:19]
	v_mfma_f32_16x16x32_bf16 v[12:15], v[158:161], v[190:193], v[12:15]
	v_mfma_f32_16x16x32_bf16 v[8:11], v[166:169], v[190:193], v[8:11]
	v_mfma_f32_16x16x32_bf16 v[4:7], v[158:161], v[198:201], v[4:7]
	v_mfma_f32_16x16x32_bf16 v[0:3], v[166:169], v[198:201], v[0:3]
	s_setprio 0
	s_barrier
	s_add_u32 s38, s38, 0x100
	s_addc_u32 s39, s39, 0
	s_cmp_ge_i32 s75, s2
	s_cbranch_scc0 .LBB0_923
	s_branch .LBB0_924
.Lhf_923:
	ds_read_b128 v[138:141], v133
	ds_read_b128 v[142:145], v133 offset:1024
	ds_read_b128 v[146:149], v133 offset:2048
	ds_read_b128 v[150:153], v133 offset:3072
	ds_read_b128 v[154:157], v134
	ds_read_b128 v[158:161], v134 offset:1024
	ds_read_b128 v[162:165], v134 offset:2048
	ds_read_b128 v[166:169], v134 offset:3072
	s_add_i32 s75, s75, 2
	s_add_u32 s77, s4, s38
	s_addc_u32 s78, s5, s39
	s_add_u32 s40, s77, 0x100
	s_addc_u32 s41, s78, 0
	s_add_u32 s79, s22, s38
	ds_read_b128 v[170:173], v135
	ds_read_b128 v[174:177], v135 offset:1024
	ds_read_b128 v[178:181], v135 offset:2048
	ds_read_b128 v[182:185], v135 offset:3072
	ds_read_b128 v[186:189], v135 offset:4096
	ds_read_b128 v[190:193], v135 offset:5120
	ds_read_b128 v[194:197], v135 offset:6144
	ds_read_b128 v[198:201], v135 offset:7168
	s_addc_u32 s84, s33, s39
	s_add_u32 s80, s79, 0x80
	s_addc_u32 s81, s84, 0
	s_add_u32 s85, s70, s38
	s_addc_u32 s86, s71, s39
	s_add_u32 s82, s85, 0x80
	s_mov_b32 m0, s66
	s_nop 0
	global_load_lds_dwordx4 v128, s[80:81]
	s_addc_u32 s83, s86, 0
	s_mov_b32 m0, s67
	s_nop 0
	global_load_lds_dwordx4 v128, s[82:83]
	s_waitcnt vmcnt(8)
	s_waitcnt lgkmcnt(0)
	s_barrier
	s_setprio 1
	s_waitcnt lgkmcnt(7)
	v_mfma_f32_16x16x32_bf16 v[124:127], v[138:141], v[170:173], 0
	v_mfma_f32_16x16x32_bf16 v[120:123], v[146:149], v[170:173], 0
	s_waitcnt lgkmcnt(5)
	v_mfma_f32_16x16x32_bf16 v[116:119], v[138:141], v[178:181], 0
	v_mfma_f32_16x16x32_bf16 v[112:115], v[146:149], v[178:181], 0
	s_waitcnt lgkmcnt(3)
	v_mfma_f32_16x16x32_bf16 v[108:111], v[138:141], v[186:189], 0
	v_mfma_f32_16x16x32_bf16 v[104:107], v[146:149], v[186:189], 0
	s_waitcnt lgkmcnt(1)
	v_mfma_f32_16x16x32_bf16 v[100:103], v[138:141], v[194:197], 0
	v_mfma_f32_16x16x32_bf16 v[96:99], v[146:149], v[194:197], 0
	v_mfma_f32_16x16x32_bf16 v[124:127], v[142:145], v[174:177], v[124:127]
	v_mfma_f32_16x16x32_bf16 v[120:123], v[150:153], v[174:177], v[120:123]
	v_mfma_f32_16x16x32_bf16 v[116:119], v[142:145], v[182:185], v[116:119]
	v_mfma_f32_16x16x32_bf16 v[112:115], v[150:153], v[182:185], v[112:115]
	v_mfma_f32_16x16x32_bf16 v[108:111], v[142:145], v[190:193], v[108:111]
	v_mfma_f32_16x16x32_bf16 v[104:107], v[150:153], v[190:193], v[104:107]
	s_waitcnt lgkmcnt(0)
	v_mfma_f32_16x16x32_bf16 v[100:103], v[142:145], v[198:201], v[100:103]
	v_mfma_f32_16x16x32_bf16 v[96:99], v[150:153], v[198:201], v[96:99]
	s_setprio 0
	s_setprio 1
	v_mfma_f32_16x16x32_bf16 v[92:95], v[154:157], v[170:173], 0
	v_mfma_f32_16x16x32_bf16 v[88:91], v[162:165], v[170:173], 0
	v_mfma_f32_16x16x32_bf16 v[84:87], v[154:157], v[178:181], 0
	v_mfma_f32_16x16x32_bf16 v[80:83], v[162:165], v[178:181], 0
	v_mfma_f32_16x16x32_bf16 v[76:79], v[154:157], v[186:189], 0
	v_mfma_f32_16x16x32_bf16 v[72:75], v[162:165], v[186:189], 0
	v_mfma_f32_16x16x32_bf16 v[68:71], v[154:157], v[194:197], 0
	v_mfma_f32_16x16x32_bf16 v[64:67], v[162:165], v[194:197], 0
	v_mfma_f32_16x16x32_bf16 v[92:95], v[158:161], v[174:177], v[92:95]
	v_mfma_f32_16x16x32_bf16 v[88:91], v[166:169], v[174:177], v[88:91]
	v_mfma_f32_16x16x32_bf16 v[84:87], v[158:161], v[182:185], v[84:87]
	v_mfma_f32_16x16x32_bf16 v[80:83], v[166:169], v[182:185], v[80:83]
	v_mfma_f32_16x16x32_bf16 v[76:79], v[158:161], v[190:193], v[76:79]
	v_mfma_f32_16x16x32_bf16 v[72:75], v[166:169], v[190:193], v[72:75]
	v_mfma_f32_16x16x32_bf16 v[68:71], v[158:161], v[198:201], v[68:71]
	v_mfma_f32_16x16x32_bf16 v[64:67], v[166:169], v[198:201], v[64:67]
	s_setprio 0
	s_barrier
	s_add_u32 s87, s6, s38
	s_addc_u32 s88, s7, s39
	s_add_u32 s80, s87, 0x100
	s_addc_u32 s81, s88, 0
	s_add_u32 s89, s68, s38
	s_addc_u32 s90, s69, s39
	s_add_u32 s82, s89, 0x100
	ds_read_b128 v[170:173], v135 offset:16384
	ds_read_b128 v[174:177], v135 offset:17408
	ds_read_b128 v[178:181], v135 offset:18432
	ds_read_b128 v[182:185], v135 offset:19456
	ds_read_b128 v[186:189], v135 offset:20480
	ds_read_b128 v[190:193], v135 offset:21504
	ds_read_b128 v[194:197], v135 offset:22528
	ds_read_b128 v[198:201], v135 offset:23552
	s_addc_u32 s83, s90, 0
	s_mov_b32 m0, s51
	s_nop 0
	global_load_lds_dwordx4 v129, s[80:81]
	s_add_u32 s91, s42, s38
	s_mov_b32 m0, s52
	s_nop 0
	global_load_lds_dwordx4 v129, s[82:83]
	s_addc_u32 s92, s43, s39
	s_add_u32 s80, s91, 0x100
	s_addc_u32 s81, s92, 0
	s_add_u32 s93, s44, s38
	s_addc_u32 s94, s45, s39
	s_add_u32 s82, s93, 0x100
	s_addc_u32 s83, s94, 0
	s_mov_b32 m0, s53
	s_nop 0
	global_load_lds_dwordx4 v129, s[80:81]
	s_mov_b32 m0, s56
	s_nop 0
	global_load_lds_dwordx4 v129, s[82:83]
	s_add_u32 s82, s72, s38
	s_addc_u32 s83, s74, s39
	s_add_u32 s80, s82, 0x100
	s_mov_b32 m0, s55
	s_nop 0
	global_load_lds_dwordx4 v128, s[40:41]
	s_addc_u32 s81, s83, 0
	s_mov_b32 m0, s57
	s_nop 0
	global_load_lds_dwordx4 v128, s[80:81]
	s_waitcnt vmcnt(8)
	s_waitcnt lgkmcnt(0)
	s_barrier
	s_setprio 1
	s_waitcnt lgkmcnt(7)
	v_mfma_f32_16x16x32_bf16 v[60:63], v[138:141], v[170:173], 0
	v_mfma_f32_16x16x32_bf16 v[56:59], v[146:149], v[170:173], 0
	s_waitcnt lgkmcnt(5)
	v_mfma_f32_16x16x32_bf16 v[52:55], v[138:141], v[178:181], 0
	v_mfma_f32_16x16x32_bf16 v[48:51], v[146:149], v[178:181], 0
	s_waitcnt lgkmcnt(3)
	v_mfma_f32_16x16x32_bf16 v[44:47], v[138:141], v[186:189], 0
	v_mfma_f32_16x16x32_bf16 v[40:43], v[146:149], v[186:189], 0
	s_waitcnt lgkmcnt(1)
	v_mfma_f32_16x16x32_bf16 v[36:39], v[138:141], v[194:197], 0
	v_mfma_f32_16x16x32_bf16 v[32:35], v[146:149], v[194:197], 0
	v_mfma_f32_16x16x32_bf16 v[60:63], v[142:145], v[174:177], v[60:63]
	v_mfma_f32_16x16x32_bf16 v[56:59], v[150:153], v[174:177], v[56:59]
	v_mfma_f32_16x16x32_bf16 v[52:55], v[142:145], v[182:185], v[52:55]
	v_mfma_f32_16x16x32_bf16 v[48:51], v[150:153], v[182:185], v[48:51]
	v_mfma_f32_16x16x32_bf16 v[44:47], v[142:145], v[190:193], v[44:47]
	v_mfma_f32_16x16x32_bf16 v[40:43], v[150:153], v[190:193], v[40:43]
	s_waitcnt lgkmcnt(0)
	v_mfma_f32_16x16x32_bf16 v[36:39], v[142:145], v[198:201], v[36:39]
	v_mfma_f32_16x16x32_bf16 v[32:35], v[150:153], v[198:201], v[32:35]
	s_setprio 0
	s_setprio 1
	v_mfma_f32_16x16x32_bf16 v[28:31], v[154:157], v[170:173], 0
	v_mfma_f32_16x16x32_bf16 v[24:27], v[162:165], v[170:173], 0
	v_mfma_f32_16x16x32_bf16 v[20:23], v[154:157], v[178:181], 0
	v_mfma_f32_16x16x32_bf16 v[16:19], v[162:165], v[178:181], 0
	v_mfma_f32_16x16x32_bf16 v[12:15], v[154:157], v[186:189], 0
	v_mfma_f32_16x16x32_bf16 v[8:11], v[162:165], v[186:189], 0
	v_mfma_f32_16x16x32_bf16 v[4:7], v[154:157], v[194:197], 0
	v_mfma_f32_16x16x32_bf16 v[0:3], v[162:165], v[194:197], 0
	v_mfma_f32_16x16x32_bf16 v[28:31], v[158:161], v[174:177], v[28:31]
	v_mfma_f32_16x16x32_bf16 v[24:27], v[166:169], v[174:177], v[24:27]
	v_mfma_f32_16x16x32_bf16 v[20:23], v[158:161], v[182:185], v[20:23]
	v_mfma_f32_16x16x32_bf16 v[16:19], v[166:169], v[182:185], v[16:19]
	v_mfma_f32_16x16x32_bf16 v[12:15], v[158:161], v[190:193], v[12:15]
	v_mfma_f32_16x16x32_bf16 v[8:11], v[166:169], v[190:193], v[8:11]
	v_mfma_f32_16x16x32_bf16 v[4:7], v[158:161], v[198:201], v[4:7]
	v_mfma_f32_16x16x32_bf16 v[0:3], v[166:169], v[198:201], v[0:3]
	s_setprio 0
	s_barrier
	ds_read_b128 v[138:141], v136
	ds_read_b128 v[142:145], v136 offset:1024
	ds_read_b128 v[146:149], v136 offset:2048
	ds_read_b128 v[150:153], v136 offset:3072
	ds_read_b128 v[154:157], v137
	ds_read_b128 v[158:161], v137 offset:1024
	ds_read_b128 v[162:165], v137 offset:2048
	ds_read_b128 v[166:169], v137 offset:3072
	ds_read_b128 v[170:173], v135 offset:32768
	ds_read_b128 v[174:177], v135 offset:33792
	ds_read_b128 v[178:181], v135 offset:34816
	ds_read_b128 v[182:185], v135 offset:35840
	ds_read_b128 v[186:189], v135 offset:36864
	ds_read_b128 v[190:193], v135 offset:37888
	ds_read_b128 v[194:197], v135 offset:38912
	ds_read_b128 v[198:201], v135 offset:39936
	s_add_u32 s40, s79, 0x100
	s_addc_u32 s41, s84, 0
	s_add_u32 s80, s85, 0x100
	s_mov_b32 m0, s58
	s_nop 0
	global_load_lds_dwordx4 v128, s[40:41]
	s_addc_u32 s81, s86, 0
	s_mov_b32 m0, s59
	s_nop 0
	global_load_lds_dwordx4 v128, s[80:81]
	s_waitcnt vmcnt(8)
	s_waitcnt lgkmcnt(0)
	s_barrier
	s_setprio 1
	s_waitcnt lgkmcnt(7)
	v_mfma_f32_16x16x32_bf16 v[124:127], v[138:141], v[170:173], v[124:127]
	v_mfma_f32_16x16x32_bf16 v[120:123], v[146:149], v[170:173], v[120:123]
	s_waitcnt lgkmcnt(5)
	v_mfma_f32_16x16x32_bf16 v[116:119], v[138:141], v[178:181], v[116:119]
	v_mfma_f32_16x16x32_bf16 v[112:115], v[146:149], v[178:181], v[112:115]
	s_waitcnt lgkmcnt(3)
	v_mfma_f32_16x16x32_bf16 v[108:111], v[138:141], v[186:189], v[108:111]
	v_mfma_f32_16x16x32_bf16 v[104:107], v[146:149], v[186:189], v[104:107]
	s_waitcnt lgkmcnt(1)
	v_mfma_f32_16x16x32_bf16 v[100:103], v[138:141], v[194:197], v[100:103]
	v_mfma_f32_16x16x32_bf16 v[96:99], v[146:149], v[194:197], v[96:99]
	v_mfma_f32_16x16x32_bf16 v[124:127], v[142:145], v[174:177], v[124:127]
	v_mfma_f32_16x16x32_bf16 v[120:123], v[150:153], v[174:177], v[120:123]
	v_mfma_f32_16x16x32_bf16 v[116:119], v[142:145], v[182:185], v[116:119]
	v_mfma_f32_16x16x32_bf16 v[112:115], v[150:153], v[182:185], v[112:115]
	v_mfma_f32_16x16x32_bf16 v[108:111], v[142:145], v[190:193], v[108:111]
	v_mfma_f32_16x16x32_bf16 v[104:107], v[150:153], v[190:193], v[104:107]
	s_waitcnt lgkmcnt(0)
	v_mfma_f32_16x16x32_bf16 v[100:103], v[142:145], v[198:201], v[100:103]
	v_mfma_f32_16x16x32_bf16 v[96:99], v[150:153], v[198:201], v[96:99]
	s_setprio 0
	s_setprio 1
	v_mfma_f32_16x16x32_bf16 v[92:95], v[154:157], v[170:173], v[92:95]
	v_mfma_f32_16x16x32_bf16 v[88:91], v[162:165], v[170:173], v[88:91]
	v_mfma_f32_16x16x32_bf16 v[84:87], v[154:157], v[178:181], v[84:87]
	v_mfma_f32_16x16x32_bf16 v[80:83], v[162:165], v[178:181], v[80:83]
	v_mfma_f32_16x16x32_bf16 v[76:79], v[154:157], v[186:189], v[76:79]
	v_mfma_f32_16x16x32_bf16 v[72:75], v[162:165], v[186:189], v[72:75]
	v_mfma_f32_16x16x32_bf16 v[68:71], v[154:157], v[194:197], v[68:71]
	v_mfma_f32_16x16x32_bf16 v[64:67], v[162:165], v[194:197], v[64:67]
	v_mfma_f32_16x16x32_bf16 v[92:95], v[158:161], v[174:177], v[92:95]
	v_mfma_f32_16x16x32_bf16 v[88:91], v[166:169], v[174:177], v[88:91]
	v_mfma_f32_16x16x32_bf16 v[84:87], v[158:161], v[182:185], v[84:87]
	v_mfma_f32_16x16x32_bf16 v[80:83], v[166:169], v[182:185], v[80:83]
	v_mfma_f32_16x16x32_bf16 v[76:79], v[158:161], v[190:193], v[76:79]
	v_mfma_f32_16x16x32_bf16 v[72:75], v[166:169], v[190:193], v[72:75]
	v_mfma_f32_16x16x32_bf16 v[68:71], v[158:161], v[198:201], v[68:71]
	v_mfma_f32_16x16x32_bf16 v[64:67], v[166:169], v[198:201], v[64:67]
	s_setprio 0
	s_barrier
	s_add_u32 s40, s87, 0x180
	s_addc_u32 s41, s88, 0
	ds_read_b128 v[170:173], v135 offset:49152
	ds_read_b128 v[174:177], v135 offset:50176
	ds_read_b128 v[178:181], v135 offset:51200
	ds_read_b128 v[182:185], v135 offset:52224
	ds_read_b128 v[186:189], v135 offset:53248
	ds_read_b128 v[190:193], v135 offset:54272
	ds_read_b128 v[194:197], v135 offset:55296
	ds_read_b128 v[198:201], v135 offset:56320
	s_add_u32 s80, s89, 0x180
	s_mov_b32 m0, s60
	s_nop 0
	global_load_lds_dwordx4 v129, s[40:41]
	s_addc_u32 s81, s90, 0
	s_mov_b32 m0, s61
	s_nop 0
	global_load_lds_dwordx4 v129, s[80:81]
	s_add_u32 s40, s91, 0x180
	s_addc_u32 s41, s92, 0
	s_add_u32 s80, s93, 0x180
	s_mov_b32 m0, s64
	s_nop 0
	global_load_lds_dwordx4 v129, s[40:41]
	s_addc_u32 s81, s94, 0
	s_mov_b32 m0, s65
	s_nop 0
	global_load_lds_dwordx4 v129, s[80:81]
	s_add_u32 s40, s77, 0x180
	s_addc_u32 s41, s78, 0
	s_add_u32 s78, s82, 0x180
	s_mov_b32 m0, s62
	s_nop 0
	global_load_lds_dwordx4 v128, s[40:41]
	s_addc_u32 s79, s83, 0
	s_mov_b32 m0, s63
	s_nop 0
	global_load_lds_dwordx4 v128, s[78:79]
	s_waitcnt vmcnt(8)
	s_waitcnt lgkmcnt(0)
	s_barrier
	s_setprio 1
	s_waitcnt lgkmcnt(7)
	v_mfma_f32_16x16x32_bf16 v[60:63], v[138:141], v[170:173], v[60:63]
	v_mfma_f32_16x16x32_bf16 v[56:59], v[146:149], v[170:173], v[56:59]
	s_waitcnt lgkmcnt(5)
	v_mfma_f32_16x16x32_bf16 v[52:55], v[138:141], v[178:181], v[52:55]
	v_mfma_f32_16x16x32_bf16 v[48:51], v[146:149], v[178:181], v[48:51]
	s_waitcnt lgkmcnt(3)
	v_mfma_f32_16x16x32_bf16 v[44:47], v[138:141], v[186:189], v[44:47]
	v_mfma_f32_16x16x32_bf16 v[40:43], v[146:149], v[186:189], v[40:43]
	s_waitcnt lgkmcnt(1)
	v_mfma_f32_16x16x32_bf16 v[36:39], v[138:141], v[194:197], v[36:39]
	v_mfma_f32_16x16x32_bf16 v[32:35], v[146:149], v[194:197], v[32:35]
	v_mfma_f32_16x16x32_bf16 v[60:63], v[142:145], v[174:177], v[60:63]
	v_mfma_f32_16x16x32_bf16 v[56:59], v[150:153], v[174:177], v[56:59]
	v_mfma_f32_16x16x32_bf16 v[52:55], v[142:145], v[182:185], v[52:55]
	v_mfma_f32_16x16x32_bf16 v[48:51], v[150:153], v[182:185], v[48:51]
	v_mfma_f32_16x16x32_bf16 v[44:47], v[142:145], v[190:193], v[44:47]
	v_mfma_f32_16x16x32_bf16 v[40:43], v[150:153], v[190:193], v[40:43]
	s_waitcnt lgkmcnt(0)
	v_mfma_f32_16x16x32_bf16 v[36:39], v[142:145], v[198:201], v[36:39]
	v_mfma_f32_16x16x32_bf16 v[32:35], v[150:153], v[198:201], v[32:35]
	s_setprio 0
	s_setprio 1
	v_mfma_f32_16x16x32_bf16 v[28:31], v[154:157], v[170:173], v[28:31]
	v_mfma_f32_16x16x32_bf16 v[24:27], v[162:165], v[170:173], v[24:27]
	v_mfma_f32_16x16x32_bf16 v[20:23], v[154:157], v[178:181], v[20:23]
	v_mfma_f32_16x16x32_bf16 v[16:19], v[162:165], v[178:181], v[16:19]
	v_mfma_f32_16x16x32_bf16 v[12:15], v[154:157], v[186:189], v[12:15]
	v_mfma_f32_16x16x32_bf16 v[8:11], v[162:165], v[186:189], v[8:11]
	v_mfma_f32_16x16x32_bf16 v[4:7], v[154:157], v[194:197], v[4:7]
	v_mfma_f32_16x16x32_bf16 v[0:3], v[162:165], v[194:197], v[0:3]
	v_mfma_f32_16x16x32_bf16 v[28:31], v[158:161], v[174:177], v[28:31]
	v_mfma_f32_16x16x32_bf16 v[24:27], v[166:169], v[174:177], v[24:27]
	v_mfma_f32_16x16x32_bf16 v[20:23], v[158:161], v[182:185], v[20:23]
	v_mfma_f32_16x16x32_bf16 v[16:19], v[166:169], v[182:185], v[16:19]
	v_mfma_f32_16x16x32_bf16 v[12:15], v[158:161], v[190:193], v[12:15]
	v_mfma_f32_16x16x32_bf16 v[8:11], v[166:169], v[190:193], v[8:11]
	v_mfma_f32_16x16x32_bf16 v[4:7], v[158:161], v[198:201], v[4:7]
	v_mfma_f32_16x16x32_bf16 v[0:3], v[166:169], v[198:201], v[0:3]
	s_setprio 0
	s_barrier
	s_add_u32 s38, s38, 0x100
	s_addc_u32 s39, s39, 0
	s_cmp_ge_i32 s75, s2
	s_cbranch_scc0 .LBB0_923
	s_branch .LBB0_924

.LBB0_940:
	s_cmp_lt_i32 s24, 3
	s_cbranch_scc1 .Lhz_942
	s_add_i32 s2, s24, -2
	s_add_u32 s23, s4, s52
	s_addc_u32 s25, s5, s53
	s_add_u32 s28, s6, s36
	s_addc_u32 s33, s7, s37
	s_add_u32 s34, s30, s36
	s_addc_u32 s35, s31, s37
	s_add_u32 s48, s6, s34
	s_addc_u32 s49, s7, s35
	s_add_u32 s68, s6, s30
	s_addc_u32 s69, s7, s31
	s_add_u32 s34, s50, s52
	s_addc_u32 s35, s51, s53
	s_add_u32 s70, s4, s34
	s_addc_u32 s71, s5, s35
	s_add_u32 s72, s4, s50
	s_addc_u32 s74, s5, s51
	s_mov_b32 s75, 0
	s_mov_b64 s[44:45], 0
	s_cmp_eq_u32 s98, 0
	s_cbranch_scc1 .Lhf_942
	ds_read_b128 v[24:27], v251
	ds_read_b128 v[28:31], v251 offset:1024
	ds_read_b128 v[16:19], v251 offset:2048
	ds_read_b128 v[20:23], v251 offset:3072
	ds_read_b128 v[8:11], v252
	ds_read_b128 v[12:15], v252 offset:1024
	ds_read_b128 v[0:3], v252 offset:2048
	ds_read_b128 v[4:7], v252 offset:3072
	s_add_i32 s75, s75, 2
	s_add_u32 s77, s4, s44
	s_addc_u32 s80, s5, s45
	s_add_u32 s46, s77, 0x100
	s_addc_u32 s47, s80, 0
	s_add_u32 s81, s23, s44
	ds_read_b128 v[164:167], v253
	ds_read_b128 v[168:171], v253 offset:1024
	ds_read_b128 v[172:175], v253 offset:2048
	ds_read_b128 v[176:179], v253 offset:3072
	ds_read_b128 v[180:183], v253 offset:4096
	ds_read_b128 v[184:187], v253 offset:5120
	ds_read_b128 v[188:191], v253 offset:6144
	ds_read_b128 v[192:195], v253 offset:7168
	s_addc_u32 s85, s25, s45
	s_add_u32 s88, s81, 0x80
	s_addc_u32 s89, s85, 0
	s_add_u32 s86, s70, s44
	s_addc_u32 s87, s71, s45
	s_add_u32 s90, s86, 0x80
	s_mov_b32 m0, s82
	s_nop 0
	global_load_lds_dwordx4 v160, s[88:89]
	s_addc_u32 s91, s87, 0
	s_mov_b32 m0, s83
	s_nop 0
	global_load_lds_dwordx4 v160, s[90:91]
	s_waitcnt vmcnt(24)
	s_waitcnt lgkmcnt(0)
	s_barrier
	s_setprio 1
	s_waitcnt lgkmcnt(6)
	v_mfma_scale_f32_16x16x128_f8f6f4 v[156:159], v[24:31], v[164:171], 0, v248, v250 op_sel_hi:[0,0,0]
	v_mfma_scale_f32_16x16x128_f8f6f4 v[152:155], v[16:23], v[164:171], 0, v248, v250 op_sel_hi:[0,0,0]
	s_waitcnt lgkmcnt(4)
	v_mfma_scale_f32_16x16x128_f8f6f4 v[148:151], v[24:31], v[172:179], 0, v248, v250 op_sel_hi:[0,0,0]
	v_mfma_scale_f32_16x16x128_f8f6f4 v[144:147], v[16:23], v[172:179], 0, v248, v250 op_sel_hi:[0,0,0]
	s_waitcnt lgkmcnt(2)
	v_mfma_scale_f32_16x16x128_f8f6f4 v[140:143], v[24:31], v[180:187], 0, v248, v250 op_sel_hi:[0,0,0]
	v_mfma_scale_f32_16x16x128_f8f6f4 v[136:139], v[16:23], v[180:187], 0, v248, v250 op_sel_hi:[0,0,0]
	s_waitcnt lgkmcnt(0)
	v_mfma_scale_f32_16x16x128_f8f6f4 v[132:135], v[24:31], v[188:195], 0, v248, v250 op_sel_hi:[0,0,0]
	v_mfma_scale_f32_16x16x128_f8f6f4 v[128:131], v[16:23], v[188:195], 0, v248, v250 op_sel_hi:[0,0,0]
	s_setprio 0
	s_setprio 1
	v_mfma_scale_f32_16x16x128_f8f6f4 v[124:127], v[8:15], v[164:171], 0, v248, v250 op_sel_hi:[0,0,0]
	v_mfma_scale_f32_16x16x128_f8f6f4 v[120:123], v[0:7], v[164:171], 0, v248, v250 op_sel_hi:[0,0,0]
	v_mfma_scale_f32_16x16x128_f8f6f4 v[116:119], v[8:15], v[172:179], 0, v248, v250 op_sel_hi:[0,0,0]
	v_mfma_scale_f32_16x16x128_f8f6f4 v[112:115], v[0:7], v[172:179], 0, v248, v250 op_sel_hi:[0,0,0]
	v_mfma_scale_f32_16x16x128_f8f6f4 v[108:111], v[8:15], v[180:187], 0, v248, v250 op_sel_hi:[0,0,0]
	v_mfma_scale_f32_16x16x128_f8f6f4 v[104:107], v[0:7], v[180:187], 0, v248, v250 op_sel_hi:[0,0,0]
	v_mfma_scale_f32_16x16x128_f8f6f4 v[100:103], v[8:15], v[188:195], 0, v248, v250 op_sel_hi:[0,0,0]
	v_mfma_scale_f32_16x16x128_f8f6f4 v[96:99], v[0:7], v[188:195], 0, v248, v250 op_sel_hi:[0,0,0]
	s_setprio 0
	s_barrier
	s_add_u32 s88, s6, s44
	s_addc_u32 s89, s7, s45
	s_add_u32 s92, s88, 0x100
	s_addc_u32 s93, s89, 0
	s_add_u32 s90, s68, s44
	s_addc_u32 s91, s69, s45
	s_add_u32 s94, s90, 0x100
	s_addc_u32 s95, s91, 0
	ds_read_b128 v[164:167], v253 offset:16384
	ds_read_b128 v[168:171], v253 offset:17408
	ds_read_b128 v[172:175], v253 offset:18432
	ds_read_b128 v[176:179], v253 offset:19456
	ds_read_b128 v[180:183], v253 offset:20480
	ds_read_b128 v[184:187], v253 offset:21504
	ds_read_b128 v[188:191], v253 offset:22528
	ds_read_b128 v[192:195], v253 offset:23552
	s_mov_b32 m0, s58
	s_nop 0
	global_load_lds_dwordx4 v161, s[92:93]
	s_add_u32 s92, s28, s44
	s_addc_u32 s93, s33, s45
	s_mov_b32 m0, s59
	s_nop 0
	global_load_lds_dwordx4 v161, s[94:95]
	s_add_u32 s94, s92, 0x100
	s_addc_u32 s95, s93, 0
	s_add_u32 s96, s48, s44
	s_addc_u32 s97, s49, s45
	s_add_u32 s34, s96, 0x100
	s_mov_b32 m0, s60
	s_nop 0
	global_load_lds_dwordx4 v161, s[94:95]
	s_addc_u32 s35, s97, 0
	s_mov_b32 m0, s61
	s_nop 0
	global_load_lds_dwordx4 v161, s[34:35]
	s_add_u32 s94, s72, s44
	s_addc_u32 s95, s74, s45
	s_add_u32 s34, s94, 0x100
	s_mov_b32 m0, s55
	s_nop 0
	global_load_lds_dwordx4 v160, s[46:47]
	s_addc_u32 s35, s95, 0
	s_mov_b32 m0, s62
	s_nop 0
	global_load_lds_dwordx4 v160, s[34:35]
	s_waitcnt vmcnt(24)
	s_waitcnt lgkmcnt(0)
	s_barrier
	s_setprio 1
	s_waitcnt lgkmcnt(6)
	v_mfma_scale_f32_16x16x128_f8f6f4 v[92:95], v[24:31], v[164:171], 0, v248, v250 op_sel_hi:[0,0,0]
	v_mfma_scale_f32_16x16x128_f8f6f4 v[88:91], v[16:23], v[164:171], 0, v248, v250 op_sel_hi:[0,0,0]
	s_waitcnt lgkmcnt(4)
	v_mfma_scale_f32_16x16x128_f8f6f4 v[84:87], v[24:31], v[172:179], 0, v248, v250 op_sel_hi:[0,0,0]
	v_mfma_scale_f32_16x16x128_f8f6f4 v[80:83], v[16:23], v[172:179], 0, v248, v250 op_sel_hi:[0,0,0]
	s_waitcnt lgkmcnt(2)
	v_mfma_scale_f32_16x16x128_f8f6f4 v[76:79], v[24:31], v[180:187], 0, v248, v250 op_sel_hi:[0,0,0]
	v_mfma_scale_f32_16x16x128_f8f6f4 v[72:75], v[16:23], v[180:187], 0, v248, v250 op_sel_hi:[0,0,0]
	s_waitcnt lgkmcnt(0)
	v_mfma_scale_f32_16x16x128_f8f6f4 v[68:71], v[24:31], v[188:195], 0, v248, v250 op_sel_hi:[0,0,0]
	v_mfma_scale_f32_16x16x128_f8f6f4 v[64:67], v[16:23], v[188:195], 0, v248, v250 op_sel_hi:[0,0,0]
	s_setprio 0
	s_setprio 1
	v_mfma_scale_f32_16x16x128_f8f6f4 v[60:63], v[8:15], v[164:171], 0, v248, v250 op_sel_hi:[0,0,0]
	v_mfma_scale_f32_16x16x128_f8f6f4 v[56:59], v[0:7], v[164:171], 0, v248, v250 op_sel_hi:[0,0,0]
	v_mfma_scale_f32_16x16x128_f8f6f4 v[52:55], v[8:15], v[172:179], 0, v248, v250 op_sel_hi:[0,0,0]
	v_mfma_scale_f32_16x16x128_f8f6f4 v[48:51], v[0:7], v[172:179], 0, v248, v250 op_sel_hi:[0,0,0]
	v_mfma_scale_f32_16x16x128_f8f6f4 v[44:47], v[8:15], v[180:187], 0, v248, v250 op_sel_hi:[0,0,0]
	v_mfma_scale_f32_16x16x128_f8f6f4 v[40:43], v[0:7], v[180:187], 0, v248, v250 op_sel_hi:[0,0,0]
	v_mfma_scale_f32_16x16x128_f8f6f4 v[36:39], v[8:15], v[188:195], 0, v248, v250 op_sel_hi:[0,0,0]
	v_mfma_scale_f32_16x16x128_f8f6f4 v[32:35], v[0:7], v[188:195], 0, v248, v250 op_sel_hi:[0,0,0]
	s_setprio 0
	s_barrier
	ds_read_b128 v[24:27], v249
	ds_read_b128 v[28:31], v249 offset:1024
	ds_read_b128 v[16:19], v249 offset:2048
	ds_read_b128 v[20:23], v249 offset:3072
	ds_read_b128 v[8:11], v162
	ds_read_b128 v[12:15], v162 offset:1024
	ds_read_b128 v[0:3], v162 offset:2048
	ds_read_b128 v[4:7], v162 offset:3072
	ds_read_b128 v[164:167], v253 offset:32768
	ds_read_b128 v[168:171], v253 offset:33792
	ds_read_b128 v[172:175], v253 offset:34816
	ds_read_b128 v[176:179], v253 offset:35840
	ds_read_b128 v[180:183], v253 offset:36864
	ds_read_b128 v[184:187], v253 offset:37888
	ds_read_b128 v[188:191], v253 offset:38912
	ds_read_b128 v[192:195], v253 offset:39936
	s_add_u32 s34, s81, 0x100
	s_addc_u32 s35, s85, 0
	s_add_u32 s46, s86, 0x100
	s_mov_b32 m0, s63
	s_nop 0
	global_load_lds_dwordx4 v160, s[34:35]
	s_addc_u32 s47, s87, 0
	s_mov_b32 m0, s64
	s_nop 0
	global_load_lds_dwordx4 v160, s[46:47]
	s_waitcnt vmcnt(8)
	s_waitcnt lgkmcnt(0)
	s_barrier
	s_setprio 1
	s_waitcnt lgkmcnt(6)
	v_mfma_scale_f32_16x16x128_f8f6f4 v[156:159], v[24:31], v[164:171], v[156:159], v248, v250 op_sel_hi:[0,0,0]
	v_mfma_scale_f32_16x16x128_f8f6f4 v[152:155], v[16:23], v[164:171], v[152:155], v248, v250 op_sel_hi:[0,0,0]
	s_waitcnt lgkmcnt(4)
	v_mfma_scale_f32_16x16x128_f8f6f4 v[148:151], v[24:31], v[172:179], v[148:151], v248, v250 op_sel_hi:[0,0,0]
	v_mfma_scale_f32_16x16x128_f8f6f4 v[144:147], v[16:23], v[172:179], v[144:147], v248, v250 op_sel_hi:[0,0,0]
	s_waitcnt lgkmcnt(2)
	v_mfma_scale_f32_16x16x128_f8f6f4 v[140:143], v[24:31], v[180:187], v[140:143], v248, v250 op_sel_hi:[0,0,0]
	v_mfma_scale_f32_16x16x128_f8f6f4 v[136:139], v[16:23], v[180:187], v[136:139], v248, v250 op_sel_hi:[0,0,0]
	s_waitcnt lgkmcnt(0)
	v_mfma_scale_f32_16x16x128_f8f6f4 v[132:135], v[24:31], v[188:195], v[132:135], v248, v250 op_sel_hi:[0,0,0]
	v_mfma_scale_f32_16x16x128_f8f6f4 v[128:131], v[16:23], v[188:195], v[128:131], v248, v250 op_sel_hi:[0,0,0]
	s_setprio 0
	s_setprio 1
	v_mfma_scale_f32_16x16x128_f8f6f4 v[124:127], v[8:15], v[164:171], v[124:127], v248, v250 op_sel_hi:[0,0,0]
	v_mfma_scale_f32_16x16x128_f8f6f4 v[120:123], v[0:7], v[164:171], v[120:123], v248, v250 op_sel_hi:[0,0,0]
	v_mfma_scale_f32_16x16x128_f8f6f4 v[116:119], v[8:15], v[172:179], v[116:119], v248, v250 op_sel_hi:[0,0,0]
	v_mfma_scale_f32_16x16x128_f8f6f4 v[112:115], v[0:7], v[172:179], v[112:115], v248, v250 op_sel_hi:[0,0,0]
	v_mfma_scale_f32_16x16x128_f8f6f4 v[108:111], v[8:15], v[180:187], v[108:111], v248, v250 op_sel_hi:[0,0,0]
	v_mfma_scale_f32_16x16x128_f8f6f4 v[104:107], v[0:7], v[180:187], v[104:107], v248, v250 op_sel_hi:[0,0,0]
	v_mfma_scale_f32_16x16x128_f8f6f4 v[100:103], v[8:15], v[188:195], v[100:103], v248, v250 op_sel_hi:[0,0,0]
	v_mfma_scale_f32_16x16x128_f8f6f4 v[96:99], v[0:7], v[188:195], v[96:99], v248, v250 op_sel_hi:[0,0,0]
	s_setprio 0
	s_barrier
	s_add_u32 s34, s88, 0x180
	s_addc_u32 s35, s89, 0
	ds_read_b128 v[164:167], v253 offset:49152
	ds_read_b128 v[168:171], v253 offset:50176
	ds_read_b128 v[172:175], v253 offset:51200
	ds_read_b128 v[176:179], v253 offset:52224
	ds_read_b128 v[180:183], v253 offset:53248
	ds_read_b128 v[184:187], v253 offset:54272
	ds_read_b128 v[188:191], v253 offset:55296
	ds_read_b128 v[192:195], v253 offset:56320
	s_add_u32 s46, s90, 0x180
	s_mov_b32 m0, s65
	s_nop 0
	global_load_lds_dwordx4 v161, s[34:35]
	s_addc_u32 s47, s91, 0
	s_mov_b32 m0, s66
	s_nop 0
	global_load_lds_dwordx4 v161, s[46:47]
	s_add_u32 s34, s92, 0x180
	s_addc_u32 s35, s93, 0
	s_add_u32 s46, s96, 0x180
	s_mov_b32 m0, s78
	s_nop 0
	global_load_lds_dwordx4 v161, s[34:35]
	s_addc_u32 s47, s97, 0
	s_mov_b32 m0, s79
	s_nop 0
	global_load_lds_dwordx4 v161, s[46:47]
	s_add_u32 s34, s77, 0x180
	s_addc_u32 s35, s80, 0
	s_add_u32 s46, s94, 0x180
	s_mov_b32 m0, s67
	s_nop 0
	global_load_lds_dwordx4 v160, s[34:35]
	s_addc_u32 s47, s95, 0
	s_mov_b32 m0, s73
	s_nop 0
	global_load_lds_dwordx4 v160, s[46:47]
	s_waitcnt vmcnt(8)
	s_waitcnt lgkmcnt(0)
	s_barrier
	s_setprio 1
	s_waitcnt lgkmcnt(6)
	v_mfma_scale_f32_16x16x128_f8f6f4 v[92:95], v[24:31], v[164:171], v[92:95], v248, v250 op_sel_hi:[0,0,0]
	v_mfma_scale_f32_16x16x128_f8f6f4 v[88:91], v[16:23], v[164:171], v[88:91], v248, v250 op_sel_hi:[0,0,0]
	s_waitcnt lgkmcnt(4)
	v_mfma_scale_f32_16x16x128_f8f6f4 v[84:87], v[24:31], v[172:179], v[84:87], v248, v250 op_sel_hi:[0,0,0]
	v_mfma_scale_f32_16x16x128_f8f6f4 v[80:83], v[16:23], v[172:179], v[80:83], v248, v250 op_sel_hi:[0,0,0]
	s_waitcnt lgkmcnt(2)
	v_mfma_scale_f32_16x16x128_f8f6f4 v[76:79], v[24:31], v[180:187], v[76:79], v248, v250 op_sel_hi:[0,0,0]
	v_mfma_scale_f32_16x16x128_f8f6f4 v[72:75], v[16:23], v[180:187], v[72:75], v248, v250 op_sel_hi:[0,0,0]
	s_waitcnt lgkmcnt(0)
	v_mfma_scale_f32_16x16x128_f8f6f4 v[68:71], v[24:31], v[188:195], v[68:71], v248, v250 op_sel_hi:[0,0,0]
	v_mfma_scale_f32_16x16x128_f8f6f4 v[64:67], v[16:23], v[188:195], v[64:67], v248, v250 op_sel_hi:[0,0,0]
	s_setprio 0
	s_setprio 1
	v_mfma_scale_f32_16x16x128_f8f6f4 v[60:63], v[8:15], v[164:171], v[60:63], v248, v250 op_sel_hi:[0,0,0]
	v_mfma_scale_f32_16x16x128_f8f6f4 v[56:59], v[0:7], v[164:171], v[56:59], v248, v250 op_sel_hi:[0,0,0]
	v_mfma_scale_f32_16x16x128_f8f6f4 v[52:55], v[8:15], v[172:179], v[52:55], v248, v250 op_sel_hi:[0,0,0]
	v_mfma_scale_f32_16x16x128_f8f6f4 v[48:51], v[0:7], v[172:179], v[48:51], v248, v250 op_sel_hi:[0,0,0]
	v_mfma_scale_f32_16x16x128_f8f6f4 v[44:47], v[8:15], v[180:187], v[44:47], v248, v250 op_sel_hi:[0,0,0]
	v_mfma_scale_f32_16x16x128_f8f6f4 v[40:43], v[0:7], v[180:187], v[40:43], v248, v250 op_sel_hi:[0,0,0]
	v_mfma_scale_f32_16x16x128_f8f6f4 v[36:39], v[8:15], v[188:195], v[36:39], v248, v250 op_sel_hi:[0,0,0]
	v_mfma_scale_f32_16x16x128_f8f6f4 v[32:35], v[0:7], v[188:195], v[32:35], v248, v250 op_sel_hi:[0,0,0]
	s_setprio 0
	s_barrier
	s_add_u32 s44, s44, 0x100
	s_addc_u32 s45, s45, 0
	s_cmp_ge_i32 s75, s2
	s_cbranch_scc0 .LBB0_942
	s_branch .LBB0_943
.Lhf_942:
	ds_read_b128 v[24:27], v251
	ds_read_b128 v[28:31], v251 offset:1024
	ds_read_b128 v[16:19], v251 offset:2048
	ds_read_b128 v[20:23], v251 offset:3072
	ds_read_b128 v[8:11], v252
	ds_read_b128 v[12:15], v252 offset:1024
	ds_read_b128 v[0:3], v252 offset:2048
	ds_read_b128 v[4:7], v252 offset:3072
	s_add_i32 s75, s75, 2
	s_add_u32 s77, s4, s44
	s_addc_u32 s80, s5, s45
	s_add_u32 s46, s77, 0x100
	s_addc_u32 s47, s80, 0
	s_add_u32 s81, s23, s44
	ds_read_b128 v[164:167], v253
	ds_read_b128 v[168:171], v253 offset:1024
	ds_read_b128 v[172:175], v253 offset:2048
	ds_read_b128 v[176:179], v253 offset:3072
	ds_read_b128 v[180:183], v253 offset:4096
	ds_read_b128 v[184:187], v253 offset:5120
	ds_read_b128 v[188:191], v253 offset:6144
	ds_read_b128 v[192:195], v253 offset:7168
	s_addc_u32 s85, s25, s45
	s_add_u32 s88, s81, 0x80
	s_addc_u32 s89, s85, 0
	s_add_u32 s86, s70, s44
	s_addc_u32 s87, s71, s45
	s_add_u32 s90, s86, 0x80
	s_mov_b32 m0, s82
	s_nop 0
	global_load_lds_dwordx4 v160, s[88:89]
	s_addc_u32 s91, s87, 0
	s_mov_b32 m0, s83
	s_nop 0
	global_load_lds_dwordx4 v160, s[90:91]
	s_waitcnt vmcnt(8)
	s_waitcnt lgkmcnt(0)
	s_barrier
	s_setprio 1
	s_waitcnt lgkmcnt(6)
	v_mfma_scale_f32_16x16x128_f8f6f4 v[156:159], v[24:31], v[164:171], 0, v248, v250 op_sel_hi:[0,0,0]
	v_mfma_scale_f32_16x16x128_f8f6f4 v[152:155], v[16:23], v[164:171], 0, v248, v250 op_sel_hi:[0,0,0]
	s_waitcnt lgkmcnt(4)
	v_mfma_scale_f32_16x16x128_f8f6f4 v[148:151], v[24:31], v[172:179], 0, v248, v250 op_sel_hi:[0,0,0]
	v_mfma_scale_f32_16x16x128_f8f6f4 v[144:147], v[16:23], v[172:179], 0, v248, v250 op_sel_hi:[0,0,0]
	s_waitcnt lgkmcnt(2)
	v_mfma_scale_f32_16x16x128_f8f6f4 v[140:143], v[24:31], v[180:187], 0, v248, v250 op_sel_hi:[0,0,0]
	v_mfma_scale_f32_16x16x128_f8f6f4 v[136:139], v[16:23], v[180:187], 0, v248, v250 op_sel_hi:[0,0,0]
	s_waitcnt lgkmcnt(0)
	v_mfma_scale_f32_16x16x128_f8f6f4 v[132:135], v[24:31], v[188:195], 0, v248, v250 op_sel_hi:[0,0,0]
	v_mfma_scale_f32_16x16x128_f8f6f4 v[128:131], v[16:23], v[188:195], 0, v248, v250 op_sel_hi:[0,0,0]
	s_setprio 0
	s_setprio 1
	v_mfma_scale_f32_16x16x128_f8f6f4 v[124:127], v[8:15], v[164:171], 0, v248, v250 op_sel_hi:[0,0,0]
	v_mfma_scale_f32_16x16x128_f8f6f4 v[120:123], v[0:7], v[164:171], 0, v248, v250 op_sel_hi:[0,0,0]
	v_mfma_scale_f32_16x16x128_f8f6f4 v[116:119], v[8:15], v[172:179], 0, v248, v250 op_sel_hi:[0,0,0]
	v_mfma_scale_f32_16x16x128_f8f6f4 v[112:115], v[0:7], v[172:179], 0, v248, v250 op_sel_hi:[0,0,0]
	v_mfma_scale_f32_16x16x128_f8f6f4 v[108:111], v[8:15], v[180:187], 0, v248, v250 op_sel_hi:[0,0,0]
	v_mfma_scale_f32_16x16x128_f8f6f4 v[104:107], v[0:7], v[180:187], 0, v248, v250 op_sel_hi:[0,0,0]
	v_mfma_scale_f32_16x16x128_f8f6f4 v[100:103], v[8:15], v[188:195], 0, v248, v250 op_sel_hi:[0,0,0]
	v_mfma_scale_f32_16x16x128_f8f6f4 v[96:99], v[0:7], v[188:195], 0, v248, v250 op_sel_hi:[0,0,0]
	s_setprio 0
	s_barrier
	s_add_u32 s88, s6, s44
	s_addc_u32 s89, s7, s45
	s_add_u32 s92, s88, 0x100
	s_addc_u32 s93, s89, 0
	s_add_u32 s90, s68, s44
	s_addc_u32 s91, s69, s45
	s_add_u32 s94, s90, 0x100
	s_addc_u32 s95, s91, 0
	ds_read_b128 v[164:167], v253 offset:16384
	ds_read_b128 v[168:171], v253 offset:17408
	ds_read_b128 v[172:175], v253 offset:18432
	ds_read_b128 v[176:179], v253 offset:19456
	ds_read_b128 v[180:183], v253 offset:20480
	ds_read_b128 v[184:187], v253 offset:21504
	ds_read_b128 v[188:191], v253 offset:22528
	ds_read_b128 v[192:195], v253 offset:23552
	s_mov_b32 m0, s58
	s_nop 0
	global_load_lds_dwordx4 v161, s[92:93]
	s_add_u32 s92, s28, s44
	s_addc_u32 s93, s33, s45
	s_mov_b32 m0, s59
	s_nop 0
	global_load_lds_dwordx4 v161, s[94:95]
	s_add_u32 s94, s92, 0x100
	s_addc_u32 s95, s93, 0
	s_add_u32 s96, s48, s44
	s_addc_u32 s97, s49, s45
	s_add_u32 s34, s96, 0x100
	s_mov_b32 m0, s60
	s_nop 0
	global_load_lds_dwordx4 v161, s[94:95]
	s_addc_u32 s35, s97, 0
	s_mov_b32 m0, s61
	s_nop 0
	global_load_lds_dwordx4 v161, s[34:35]
	s_add_u32 s94, s72, s44
	s_addc_u32 s95, s74, s45
	s_add_u32 s34, s94, 0x100
	s_mov_b32 m0, s55
	s_nop 0
	global_load_lds_dwordx4 v160, s[46:47]
	s_addc_u32 s35, s95, 0
	s_mov_b32 m0, s62
	s_nop 0
	global_load_lds_dwordx4 v160, s[34:35]
	s_waitcnt vmcnt(8)
	s_waitcnt lgkmcnt(0)
	s_barrier
	s_setprio 1
	s_waitcnt lgkmcnt(6)
	v_mfma_scale_f32_16x16x128_f8f6f4 v[92:95], v[24:31], v[164:171], 0, v248, v250 op_sel_hi:[0,0,0]
	v_mfma_scale_f32_16x16x128_f8f6f4 v[88:91], v[16:23], v[164:171], 0, v248, v250 op_sel_hi:[0,0,0]
	s_waitcnt lgkmcnt(4)
	v_mfma_scale_f32_16x16x128_f8f6f4 v[84:87], v[24:31], v[172:179], 0, v248, v250 op_sel_hi:[0,0,0]
	v_mfma_scale_f32_16x16x128_f8f6f4 v[80:83], v[16:23], v[172:179], 0, v248, v250 op_sel_hi:[0,0,0]
	s_waitcnt lgkmcnt(2)
	v_mfma_scale_f32_16x16x128_f8f6f4 v[76:79], v[24:31], v[180:187], 0, v248, v250 op_sel_hi:[0,0,0]
	v_mfma_scale_f32_16x16x128_f8f6f4 v[72:75], v[16:23], v[180:187], 0, v248, v250 op_sel_hi:[0,0,0]
	s_waitcnt lgkmcnt(0)
	v_mfma_scale_f32_16x16x128_f8f6f4 v[68:71], v[24:31], v[188:195], 0, v248, v250 op_sel_hi:[0,0,0]
	v_mfma_scale_f32_16x16x128_f8f6f4 v[64:67], v[16:23], v[188:195], 0, v248, v250 op_sel_hi:[0,0,0]
	s_setprio 0
	s_setprio 1
	v_mfma_scale_f32_16x16x128_f8f6f4 v[60:63], v[8:15], v[164:171], 0, v248, v250 op_sel_hi:[0,0,0]
	v_mfma_scale_f32_16x16x128_f8f6f4 v[56:59], v[0:7], v[164:171], 0, v248, v250 op_sel_hi:[0,0,0]
	v_mfma_scale_f32_16x16x128_f8f6f4 v[52:55], v[8:15], v[172:179], 0, v248, v250 op_sel_hi:[0,0,0]
	v_mfma_scale_f32_16x16x128_f8f6f4 v[48:51], v[0:7], v[172:179], 0, v248, v250 op_sel_hi:[0,0,0]
	v_mfma_scale_f32_16x16x128_f8f6f4 v[44:47], v[8:15], v[180:187], 0, v248, v250 op_sel_hi:[0,0,0]
	v_mfma_scale_f32_16x16x128_f8f6f4 v[40:43], v[0:7], v[180:187], 0, v248, v250 op_sel_hi:[0,0,0]
	v_mfma_scale_f32_16x16x128_f8f6f4 v[36:39], v[8:15], v[188:195], 0, v248, v250 op_sel_hi:[0,0,0]
	v_mfma_scale_f32_16x16x128_f8f6f4 v[32:35], v[0:7], v[188:195], 0, v248, v250 op_sel_hi:[0,0,0]
	s_setprio 0
	s_barrier
	ds_read_b128 v[24:27], v249
	ds_read_b128 v[28:31], v249 offset:1024
	ds_read_b128 v[16:19], v249 offset:2048
	ds_read_b128 v[20:23], v249 offset:3072
	ds_read_b128 v[8:11], v162
	ds_read_b128 v[12:15], v162 offset:1024
	ds_read_b128 v[0:3], v162 offset:2048
	ds_read_b128 v[4:7], v162 offset:3072
	ds_read_b128 v[164:167], v253 offset:32768
	ds_read_b128 v[168:171], v253 offset:33792
	ds_read_b128 v[172:175], v253 offset:34816
	ds_read_b128 v[176:179], v253 offset:35840
	ds_read_b128 v[180:183], v253 offset:36864
	ds_read_b128 v[184:187], v253 offset:37888
	ds_read_b128 v[188:191], v253 offset:38912
	ds_read_b128 v[192:195], v253 offset:39936
	s_add_u32 s34, s81, 0x100
	s_addc_u32 s35, s85, 0
	s_add_u32 s46, s86, 0x100
	s_mov_b32 m0, s63
	s_nop 0
	global_load_lds_dwordx4 v160, s[34:35]
	s_addc_u32 s47, s87, 0
	s_mov_b32 m0, s64
	s_nop 0
	global_load_lds_dwordx4 v160, s[46:47]
	s_waitcnt vmcnt(8)
	s_waitcnt lgkmcnt(0)
	s_barrier
	s_setprio 1
	s_waitcnt lgkmcnt(6)
	v_mfma_scale_f32_16x16x128_f8f6f4 v[156:159], v[24:31], v[164:171], v[156:159], v248, v250 op_sel_hi:[0,0,0]
	v_mfma_scale_f32_16x16x128_f8f6f4 v[152:155], v[16:23], v[164:171], v[152:155], v248, v250 op_sel_hi:[0,0,0]
	s_waitcnt lgkmcnt(4)
	v_mfma_scale_f32_16x16x128_f8f6f4 v[148:151], v[24:31], v[172:179], v[148:151], v248, v250 op_sel_hi:[0,0,0]
	v_mfma_scale_f32_16x16x128_f8f6f4 v[144:147], v[16:23], v[172:179], v[144:147], v248, v250 op_sel_hi:[0,0,0]
	s_waitcnt lgkmcnt(2)
	v_mfma_scale_f32_16x16x128_f8f6f4 v[140:143], v[24:31], v[180:187], v[140:143], v248, v250 op_sel_hi:[0,0,0]
	v_mfma_scale_f32_16x16x128_f8f6f4 v[136:139], v[16:23], v[180:187], v[136:139], v248, v250 op_sel_hi:[0,0,0]
	s_waitcnt lgkmcnt(0)
	v_mfma_scale_f32_16x16x128_f8f6f4 v[132:135], v[24:31], v[188:195], v[132:135], v248, v250 op_sel_hi:[0,0,0]
	v_mfma_scale_f32_16x16x128_f8f6f4 v[128:131], v[16:23], v[188:195], v[128:131], v248, v250 op_sel_hi:[0,0,0]
	s_setprio 0
	s_setprio 1
	v_mfma_scale_f32_16x16x128_f8f6f4 v[124:127], v[8:15], v[164:171], v[124:127], v248, v250 op_sel_hi:[0,0,0]
	v_mfma_scale_f32_16x16x128_f8f6f4 v[120:123], v[0:7], v[164:171], v[120:123], v248, v250 op_sel_hi:[0,0,0]
	v_mfma_scale_f32_16x16x128_f8f6f4 v[116:119], v[8:15], v[172:179], v[116:119], v248, v250 op_sel_hi:[0,0,0]
	v_mfma_scale_f32_16x16x128_f8f6f4 v[112:115], v[0:7], v[172:179], v[112:115], v248, v250 op_sel_hi:[0,0,0]
	v_mfma_scale_f32_16x16x128_f8f6f4 v[108:111], v[8:15], v[180:187], v[108:111], v248, v250 op_sel_hi:[0,0,0]
	v_mfma_scale_f32_16x16x128_f8f6f4 v[104:107], v[0:7], v[180:187], v[104:107], v248, v250 op_sel_hi:[0,0,0]
	v_mfma_scale_f32_16x16x128_f8f6f4 v[100:103], v[8:15], v[188:195], v[100:103], v248, v250 op_sel_hi:[0,0,0]
	v_mfma_scale_f32_16x16x128_f8f6f4 v[96:99], v[0:7], v[188:195], v[96:99], v248, v250 op_sel_hi:[0,0,0]
	s_setprio 0
	s_barrier
	s_add_u32 s34, s88, 0x180
	s_addc_u32 s35, s89, 0
	ds_read_b128 v[164:167], v253 offset:49152
	ds_read_b128 v[168:171], v253 offset:50176
	ds_read_b128 v[172:175], v253 offset:51200
	ds_read_b128 v[176:179], v253 offset:52224
	ds_read_b128 v[180:183], v253 offset:53248
	ds_read_b128 v[184:187], v253 offset:54272
	ds_read_b128 v[188:191], v253 offset:55296
	ds_read_b128 v[192:195], v253 offset:56320
	s_add_u32 s46, s90, 0x180
	s_mov_b32 m0, s65
	s_nop 0
	global_load_lds_dwordx4 v161, s[34:35]
	s_addc_u32 s47, s91, 0
	s_mov_b32 m0, s66
	s_nop 0
	global_load_lds_dwordx4 v161, s[46:47]
	s_add_u32 s34, s92, 0x180
	s_addc_u32 s35, s93, 0
	s_add_u32 s46, s96, 0x180
	s_mov_b32 m0, s78
	s_nop 0
	global_load_lds_dwordx4 v161, s[34:35]
	s_addc_u32 s47, s97, 0
	s_mov_b32 m0, s79
	s_nop 0
	global_load_lds_dwordx4 v161, s[46:47]
	s_add_u32 s34, s77, 0x180
	s_addc_u32 s35, s80, 0
	s_add_u32 s46, s94, 0x180
	s_mov_b32 m0, s67
	s_nop 0
	global_load_lds_dwordx4 v160, s[34:35]
	s_addc_u32 s47, s95, 0
	s_mov_b32 m0, s73
	s_nop 0
	global_load_lds_dwordx4 v160, s[46:47]
	s_waitcnt vmcnt(8)
	s_waitcnt lgkmcnt(0)
	s_barrier
	s_setprio 1
	s_waitcnt lgkmcnt(6)
	v_mfma_scale_f32_16x16x128_f8f6f4 v[92:95], v[24:31], v[164:171], v[92:95], v248, v250 op_sel_hi:[0,0,0]
	v_mfma_scale_f32_16x16x128_f8f6f4 v[88:91], v[16:23], v[164:171], v[88:91], v248, v250 op_sel_hi:[0,0,0]
	s_waitcnt lgkmcnt(4)
	v_mfma_scale_f32_16x16x128_f8f6f4 v[84:87], v[24:31], v[172:179], v[84:87], v248, v250 op_sel_hi:[0,0,0]
	v_mfma_scale_f32_16x16x128_f8f6f4 v[80:83], v[16:23], v[172:179], v[80:83], v248, v250 op_sel_hi:[0,0,0]
	s_waitcnt lgkmcnt(2)
	v_mfma_scale_f32_16x16x128_f8f6f4 v[76:79], v[24:31], v[180:187], v[76:79], v248, v250 op_sel_hi:[0,0,0]
	v_mfma_scale_f32_16x16x128_f8f6f4 v[72:75], v[16:23], v[180:187], v[72:75], v248, v250 op_sel_hi:[0,0,0]
	s_waitcnt lgkmcnt(0)
	v_mfma_scale_f32_16x16x128_f8f6f4 v[68:71], v[24:31], v[188:195], v[68:71], v248, v250 op_sel_hi:[0,0,0]
	v_mfma_scale_f32_16x16x128_f8f6f4 v[64:67], v[16:23], v[188:195], v[64:67], v248, v250 op_sel_hi:[0,0,0]
	s_setprio 0
	s_setprio 1
	v_mfma_scale_f32_16x16x128_f8f6f4 v[60:63], v[8:15], v[164:171], v[60:63], v248, v250 op_sel_hi:[0,0,0]
	v_mfma_scale_f32_16x16x128_f8f6f4 v[56:59], v[0:7], v[164:171], v[56:59], v248, v250 op_sel_hi:[0,0,0]
	v_mfma_scale_f32_16x16x128_f8f6f4 v[52:55], v[8:15], v[172:179], v[52:55], v248, v250 op_sel_hi:[0,0,0]
	v_mfma_scale_f32_16x16x128_f8f6f4 v[48:51], v[0:7], v[172:179], v[48:51], v248, v250 op_sel_hi:[0,0,0]
	v_mfma_scale_f32_16x16x128_f8f6f4 v[44:47], v[8:15], v[180:187], v[44:47], v248, v250 op_sel_hi:[0,0,0]
	v_mfma_scale_f32_16x16x128_f8f6f4 v[40:43], v[0:7], v[180:187], v[40:43], v248, v250 op_sel_hi:[0,0,0]
	v_mfma_scale_f32_16x16x128_f8f6f4 v[36:39], v[8:15], v[188:195], v[36:39], v248, v250 op_sel_hi:[0,0,0]
	v_mfma_scale_f32_16x16x128_f8f6f4 v[32:35], v[0:7], v[188:195], v[32:35], v248, v250 op_sel_hi:[0,0,0]
	s_setprio 0
	s_barrier
	s_add_u32 s44, s44, 0x100
	s_addc_u32 s45, s45, 0
	s_cmp_ge_i32 s75, s2
	s_cbranch_scc0 .LBB0_942
	s_branch .LBB0_943

.LBB0_1016:
	s_cmp_lt_i32 s2, 3
	s_cbranch_scc1 .Lhz_1018
	s_mul_i32 s13, s47, 3
	s_mul_hi_u32 s19, s46, 3
	s_add_i32 s10, s2, -2
	s_add_i32 s24, s19, s13
	s_mul_i32 s25, s46, 3
	s_add_u32 s13, s38, s25
	s_addc_u32 s19, s39, s24
	s_add_u32 s13, s6, s13
	s_addc_u32 s19, s7, s19
	s_lshl_b64 s[48:49], s[46:47], 1
	s_waitcnt lgkmcnt(0)
	v_writelane_b32 v254, s40, 0
	s_mov_b32 s1, s20
	s_mov_b64 s[20:21], s[26:27]
	s_add_u32 s26, s34, s38
	v_writelane_b32 v254, s41, 1
	s_addc_u32 s27, s35, s39
	v_writelane_b32 v254, s42, 2
	s_add_u32 s33, s26, s25
	v_writelane_b32 v254, s43, 3
	s_mov_b64 s[42:43], s[36:37]
	s_addc_u32 s36, s27, s24
	s_add_u32 s33, s6, s33
	s_addc_u32 s58, s7, s36
	s_add_u32 s59, s6, s25
	s_addc_u32 s68, s7, s24
	s_add_u32 s36, s34, s25
	s_addc_u32 s37, s35, s24
	s_add_u32 s69, s6, s36
	s_addc_u32 s70, s7, s37
	s_add_u32 s36, s38, s48
	s_addc_u32 s37, s39, s49
	s_add_u32 s71, s6, s36
	s_addc_u32 s72, s7, s37
	s_add_u32 s26, s26, s48
	s_addc_u32 s27, s27, s49
	s_add_u32 s74, s6, s26
	s_addc_u32 s75, s7, s27
	s_add_u32 s87, s6, s48
	s_addc_u32 s88, s7, s49
	s_add_u32 s26, s34, s48
	s_addc_u32 s27, s35, s49
	s_add_u32 s89, s6, s26
	s_addc_u32 s90, s7, s27
	s_add_u32 s91, s4, s25
	s_addc_u32 s92, s5, s24
	s_add_u32 s25, s52, s25
	s_addc_u32 s24, s53, s24
	s_add_u32 s93, s4, s25
	s_addc_u32 s94, s5, s24
	s_add_u32 s24, s56, s48
	s_addc_u32 s25, s57, s49
	s_add_u32 s95, s4, s24
	s_addc_u32 s96, s5, s25
	s_add_u32 s24, s52, s56
	s_addc_u32 s25, s53, s57
	s_add_u32 s26, s24, s48
	s_addc_u32 s27, s25, s49
	s_add_u32 s97, s4, s26
	s_addc_u32 vcc_lo, s5, s27
	s_add_u32 vcc_hi, s4, s48
	s_addc_u32 s61, s5, s49
	s_add_u32 s26, s52, s48
	s_addc_u32 s27, s53, s49
	s_add_u32 s36, s4, s26
	s_addc_u32 s37, s5, s27
	s_add_u32 s26, s56, s46
	s_addc_u32 s27, s57, s47
	s_add_u32 s60, s4, s26
	s_addc_u32 s78, s5, s27
	s_add_u32 s24, s24, s46
	s_addc_u32 s25, s25, s47
	s_add_u32 s40, s4, s24
	s_addc_u32 s41, s5, s25
	s_mov_b32 s79, 0
	s_mov_b64 s[50:51], 0
	s_cmp_eq_u32 s98, 0
	s_cbranch_scc1 .Lhf_1018
	ds_read_b128 v[130:133], v173
	ds_read_b128 v[134:137], v173 offset:1024
	ds_read_b128 v[138:141], v173 offset:2048
	ds_read_b128 v[142:145], v173 offset:3072
	ds_read_b128 v[146:149], v174
	ds_read_b128 v[150:153], v174 offset:1024
	ds_read_b128 v[154:157], v174 offset:2048
	ds_read_b128 v[162:165], v174 offset:3072
	s_add_i32 s79, s79, 2
	s_add_u32 s54, vcc_hi, s50
	s_addc_u32 s55, s61, s51
	ds_read_b128 v[166:169], v175
	ds_read_b128 v[178:181], v175 offset:1024
	ds_read_b128 v[182:185], v175 offset:2048
	ds_read_b128 v[186:189], v175 offset:3072
	ds_read_b128 v[190:193], v175 offset:4096
	ds_read_b128 v[194:197], v175 offset:5120
	ds_read_b128 v[198:201], v175 offset:6144
	ds_read_b128 v[202:205], v175 offset:7168
	s_add_u32 s24, s60, s50
	s_addc_u32 s25, s78, s51
	s_add_u32 s26, s40, s50
	s_mov_b32 m0, s85
	s_nop 0
	global_load_lds_dwordx4 v128, s[24:25]
	s_addc_u32 s27, s41, s51
	s_mov_b32 m0, s86
	s_nop 0
	global_load_lds_dwordx4 v128, s[26:27]
	s_waitcnt vmcnt(24)
	s_waitcnt lgkmcnt(0)
	s_barrier
	s_setprio 1
	s_waitcnt lgkmcnt(7)
	v_mfma_f32_16x16x32_bf16 v[124:127], v[130:133], v[166:169], 0
	v_mfma_f32_16x16x32_bf16 v[120:123], v[138:141], v[166:169], 0
	s_waitcnt lgkmcnt(5)
	v_mfma_f32_16x16x32_bf16 v[116:119], v[130:133], v[182:185], 0
	v_mfma_f32_16x16x32_bf16 v[112:115], v[138:141], v[182:185], 0
	s_waitcnt lgkmcnt(3)
	v_mfma_f32_16x16x32_bf16 v[108:111], v[130:133], v[190:193], 0
	v_mfma_f32_16x16x32_bf16 v[104:107], v[138:141], v[190:193], 0
	s_waitcnt lgkmcnt(1)
	v_mfma_f32_16x16x32_bf16 v[100:103], v[130:133], v[198:201], 0
	v_mfma_f32_16x16x32_bf16 v[96:99], v[138:141], v[198:201], 0
	v_mfma_f32_16x16x32_bf16 v[124:127], v[134:137], v[178:181], v[124:127]
	v_mfma_f32_16x16x32_bf16 v[120:123], v[142:145], v[178:181], v[120:123]
	v_mfma_f32_16x16x32_bf16 v[116:119], v[134:137], v[186:189], v[116:119]
	v_mfma_f32_16x16x32_bf16 v[112:115], v[142:145], v[186:189], v[112:115]
	v_mfma_f32_16x16x32_bf16 v[108:111], v[134:137], v[194:197], v[108:111]
	v_mfma_f32_16x16x32_bf16 v[104:107], v[142:145], v[194:197], v[104:107]
	s_waitcnt lgkmcnt(0)
	v_mfma_f32_16x16x32_bf16 v[100:103], v[134:137], v[202:205], v[100:103]
	v_mfma_f32_16x16x32_bf16 v[96:99], v[142:145], v[202:205], v[96:99]
	s_setprio 0
	s_setprio 1
	v_mfma_f32_16x16x32_bf16 v[92:95], v[146:149], v[166:169], 0
	v_mfma_f32_16x16x32_bf16 v[88:91], v[154:157], v[166:169], 0
	v_mfma_f32_16x16x32_bf16 v[84:87], v[146:149], v[182:185], 0
	v_mfma_f32_16x16x32_bf16 v[80:83], v[154:157], v[182:185], 0
	v_mfma_f32_16x16x32_bf16 v[76:79], v[146:149], v[190:193], 0
	v_mfma_f32_16x16x32_bf16 v[72:75], v[154:157], v[190:193], 0
	v_mfma_f32_16x16x32_bf16 v[68:71], v[146:149], v[198:201], 0
	v_mfma_f32_16x16x32_bf16 v[64:67], v[154:157], v[198:201], 0
	v_mfma_f32_16x16x32_bf16 v[92:95], v[150:153], v[178:181], v[92:95]
	v_mfma_f32_16x16x32_bf16 v[88:91], v[162:165], v[178:181], v[88:91]
	v_mfma_f32_16x16x32_bf16 v[84:87], v[150:153], v[186:189], v[84:87]
	v_mfma_f32_16x16x32_bf16 v[80:83], v[162:165], v[186:189], v[80:83]
	v_mfma_f32_16x16x32_bf16 v[76:79], v[150:153], v[194:197], v[76:79]
	v_mfma_f32_16x16x32_bf16 v[72:75], v[162:165], v[194:197], v[72:75]
	v_mfma_f32_16x16x32_bf16 v[68:71], v[150:153], v[202:205], v[68:71]
	v_mfma_f32_16x16x32_bf16 v[64:67], v[162:165], v[202:205], v[64:67]
	s_setprio 0
	s_barrier
	s_add_u32 s24, s87, s50
	s_addc_u32 s25, s88, s51
	s_add_u32 s26, s89, s50
	ds_read_b128 v[166:169], v175 offset:16384
	ds_read_b128 v[178:181], v175 offset:17408
	ds_read_b128 v[182:185], v175 offset:18432
	ds_read_b128 v[186:189], v175 offset:19456
	ds_read_b128 v[190:193], v175 offset:20480
	ds_read_b128 v[194:197], v175 offset:21504
	ds_read_b128 v[198:201], v175 offset:22528
	ds_read_b128 v[202:205], v175 offset:23552
	s_addc_u32 s27, s90, s51
	s_mov_b32 m0, s62
	s_nop 0
	global_load_lds_dwordx4 v129, s[24:25]
	s_add_u32 s24, s71, s50
	s_mov_b32 m0, s63
	s_nop 0
	global_load_lds_dwordx4 v129, s[26:27]
	s_addc_u32 s25, s72, s51
	s_add_u32 s26, s74, s50
	s_mov_b32 m0, s64
	s_nop 0
	global_load_lds_dwordx4 v129, s[24:25]
	s_addc_u32 s27, s75, s51
	s_mov_b32 m0, s65
	s_nop 0
	global_load_lds_dwordx4 v129, s[26:27]
	s_add_u32 s24, s36, s50
	s_mov_b32 m0, s3
	s_nop 0
	global_load_lds_dwordx4 v128, s[54:55]
	s_addc_u32 s25, s37, s51
	s_mov_b32 m0, s66
	s_nop 0
	global_load_lds_dwordx4 v128, s[24:25]
	s_waitcnt vmcnt(24)
	s_waitcnt lgkmcnt(0)
	s_barrier
	s_setprio 1
	s_waitcnt lgkmcnt(7)
	v_mfma_f32_16x16x32_bf16 v[60:63], v[130:133], v[166:169], 0
	v_mfma_f32_16x16x32_bf16 v[56:59], v[138:141], v[166:169], 0
	s_waitcnt lgkmcnt(5)
	v_mfma_f32_16x16x32_bf16 v[52:55], v[130:133], v[182:185], 0
	v_mfma_f32_16x16x32_bf16 v[48:51], v[138:141], v[182:185], 0
	s_waitcnt lgkmcnt(3)
	v_mfma_f32_16x16x32_bf16 v[44:47], v[130:133], v[190:193], 0
	v_mfma_f32_16x16x32_bf16 v[40:43], v[138:141], v[190:193], 0
	s_waitcnt lgkmcnt(1)
	v_mfma_f32_16x16x32_bf16 v[36:39], v[130:133], v[198:201], 0
	v_mfma_f32_16x16x32_bf16 v[32:35], v[138:141], v[198:201], 0
	v_mfma_f32_16x16x32_bf16 v[60:63], v[134:137], v[178:181], v[60:63]
	v_mfma_f32_16x16x32_bf16 v[56:59], v[142:145], v[178:181], v[56:59]
	v_mfma_f32_16x16x32_bf16 v[52:55], v[134:137], v[186:189], v[52:55]
	v_mfma_f32_16x16x32_bf16 v[48:51], v[142:145], v[186:189], v[48:51]
	v_mfma_f32_16x16x32_bf16 v[44:47], v[134:137], v[194:197], v[44:47]
	v_mfma_f32_16x16x32_bf16 v[40:43], v[142:145], v[194:197], v[40:43]
	s_waitcnt lgkmcnt(0)
	v_mfma_f32_16x16x32_bf16 v[36:39], v[134:137], v[202:205], v[36:39]
	v_mfma_f32_16x16x32_bf16 v[32:35], v[142:145], v[202:205], v[32:35]
	s_setprio 0
	s_setprio 1
	v_mfma_f32_16x16x32_bf16 v[28:31], v[146:149], v[166:169], 0
	v_mfma_f32_16x16x32_bf16 v[24:27], v[154:157], v[166:169], 0
	v_mfma_f32_16x16x32_bf16 v[20:23], v[146:149], v[182:185], 0
	v_mfma_f32_16x16x32_bf16 v[16:19], v[154:157], v[182:185], 0
	v_mfma_f32_16x16x32_bf16 v[12:15], v[146:149], v[190:193], 0
	v_mfma_f32_16x16x32_bf16 v[8:11], v[154:157], v[190:193], 0
	v_mfma_f32_16x16x32_bf16 v[4:7], v[146:149], v[198:201], 0
	v_mfma_f32_16x16x32_bf16 v[0:3], v[154:157], v[198:201], 0
	v_mfma_f32_16x16x32_bf16 v[28:31], v[150:153], v[178:181], v[28:31]
	v_mfma_f32_16x16x32_bf16 v[24:27], v[162:165], v[178:181], v[24:27]
	v_mfma_f32_16x16x32_bf16 v[20:23], v[150:153], v[186:189], v[20:23]
	v_mfma_f32_16x16x32_bf16 v[16:19], v[162:165], v[186:189], v[16:19]
	v_mfma_f32_16x16x32_bf16 v[12:15], v[150:153], v[194:197], v[12:15]
	v_mfma_f32_16x16x32_bf16 v[8:11], v[162:165], v[194:197], v[8:11]
	v_mfma_f32_16x16x32_bf16 v[4:7], v[150:153], v[202:205], v[4:7]
	v_mfma_f32_16x16x32_bf16 v[0:3], v[162:165], v[202:205], v[0:3]
	s_setprio 0
	s_barrier
	ds_read_b128 v[130:133], v176
	ds_read_b128 v[134:137], v176 offset:1024
	ds_read_b128 v[138:141], v176 offset:2048
	ds_read_b128 v[142:145], v176 offset:3072
	ds_read_b128 v[146:149], v177
	ds_read_b128 v[150:153], v177 offset:1024
	ds_read_b128 v[154:157], v177 offset:2048
	ds_read_b128 v[162:165], v177 offset:3072
	ds_read_b128 v[166:169], v175 offset:32768
	ds_read_b128 v[178:181], v175 offset:33792
	ds_read_b128 v[182:185], v175 offset:34816
	ds_read_b128 v[186:189], v175 offset:35840
	ds_read_b128 v[190:193], v175 offset:36864
	ds_read_b128 v[194:197], v175 offset:37888
	ds_read_b128 v[198:201], v175 offset:38912
	ds_read_b128 v[202:205], v175 offset:39936
	s_add_u32 s24, s95, s50
	s_addc_u32 s25, s96, s51
	s_add_u32 s26, s97, s50
	s_mov_b32 m0, s67
	s_nop 0
	global_load_lds_dwordx4 v128, s[24:25]
	s_addc_u32 s27, vcc_lo, s51
	s_mov_b32 m0, s73
	s_nop 0
	global_load_lds_dwordx4 v128, s[26:27]
	s_waitcnt vmcnt(8)
	s_waitcnt lgkmcnt(0)
	s_barrier
	s_setprio 1
	s_waitcnt lgkmcnt(7)
	v_mfma_f32_16x16x32_bf16 v[124:127], v[130:133], v[166:169], v[124:127]
	v_mfma_f32_16x16x32_bf16 v[120:123], v[138:141], v[166:169], v[120:123]
	s_waitcnt lgkmcnt(5)
	v_mfma_f32_16x16x32_bf16 v[116:119], v[130:133], v[182:185], v[116:119]
	v_mfma_f32_16x16x32_bf16 v[112:115], v[138:141], v[182:185], v[112:115]
	s_waitcnt lgkmcnt(3)
	v_mfma_f32_16x16x32_bf16 v[108:111], v[130:133], v[190:193], v[108:111]
	v_mfma_f32_16x16x32_bf16 v[104:107], v[138:141], v[190:193], v[104:107]
	s_waitcnt lgkmcnt(1)
	v_mfma_f32_16x16x32_bf16 v[100:103], v[130:133], v[198:201], v[100:103]
	v_mfma_f32_16x16x32_bf16 v[96:99], v[138:141], v[198:201], v[96:99]
	v_mfma_f32_16x16x32_bf16 v[124:127], v[134:137], v[178:181], v[124:127]
	v_mfma_f32_16x16x32_bf16 v[120:123], v[142:145], v[178:181], v[120:123]
	v_mfma_f32_16x16x32_bf16 v[116:119], v[134:137], v[186:189], v[116:119]
	v_mfma_f32_16x16x32_bf16 v[112:115], v[142:145], v[186:189], v[112:115]
	v_mfma_f32_16x16x32_bf16 v[108:111], v[134:137], v[194:197], v[108:111]
	v_mfma_f32_16x16x32_bf16 v[104:107], v[142:145], v[194:197], v[104:107]
	s_waitcnt lgkmcnt(0)
	v_mfma_f32_16x16x32_bf16 v[100:103], v[134:137], v[202:205], v[100:103]
	v_mfma_f32_16x16x32_bf16 v[96:99], v[142:145], v[202:205], v[96:99]
	s_setprio 0
	s_setprio 1
	v_mfma_f32_16x16x32_bf16 v[92:95], v[146:149], v[166:169], v[92:95]
	v_mfma_f32_16x16x32_bf16 v[88:91], v[154:157], v[166:169], v[88:91]
	v_mfma_f32_16x16x32_bf16 v[84:87], v[146:149], v[182:185], v[84:87]
	v_mfma_f32_16x16x32_bf16 v[80:83], v[154:157], v[182:185], v[80:83]
	v_mfma_f32_16x16x32_bf16 v[76:79], v[146:149], v[190:193], v[76:79]
	v_mfma_f32_16x16x32_bf16 v[72:75], v[154:157], v[190:193], v[72:75]
	v_mfma_f32_16x16x32_bf16 v[68:71], v[146:149], v[198:201], v[68:71]
	v_mfma_f32_16x16x32_bf16 v[64:67], v[154:157], v[198:201], v[64:67]
	v_mfma_f32_16x16x32_bf16 v[92:95], v[150:153], v[178:181], v[92:95]
	v_mfma_f32_16x16x32_bf16 v[88:91], v[162:165], v[178:181], v[88:91]
	v_mfma_f32_16x16x32_bf16 v[84:87], v[150:153], v[186:189], v[84:87]
	v_mfma_f32_16x16x32_bf16 v[80:83], v[162:165], v[186:189], v[80:83]
	v_mfma_f32_16x16x32_bf16 v[76:79], v[150:153], v[194:197], v[76:79]
	v_mfma_f32_16x16x32_bf16 v[72:75], v[162:165], v[194:197], v[72:75]
	v_mfma_f32_16x16x32_bf16 v[68:71], v[150:153], v[202:205], v[68:71]
	v_mfma_f32_16x16x32_bf16 v[64:67], v[162:165], v[202:205], v[64:67]
	s_setprio 0
	s_barrier
	s_add_u32 s24, s59, s50
	s_addc_u32 s25, s68, s51
	s_add_u32 s26, s69, s50
	s_addc_u32 s27, s70, s51
	ds_read_b128 v[166:169], v175 offset:49152
	ds_read_b128 v[178:181], v175 offset:50176
	ds_read_b128 v[182:185], v175 offset:51200
	ds_read_b128 v[186:189], v175 offset:52224
	ds_read_b128 v[190:193], v175 offset:53248
	ds_read_b128 v[194:197], v175 offset:54272
	ds_read_b128 v[198:201], v175 offset:55296
	ds_read_b128 v[202:205], v175 offset:56320
	s_mov_b32 m0, s9
	s_nop 0
	global_load_lds_dwordx4 v129, s[24:25]
	s_add_u32 s24, s13, s50
	s_addc_u32 s25, s19, s51
	s_mov_b32 m0, s80
	s_nop 0
	global_load_lds_dwordx4 v129, s[26:27]
	s_add_u32 s26, s33, s50
	s_addc_u32 s27, s58, s51
	s_mov_b32 m0, s83
	s_nop 0
	global_load_lds_dwordx4 v129, s[24:25]
	s_add_u32 s24, s91, s50
	s_mov_b32 m0, s84
	s_nop 0
	global_load_lds_dwordx4 v129, s[26:27]
	s_addc_u32 s25, s92, s51
	s_add_u32 s26, s93, s50
	s_mov_b32 m0, s81
	s_nop 0
	global_load_lds_dwordx4 v128, s[24:25]
	s_addc_u32 s27, s94, s51
	s_mov_b32 m0, s82
	s_nop 0
	global_load_lds_dwordx4 v128, s[26:27]
	s_waitcnt vmcnt(8)
	s_waitcnt lgkmcnt(0)
	s_barrier
	s_setprio 1
	s_waitcnt lgkmcnt(7)
	v_mfma_f32_16x16x32_bf16 v[60:63], v[130:133], v[166:169], v[60:63]
	v_mfma_f32_16x16x32_bf16 v[56:59], v[138:141], v[166:169], v[56:59]
	s_waitcnt lgkmcnt(5)
	v_mfma_f32_16x16x32_bf16 v[52:55], v[130:133], v[182:185], v[52:55]
	v_mfma_f32_16x16x32_bf16 v[48:51], v[138:141], v[182:185], v[48:51]
	s_waitcnt lgkmcnt(3)
	v_mfma_f32_16x16x32_bf16 v[44:47], v[130:133], v[190:193], v[44:47]
	v_mfma_f32_16x16x32_bf16 v[40:43], v[138:141], v[190:193], v[40:43]
	s_waitcnt lgkmcnt(1)
	v_mfma_f32_16x16x32_bf16 v[36:39], v[130:133], v[198:201], v[36:39]
	v_mfma_f32_16x16x32_bf16 v[32:35], v[138:141], v[198:201], v[32:35]
	v_mfma_f32_16x16x32_bf16 v[60:63], v[134:137], v[178:181], v[60:63]
	v_mfma_f32_16x16x32_bf16 v[56:59], v[142:145], v[178:181], v[56:59]
	v_mfma_f32_16x16x32_bf16 v[52:55], v[134:137], v[186:189], v[52:55]
	v_mfma_f32_16x16x32_bf16 v[48:51], v[142:145], v[186:189], v[48:51]
	v_mfma_f32_16x16x32_bf16 v[44:47], v[134:137], v[194:197], v[44:47]
	v_mfma_f32_16x16x32_bf16 v[40:43], v[142:145], v[194:197], v[40:43]
	s_waitcnt lgkmcnt(0)
	v_mfma_f32_16x16x32_bf16 v[36:39], v[134:137], v[202:205], v[36:39]
	v_mfma_f32_16x16x32_bf16 v[32:35], v[142:145], v[202:205], v[32:35]
	s_setprio 0
	s_setprio 1
	v_mfma_f32_16x16x32_bf16 v[28:31], v[146:149], v[166:169], v[28:31]
	v_mfma_f32_16x16x32_bf16 v[24:27], v[154:157], v[166:169], v[24:27]
	v_mfma_f32_16x16x32_bf16 v[20:23], v[146:149], v[182:185], v[20:23]
	v_mfma_f32_16x16x32_bf16 v[16:19], v[154:157], v[182:185], v[16:19]
	v_mfma_f32_16x16x32_bf16 v[12:15], v[146:149], v[190:193], v[12:15]
	v_mfma_f32_16x16x32_bf16 v[8:11], v[154:157], v[190:193], v[8:11]
	v_mfma_f32_16x16x32_bf16 v[4:7], v[146:149], v[198:201], v[4:7]
	v_mfma_f32_16x16x32_bf16 v[0:3], v[154:157], v[198:201], v[0:3]
	v_mfma_f32_16x16x32_bf16 v[28:31], v[150:153], v[178:181], v[28:31]
	v_mfma_f32_16x16x32_bf16 v[24:27], v[162:165], v[178:181], v[24:27]
	v_mfma_f32_16x16x32_bf16 v[20:23], v[150:153], v[186:189], v[20:23]
	v_mfma_f32_16x16x32_bf16 v[16:19], v[162:165], v[186:189], v[16:19]
	v_mfma_f32_16x16x32_bf16 v[12:15], v[150:153], v[194:197], v[12:15]
	v_mfma_f32_16x16x32_bf16 v[8:11], v[162:165], v[194:197], v[8:11]
	v_mfma_f32_16x16x32_bf16 v[4:7], v[150:153], v[202:205], v[4:7]
	v_mfma_f32_16x16x32_bf16 v[0:3], v[162:165], v[202:205], v[0:3]
	s_setprio 0
	s_barrier
	s_add_u32 s50, s50, s48
	s_addc_u32 s51, s51, s49
	s_cmp_ge_i32 s79, s10
	s_cbranch_scc0 .LBB0_1018
	s_branch .Lkloop_exit_1018
.Lhf_1018:
	ds_read_b128 v[130:133], v173
	ds_read_b128 v[134:137], v173 offset:1024
	ds_read_b128 v[138:141], v173 offset:2048
	ds_read_b128 v[142:145], v173 offset:3072
	ds_read_b128 v[146:149], v174
	ds_read_b128 v[150:153], v174 offset:1024
	ds_read_b128 v[154:157], v174 offset:2048
	ds_read_b128 v[162:165], v174 offset:3072
	s_add_i32 s79, s79, 2
	s_add_u32 s54, vcc_hi, s50
	s_addc_u32 s55, s61, s51
	ds_read_b128 v[166:169], v175
	ds_read_b128 v[178:181], v175 offset:1024
	ds_read_b128 v[182:185], v175 offset:2048
	ds_read_b128 v[186:189], v175 offset:3072
	ds_read_b128 v[190:193], v175 offset:4096
	ds_read_b128 v[194:197], v175 offset:5120
	ds_read_b128 v[198:201], v175 offset:6144
	ds_read_b128 v[202:205], v175 offset:7168
	s_add_u32 s24, s60, s50
	s_addc_u32 s25, s78, s51
	s_add_u32 s26, s40, s50
	s_mov_b32 m0, s85
	s_nop 0
	global_load_lds_dwordx4 v128, s[24:25]
	s_addc_u32 s27, s41, s51
	s_mov_b32 m0, s86
	s_nop 0
	global_load_lds_dwordx4 v128, s[26:27]
	s_waitcnt vmcnt(8)
	s_waitcnt lgkmcnt(0)
	s_barrier
	s_setprio 1
	s_waitcnt lgkmcnt(7)
	v_mfma_f32_16x16x32_bf16 v[124:127], v[130:133], v[166:169], 0
	v_mfma_f32_16x16x32_bf16 v[120:123], v[138:141], v[166:169], 0
	s_waitcnt lgkmcnt(5)
	v_mfma_f32_16x16x32_bf16 v[116:119], v[130:133], v[182:185], 0
	v_mfma_f32_16x16x32_bf16 v[112:115], v[138:141], v[182:185], 0
	s_waitcnt lgkmcnt(3)
	v_mfma_f32_16x16x32_bf16 v[108:111], v[130:133], v[190:193], 0
	v_mfma_f32_16x16x32_bf16 v[104:107], v[138:141], v[190:193], 0
	s_waitcnt lgkmcnt(1)
	v_mfma_f32_16x16x32_bf16 v[100:103], v[130:133], v[198:201], 0
	v_mfma_f32_16x16x32_bf16 v[96:99], v[138:141], v[198:201], 0
	v_mfma_f32_16x16x32_bf16 v[124:127], v[134:137], v[178:181], v[124:127]
	v_mfma_f32_16x16x32_bf16 v[120:123], v[142:145], v[178:181], v[120:123]
	v_mfma_f32_16x16x32_bf16 v[116:119], v[134:137], v[186:189], v[116:119]
	v_mfma_f32_16x16x32_bf16 v[112:115], v[142:145], v[186:189], v[112:115]
	v_mfma_f32_16x16x32_bf16 v[108:111], v[134:137], v[194:197], v[108:111]
	v_mfma_f32_16x16x32_bf16 v[104:107], v[142:145], v[194:197], v[104:107]
	s_waitcnt lgkmcnt(0)
	v_mfma_f32_16x16x32_bf16 v[100:103], v[134:137], v[202:205], v[100:103]
	v_mfma_f32_16x16x32_bf16 v[96:99], v[142:145], v[202:205], v[96:99]
	s_setprio 0
	s_setprio 1
	v_mfma_f32_16x16x32_bf16 v[92:95], v[146:149], v[166:169], 0
	v_mfma_f32_16x16x32_bf16 v[88:91], v[154:157], v[166:169], 0
	v_mfma_f32_16x16x32_bf16 v[84:87], v[146:149], v[182:185], 0
	v_mfma_f32_16x16x32_bf16 v[80:83], v[154:157], v[182:185], 0
	v_mfma_f32_16x16x32_bf16 v[76:79], v[146:149], v[190:193], 0
	v_mfma_f32_16x16x32_bf16 v[72:75], v[154:157], v[190:193], 0
	v_mfma_f32_16x16x32_bf16 v[68:71], v[146:149], v[198:201], 0
	v_mfma_f32_16x16x32_bf16 v[64:67], v[154:157], v[198:201], 0
	v_mfma_f32_16x16x32_bf16 v[92:95], v[150:153], v[178:181], v[92:95]
	v_mfma_f32_16x16x32_bf16 v[88:91], v[162:165], v[178:181], v[88:91]
	v_mfma_f32_16x16x32_bf16 v[84:87], v[150:153], v[186:189], v[84:87]
	v_mfma_f32_16x16x32_bf16 v[80:83], v[162:165], v[186:189], v[80:83]
	v_mfma_f32_16x16x32_bf16 v[76:79], v[150:153], v[194:197], v[76:79]
	v_mfma_f32_16x16x32_bf16 v[72:75], v[162:165], v[194:197], v[72:75]
	v_mfma_f32_16x16x32_bf16 v[68:71], v[150:153], v[202:205], v[68:71]
	v_mfma_f32_16x16x32_bf16 v[64:67], v[162:165], v[202:205], v[64:67]
	s_setprio 0
	s_barrier
	s_add_u32 s24, s87, s50
	s_addc_u32 s25, s88, s51
	s_add_u32 s26, s89, s50
	ds_read_b128 v[166:169], v175 offset:16384
	ds_read_b128 v[178:181], v175 offset:17408
	ds_read_b128 v[182:185], v175 offset:18432
	ds_read_b128 v[186:189], v175 offset:19456
	ds_read_b128 v[190:193], v175 offset:20480
	ds_read_b128 v[194:197], v175 offset:21504
	ds_read_b128 v[198:201], v175 offset:22528
	ds_read_b128 v[202:205], v175 offset:23552
	s_addc_u32 s27, s90, s51
	s_mov_b32 m0, s62
	s_nop 0
	global_load_lds_dwordx4 v129, s[24:25]
	s_add_u32 s24, s71, s50
	s_mov_b32 m0, s63
	s_nop 0
	global_load_lds_dwordx4 v129, s[26:27]
	s_addc_u32 s25, s72, s51
	s_add_u32 s26, s74, s50
	s_mov_b32 m0, s64
	s_nop 0
	global_load_lds_dwordx4 v129, s[24:25]
	s_addc_u32 s27, s75, s51
	s_mov_b32 m0, s65
	s_nop 0
	global_load_lds_dwordx4 v129, s[26:27]
	s_add_u32 s24, s36, s50
	s_mov_b32 m0, s3
	s_nop 0
	global_load_lds_dwordx4 v128, s[54:55]
	s_addc_u32 s25, s37, s51
	s_mov_b32 m0, s66
	s_nop 0
	global_load_lds_dwordx4 v128, s[24:25]
	s_waitcnt vmcnt(8)
	s_waitcnt lgkmcnt(0)
	s_barrier
	s_setprio 1
	s_waitcnt lgkmcnt(7)
	v_mfma_f32_16x16x32_bf16 v[60:63], v[130:133], v[166:169], 0
	v_mfma_f32_16x16x32_bf16 v[56:59], v[138:141], v[166:169], 0
	s_waitcnt lgkmcnt(5)
	v_mfma_f32_16x16x32_bf16 v[52:55], v[130:133], v[182:185], 0
	v_mfma_f32_16x16x32_bf16 v[48:51], v[138:141], v[182:185], 0
	s_waitcnt lgkmcnt(3)
	v_mfma_f32_16x16x32_bf16 v[44:47], v[130:133], v[190:193], 0
	v_mfma_f32_16x16x32_bf16 v[40:43], v[138:141], v[190:193], 0
	s_waitcnt lgkmcnt(1)
	v_mfma_f32_16x16x32_bf16 v[36:39], v[130:133], v[198:201], 0
	v_mfma_f32_16x16x32_bf16 v[32:35], v[138:141], v[198:201], 0
	v_mfma_f32_16x16x32_bf16 v[60:63], v[134:137], v[178:181], v[60:63]
	v_mfma_f32_16x16x32_bf16 v[56:59], v[142:145], v[178:181], v[56:59]
	v_mfma_f32_16x16x32_bf16 v[52:55], v[134:137], v[186:189], v[52:55]
	v_mfma_f32_16x16x32_bf16 v[48:51], v[142:145], v[186:189], v[48:51]
	v_mfma_f32_16x16x32_bf16 v[44:47], v[134:137], v[194:197], v[44:47]
	v_mfma_f32_16x16x32_bf16 v[40:43], v[142:145], v[194:197], v[40:43]
	s_waitcnt lgkmcnt(0)
	v_mfma_f32_16x16x32_bf16 v[36:39], v[134:137], v[202:205], v[36:39]
	v_mfma_f32_16x16x32_bf16 v[32:35], v[142:145], v[202:205], v[32:35]
	s_setprio 0
	s_setprio 1
	v_mfma_f32_16x16x32_bf16 v[28:31], v[146:149], v[166:169], 0
	v_mfma_f32_16x16x32_bf16 v[24:27], v[154:157], v[166:169], 0
	v_mfma_f32_16x16x32_bf16 v[20:23], v[146:149], v[182:185], 0
	v_mfma_f32_16x16x32_bf16 v[16:19], v[154:157], v[182:185], 0
	v_mfma_f32_16x16x32_bf16 v[12:15], v[146:149], v[190:193], 0
	v_mfma_f32_16x16x32_bf16 v[8:11], v[154:157], v[190:193], 0
	v_mfma_f32_16x16x32_bf16 v[4:7], v[146:149], v[198:201], 0
	v_mfma_f32_16x16x32_bf16 v[0:3], v[154:157], v[198:201], 0
	v_mfma_f32_16x16x32_bf16 v[28:31], v[150:153], v[178:181], v[28:31]
	v_mfma_f32_16x16x32_bf16 v[24:27], v[162:165], v[178:181], v[24:27]
	v_mfma_f32_16x16x32_bf16 v[20:23], v[150:153], v[186:189], v[20:23]
	v_mfma_f32_16x16x32_bf16 v[16:19], v[162:165], v[186:189], v[16:19]
	v_mfma_f32_16x16x32_bf16 v[12:15], v[150:153], v[194:197], v[12:15]
	v_mfma_f32_16x16x32_bf16 v[8:11], v[162:165], v[194:197], v[8:11]
	v_mfma_f32_16x16x32_bf16 v[4:7], v[150:153], v[202:205], v[4:7]
	v_mfma_f32_16x16x32_bf16 v[0:3], v[162:165], v[202:205], v[0:3]
	s_setprio 0
	s_barrier
	ds_read_b128 v[130:133], v176
	ds_read_b128 v[134:137], v176 offset:1024
	ds_read_b128 v[138:141], v176 offset:2048
	ds_read_b128 v[142:145], v176 offset:3072
	ds_read_b128 v[146:149], v177
	ds_read_b128 v[150:153], v177 offset:1024
	ds_read_b128 v[154:157], v177 offset:2048
	ds_read_b128 v[162:165], v177 offset:3072
	ds_read_b128 v[166:169], v175 offset:32768
	ds_read_b128 v[178:181], v175 offset:33792
	ds_read_b128 v[182:185], v175 offset:34816
	ds_read_b128 v[186:189], v175 offset:35840
	ds_read_b128 v[190:193], v175 offset:36864
	ds_read_b128 v[194:197], v175 offset:37888
	ds_read_b128 v[198:201], v175 offset:38912
	ds_read_b128 v[202:205], v175 offset:39936
	s_add_u32 s24, s95, s50
	s_addc_u32 s25, s96, s51
	s_add_u32 s26, s97, s50
	s_mov_b32 m0, s67
	s_nop 0
	global_load_lds_dwordx4 v128, s[24:25]
	s_addc_u32 s27, vcc_lo, s51
	s_mov_b32 m0, s73
	s_nop 0
	global_load_lds_dwordx4 v128, s[26:27]
	s_waitcnt vmcnt(8)
	s_waitcnt lgkmcnt(0)
	s_barrier
	s_setprio 1
	s_waitcnt lgkmcnt(7)
	v_mfma_f32_16x16x32_bf16 v[124:127], v[130:133], v[166:169], v[124:127]
	v_mfma_f32_16x16x32_bf16 v[120:123], v[138:141], v[166:169], v[120:123]
	s_waitcnt lgkmcnt(5)
	v_mfma_f32_16x16x32_bf16 v[116:119], v[130:133], v[182:185], v[116:119]
	v_mfma_f32_16x16x32_bf16 v[112:115], v[138:141], v[182:185], v[112:115]
	s_waitcnt lgkmcnt(3)
	v_mfma_f32_16x16x32_bf16 v[108:111], v[130:133], v[190:193], v[108:111]
	v_mfma_f32_16x16x32_bf16 v[104:107], v[138:141], v[190:193], v[104:107]
	s_waitcnt lgkmcnt(1)
	v_mfma_f32_16x16x32_bf16 v[100:103], v[130:133], v[198:201], v[100:103]
	v_mfma_f32_16x16x32_bf16 v[96:99], v[138:141], v[198:201], v[96:99]
	v_mfma_f32_16x16x32_bf16 v[124:127], v[134:137], v[178:181], v[124:127]
	v_mfma_f32_16x16x32_bf16 v[120:123], v[142:145], v[178:181], v[120:123]
	v_mfma_f32_16x16x32_bf16 v[116:119], v[134:137], v[186:189], v[116:119]
	v_mfma_f32_16x16x32_bf16 v[112:115], v[142:145], v[186:189], v[112:115]
	v_mfma_f32_16x16x32_bf16 v[108:111], v[134:137], v[194:197], v[108:111]
	v_mfma_f32_16x16x32_bf16 v[104:107], v[142:145], v[194:197], v[104:107]
	s_waitcnt lgkmcnt(0)
	v_mfma_f32_16x16x32_bf16 v[100:103], v[134:137], v[202:205], v[100:103]
	v_mfma_f32_16x16x32_bf16 v[96:99], v[142:145], v[202:205], v[96:99]
	s_setprio 0
	s_setprio 1
	v_mfma_f32_16x16x32_bf16 v[92:95], v[146:149], v[166:169], v[92:95]
	v_mfma_f32_16x16x32_bf16 v[88:91], v[154:157], v[166:169], v[88:91]
	v_mfma_f32_16x16x32_bf16 v[84:87], v[146:149], v[182:185], v[84:87]
	v_mfma_f32_16x16x32_bf16 v[80:83], v[154:157], v[182:185], v[80:83]
	v_mfma_f32_16x16x32_bf16 v[76:79], v[146:149], v[190:193], v[76:79]
	v_mfma_f32_16x16x32_bf16 v[72:75], v[154:157], v[190:193], v[72:75]
	v_mfma_f32_16x16x32_bf16 v[68:71], v[146:149], v[198:201], v[68:71]
	v_mfma_f32_16x16x32_bf16 v[64:67], v[154:157], v[198:201], v[64:67]
	v_mfma_f32_16x16x32_bf16 v[92:95], v[150:153], v[178:181], v[92:95]
	v_mfma_f32_16x16x32_bf16 v[88:91], v[162:165], v[178:181], v[88:91]
	v_mfma_f32_16x16x32_bf16 v[84:87], v[150:153], v[186:189], v[84:87]
	v_mfma_f32_16x16x32_bf16 v[80:83], v[162:165], v[186:189], v[80:83]
	v_mfma_f32_16x16x32_bf16 v[76:79], v[150:153], v[194:197], v[76:79]
	v_mfma_f32_16x16x32_bf16 v[72:75], v[162:165], v[194:197], v[72:75]
	v_mfma_f32_16x16x32_bf16 v[68:71], v[150:153], v[202:205], v[68:71]
	v_mfma_f32_16x16x32_bf16 v[64:67], v[162:165], v[202:205], v[64:67]
	s_setprio 0
	s_barrier
	s_add_u32 s24, s59, s50
	s_addc_u32 s25, s68, s51
	s_add_u32 s26, s69, s50
	s_addc_u32 s27, s70, s51
	ds_read_b128 v[166:169], v175 offset:49152
	ds_read_b128 v[178:181], v175 offset:50176
	ds_read_b128 v[182:185], v175 offset:51200
	ds_read_b128 v[186:189], v175 offset:52224
	ds_read_b128 v[190:193], v175 offset:53248
	ds_read_b128 v[194:197], v175 offset:54272
	ds_read_b128 v[198:201], v175 offset:55296
	ds_read_b128 v[202:205], v175 offset:56320
	s_mov_b32 m0, s9
	s_nop 0
	global_load_lds_dwordx4 v129, s[24:25]
	s_add_u32 s24, s13, s50
	s_addc_u32 s25, s19, s51
	s_mov_b32 m0, s80
	s_nop 0
	global_load_lds_dwordx4 v129, s[26:27]
	s_add_u32 s26, s33, s50
	s_addc_u32 s27, s58, s51
	s_mov_b32 m0, s83
	s_nop 0
	global_load_lds_dwordx4 v129, s[24:25]
	s_add_u32 s24, s91, s50
	s_mov_b32 m0, s84
	s_nop 0
	global_load_lds_dwordx4 v129, s[26:27]
	s_addc_u32 s25, s92, s51
	s_add_u32 s26, s93, s50
	s_mov_b32 m0, s81
	s_nop 0
	global_load_lds_dwordx4 v128, s[24:25]
	s_addc_u32 s27, s94, s51
	s_mov_b32 m0, s82
	s_nop 0
	global_load_lds_dwordx4 v128, s[26:27]
	s_waitcnt vmcnt(8)
	s_waitcnt lgkmcnt(0)
	s_barrier
	s_setprio 1
	s_waitcnt lgkmcnt(7)
	v_mfma_f32_16x16x32_bf16 v[60:63], v[130:133], v[166:169], v[60:63]
	v_mfma_f32_16x16x32_bf16 v[56:59], v[138:141], v[166:169], v[56:59]
	s_waitcnt lgkmcnt(5)
	v_mfma_f32_16x16x32_bf16 v[52:55], v[130:133], v[182:185], v[52:55]
	v_mfma_f32_16x16x32_bf16 v[48:51], v[138:141], v[182:185], v[48:51]
	s_waitcnt lgkmcnt(3)
	v_mfma_f32_16x16x32_bf16 v[44:47], v[130:133], v[190:193], v[44:47]
	v_mfma_f32_16x16x32_bf16 v[40:43], v[138:141], v[190:193], v[40:43]
	s_waitcnt lgkmcnt(1)
	v_mfma_f32_16x16x32_bf16 v[36:39], v[130:133], v[198:201], v[36:39]
	v_mfma_f32_16x16x32_bf16 v[32:35], v[138:141], v[198:201], v[32:35]
	v_mfma_f32_16x16x32_bf16 v[60:63], v[134:137], v[178:181], v[60:63]
	v_mfma_f32_16x16x32_bf16 v[56:59], v[142:145], v[178:181], v[56:59]
	v_mfma_f32_16x16x32_bf16 v[52:55], v[134:137], v[186:189], v[52:55]
	v_mfma_f32_16x16x32_bf16 v[48:51], v[142:145], v[186:189], v[48:51]
	v_mfma_f32_16x16x32_bf16 v[44:47], v[134:137], v[194:197], v[44:47]
	v_mfma_f32_16x16x32_bf16 v[40:43], v[142:145], v[194:197], v[40:43]
	s_waitcnt lgkmcnt(0)
	v_mfma_f32_16x16x32_bf16 v[36:39], v[134:137], v[202:205], v[36:39]
	v_mfma_f32_16x16x32_bf16 v[32:35], v[142:145], v[202:205], v[32:35]
	s_setprio 0
	s_setprio 1
	v_mfma_f32_16x16x32_bf16 v[28:31], v[146:149], v[166:169], v[28:31]
	v_mfma_f32_16x16x32_bf16 v[24:27], v[154:157], v[166:169], v[24:27]
	v_mfma_f32_16x16x32_bf16 v[20:23], v[146:149], v[182:185], v[20:23]
	v_mfma_f32_16x16x32_bf16 v[16:19], v[154:157], v[182:185], v[16:19]
	v_mfma_f32_16x16x32_bf16 v[12:15], v[146:149], v[190:193], v[12:15]
	v_mfma_f32_16x16x32_bf16 v[8:11], v[154:157], v[190:193], v[8:11]
	v_mfma_f32_16x16x32_bf16 v[4:7], v[146:149], v[198:201], v[4:7]
	v_mfma_f32_16x16x32_bf16 v[0:3], v[154:157], v[198:201], v[0:3]
	v_mfma_f32_16x16x32_bf16 v[28:31], v[150:153], v[178:181], v[28:31]
	v_mfma_f32_16x16x32_bf16 v[24:27], v[162:165], v[178:181], v[24:27]
	v_mfma_f32_16x16x32_bf16 v[20:23], v[150:153], v[186:189], v[20:23]
	v_mfma_f32_16x16x32_bf16 v[16:19], v[162:165], v[186:189], v[16:19]
	v_mfma_f32_16x16x32_bf16 v[12:15], v[150:153], v[194:197], v[12:15]
	v_mfma_f32_16x16x32_bf16 v[8:11], v[162:165], v[194:197], v[8:11]
	v_mfma_f32_16x16x32_bf16 v[4:7], v[150:153], v[202:205], v[4:7]
	v_mfma_f32_16x16x32_bf16 v[0:3], v[162:165], v[202:205], v[0:3]
	s_setprio 0
	s_barrier
	s_add_u32 s50, s50, s48
	s_addc_u32 s51, s51, s49
	s_cmp_ge_i32 s79, s10
	s_cbranch_scc0 .LBB0_1018
	s_branch .Lkloop_exit_1018
